# all plain stores made write-through (sc1) so the barrier-time L2 write-back has nothing left to flush
# baseline (speedup 1.0000x reference)
.LBB0_8:
	s_cmpk_gt_i32 s53, 0x67f
	s_mov_b64 s[48:49], -1
	s_cbranch_scc0 .LBB0_26
	s_cmpk_gt_u32 s53, 0x7bf
	s_cbranch_scc0 .LBB0_23
	s_cmpk_gt_u32 s53, 0x8bf
	s_cbranch_scc0 .LBB0_20
	s_cmpk_gt_u32 s53, 0x9bf
	s_cbranch_scc0 .LBB0_17
	s_cmpk_gt_u32 s53, 0xf3f
	s_cbranch_scc0 .LBB0_14
	s_and_b32 s4, s50, 0x7fffffc0
	s_addk_i32 s4, 0xc300
	s_and_b32 s33, s3, 0x3c0
	s_lshl_b32 s28, s33, 2
	v_or_b32_e32 v24, s4, v1
	v_mov_b32_e32 v25, v3
	v_lshl_add_u64 v[28:29], v[4:5], 0, s[28:29]
	v_lshlrev_b64 v[24:25], 12, v[24:25]
	v_lshl_add_u64 v[24:25], v[28:29], 0, v[24:25]
	v_add_u32_e32 v30, s4, v16
	v_mov_b32_e32 v31, v3
	flat_load_dwordx4 v[24:27], v[24:25]
	v_lshlrev_b64 v[30:31], 12, v[30:31]
	v_lshl_add_u64 v[28:29], v[28:29], 0, v[30:31]
	flat_load_dwordx4 v[28:31], v[28:29]
	v_add_u32_e32 v23, s33, v17
	v_mul_u32_u24_e32 v23, 0xb00, v23
	v_mov_b32_e32 v33, v3
	v_lshlrev_b32_e32 v32, 1, v23
	s_mov_b32 s5, s29
	v_lshl_add_u64 v[32:33], s[30:31], 0, v[32:33]
	v_lshl_add_u64 v[32:33], s[4:5], 1, v[32:33]
	v_lshl_add_u64 v[32:33], v[32:33], 0, v[2:3]
	s_mov_b64 s[48:49], 0
	s_waitcnt vmcnt(0) lgkmcnt(0)
	ds_write2_b32 v18, v24, v25 offset1:1
	ds_write2_b32 v18, v26, v27 offset0:2 offset1:3
	ds_write2_b32 v19, v28, v29 offset1:1
	ds_write2_b32 v20, v30, v31 offset1:1
	s_waitcnt lgkmcnt(0)
	s_barrier
	ds_read2_b32 v[24:25], v21 offset1:65
	ds_read2_b32 v[26:27], v21 offset0:130 offset1:195
	ds_read2_b32 v[28:29], v22 offset0:4 offset1:69
	ds_read2_b32 v[30:31], v22 offset0:134 offset1:199
	s_waitcnt lgkmcnt(3)
	v_cvt_pk_bf16_f32 v24, v24, v25
	s_waitcnt lgkmcnt(2)
	v_cvt_pk_bf16_f32 v25, v26, v27
	s_waitcnt lgkmcnt(1)
	v_cvt_pk_bf16_f32 v26, v28, v29
	s_waitcnt lgkmcnt(0)
	v_cvt_pk_bf16_f32 v27, v30, v31
	flat_store_dwordx4 v[32:33], v[24:27] sc1
	s_waitcnt lgkmcnt(0)
	s_barrier
.LBB0_14:
	s_andn2_b64 vcc, exec, s[48:49]
	s_cbranch_vccnz .LBB0_16
	s_add_i32 s4, s53, 0xf640
	s_and_b32 s5, s4, 0xffff
	s_mul_i32 s5, s5, 0xba2f
	s_lshr_b32 s28, s5, 16
	s_lshr_b32 s5, s5, 22
	s_mulk_i32 s5, 0x58
	s_sub_i32 s4, s4, s5
	s_and_b32 s5, s28, 0xffc0
	s_lshl_b32 s4, s4, 6
	s_and_b32 s4, s4, 0xffc0
	v_or_b32_e32 v23, s5, v1
	s_lshl_b32 s28, s4, 2
	v_mul_u32_u24_e32 v23, 0x1600, v23
	v_lshl_add_u64 v[28:29], v[6:7], 0, s[28:29]
	v_lshlrev_b32_e32 v24, 2, v23
	v_mov_b32_e32 v25, v3
	v_add_u32_e32 v23, s5, v16
	v_lshl_add_u64 v[24:25], v[28:29], 0, v[24:25]
	v_mul_u32_u24_e32 v23, 0x1600, v23
	flat_load_dwordx4 v[24:27], v[24:25]
	v_lshlrev_b32_e32 v30, 2, v23
	v_mov_b32_e32 v31, v3
	v_lshl_add_u64 v[28:29], v[28:29], 0, v[30:31]
	flat_load_dwordx4 v[28:31], v[28:29]
	v_mov_b32_e32 v33, v3
	v_add_lshl_u32 v32, v17, s4, 11
	v_lshl_add_u64 v[32:33], s[34:35], 0, v[32:33]
	s_lshl_b32 s28, s5, 1
	v_lshl_add_u64 v[32:33], v[32:33], 0, s[28:29]
	v_lshl_add_u64 v[32:33], v[32:33], 0, v[2:3]
	s_waitcnt vmcnt(0) lgkmcnt(0)
	ds_write2_b32 v18, v24, v25 offset1:1
	ds_write2_b32 v18, v26, v27 offset0:2 offset1:3
	ds_write2_b32 v19, v28, v29 offset1:1
	ds_write2_b32 v20, v30, v31 offset1:1
	s_waitcnt lgkmcnt(0)
	s_barrier
	ds_read2_b32 v[24:25], v21 offset1:65
	ds_read2_b32 v[26:27], v21 offset0:130 offset1:195
	ds_read2_b32 v[28:29], v22 offset0:4 offset1:69
	ds_read2_b32 v[30:31], v22 offset0:134 offset1:199
	s_waitcnt lgkmcnt(3)
	v_cvt_pk_bf16_f32 v24, v24, v25
	s_waitcnt lgkmcnt(2)
	v_cvt_pk_bf16_f32 v25, v26, v27
	s_waitcnt lgkmcnt(1)
	v_cvt_pk_bf16_f32 v26, v28, v29
	s_waitcnt lgkmcnt(0)
	v_cvt_pk_bf16_f32 v27, v30, v31
	flat_store_dwordx4 v[32:33], v[24:27] sc1
	s_waitcnt lgkmcnt(0)
	s_barrier

.LBB0_17:
	s_andn2_b64 vcc, exec, s[48:49]
	s_cbranch_vccnz .LBB0_19
	s_and_b32 s4, s50, 0x3fc0
	s_addk_i32 s4, 0xdd00
	s_and_b32 s33, s3, 0x3c0
	s_lshl_b32 s28, s33, 2
	v_or_b32_e32 v24, s4, v1
	v_mov_b32_e32 v25, v3
	v_lshl_add_u64 v[28:29], v[8:9], 0, s[28:29]
	v_lshlrev_b64 v[24:25], 12, v[24:25]
	v_lshl_add_u64 v[24:25], v[28:29], 0, v[24:25]
	v_add_u32_e32 v30, s4, v16
	v_mov_b32_e32 v31, v3
	flat_load_dwordx4 v[24:27], v[24:25]
	v_lshlrev_b64 v[30:31], 12, v[30:31]
	v_lshl_add_u64 v[28:29], v[28:29], 0, v[30:31]
	flat_load_dwordx4 v[28:31], v[28:29]
	v_mov_b32_e32 v33, v3
	v_add_lshl_u32 v32, s33, v17, 11
	s_mov_b32 s5, s29
	v_lshl_add_u64 v[32:33], s[36:37], 0, v[32:33]
	v_lshl_add_u64 v[32:33], s[4:5], 1, v[32:33]
	v_lshl_add_u64 v[32:33], v[32:33], 0, v[2:3]
	s_waitcnt vmcnt(0) lgkmcnt(0)
	ds_write2_b32 v18, v24, v25 offset1:1
	ds_write2_b32 v18, v26, v27 offset0:2 offset1:3
	ds_write2_b32 v19, v28, v29 offset1:1
	ds_write2_b32 v20, v30, v31 offset1:1
	s_waitcnt lgkmcnt(0)
	s_barrier
	ds_read2_b32 v[24:25], v21 offset1:65
	ds_read2_b32 v[26:27], v21 offset0:130 offset1:195
	ds_read2_b32 v[28:29], v22 offset0:4 offset1:69
	ds_read2_b32 v[30:31], v22 offset0:134 offset1:199
	s_waitcnt lgkmcnt(3)
	v_cvt_pk_bf16_f32 v24, v24, v25
	s_waitcnt lgkmcnt(2)
	v_cvt_pk_bf16_f32 v25, v26, v27
	s_waitcnt lgkmcnt(1)
	v_cvt_pk_bf16_f32 v26, v28, v29
	s_waitcnt lgkmcnt(0)
	v_cvt_pk_bf16_f32 v27, v30, v31
	flat_store_dwordx4 v[32:33], v[24:27] sc1
	s_waitcnt lgkmcnt(0)
	s_barrier

.LBB0_20:
	s_andn2_b64 vcc, exec, s[48:49]
	s_cbranch_vccnz .LBB0_22
	s_and_b32 s4, s50, 0x3fc0
	s_addk_i32 s4, 0xe100
	s_and_b32 s33, s3, 0x3c0
	s_lshl_b32 s28, s33, 2
	v_or_b32_e32 v24, s4, v1
	v_mov_b32_e32 v25, v3
	v_lshl_add_u64 v[28:29], v[10:11], 0, s[28:29]
	v_lshlrev_b64 v[24:25], 12, v[24:25]
	v_lshl_add_u64 v[24:25], v[28:29], 0, v[24:25]
	v_add_u32_e32 v30, s4, v16
	v_mov_b32_e32 v31, v3
	flat_load_dwordx4 v[24:27], v[24:25]
	v_lshlrev_b64 v[30:31], 12, v[30:31]
	v_lshl_add_u64 v[28:29], v[28:29], 0, v[30:31]
	flat_load_dwordx4 v[28:31], v[28:29]
	v_add_u32_e32 v23, s33, v17
	v_mul_u32_u24_e32 v23, 0x900, v23
	v_mov_b32_e32 v33, v3
	v_lshlrev_b32_e32 v32, 1, v23
	s_mov_b32 s5, s29
	v_lshl_add_u64 v[32:33], s[6:7], 0, v[32:33]
	v_lshl_add_u64 v[32:33], s[4:5], 1, v[32:33]
	v_lshl_add_u64 v[32:33], v[32:33], 0, v[2:3]
	v_add_co_u32_e32 v32, vcc, 0xf80000, v32
	s_waitcnt vmcnt(0) lgkmcnt(0)
	ds_write2_b32 v18, v24, v25 offset1:1
	ds_write2_b32 v18, v26, v27 offset0:2 offset1:3
	ds_write2_b32 v19, v28, v29 offset1:1
	ds_write2_b32 v20, v30, v31 offset1:1
	s_waitcnt lgkmcnt(0)
	s_barrier
	ds_read2_b32 v[24:25], v21 offset1:65
	ds_read2_b32 v[26:27], v21 offset0:130 offset1:195
	ds_read2_b32 v[28:29], v22 offset0:4 offset1:69
	ds_read2_b32 v[30:31], v22 offset0:134 offset1:199
	v_addc_co_u32_e32 v33, vcc, 0, v33, vcc
	s_waitcnt lgkmcnt(3)
	v_cvt_pk_bf16_f32 v24, v24, v25
	s_waitcnt lgkmcnt(2)
	v_cvt_pk_bf16_f32 v25, v26, v27
	s_waitcnt lgkmcnt(1)
	v_cvt_pk_bf16_f32 v26, v28, v29
	s_waitcnt lgkmcnt(0)
	v_cvt_pk_bf16_f32 v27, v30, v31
	flat_store_dwordx4 v[32:33], v[24:27] offset:2560 sc1
	s_waitcnt lgkmcnt(0)
	s_barrier

.LBB0_23:
	s_andn2_b64 vcc, exec, s[48:49]
	s_cbranch_vccnz .LBB0_25
	s_and_b32 s4, s50, 0x1fc0
	s_addk_i32 s4, 0xe600
	s_and_b32 s33, s3, 0x3c0
	s_lshl_b32 s28, s33, 2
	v_or_b32_e32 v24, s4, v1
	v_mov_b32_e32 v25, v3
	v_lshl_add_u64 v[28:29], v[12:13], 0, s[28:29]
	v_lshlrev_b64 v[24:25], 12, v[24:25]
	v_lshl_add_u64 v[24:25], v[28:29], 0, v[24:25]
	v_add_u32_e32 v30, s4, v16
	v_mov_b32_e32 v31, v3
	flat_load_dwordx4 v[24:27], v[24:25]
	v_lshlrev_b64 v[30:31], 12, v[30:31]
	v_lshl_add_u64 v[28:29], v[28:29], 0, v[30:31]
	flat_load_dwordx4 v[28:31], v[28:29]
	v_add_u32_e32 v23, s33, v17
	v_mul_u32_u24_e32 v23, 0x900, v23
	v_mov_b32_e32 v33, v3
	v_lshlrev_b32_e32 v32, 1, v23
	s_mov_b32 s5, s29
	v_lshl_add_u64 v[32:33], s[46:47], 0, v[32:33]
	v_lshl_add_u64 v[32:33], s[4:5], 1, v[32:33]
	v_lshl_add_u64 v[32:33], v[32:33], 0, v[2:3]
	s_waitcnt vmcnt(0) lgkmcnt(0)
	ds_write2_b32 v18, v24, v25 offset1:1
	ds_write2_b32 v18, v26, v27 offset0:2 offset1:3
	ds_write2_b32 v19, v28, v29 offset1:1
	ds_write2_b32 v20, v30, v31 offset1:1
	s_waitcnt lgkmcnt(0)
	s_barrier
	ds_read2_b32 v[24:25], v21 offset1:65
	ds_read2_b32 v[26:27], v21 offset0:130 offset1:195
	ds_read2_b32 v[28:29], v22 offset0:4 offset1:69
	ds_read2_b32 v[30:31], v22 offset0:134 offset1:199
	s_waitcnt lgkmcnt(3)
	v_cvt_pk_bf16_f32 v24, v24, v25
	s_waitcnt lgkmcnt(2)
	v_cvt_pk_bf16_f32 v25, v26, v27
	s_waitcnt lgkmcnt(1)
	v_cvt_pk_bf16_f32 v26, v28, v29
	s_waitcnt lgkmcnt(0)
	v_cvt_pk_bf16_f32 v27, v30, v31
	flat_store_dwordx4 v[32:33], v[24:27] sc1
	s_waitcnt lgkmcnt(0)
	s_barrier

.LBB0_26:
	s_andn2_b64 vcc, exec, s[48:49]
	s_cbranch_vccnz .LBB0_7
	s_mul_hi_i32 s4, s53, 0x4ec4ec4f
	s_lshr_b32 s5, s4, 31
	s_ashr_i32 s4, s4, 5
	s_add_i32 s5, s4, s5
	s_lshl_b32 s4, s5, 6
	s_mulk_i32 s5, 0xe600
	s_add_i32 s44, s3, s5
	s_ashr_i32 s45, s44, 31
	v_lshl_add_u64 v[28:29], s[44:45], 2, v[14:15]
	v_or_b32_e32 v23, s4, v1
	v_mad_i64_i32 v[24:25], s[48:49], v23, s52, v[28:29]
	flat_load_dwordx4 v[24:27], v[24:25]
	v_add_u32_e32 v23, s4, v16
	v_mad_i64_i32 v[28:29], s[48:49], v23, s52, v[28:29]
	flat_load_dwordx4 v[28:31], v[28:29]
	v_add_u32_e32 v32, s44, v17
	v_ashrrev_i32_e32 v33, 31, v32
	v_lshlrev_b64 v[32:33], 11, v[32:33]
	s_ashr_i32 s5, s4, 31
	v_lshl_add_u64 v[32:33], s[6:7], 0, v[32:33]
	v_lshl_add_u64 v[32:33], s[4:5], 1, v[32:33]
	v_lshl_add_u64 v[32:33], v[32:33], 0, v[2:3]
	s_waitcnt vmcnt(0) lgkmcnt(0)
	ds_write2_b32 v18, v24, v25 offset1:1
	ds_write2_b32 v18, v26, v27 offset0:2 offset1:3
	ds_write2_b32 v19, v28, v29 offset1:1
	ds_write2_b32 v20, v30, v31 offset1:1
	s_waitcnt lgkmcnt(0)
	s_barrier
	ds_read2_b32 v[24:25], v21 offset1:65
	ds_read2_b32 v[26:27], v21 offset0:130 offset1:195
	ds_read2_b32 v[28:29], v22 offset0:4 offset1:69
	ds_read2_b32 v[30:31], v22 offset0:134 offset1:199
	s_waitcnt lgkmcnt(3)
	v_cvt_pk_bf16_f32 v24, v24, v25
	s_waitcnt lgkmcnt(2)
	v_cvt_pk_bf16_f32 v25, v26, v27
	s_waitcnt lgkmcnt(1)
	v_cvt_pk_bf16_f32 v26, v28, v29
	s_waitcnt lgkmcnt(0)
	v_cvt_pk_bf16_f32 v27, v30, v31
	flat_store_dwordx4 v[32:33], v[24:27] sc1
	s_waitcnt lgkmcnt(0)
	s_barrier
	s_branch .LBB0_7

.LBB0_30:
	v_bfe_u32 v22, v14, 15, 1
	v_ashrrev_i32_e32 v4, 18, v14
	v_bfe_u32 v17, v14, 14, 1
	v_mad_u32_u24 v20, v22, 5, v4
	v_cmp_eq_u32_e32 vcc, 0, v17
	v_ashrrev_i32_e32 v21, 31, v20
	v_bfe_u32 v15, v14, 6, 8
	v_ashrrev_i32_e32 v16, 16, v14
	v_cndmask_b32_e32 v19, v10, v11, vcc
	v_cndmask_b32_e32 v18, v12, v13, vcc
	v_lshlrev_b64 v[20:21], 18, v[20:21]
	v_lshlrev_b32_e32 v4, 10, v15
	v_lshlrev_b32_e32 v23, 8, v16
	v_lshl_add_u64 v[18:19], v[18:19], 0, v[20:21]
	v_lshl_add_u64 v[18:19], v[18:19], 0, v[4:5]
	v_and_b32_e32 v4, 0x300, v23
	v_lshl_add_u64 v[18:19], v[18:19], 0, v[4:5]
	v_lshl_add_u64 v[18:19], v[18:19], 0, v[6:7]
	flat_load_dword v18, v[18:19]
	v_lshl_or_b32 v4, v22, 7, v9
	v_lshlrev_b32_e32 v19, 4, v17
	v_ashrrev_i32_e32 v17, 31, v16
	v_or3_b32 v4, v4, v19, v3
	v_lshlrev_b64 v[16:17], 17, v[16:17]
	v_add_u32_e32 v14, s28, v14
	v_lshl_or_b32 v16, v4, 9, v16
	v_cmp_lt_i32_e32 vcc, s3, v14
	v_lshl_add_u64 v[16:17], s[34:35], 0, v[16:17]
	v_lshlrev_b32_e32 v4, 1, v15
	s_or_b64 s[36:37], vcc, s[36:37]
	v_lshl_add_u64 v[16:17], v[16:17], 0, v[4:5]
	s_waitcnt vmcnt(0) lgkmcnt(0)
	v_cvt_pk_bf16_f32 v4, v18, v18
	flat_store_short v[16:17], v4 sc1
	s_andn2_b64 exec, exec, s[36:37]
	s_cbranch_execnz .LBB0_30

.LBB0_33:
	v_ashrrev_i32_e32 v7, 31, v6
	v_add_u32_e32 v8, s28, v8
	v_lshl_add_u64 v[10:11], v[6:7], 2, s[26:27]
	v_cmp_lt_i32_e32 vcc, s4, v8
	flat_load_dwordx2 v[10:11], v[10:11]
	v_add_u32_e32 v6, s3, v6
	s_or_b64 s[30:31], vcc, s[30:31]
	s_waitcnt vmcnt(0) lgkmcnt(0)
	v_cvt_pk_bf16_f32 v7, v10, v11
	flat_store_dword v[4:5], v7 sc1
	v_lshl_add_u64 v[4:5], v[4:5], 0, s[14:15]
	s_andn2_b64 exec, exec, s[30:31]
	s_cbranch_execnz .LBB0_33

.LBB0_36:
	v_lshl_add_u64 v[8:9], s[12:13], 0, v[4:5]
	flat_load_dword v7, v[8:9]
	v_lshl_add_u64 v[8:9], s[6:7], 0, v[4:5]
	v_add_co_u32_e32 v12, vcc, 0x51f6000, v8
	v_lshl_add_u64 v[10:11], s[24:25], 0, v[4:5]
	s_nop 0
	v_addc_co_u32_e32 v13, vcc, 0, v9, vcc
	v_add_u32_e32 v2, s28, v2
	s_waitcnt vmcnt(0) lgkmcnt(0)
	v_mul_f32_e32 v7, 0xbfb8aa3b, v7
	flat_store_dword v[12:13], v7 sc1
	flat_load_dword v7, v[10:11]
	v_add_co_u32_e32 v12, vcc, 0x51f8000, v8
	v_lshl_add_u64 v[10:11], s[8:9], 0, v[4:5]
	s_nop 0
	v_addc_co_u32_e32 v13, vcc, 0, v9, vcc
	v_cmp_lt_i32_e32 vcc, s37, v2
	s_or_b64 s[26:27], vcc, s[26:27]
	v_add_co_u32_e32 v8, vcc, 0x51fb000, v8
	v_lshl_add_u64 v[4:5], v[4:5], 0, s[14:15]
	s_nop 0
	v_addc_co_u32_e32 v9, vcc, 0, v9, vcc
	s_waitcnt vmcnt(0) lgkmcnt(0)
	v_mul_f32_e32 v7, 0xbfb8aa3b, v7
	flat_store_dword v[12:13], v7 offset:2048 sc1
	flat_load_dword v7, v[10:11]
	s_waitcnt vmcnt(0) lgkmcnt(0)
	v_mul_f32_e32 v10, 0xbfb8aa3b, v7
	v_fma_f32 v11, v7, s3, -v10
	v_rndne_f32_e32 v12, v10
	v_fmac_f32_e32 v11, 0xb2a5705f, v7
	v_sub_f32_e32 v10, v10, v12
	v_add_f32_e32 v10, v10, v11
	v_cvt_i32_f32_e32 v12, v12
	v_exp_f32_e32 v10, v10
	v_cmp_nlt_f32_e32 vcc, s29, v7
	v_ldexp_f32 v10, v10, v12
	s_nop 0
	v_cndmask_b32_e32 v10, 0, v10, vcc
	v_cmp_ngt_f32_e32 vcc, s30, v7
	s_nop 1
	v_cndmask_b32_e32 v7, v3, v10, vcc
	v_add_f32_e32 v12, 1.0, v7
	v_add_f32_e32 v13, -1.0, v12
	v_frexp_mant_f32_e32 v14, v12
	v_cvt_f64_f32_e32 v[10:11], v12
	v_sub_f32_e32 v15, v13, v12
	v_frexp_exp_i32_f64_e32 v10, v[10:11]
	v_cmp_gt_f32_e32 vcc, s34, v14
	v_sub_f32_e32 v13, v7, v13
	v_add_f32_e32 v11, 1.0, v15
	v_subbrev_co_u32_e32 v10, vcc, 0, v10, vcc
	v_add_f32_e32 v11, v13, v11
	v_sub_u32_e32 v13, 0, v10
	v_cvt_f32_i32_e32 v10, v10
	v_ldexp_f32 v12, v12, v13
	v_ldexp_f32 v11, v11, v13
	v_add_f32_e32 v13, -1.0, v12
	v_add_f32_e32 v14, 1.0, v12
	v_add_f32_e32 v15, 1.0, v13
	v_add_f32_e32 v16, -1.0, v14
	v_sub_f32_e32 v15, v12, v15
	v_sub_f32_e32 v12, v12, v16
	v_mul_f32_e32 v16, 0x3f317218, v10
	v_add_f32_e32 v15, v11, v15
	v_add_f32_e32 v11, v11, v12
	v_fma_f32 v12, v10, s35, -v16
	v_add_f32_e32 v17, v13, v15
	v_add_f32_e32 v18, v14, v11
	v_fmac_f32_e32 v12, 0xb102e308, v10
	v_sub_f32_e32 v10, v13, v17
	v_sub_f32_e32 v13, v14, v18
	v_rcp_f32_e32 v14, v18
	v_add_f32_e32 v19, v16, v12
	v_add_f32_e32 v11, v11, v13
	v_sub_f32_e32 v13, v19, v16
	v_sub_f32_e32 v12, v12, v13
	v_mul_f32_e32 v13, v17, v14
	v_add_f32_e32 v10, v15, v10
	v_mul_f32_e32 v15, v18, v13
	v_fma_f32 v16, v13, v18, -v15
	v_fmac_f32_e32 v16, v13, v11
	v_add_f32_e32 v20, v15, v16
	v_sub_f32_e32 v21, v17, v20
	v_sub_f32_e32 v15, v20, v15
	v_sub_f32_e32 v17, v17, v21
	v_sub_f32_e32 v15, v15, v16
	v_sub_f32_e32 v16, v17, v20
	v_add_f32_e32 v10, v10, v16
	v_add_f32_e32 v10, v15, v10
	v_add_f32_e32 v15, v21, v10
	v_mul_f32_e32 v16, v14, v15
	v_sub_f32_e32 v17, v21, v15
	v_mul_f32_e32 v20, v18, v16
	v_add_f32_e32 v10, v10, v17
	v_add_f32_e32 v17, v13, v16
	v_fma_f32 v18, v16, v18, -v20
	v_sub_f32_e32 v13, v17, v13
	v_fmac_f32_e32 v18, v16, v11
	v_sub_f32_e32 v11, v16, v13
	v_add_f32_e32 v13, v20, v18
	v_sub_f32_e32 v16, v13, v20
	v_sub_f32_e32 v20, v15, v13
	v_sub_f32_e32 v15, v15, v20
	v_sub_f32_e32 v13, v15, v13
	v_sub_f32_e32 v16, v16, v18
	v_add_f32_e32 v10, v10, v13
	v_add_f32_e32 v10, v16, v10
	v_add_f32_e32 v10, v20, v10
	v_mul_f32_e32 v10, v14, v10
	v_add_f32_e32 v10, v11, v10
	v_add_f32_e32 v11, v17, v10
	v_mul_f32_e32 v13, v11, v11
	v_fmamk_f32 v16, v13, 0x3e9b6dac, v6
	v_sub_f32_e32 v14, v11, v17
	v_ldexp_f32 v15, v11, 1
	v_mul_f32_e32 v11, v11, v13
	v_fmaak_f32 v13, v13, v16, 0x3f2aaada
	v_mul_f32_e32 v11, v11, v13
	v_add_f32_e32 v13, v15, v11
	v_sub_f32_e32 v10, v10, v14
	v_sub_f32_e32 v14, v13, v15
	v_ldexp_f32 v10, v10, 1
	v_sub_f32_e32 v11, v11, v14
	v_add_f32_e32 v10, v10, v11
	v_add_f32_e32 v11, v13, v10
	v_sub_f32_e32 v13, v11, v13
	v_add_f32_e32 v14, v19, v11
	v_sub_f32_e32 v10, v10, v13
	v_sub_f32_e32 v13, v14, v19
	v_sub_f32_e32 v15, v14, v13
	v_sub_f32_e32 v11, v11, v13
	v_add_f32_e32 v13, v12, v10
	v_sub_f32_e32 v15, v19, v15
	v_sub_f32_e32 v16, v13, v12
	v_add_f32_e32 v11, v11, v15
	v_sub_f32_e32 v15, v13, v16
	v_sub_f32_e32 v10, v10, v16
	v_sub_f32_e32 v12, v12, v15
	v_add_f32_e32 v11, v13, v11
	v_add_f32_e32 v10, v10, v12
	v_add_f32_e32 v12, v14, v11
	v_sub_f32_e32 v13, v12, v14
	v_sub_f32_e32 v11, v11, v13
	v_add_f32_e32 v10, v10, v11
	v_add_f32_e32 v10, v12, v10
	v_cmp_neq_f32_e32 vcc, s31, v7
	s_nop 1
	v_cndmask_b32_e32 v10, v3, v10, vcc
	v_cmp_lt_f32_e64 vcc, |v7|, s36
	s_nop 1
	v_cndmask_b32_e32 v7, v10, v7, vcc
	v_mul_f32_e32 v7, 0xc138aa3b, v7
	flat_store_dword v[8:9], v7 sc1
	s_andn2_b64 exec, exec, s[26:27]
	s_cbranch_execnz .LBB0_36

.LBB0_40:
	s_mov_b32 s6, 0xfffdc000
	v_add_co_u32_e64 v38, s[6:7], s6, v6
	v_add_co_u32_e32 v14, vcc, 0xfffd6000, v6
	s_nop 0
	v_addc_co_u32_e64 v39, s[6:7], -1, v7, s[6:7]
	s_mov_b32 s6, 0xfffe2000
	s_nop 0
	v_add_co_u32_e64 v40, s[6:7], s6, v6
	flat_load_dword v16, v[6:7]
	s_nop 0
	v_addc_co_u32_e64 v41, s[6:7], -1, v7, s[6:7]
	s_mov_b32 s6, 0xfffe8000
	s_nop 0
	v_add_co_u32_e64 v42, s[6:7], s6, v6
	v_addc_co_u32_e32 v15, vcc, -1, v7, vcc
	s_nop 0
	v_addc_co_u32_e64 v43, s[6:7], -1, v7, s[6:7]
	s_mov_b32 s6, 0xfffee000
	s_nop 0
	v_add_co_u32_e64 v44, s[6:7], s6, v6
	v_readlane_b32 s9, v27, s96
	s_nop 0
	v_addc_co_u32_e64 v45, s[6:7], -1, v7, s[6:7]
	s_mov_b32 s6, 0xffff4000
	s_nop 0
	v_add_co_u32_e64 v46, s[6:7], s6, v6
	v_readlane_b32 s11, v28, s96
	s_nop 0
	v_addc_co_u32_e64 v47, s[6:7], -1, v7, s[6:7]
	s_movk_i32 s6, 0xa000
	s_nop 0
	v_add_co_u32_e64 v48, s[6:7], s6, v6
	v_readlane_b32 s26, v29, s96
	s_nop 0
	v_addc_co_u32_e64 v49, s[6:7], -1, v7, s[6:7]
	flat_load_dword v38, v[38:39]
	s_nop 0
	flat_load_dword v40, v[40:41]
	s_nop 0
	flat_load_dword v42, v[42:43]
	s_nop 0
	flat_load_dword v44, v[44:45]
	s_nop 0
	flat_load_dword v46, v[46:47]
	s_nop 0
	flat_load_dword v18, v[48:49]
	s_nop 0
	flat_load_dword v14, v[14:15]
	v_readlane_b32 s97, v30, s96
	v_readlane_b32 s27, v31, s96
	v_readlane_b32 s10, v32, s96
	v_readlane_b32 s8, v33, s96
	v_readlane_b32 s29, v35, s96
	v_readlane_b32 s28, v36, s96
	s_add_i32 s36, s96, 1
	s_add_i32 s52, s96, 2
	v_readlane_b32 s7, v27, s36
	v_readlane_b32 s31, v28, s36
	v_readlane_b32 s34, v29, s36
	v_readlane_b32 s94, v30, s36
	v_readlane_b32 s35, v31, s36
	v_readlane_b32 s30, v32, s36
	v_readlane_b32 s6, v33, s36
	v_readlane_b32 s47, v35, s36
	v_readlane_b32 s46, v36, s36
	s_add_i32 s33, s96, 3
	v_readlane_b32 s37, v27, s52
	v_readlane_b32 s49, v28, s52
	v_readlane_b32 s50, v29, s52
	v_readlane_b32 s44, v30, s52
	v_readlane_b32 s51, v31, s52
	v_readlane_b32 s48, v32, s52
	v_readlane_b32 s36, v33, s52
	v_readlane_b32 s53, v35, s52
	v_readlane_b32 s52, v36, s52
	s_add_i32 s68, s96, 4
	v_readlane_b32 s55, v27, s33
	v_readlane_b32 s57, v28, s33
	v_readlane_b32 s58, v29, s33
	v_readlane_b32 s45, v30, s33
	v_readlane_b32 s59, v31, s33
	v_readlane_b32 s56, v32, s33
	v_readlane_b32 s54, v33, s33
	v_readlane_b32 s63, v35, s33
	v_readlane_b32 s62, v36, s33
	s_add_i32 s4, s96, 5
	v_readlane_b32 s61, v27, s68
	v_readlane_b32 s65, v28, s68
	v_readlane_b32 s66, v29, s68
	v_readlane_b32 s33, v30, s68
	v_readlane_b32 s67, v31, s68
	v_readlane_b32 s64, v32, s68
	v_readlane_b32 s60, v33, s68
	v_readlane_b32 s71, v35, s68
	v_readlane_b32 s70, v36, s68
	s_add_i32 s5, s96, 6
	v_readlane_b32 s69, v27, s4
	v_readlane_b32 s73, v28, s4
	v_readlane_b32 s74, v29, s4
	v_readlane_b32 vcc_lo, v30, s4
	v_readlane_b32 s75, v31, s4
	v_readlane_b32 s72, v32, s4
	v_readlane_b32 s68, v33, s4
	v_readlane_b32 s79, v35, s4
	v_readlane_b32 s78, v36, s4
	s_add_i32 s40, s96, 7
	v_readlane_b32 s77, v27, s5
	v_readlane_b32 s81, v28, s5
	v_readlane_b32 s82, v29, s5
	v_readlane_b32 vcc_hi, v30, s5
	v_readlane_b32 s83, v31, s5
	v_readlane_b32 s80, v32, s5
	v_readlane_b32 s76, v33, s5
	v_readlane_b32 s87, v35, s5
	v_readlane_b32 s86, v36, s5
	s_add_i32 s96, s96, 8
	v_readlane_b32 s85, v27, s40
	v_readlane_b32 s89, v28, s40
	v_readlane_b32 s90, v29, s40
	v_readlane_b32 s91, v31, s40
	v_readlane_b32 s88, v32, s40
	v_readlane_b32 s84, v33, s40
	v_readlane_b32 s93, v35, s40
	v_readlane_b32 s92, v36, s40
	v_readlane_b32 s4, v30, s40
	s_mov_b64 s[40:41], 0x30000
	s_cmp_eq_u32 s96, 64
	s_waitcnt vmcnt(0) lgkmcnt(0)
	v_fmac_f32_e32 v34, s97, v14
	v_pk_fma_f32 v[12:13], v[14:15], s[26:27], v[12:13] op_sel_hi:[0,1,1]
	v_pk_fma_f32 v[10:11], v[14:15], s[10:11], v[10:11] op_sel_hi:[0,1,1]
	v_pk_fma_f32 v[8:9], v[14:15], s[8:9], v[8:9] op_sel_hi:[0,1,1]
	v_pk_fma_f32 v[4:5], v[14:15], s[28:29], v[4:5] op_sel_hi:[0,1,1]
	v_fmac_f32_e32 v34, s94, v38
	v_pk_fma_f32 v[12:13], v[38:39], s[34:35], v[12:13] op_sel_hi:[0,1,1]
	v_pk_fma_f32 v[10:11], v[38:39], s[30:31], v[10:11] op_sel_hi:[0,1,1]
	v_pk_fma_f32 v[8:9], v[38:39], s[6:7], v[8:9] op_sel_hi:[0,1,1]
	v_pk_fma_f32 v[4:5], v[38:39], s[46:47], v[4:5] op_sel_hi:[0,1,1]
	v_fmac_f32_e32 v34, s44, v40
	v_pk_fma_f32 v[12:13], v[40:41], s[50:51], v[12:13] op_sel_hi:[0,1,1]
	v_pk_fma_f32 v[10:11], v[40:41], s[48:49], v[10:11] op_sel_hi:[0,1,1]
	v_pk_fma_f32 v[8:9], v[40:41], s[36:37], v[8:9] op_sel_hi:[0,1,1]
	v_pk_fma_f32 v[4:5], v[40:41], s[52:53], v[4:5] op_sel_hi:[0,1,1]
	v_fmac_f32_e32 v34, s45, v42
	v_pk_fma_f32 v[12:13], v[42:43], s[58:59], v[12:13] op_sel_hi:[0,1,1]
	v_pk_fma_f32 v[10:11], v[42:43], s[56:57], v[10:11] op_sel_hi:[0,1,1]
	v_pk_fma_f32 v[8:9], v[42:43], s[54:55], v[8:9] op_sel_hi:[0,1,1]
	v_pk_fma_f32 v[4:5], v[42:43], s[62:63], v[4:5] op_sel_hi:[0,1,1]
	v_fmac_f32_e32 v34, s33, v44
	v_pk_fma_f32 v[12:13], v[44:45], s[66:67], v[12:13] op_sel_hi:[0,1,1]
	v_pk_fma_f32 v[10:11], v[44:45], s[64:65], v[10:11] op_sel_hi:[0,1,1]
	v_pk_fma_f32 v[8:9], v[44:45], s[60:61], v[8:9] op_sel_hi:[0,1,1]
	v_pk_fma_f32 v[4:5], v[44:45], s[70:71], v[4:5] op_sel_hi:[0,1,1]
	v_fmac_f32_e32 v34, vcc_lo, v46
	v_pk_fma_f32 v[12:13], v[46:47], s[74:75], v[12:13] op_sel_hi:[0,1,1]
	v_pk_fma_f32 v[10:11], v[46:47], s[72:73], v[10:11] op_sel_hi:[0,1,1]
	v_pk_fma_f32 v[8:9], v[46:47], s[68:69], v[8:9] op_sel_hi:[0,1,1]
	v_pk_fma_f32 v[4:5], v[46:47], s[78:79], v[4:5] op_sel_hi:[0,1,1]
	v_fmac_f32_e32 v34, vcc_hi, v18
	v_pk_fma_f32 v[12:13], v[18:19], s[82:83], v[12:13] op_sel_hi:[0,1,1]
	v_pk_fma_f32 v[10:11], v[18:19], s[80:81], v[10:11] op_sel_hi:[0,1,1]
	v_pk_fma_f32 v[8:9], v[18:19], s[76:77], v[8:9] op_sel_hi:[0,1,1]
	v_pk_fma_f32 v[4:5], v[18:19], s[86:87], v[4:5] op_sel_hi:[0,1,1]
	v_lshl_add_u64 v[6:7], v[6:7], 0, s[40:41]
	v_fmac_f32_e32 v34, s4, v16
	v_pk_fma_f32 v[12:13], v[16:17], s[90:91], v[12:13] op_sel_hi:[0,1,1]
	v_pk_fma_f32 v[10:11], v[16:17], s[88:89], v[10:11] op_sel_hi:[0,1,1]
	v_pk_fma_f32 v[8:9], v[16:17], s[84:85], v[8:9] op_sel_hi:[0,1,1]
	v_pk_fma_f32 v[4:5], v[16:17], s[92:93], v[4:5] op_sel_hi:[0,1,1]
	s_cbranch_scc0 .LBB0_40
	v_lshl_add_u32 v14, v26, 3, v26
	v_mov_b64_e32 v[6:7], s[14:15]
	v_mad_i64_i32 v[6:7], s[4:5], v14, s39, v[6:7]
	v_lshl_add_u64 v[2:3], v[2:3], 2, v[6:7]
	v_add_co_u32_e32 v6, vcc, 0x6000, v2
	flat_store_dword v[2:3], v9 sc1
	s_nop 0
	v_addc_co_u32_e32 v7, vcc, 0, v3, vcc
	flat_store_dword v[6:7], v11 sc1
	v_add_co_u32_e32 v6, vcc, 0xc000, v2
	v_add_u32_e32 v17, s3, v17
	s_nop 0
	v_addc_co_u32_e32 v7, vcc, 0, v3, vcc
	flat_store_dword v[6:7], v12 sc1
	v_add_co_u32_e32 v6, vcc, 0x12000, v2
	s_movk_i32 s4, 0x5ff
	s_nop 0
	v_addc_co_u32_e32 v7, vcc, 0, v3, vcc
	flat_store_dword v[6:7], v34 sc1
	v_add_co_u32_e32 v6, vcc, 0x18000, v2
	s_nop 1
	v_addc_co_u32_e32 v7, vcc, 0, v3, vcc
	flat_store_dword v[6:7], v13 sc1
	v_add_co_u32_e32 v6, vcc, 0x1e000, v2
	s_nop 1
	v_addc_co_u32_e32 v7, vcc, 0, v3, vcc
	flat_store_dword v[6:7], v10 sc1
	v_add_co_u32_e32 v6, vcc, 0x24000, v2
	s_nop 1
	v_addc_co_u32_e32 v7, vcc, 0, v3, vcc
	flat_store_dword v[6:7], v8 sc1
	v_add_co_u32_e32 v6, vcc, 0x2a000, v2
	s_nop 1
	v_addc_co_u32_e32 v7, vcc, 0, v3, vcc
	v_add_co_u32_e32 v2, vcc, 0x30000, v2
	flat_store_dword v[6:7], v5 sc1
	s_nop 0
	v_addc_co_u32_e32 v3, vcc, 0, v3, vcc
	v_cmp_lt_i32_e32 vcc, s4, v17
	s_or_b64 s[24:25], vcc, s[24:25]
	flat_store_dword v[2:3], v4 sc1
	s_andn2_b64 exec, exec, s[24:25]
	s_cbranch_execnz .LBB0_39

.LBB0_58:
	v_mul_hi_i32 v1, v0, s4
	v_lshrrev_b32_e32 v2, 31, v1
	v_ashrrev_i32_e32 v1, 10, v1
	v_add_u32_e32 v1, v1, v2
	v_mul_i32_i24_e32 v4, 0x1800, v1
	v_sub_u32_e32 v4, v0, v4
	v_ashrrev_i32_e32 v5, 31, v4
	v_lshlrev_b64 v[4:5], 2, v[4:5]
	v_mul_hi_i32_i24_e32 v3, 0x6000, v1
	v_mul_i32_i24_e32 v2, 0x6000, v1
	v_lshl_add_u64 v[6:7], s[8:9], 0, v[4:5]
	v_lshl_add_u64 v[4:5], s[22:23], 0, v[4:5]
	v_lshl_add_u64 v[2:3], v[4:5], 0, v[2:3]
	v_add_co_u32_e32 v4, vcc, s5, v2
	flat_load_dword v28, v[6:7]
	s_nop 0
	v_addc_co_u32_e32 v5, vcc, 0, v3, vcc
	v_add_co_u32_e32 v6, vcc, s28, v2
	v_ashrrev_i32_e32 v1, 31, v0
	s_nop 0
	v_addc_co_u32_e32 v7, vcc, 0, v3, vcc
	v_add_co_u32_e32 v8, vcc, s29, v2
	s_nop 1
	v_addc_co_u32_e32 v9, vcc, 0, v3, vcc
	v_add_co_u32_e32 v10, vcc, s30, v2
	s_nop 1
	v_addc_co_u32_e32 v11, vcc, 0, v3, vcc
	v_add_co_u32_e32 v12, vcc, s31, v2
	s_nop 1
	v_addc_co_u32_e32 v13, vcc, 0, v3, vcc
	v_add_co_u32_e32 v14, vcc, s33, v2
	s_nop 1
	v_addc_co_u32_e32 v15, vcc, 0, v3, vcc
	v_add_co_u32_e32 v16, vcc, s34, v2
	s_nop 1
	v_addc_co_u32_e32 v17, vcc, 0, v3, vcc
	v_add_co_u32_e32 v18, vcc, s35, v2
	s_nop 1
	v_addc_co_u32_e32 v19, vcc, 0, v3, vcc
	v_add_co_u32_e32 v20, vcc, s36, v2
	s_nop 1
	v_addc_co_u32_e32 v21, vcc, 0, v3, vcc
	v_add_co_u32_e32 v22, vcc, s37, v2
	s_nop 1
	v_addc_co_u32_e32 v23, vcc, 0, v3, vcc
	v_add_co_u32_e32 v24, vcc, s39, v2
	s_nop 1
	v_addc_co_u32_e32 v25, vcc, 0, v3, vcc
	v_add_co_u32_e32 v26, vcc, s44, v2
	flat_load_dword v29, v[2:3]
	flat_load_dword v30, v[4:5]
	flat_load_dword v31, v[6:7]
	s_nop 0
	flat_load_dword v8, v[8:9]
	s_nop 0
	flat_load_dword v9, v[10:11]
	s_nop 0
	flat_load_dword v10, v[12:13]
	flat_load_dword v11, v[14:15]
	s_nop 0
	flat_load_dword v12, v[16:17]
	flat_load_dword v13, v[18:19]
	flat_load_dword v14, v[20:21]
	flat_load_dword v15, v[22:23]
	s_nop 0
	flat_load_dword v16, v[24:25]
	v_addc_co_u32_e32 v27, vcc, 0, v3, vcc
	v_add_co_u32_e32 v4, vcc, s45, v2
	s_nop 1
	v_addc_co_u32_e32 v5, vcc, 0, v3, vcc
	v_add_co_u32_e32 v6, vcc, s46, v2
	flat_load_dword v17, v[26:27]
	s_nop 0
	flat_load_dword v4, v[4:5]
	v_addc_co_u32_e32 v7, vcc, 0, v3, vcc
	v_add_co_u32_e32 v2, vcc, 0x32a000, v2
	s_nop 1
	v_addc_co_u32_e32 v3, vcc, 0, v3, vcc
	flat_load_dword v5, v[6:7]
	s_nop 0
	flat_load_dword v6, v[2:3]
	v_lshl_add_u64 v[2:3], v[0:1], 2, s[24:25]
	v_add_u32_e32 v0, s3, v0
	v_cmp_lt_i32_e32 vcc, s47, v0
	s_or_b64 s[26:27], vcc, s[26:27]
	s_waitcnt vmcnt(0) lgkmcnt(0)
	v_add_f32_e32 v1, v28, v29
	v_add_f32_e32 v1, v1, v30
	v_add_f32_e32 v1, v1, v31
	v_add_f32_e32 v1, v1, v8
	v_add_f32_e32 v1, v1, v9
	v_add_f32_e32 v1, v1, v10
	v_add_f32_e32 v1, v1, v11
	v_add_f32_e32 v1, v1, v12
	v_add_f32_e32 v1, v1, v13
	v_add_f32_e32 v1, v1, v14
	v_add_f32_e32 v1, v1, v15
	v_add_f32_e32 v1, v1, v16
	v_add_f32_e32 v1, v1, v17
	v_add_f32_e32 v1, v1, v4
	v_add_f32_e32 v1, v1, v5
	v_add_f32_e32 v1, v1, v6
	flat_store_dword v[2:3], v1 sc1
	s_andn2_b64 exec, exec, s[26:27]
	s_cbranch_execnz .LBB0_58

.LBB0_68:
	flat_load_dwordx4 v[44:47], v[32:33]
	flat_load_dwordx4 v[48:51], v[32:33] offset:16
	flat_load_dwordx4 v[52:55], v[32:33] offset:2048
	flat_load_dwordx4 v[56:59], v[32:33] offset:2064
	ds_read_b128 v[60:63], v34 offset:2048
	ds_read_b128 v[64:67], v34 offset:2064
	ds_read_b128 v[68:71], v34 offset:6144
	ds_read_b128 v[72:75], v34 offset:6160
	v_lshl_add_u64 v[76:77], v[24:25], 0, s[26:27]
	s_add_u32 s26, s26, 0x800
	s_addc_u32 s27, s27, 0
	v_lshl_add_u64 v[32:33], v[32:33], 0, s[20:21]
	s_cmp_eq_u32 s26, 0x10000
	s_waitcnt vmcnt(0) lgkmcnt(0)
	v_mov_b32_e32 v80, v45
	v_mov_b32_e32 v81, v49
	v_mov_b32_e32 v78, v44
	v_mov_b32_e32 v79, v48
	v_mov_b32_e32 v84, v53
	v_mov_b32_e32 v85, v57
	v_pk_mul_f32 v[80:81], v[80:81], v[80:81]
	v_mov_b32_e32 v82, v52
	v_mov_b32_e32 v83, v56
	v_mov_b32_e32 v86, v46
	v_mov_b32_e32 v87, v50
	v_pk_mul_f32 v[84:85], v[84:85], v[84:85]
	v_pk_fma_f32 v[78:79], v[78:79], v[78:79], v[80:81]
	v_mov_b32_e32 v88, v54
	v_mov_b32_e32 v89, v58
	v_mov_b32_e32 v90, v47
	v_mov_b32_e32 v91, v51
	v_pk_fma_f32 v[80:81], v[82:83], v[82:83], v[84:85]
	v_pk_fma_f32 v[78:79], v[86:87], v[86:87], v[78:79]
	v_mov_b32_e32 v92, v55
	v_mov_b32_e32 v93, v59
	v_pk_fma_f32 v[80:81], v[88:89], v[88:89], v[80:81]
	v_pk_fma_f32 v[78:79], v[90:91], v[90:91], v[78:79]
	v_pk_fma_f32 v[80:81], v[92:93], v[92:93], v[80:81]
	v_add_f32_e32 v18, v78, v79
	v_add_f32_e32 v18, v18, v80
	v_add_f32_e32 v18, v18, v81
	ds_bpermute_b32 v29, v35, v18
	s_waitcnt lgkmcnt(0)
	v_add_f32_e32 v18, v18, v29
	ds_bpermute_b32 v29, v36, v18
	s_waitcnt lgkmcnt(0)
	v_add_f32_e32 v18, v18, v29
	ds_bpermute_b32 v29, v37, v18
	s_waitcnt lgkmcnt(0)
	v_add_f32_e32 v18, v18, v29
	ds_bpermute_b32 v29, v38, v18
	s_waitcnt lgkmcnt(0)
	v_add_f32_e32 v18, v18, v29
	ds_bpermute_b32 v29, v39, v18
	s_waitcnt lgkmcnt(0)
	v_add_f32_e32 v18, v18, v29
	ds_bpermute_b32 v29, v40, v18
	s_waitcnt lgkmcnt(0)
	v_add_f32_e32 v18, v18, v29
	v_fmamk_f32 v18, v18, 0x3a800000, v42
	v_mul_f32_e32 v29, 0x4b800000, v18
	v_cmp_gt_f32_e32 vcc, s46, v18
	s_nop 1
	v_cndmask_b32_e32 v18, v18, v29, vcc
	v_rsq_f32_e32 v18, v18
	s_nop 0
	v_mul_f32_e32 v29, 0x45800000, v18
	v_cndmask_b32_e32 v18, v18, v29, vcc
	v_pk_mul_f32 v[44:45], v[44:45], v[18:19] op_sel_hi:[1,0]
	v_pk_mul_f32 v[46:47], v[46:47], v[18:19] op_sel_hi:[1,0]
	v_pk_mul_f32 v[48:49], v[48:49], v[18:19] op_sel_hi:[1,0]
	v_pk_mul_f32 v[50:51], v[50:51], v[18:19] op_sel_hi:[1,0]
	v_pk_fma_f32 v[46:47], v[2:3], v[46:47], v[10:11]
	v_pk_fma_f32 v[44:45], v[0:1], v[44:45], v[8:9]
	v_pk_mul_f32 v[52:53], v[52:53], v[18:19] op_sel_hi:[1,0]
	v_pk_mul_f32 v[54:55], v[54:55], v[18:19] op_sel_hi:[1,0]
	v_pk_mul_f32 v[56:57], v[56:57], v[18:19] op_sel_hi:[1,0]
	v_pk_mul_f32 v[58:59], v[58:59], v[18:19] op_sel_hi:[1,0]
	v_pk_fma_f32 v[50:51], v[6:7], v[50:51], v[14:15]
	v_pk_fma_f32 v[48:49], v[4:5], v[48:49], v[12:13]
	v_cvt_pk_bf16_f32 v44, v44, v45
	v_cvt_pk_bf16_f32 v45, v46, v47
	v_cvt_pk_bf16_f32 v47, v50, v51
	v_pk_fma_f32 v[54:55], v[62:63], v[54:55], v[70:71]
	v_cvt_pk_bf16_f32 v46, v48, v49
	v_pk_fma_f32 v[52:53], v[60:61], v[52:53], v[68:69]
	v_pk_fma_f32 v[58:59], v[66:67], v[58:59], v[74:75]
	v_pk_fma_f32 v[56:57], v[64:65], v[56:57], v[72:73]
	v_cvt_pk_bf16_f32 v48, v52, v53
	v_cvt_pk_bf16_f32 v49, v54, v55
	v_cvt_pk_bf16_f32 v51, v58, v59
	s_nop 0
	v_cvt_pk_bf16_f32 v50, v56, v57
	flat_store_dwordx4 v[76:77], v[44:47] sc1
	flat_store_dwordx4 v[76:77], v[48:51] offset:1024 sc1
	s_cbranch_scc0 .LBB0_68
	s_ashr_i32 s25, s24, 31
	v_lshl_add_u64 v[32:33], s[24:25], 3, v[16:17]
	v_lshlrev_b64 v[0:1], 12, v[32:33]
	v_lshl_add_u64 v[44:45], v[20:21], 0, v[0:1]
	flat_load_dwordx4 v[0:3], v[44:45]
	flat_load_dwordx4 v[4:7], v[44:45] offset:16
	flat_load_dwordx4 v[8:11], v[44:45] offset:2048
	flat_load_dwordx4 v[12:15], v[44:45] offset:2064
	v_lshlrev_b64 v[32:33], 11, v[32:33]
	v_lshl_add_u64 v[32:33], s[12:13], 0, v[32:33]
	v_lshl_add_u64 v[32:33], v[32:33], 0, s[22:23]
	s_add_i32 s24, s24, s38
	v_lshl_add_u64 v[24:25], v[24:25], 0, s[16:17]
	s_cmpk_gt_i32 s24, 0xff
	v_lshl_add_u64 v[26:27], v[26:27], 0, s[18:19]
	s_waitcnt vmcnt(0) lgkmcnt(0)
	v_mov_b32_e32 v46, v1
	v_mov_b32_e32 v47, v5
	v_mov_b32_e32 v44, v0
	v_mov_b32_e32 v45, v4
	v_mov_b32_e32 v54, v9
	v_mov_b32_e32 v55, v13
	v_pk_mul_f32 v[46:47], v[46:47], v[46:47]
	v_mov_b32_e32 v48, v2
	v_mov_b32_e32 v49, v6
	v_mov_b32_e32 v52, v8
	v_mov_b32_e32 v53, v12
	v_pk_mul_f32 v[54:55], v[54:55], v[54:55]
	v_pk_fma_f32 v[44:45], v[44:45], v[44:45], v[46:47]
	v_mov_b32_e32 v50, v3
	v_mov_b32_e32 v51, v7
	v_mov_b32_e32 v56, v10
	v_mov_b32_e32 v57, v14
	v_pk_fma_f32 v[46:47], v[52:53], v[52:53], v[54:55]
	v_pk_fma_f32 v[44:45], v[48:49], v[48:49], v[44:45]
	v_mov_b32_e32 v58, v11
	v_mov_b32_e32 v59, v15
	v_pk_fma_f32 v[46:47], v[56:57], v[56:57], v[46:47]
	v_pk_fma_f32 v[44:45], v[50:51], v[50:51], v[44:45]
	v_pk_fma_f32 v[46:47], v[58:59], v[58:59], v[46:47]
	v_add_f32_e32 v18, v44, v45
	v_add_f32_e32 v18, v18, v46
	v_add_f32_e32 v18, v18, v47
	ds_bpermute_b32 v29, v35, v18
	ds_read_b128 v[44:47], v34 offset:8192
	ds_read_b128 v[48:51], v34 offset:8208
	ds_read_b128 v[52:55], v34 offset:12288
	ds_read_b128 v[56:59], v34 offset:12304
	ds_read_b128 v[60:63], v34 offset:10240
	ds_read_b128 v[64:67], v34 offset:10256
	ds_read_b128 v[68:71], v34 offset:14336
	ds_read_b128 v[72:75], v34 offset:14352
	s_waitcnt lgkmcnt(8)
	v_add_f32_e32 v18, v18, v29
	ds_bpermute_b32 v29, v36, v18
	s_waitcnt lgkmcnt(0)
	v_add_f32_e32 v18, v18, v29
	ds_bpermute_b32 v29, v37, v18
	s_waitcnt lgkmcnt(0)
	v_add_f32_e32 v18, v18, v29
	ds_bpermute_b32 v31, v38, v18
	v_mov_b32_e32 v29, v19
	v_lshl_add_u64 v[76:77], v[32:33], 0, v[28:29]
	s_waitcnt lgkmcnt(0)
	v_add_f32_e32 v18, v18, v31
	ds_bpermute_b32 v43, v39, v18
	v_mov_b32_e32 v31, v19
	v_lshl_add_u64 v[32:33], v[32:33], 0, v[30:31]
	s_waitcnt lgkmcnt(0)
	v_add_f32_e32 v18, v18, v43
	ds_bpermute_b32 v43, v40, v18
	s_waitcnt lgkmcnt(0)
	v_add_f32_e32 v18, v18, v43
	v_fmamk_f32 v18, v18, 0x3a800000, v42
	v_mul_f32_e32 v43, 0x4b800000, v18
	v_cmp_gt_f32_e32 vcc, s46, v18
	s_nop 1
	v_cndmask_b32_e32 v18, v18, v43, vcc
	v_rsq_f32_e32 v18, v18
	s_nop 0
	v_mul_f32_e32 v29, 0x45800000, v18
	v_cndmask_b32_e32 v18, v18, v29, vcc
	v_pk_mul_f32 v[0:1], v[0:1], v[18:19] op_sel_hi:[1,0]
	v_pk_mul_f32 v[2:3], v[2:3], v[18:19] op_sel_hi:[1,0]
	v_pk_mul_f32 v[4:5], v[4:5], v[18:19] op_sel_hi:[1,0]
	v_pk_mul_f32 v[6:7], v[6:7], v[18:19] op_sel_hi:[1,0]
	v_pk_fma_f32 v[2:3], v[46:47], v[2:3], v[54:55]
	v_pk_fma_f32 v[0:1], v[44:45], v[0:1], v[52:53]
	v_pk_mul_f32 v[8:9], v[8:9], v[18:19] op_sel_hi:[1,0]
	v_pk_mul_f32 v[10:11], v[10:11], v[18:19] op_sel_hi:[1,0]
	v_pk_mul_f32 v[12:13], v[12:13], v[18:19] op_sel_hi:[1,0]
	v_pk_mul_f32 v[14:15], v[14:15], v[18:19] op_sel_hi:[1,0]
	v_pk_fma_f32 v[6:7], v[50:51], v[6:7], v[58:59]
	v_pk_fma_f32 v[4:5], v[48:49], v[4:5], v[56:57]
	v_cvt_pk_bf16_f32 v0, v0, v1
	v_cvt_pk_bf16_f32 v1, v2, v3
	v_cvt_pk_bf16_f32 v3, v6, v7
	v_pk_fma_f32 v[10:11], v[62:63], v[10:11], v[70:71]
	v_cvt_pk_bf16_f32 v2, v4, v5
	v_pk_fma_f32 v[8:9], v[60:61], v[8:9], v[68:69]
	v_pk_fma_f32 v[14:15], v[66:67], v[14:15], v[74:75]
	v_pk_fma_f32 v[12:13], v[64:65], v[12:13], v[72:73]
	v_cvt_pk_bf16_f32 v4, v8, v9
	v_cvt_pk_bf16_f32 v5, v10, v11
	v_cvt_pk_bf16_f32 v7, v14, v15
	s_nop 0
	v_cvt_pk_bf16_f32 v6, v12, v13
	flat_store_dwordx4 v[76:77], v[0:3] sc1
	flat_store_dwordx4 v[32:33], v[4:7] sc1
	s_cbranch_scc0 .LBB0_61

.LBB0_140:
	s_lshl_b32 s4, s12, 8
	s_add_i32 s4, s4, s66
	v_add_u32_e32 v150, s4, v148
	s_lshl_b32 s4, s10, 8
	s_or_b32 s4, s4, s67
	s_cmpk_lt_i32 s12, 0x100
	v_add_u32_e32 v151, 0xffff0000, v150
	v_mov_b64_e32 v[152:153], s[28:29]
	v_mov_b64_e32 v[166:167], s[26:27]
	v_lshl_add_u32 v148, v160, 3, s4
	v_mad_i64_i32 v[152:153], s[4:5], v151, s72, v[152:153]
	v_mad_i64_i32 v[166:167], s[4:5], v150, s73, v[166:167]
	s_cselect_b64 s[12:13], -1, 0
	v_ashrrev_i32_e32 v149, 31, v148
	v_cndmask_b32_e64 v153, v153, v167, s[12:13]
	v_cndmask_b32_e64 v152, v152, v166, s[12:13]
	v_lshl_add_u64 v[152:153], v[148:149], 1, v[152:153]
	s_and_b64 vcc, exec, s[8:9]
	v_cvt_pk_bf16_f32 v162, v124, v125
	v_cvt_pk_bf16_f32 v163, v126, v127
	v_cvt_pk_bf16_f32 v164, v120, v121
	v_cvt_pk_bf16_f32 v165, v122, v123
	flat_store_dwordx4 v[152:153], v[162:165] sc1
	s_cbranch_vccnz .LBB0_142
	s_nop 0
	v_pk_mul_f32 v[162:163], v[116:117], v[116:117]
	s_nop 0
	v_pk_fma_f32 v[162:163], v[162:163], s[46:47], v[146:147] op_sel_hi:[1,0,0]
	s_nop 0
	v_pk_mul_f32 v[162:163], v[116:117], v[162:163]
	s_nop 0
	v_exp_f32_e32 v162, v162
	v_exp_f32_e32 v163, v163
	s_nop 0
	v_pk_add_f32 v[162:163], v[162:163], 1.0 op_sel_hi:[1,0]
	s_nop 0
	v_rcp_f32_e32 v162, v162
	v_rcp_f32_e32 v163, v163
	s_nop 0
	v_pk_mul_f32 v[116:117], v[116:117], v[162:163]

.LBB0_148:
	s_cmp_eq_u32 s11, 2
	s_cselect_b64 s[58:59], -1, 0
	s_lshl_b32 s4, s10, 2
	s_sub_i32 s56, s4, 56
	s_ashr_i32 s57, s56, 31
	v_ashrrev_i32_e32 v151, 31, v150
	s_cmp_lg_u32 s11, 2
	v_cmp_eq_u32_e64 s[10:11], 0, v160
	v_cvt_pk_bf16_f32 v160, v116, v117
	v_cvt_pk_bf16_f32 v161, v118, v119
	v_cvt_pk_bf16_f32 v162, v112, v113
	v_cvt_pk_bf16_f32 v163, v114, v115
	flat_store_dwordx4 v[152:153], v[160:163] offset:256 sc1
	s_cbranch_scc1 .LBB0_152
	v_pk_mul_f32 v[124:125], v[124:125], v[124:125]
	v_pk_mul_f32 v[126:127], v[126:127], v[126:127]
	v_pk_mul_f32 v[120:121], v[120:121], v[120:121]
	v_add_f32_e32 v126, v126, v127
	v_add_f32_e32 v124, v124, v125
	v_pk_mul_f32 v[122:123], v[122:123], v[122:123]
	v_add_f32_e32 v124, v124, v126
	v_add_f32_e32 v120, v120, v121
	v_pk_mul_f32 v[116:117], v[116:117], v[116:117]
	v_add_f32_e32 v120, v124, v120
	v_add_f32_e32 v121, v122, v123
	v_pk_mul_f32 v[118:119], v[118:119], v[118:119]
	v_add_f32_e32 v120, v120, v121
	v_add_f32_e32 v116, v116, v117
	v_pk_mul_f32 v[112:113], v[112:113], v[112:113]
	v_add_f32_e32 v116, v120, v116
	v_add_f32_e32 v117, v118, v119
	v_pk_mul_f32 v[114:115], v[114:115], v[114:115]
	v_add_f32_e32 v116, v116, v117
	v_add_f32_e32 v112, v112, v113
	v_add_f32_e32 v112, v116, v112
	v_add_f32_e32 v113, v114, v115
	v_and_b32_e32 v114, 64, v159
	v_add_f32_e32 v112, v112, v113
	v_xor_b32_e32 v113, 16, v159
	v_add_u32_e32 v114, 64, v114
	v_cmp_lt_i32_e32 vcc, v113, v114
	s_nop 1
	v_cndmask_b32_e32 v113, v159, v113, vcc
	v_lshlrev_b32_e32 v113, 2, v113
	ds_bpermute_b32 v113, v113, v112
	s_waitcnt lgkmcnt(0)
	v_add_f32_e32 v112, v112, v113
	v_xor_b32_e32 v113, 32, v159
	v_cmp_lt_i32_e32 vcc, v113, v114
	s_nop 1
	v_cndmask_b32_e32 v113, v159, v113, vcc
	v_lshlrev_b32_e32 v113, 2, v113
	ds_bpermute_b32 v113, v113, v112
	s_and_saveexec_b64 s[14:15], s[10:11]
	s_cbranch_execz .LBB0_151
	v_lshlrev_b64 v[114:115], 6, v[150:151]
	v_lshl_add_u64 v[114:115], s[30:31], 0, v[114:115]
	v_lshl_add_u64 v[114:115], s[56:57], 2, v[114:115]
	s_lshl_b32 s22, s65, 2
	v_lshl_add_u64 v[114:115], v[114:115], 0, s[22:23]
	s_waitcnt lgkmcnt(0)
	v_add_f32_e32 v112, v112, v113
	flat_store_dword v[114:115], v112 sc1

.LBB0_160:
	v_add_u32_e32 v112, 16, v150
	s_waitcnt lgkmcnt(0)
	v_add_u32_e32 v113, 0xffff0010, v150
	v_mov_b64_e32 v[114:115], s[26:27]
	v_mov_b64_e32 v[120:121], s[28:29]
	v_mad_i64_i32 v[114:115], s[4:5], v112, s73, v[114:115]
	v_mad_i64_i32 v[120:121], s[4:5], v113, s72, v[120:121]
	v_cndmask_b32_e64 v115, v121, v115, s[12:13]
	v_cndmask_b32_e64 v114, v120, v114, s[12:13]
	v_lshl_add_u64 v[114:115], v[148:149], 1, v[114:115]
	s_and_b64 vcc, exec, s[8:9]
	v_cvt_pk_bf16_f32 v116, v108, v109
	v_cvt_pk_bf16_f32 v117, v110, v111
	v_cvt_pk_bf16_f32 v118, v104, v105
	v_cvt_pk_bf16_f32 v119, v106, v107
	flat_store_dwordx4 v[114:115], v[116:119] sc1
	s_cbranch_vccnz .LBB0_162
	s_nop 0
	v_pk_mul_f32 v[116:117], v[100:101], v[100:101]
	s_nop 0
	v_pk_fma_f32 v[116:117], v[116:117], s[46:47], v[146:147] op_sel_hi:[1,0,0]
	s_nop 0
	v_pk_mul_f32 v[116:117], v[100:101], v[116:117]
	s_nop 0
	v_exp_f32_e32 v116, v116
	v_exp_f32_e32 v117, v117
	s_nop 0
	v_pk_add_f32 v[116:117], v[116:117], 1.0 op_sel_hi:[1,0]
	s_nop 0
	v_rcp_f32_e32 v116, v116
	v_rcp_f32_e32 v117, v117
	s_nop 0
	v_pk_mul_f32 v[100:101], v[100:101], v[116:117]

.LBB0_168:
	v_cndmask_b32_e64 v113, 0, 1, s[58:59]
	v_cmp_ne_u32_e64 s[14:15], 1, v113
	s_andn2_b64 vcc, exec, s[58:59]
	v_cvt_pk_bf16_f32 v116, v100, v101
	v_cvt_pk_bf16_f32 v117, v102, v103
	v_cvt_pk_bf16_f32 v118, v96, v97
	v_cvt_pk_bf16_f32 v119, v98, v99
	flat_store_dwordx4 v[114:115], v[116:119] offset:256 sc1
	s_cbranch_vccnz .LBB0_172
	v_pk_mul_f32 v[108:109], v[108:109], v[108:109]
	v_pk_mul_f32 v[110:111], v[110:111], v[110:111]
	v_pk_mul_f32 v[104:105], v[104:105], v[104:105]
	v_add_f32_e32 v110, v110, v111
	v_add_f32_e32 v108, v108, v109
	v_pk_mul_f32 v[106:107], v[106:107], v[106:107]
	v_add_f32_e32 v108, v108, v110
	v_add_f32_e32 v104, v104, v105
	v_pk_mul_f32 v[100:101], v[100:101], v[100:101]
	v_add_f32_e32 v104, v108, v104
	v_add_f32_e32 v105, v106, v107
	v_pk_mul_f32 v[102:103], v[102:103], v[102:103]
	v_add_f32_e32 v104, v104, v105
	v_add_f32_e32 v100, v100, v101
	v_pk_mul_f32 v[96:97], v[96:97], v[96:97]
	v_add_f32_e32 v100, v104, v100
	v_add_f32_e32 v101, v102, v103
	v_pk_mul_f32 v[98:99], v[98:99], v[98:99]
	v_add_f32_e32 v100, v100, v101
	v_add_f32_e32 v96, v96, v97
	v_add_f32_e32 v96, v100, v96
	v_add_f32_e32 v97, v98, v99
	v_and_b32_e32 v98, 64, v159
	v_add_f32_e32 v96, v96, v97
	v_xor_b32_e32 v97, 16, v159
	v_add_u32_e32 v98, 64, v98
	v_cmp_lt_i32_e32 vcc, v97, v98
	s_nop 1
	v_cndmask_b32_e32 v97, v159, v97, vcc
	v_lshlrev_b32_e32 v97, 2, v97
	ds_bpermute_b32 v97, v97, v96
	s_waitcnt lgkmcnt(0)
	v_add_f32_e32 v96, v96, v97
	v_xor_b32_e32 v97, 32, v159
	v_cmp_lt_i32_e32 vcc, v97, v98
	s_nop 1
	v_cndmask_b32_e32 v97, v159, v97, vcc
	v_lshlrev_b32_e32 v97, 2, v97
	ds_bpermute_b32 v97, v97, v96
	s_and_saveexec_b64 s[58:59], s[10:11]
	s_cbranch_execz .LBB0_171
	v_ashrrev_i32_e32 v113, 31, v112
	v_lshlrev_b64 v[98:99], 6, v[112:113]
	v_lshl_add_u64 v[98:99], s[30:31], 0, v[98:99]
	v_lshl_add_u64 v[98:99], s[56:57], 2, v[98:99]
	s_lshl_b32 s22, s65, 2
	v_lshl_add_u64 v[98:99], v[98:99], 0, s[22:23]
	s_waitcnt lgkmcnt(0)
	v_add_f32_e32 v96, v96, v97
	flat_store_dword v[98:99], v96 sc1

.LBB0_180:
	v_add_u32_e32 v96, 32, v150
	s_waitcnt lgkmcnt(0)
	v_add_u32_e32 v97, 0xffff0020, v150
	v_mov_b64_e32 v[98:99], s[26:27]
	v_mov_b64_e32 v[104:105], s[28:29]
	v_mad_i64_i32 v[98:99], s[4:5], v96, s73, v[98:99]
	v_mad_i64_i32 v[104:105], s[4:5], v97, s72, v[104:105]
	v_cndmask_b32_e64 v99, v105, v99, s[12:13]
	v_cndmask_b32_e64 v98, v104, v98, s[12:13]
	v_lshl_add_u64 v[98:99], v[148:149], 1, v[98:99]
	s_and_b64 vcc, exec, s[8:9]
	v_cvt_pk_bf16_f32 v100, v92, v93
	v_cvt_pk_bf16_f32 v101, v94, v95
	v_cvt_pk_bf16_f32 v102, v88, v89
	v_cvt_pk_bf16_f32 v103, v90, v91
	flat_store_dwordx4 v[98:99], v[100:103] sc1
	s_cbranch_vccnz .LBB0_182
	s_nop 0
	v_pk_mul_f32 v[100:101], v[84:85], v[84:85]
	s_nop 0
	v_pk_fma_f32 v[100:101], v[100:101], s[46:47], v[146:147] op_sel_hi:[1,0,0]
	s_nop 0
	v_pk_mul_f32 v[100:101], v[84:85], v[100:101]
	s_nop 0
	v_exp_f32_e32 v100, v100
	v_exp_f32_e32 v101, v101
	s_nop 0
	v_pk_add_f32 v[100:101], v[100:101], 1.0 op_sel_hi:[1,0]
	s_nop 0
	v_rcp_f32_e32 v100, v100
	v_rcp_f32_e32 v101, v101
	s_nop 0
	v_pk_mul_f32 v[84:85], v[84:85], v[100:101]

.LBB0_188:
	s_and_b64 vcc, exec, s[14:15]
	v_cvt_pk_bf16_f32 v100, v84, v85
	v_cvt_pk_bf16_f32 v101, v86, v87
	v_cvt_pk_bf16_f32 v102, v80, v81
	v_cvt_pk_bf16_f32 v103, v82, v83
	flat_store_dwordx4 v[98:99], v[100:103] offset:256 sc1
	s_cbranch_vccnz .LBB0_192
	v_pk_mul_f32 v[92:93], v[92:93], v[92:93]
	v_pk_mul_f32 v[94:95], v[94:95], v[94:95]
	v_pk_mul_f32 v[88:89], v[88:89], v[88:89]
	v_add_f32_e32 v94, v94, v95
	v_add_f32_e32 v92, v92, v93
	v_pk_mul_f32 v[90:91], v[90:91], v[90:91]
	v_add_f32_e32 v92, v92, v94
	v_add_f32_e32 v88, v88, v89
	v_pk_mul_f32 v[84:85], v[84:85], v[84:85]
	v_add_f32_e32 v88, v92, v88
	v_add_f32_e32 v89, v90, v91
	v_pk_mul_f32 v[86:87], v[86:87], v[86:87]
	v_add_f32_e32 v88, v88, v89
	v_add_f32_e32 v84, v84, v85
	v_pk_mul_f32 v[80:81], v[80:81], v[80:81]
	v_add_f32_e32 v84, v88, v84
	v_add_f32_e32 v85, v86, v87
	v_pk_mul_f32 v[82:83], v[82:83], v[82:83]
	v_add_f32_e32 v84, v84, v85
	v_add_f32_e32 v80, v80, v81
	v_add_f32_e32 v80, v84, v80
	v_add_f32_e32 v81, v82, v83
	v_and_b32_e32 v82, 64, v159
	v_add_f32_e32 v80, v80, v81
	v_xor_b32_e32 v81, 16, v159
	v_add_u32_e32 v82, 64, v82
	v_cmp_lt_i32_e32 vcc, v81, v82
	s_nop 1
	v_cndmask_b32_e32 v81, v159, v81, vcc
	v_lshlrev_b32_e32 v81, 2, v81
	ds_bpermute_b32 v81, v81, v80
	s_waitcnt lgkmcnt(0)
	v_add_f32_e32 v80, v80, v81
	v_xor_b32_e32 v81, 32, v159
	v_cmp_lt_i32_e32 vcc, v81, v82
	s_nop 1
	v_cndmask_b32_e32 v81, v159, v81, vcc
	v_lshlrev_b32_e32 v81, 2, v81
	ds_bpermute_b32 v81, v81, v80
	s_and_saveexec_b64 s[58:59], s[10:11]
	s_cbranch_execz .LBB0_191
	v_ashrrev_i32_e32 v97, 31, v96
	v_lshlrev_b64 v[82:83], 6, v[96:97]
	v_lshl_add_u64 v[82:83], s[30:31], 0, v[82:83]
	v_lshl_add_u64 v[82:83], s[56:57], 2, v[82:83]
	s_lshl_b32 s22, s65, 2
	v_lshl_add_u64 v[82:83], v[82:83], 0, s[22:23]
	s_waitcnt lgkmcnt(0)
	v_add_f32_e32 v80, v80, v81
	flat_store_dword v[82:83], v80 sc1

.LBB0_200:
	v_add_u32_e32 v80, 48, v150
	s_waitcnt lgkmcnt(0)
	v_add_u32_e32 v81, 0xffff0030, v150
	v_mov_b64_e32 v[82:83], s[26:27]
	v_mov_b64_e32 v[88:89], s[28:29]
	v_mad_i64_i32 v[82:83], s[4:5], v80, s73, v[82:83]
	v_mad_i64_i32 v[88:89], s[4:5], v81, s72, v[88:89]
	v_cndmask_b32_e64 v83, v89, v83, s[12:13]
	v_cndmask_b32_e64 v82, v88, v82, s[12:13]
	v_lshl_add_u64 v[82:83], v[148:149], 1, v[82:83]
	s_and_b64 vcc, exec, s[8:9]
	v_cvt_pk_bf16_f32 v84, v76, v77
	v_cvt_pk_bf16_f32 v85, v78, v79
	v_cvt_pk_bf16_f32 v86, v72, v73
	v_cvt_pk_bf16_f32 v87, v74, v75
	flat_store_dwordx4 v[82:83], v[84:87] sc1
	s_cbranch_vccnz .LBB0_202
	s_nop 0
	v_pk_mul_f32 v[84:85], v[68:69], v[68:69]
	s_nop 0
	v_pk_fma_f32 v[84:85], v[84:85], s[46:47], v[146:147] op_sel_hi:[1,0,0]
	s_nop 0
	v_pk_mul_f32 v[84:85], v[68:69], v[84:85]
	s_nop 0
	v_exp_f32_e32 v84, v84
	v_exp_f32_e32 v85, v85
	s_nop 0
	v_pk_add_f32 v[84:85], v[84:85], 1.0 op_sel_hi:[1,0]
	s_nop 0
	v_rcp_f32_e32 v84, v84
	v_rcp_f32_e32 v85, v85
	s_nop 0
	v_pk_mul_f32 v[68:69], v[68:69], v[84:85]

.LBB0_208:
	s_and_b64 vcc, exec, s[14:15]
	v_cvt_pk_bf16_f32 v84, v68, v69
	v_cvt_pk_bf16_f32 v85, v70, v71
	v_cvt_pk_bf16_f32 v86, v64, v65
	v_cvt_pk_bf16_f32 v87, v66, v67
	flat_store_dwordx4 v[82:83], v[84:87] offset:256 sc1
	s_cbranch_vccnz .LBB0_212
	v_pk_mul_f32 v[76:77], v[76:77], v[76:77]
	v_pk_mul_f32 v[78:79], v[78:79], v[78:79]
	v_pk_mul_f32 v[72:73], v[72:73], v[72:73]
	v_add_f32_e32 v78, v78, v79
	v_add_f32_e32 v76, v76, v77
	v_pk_mul_f32 v[74:75], v[74:75], v[74:75]
	v_add_f32_e32 v76, v76, v78
	v_add_f32_e32 v72, v72, v73
	v_pk_mul_f32 v[68:69], v[68:69], v[68:69]
	v_add_f32_e32 v72, v76, v72
	v_add_f32_e32 v73, v74, v75
	v_pk_mul_f32 v[70:71], v[70:71], v[70:71]
	v_add_f32_e32 v72, v72, v73
	v_add_f32_e32 v68, v68, v69
	v_pk_mul_f32 v[64:65], v[64:65], v[64:65]
	v_add_f32_e32 v68, v72, v68
	v_add_f32_e32 v69, v70, v71
	v_pk_mul_f32 v[66:67], v[66:67], v[66:67]
	v_add_f32_e32 v68, v68, v69
	v_add_f32_e32 v64, v64, v65
	v_add_f32_e32 v64, v68, v64
	v_add_f32_e32 v65, v66, v67
	v_and_b32_e32 v66, 64, v159
	v_add_f32_e32 v64, v64, v65
	v_xor_b32_e32 v65, 16, v159
	v_add_u32_e32 v66, 64, v66
	v_cmp_lt_i32_e32 vcc, v65, v66
	s_nop 1
	v_cndmask_b32_e32 v65, v159, v65, vcc
	v_lshlrev_b32_e32 v65, 2, v65
	ds_bpermute_b32 v65, v65, v64
	s_waitcnt lgkmcnt(0)
	v_add_f32_e32 v64, v64, v65
	v_xor_b32_e32 v65, 32, v159
	v_cmp_lt_i32_e32 vcc, v65, v66
	s_nop 1
	v_cndmask_b32_e32 v65, v159, v65, vcc
	v_lshlrev_b32_e32 v65, 2, v65
	ds_bpermute_b32 v65, v65, v64
	s_and_saveexec_b64 s[58:59], s[10:11]
	s_cbranch_execz .LBB0_211
	v_ashrrev_i32_e32 v81, 31, v80
	v_lshlrev_b64 v[66:67], 6, v[80:81]
	v_lshl_add_u64 v[66:67], s[30:31], 0, v[66:67]
	v_lshl_add_u64 v[66:67], s[56:57], 2, v[66:67]
	s_lshl_b32 s22, s65, 2
	v_lshl_add_u64 v[66:67], v[66:67], 0, s[22:23]
	s_waitcnt lgkmcnt(0)
	v_add_f32_e32 v64, v64, v65
	flat_store_dword v[66:67], v64 sc1

.LBB0_220:
	v_add_u32_e32 v64, 0x80, v150
	s_waitcnt lgkmcnt(0)
	v_add_u32_e32 v65, 0xffff0080, v150
	v_mov_b64_e32 v[66:67], s[26:27]
	v_mov_b64_e32 v[72:73], s[28:29]
	v_mad_i64_i32 v[66:67], s[4:5], v64, s73, v[66:67]
	v_mad_i64_i32 v[72:73], s[4:5], v65, s72, v[72:73]
	v_cndmask_b32_e64 v67, v73, v67, s[12:13]
	v_cndmask_b32_e64 v66, v72, v66, s[12:13]
	v_lshl_add_u64 v[66:67], v[148:149], 1, v[66:67]
	s_and_b64 vcc, exec, s[8:9]
	v_cvt_pk_bf16_f32 v68, v60, v61
	v_cvt_pk_bf16_f32 v69, v62, v63
	v_cvt_pk_bf16_f32 v70, v56, v57
	v_cvt_pk_bf16_f32 v71, v58, v59
	flat_store_dwordx4 v[66:67], v[68:71] sc1
	s_cbranch_vccnz .LBB0_222
	s_nop 0
	v_pk_mul_f32 v[68:69], v[52:53], v[52:53]
	s_nop 0
	v_pk_fma_f32 v[68:69], v[68:69], s[46:47], v[146:147] op_sel_hi:[1,0,0]
	s_nop 0
	v_pk_mul_f32 v[68:69], v[52:53], v[68:69]
	s_nop 0
	v_exp_f32_e32 v68, v68
	v_exp_f32_e32 v69, v69
	s_nop 0
	v_pk_add_f32 v[68:69], v[68:69], 1.0 op_sel_hi:[1,0]
	s_nop 0
	v_rcp_f32_e32 v68, v68
	v_rcp_f32_e32 v69, v69
	s_nop 0
	v_pk_mul_f32 v[52:53], v[52:53], v[68:69]

.LBB0_228:
	s_and_b64 vcc, exec, s[14:15]
	v_cvt_pk_bf16_f32 v68, v52, v53
	v_cvt_pk_bf16_f32 v69, v54, v55
	v_cvt_pk_bf16_f32 v70, v48, v49
	v_cvt_pk_bf16_f32 v71, v50, v51
	flat_store_dwordx4 v[66:67], v[68:71] offset:256 sc1
	s_cbranch_vccnz .LBB0_232
	v_pk_mul_f32 v[60:61], v[60:61], v[60:61]
	v_pk_mul_f32 v[62:63], v[62:63], v[62:63]
	v_pk_mul_f32 v[56:57], v[56:57], v[56:57]
	v_add_f32_e32 v62, v62, v63
	v_add_f32_e32 v60, v60, v61
	v_pk_mul_f32 v[58:59], v[58:59], v[58:59]
	v_add_f32_e32 v60, v60, v62
	v_add_f32_e32 v56, v56, v57
	v_pk_mul_f32 v[52:53], v[52:53], v[52:53]
	v_add_f32_e32 v56, v60, v56
	v_add_f32_e32 v57, v58, v59
	v_pk_mul_f32 v[54:55], v[54:55], v[54:55]
	v_add_f32_e32 v56, v56, v57
	v_add_f32_e32 v52, v52, v53
	v_pk_mul_f32 v[48:49], v[48:49], v[48:49]
	v_add_f32_e32 v52, v56, v52
	v_add_f32_e32 v53, v54, v55
	v_pk_mul_f32 v[50:51], v[50:51], v[50:51]
	v_add_f32_e32 v52, v52, v53
	v_add_f32_e32 v48, v48, v49
	v_add_f32_e32 v48, v52, v48
	v_add_f32_e32 v49, v50, v51
	v_and_b32_e32 v50, 64, v159
	v_add_f32_e32 v48, v48, v49
	v_xor_b32_e32 v49, 16, v159
	v_add_u32_e32 v50, 64, v50
	v_cmp_lt_i32_e32 vcc, v49, v50
	s_nop 1
	v_cndmask_b32_e32 v49, v159, v49, vcc
	v_lshlrev_b32_e32 v49, 2, v49
	ds_bpermute_b32 v49, v49, v48
	s_waitcnt lgkmcnt(0)
	v_add_f32_e32 v48, v48, v49
	v_xor_b32_e32 v49, 32, v159
	v_cmp_lt_i32_e32 vcc, v49, v50
	s_nop 1
	v_cndmask_b32_e32 v49, v159, v49, vcc
	v_lshlrev_b32_e32 v49, 2, v49
	ds_bpermute_b32 v49, v49, v48
	s_and_saveexec_b64 s[58:59], s[10:11]
	s_cbranch_execz .LBB0_231
	v_ashrrev_i32_e32 v65, 31, v64
	v_lshlrev_b64 v[50:51], 6, v[64:65]
	v_lshl_add_u64 v[50:51], s[30:31], 0, v[50:51]
	v_lshl_add_u64 v[50:51], s[56:57], 2, v[50:51]
	s_lshl_b32 s22, s65, 2
	v_lshl_add_u64 v[50:51], v[50:51], 0, s[22:23]
	s_waitcnt lgkmcnt(0)
	v_add_f32_e32 v48, v48, v49
	flat_store_dword v[50:51], v48 sc1

.LBB0_240:
	v_add_u32_e32 v48, 0x90, v150
	s_waitcnt lgkmcnt(0)
	v_add_u32_e32 v49, 0xffff0090, v150
	v_mov_b64_e32 v[50:51], s[26:27]
	v_mov_b64_e32 v[56:57], s[28:29]
	v_mad_i64_i32 v[50:51], s[4:5], v48, s73, v[50:51]
	v_mad_i64_i32 v[56:57], s[4:5], v49, s72, v[56:57]
	v_cndmask_b32_e64 v51, v57, v51, s[12:13]
	v_cndmask_b32_e64 v50, v56, v50, s[12:13]
	v_lshl_add_u64 v[50:51], v[148:149], 1, v[50:51]
	s_and_b64 vcc, exec, s[8:9]
	v_cvt_pk_bf16_f32 v52, v44, v45
	v_cvt_pk_bf16_f32 v53, v46, v47
	v_cvt_pk_bf16_f32 v54, v40, v41
	v_cvt_pk_bf16_f32 v55, v42, v43
	flat_store_dwordx4 v[50:51], v[52:55] sc1
	s_cbranch_vccnz .LBB0_242
	s_nop 0
	v_pk_mul_f32 v[52:53], v[36:37], v[36:37]
	s_nop 0
	v_pk_fma_f32 v[52:53], v[52:53], s[46:47], v[146:147] op_sel_hi:[1,0,0]
	s_nop 0
	v_pk_mul_f32 v[52:53], v[36:37], v[52:53]
	s_nop 0
	v_exp_f32_e32 v52, v52
	v_exp_f32_e32 v53, v53
	s_nop 0
	v_pk_add_f32 v[52:53], v[52:53], 1.0 op_sel_hi:[1,0]
	s_nop 0
	v_rcp_f32_e32 v52, v52
	v_rcp_f32_e32 v53, v53
	s_nop 0
	v_pk_mul_f32 v[36:37], v[36:37], v[52:53]

.LBB0_248:
	s_and_b64 vcc, exec, s[14:15]
	v_cvt_pk_bf16_f32 v52, v36, v37
	v_cvt_pk_bf16_f32 v53, v38, v39
	v_cvt_pk_bf16_f32 v54, v32, v33
	v_cvt_pk_bf16_f32 v55, v34, v35
	flat_store_dwordx4 v[50:51], v[52:55] offset:256 sc1
	s_cbranch_vccnz .LBB0_252
	v_pk_mul_f32 v[44:45], v[44:45], v[44:45]
	v_pk_mul_f32 v[46:47], v[46:47], v[46:47]
	v_pk_mul_f32 v[40:41], v[40:41], v[40:41]
	v_add_f32_e32 v46, v46, v47
	v_add_f32_e32 v44, v44, v45
	v_pk_mul_f32 v[42:43], v[42:43], v[42:43]
	v_add_f32_e32 v44, v44, v46
	v_add_f32_e32 v40, v40, v41
	v_pk_mul_f32 v[36:37], v[36:37], v[36:37]
	v_add_f32_e32 v40, v44, v40
	v_add_f32_e32 v41, v42, v43
	v_pk_mul_f32 v[38:39], v[38:39], v[38:39]
	v_add_f32_e32 v40, v40, v41
	v_add_f32_e32 v36, v36, v37
	v_pk_mul_f32 v[32:33], v[32:33], v[32:33]
	v_add_f32_e32 v36, v40, v36
	v_add_f32_e32 v37, v38, v39
	v_pk_mul_f32 v[34:35], v[34:35], v[34:35]
	v_add_f32_e32 v36, v36, v37
	v_add_f32_e32 v32, v32, v33
	v_add_f32_e32 v32, v36, v32
	v_add_f32_e32 v33, v34, v35
	v_and_b32_e32 v34, 64, v159
	v_add_f32_e32 v32, v32, v33
	v_xor_b32_e32 v33, 16, v159
	v_add_u32_e32 v34, 64, v34
	v_cmp_lt_i32_e32 vcc, v33, v34
	s_nop 1
	v_cndmask_b32_e32 v33, v159, v33, vcc
	v_lshlrev_b32_e32 v33, 2, v33
	ds_bpermute_b32 v33, v33, v32
	s_waitcnt lgkmcnt(0)
	v_add_f32_e32 v32, v32, v33
	v_xor_b32_e32 v33, 32, v159
	v_cmp_lt_i32_e32 vcc, v33, v34
	s_nop 1
	v_cndmask_b32_e32 v33, v159, v33, vcc
	v_lshlrev_b32_e32 v33, 2, v33
	ds_bpermute_b32 v33, v33, v32
	s_and_saveexec_b64 s[58:59], s[10:11]
	s_cbranch_execz .LBB0_251
	v_ashrrev_i32_e32 v49, 31, v48
	v_lshlrev_b64 v[34:35], 6, v[48:49]
	v_lshl_add_u64 v[34:35], s[30:31], 0, v[34:35]
	v_lshl_add_u64 v[34:35], s[56:57], 2, v[34:35]
	s_lshl_b32 s22, s65, 2
	v_lshl_add_u64 v[34:35], v[34:35], 0, s[22:23]
	s_waitcnt lgkmcnt(0)
	v_add_f32_e32 v32, v32, v33
	flat_store_dword v[34:35], v32 sc1

.LBB0_260:
	v_add_u32_e32 v32, 0xa0, v150
	s_waitcnt lgkmcnt(0)
	v_add_u32_e32 v33, 0xffff00a0, v150
	v_mov_b64_e32 v[34:35], s[26:27]
	v_mov_b64_e32 v[40:41], s[28:29]
	v_mad_i64_i32 v[34:35], s[4:5], v32, s73, v[34:35]
	v_mad_i64_i32 v[40:41], s[4:5], v33, s72, v[40:41]
	v_cndmask_b32_e64 v35, v41, v35, s[12:13]
	v_cndmask_b32_e64 v34, v40, v34, s[12:13]
	v_lshl_add_u64 v[34:35], v[148:149], 1, v[34:35]
	s_and_b64 vcc, exec, s[8:9]
	v_cvt_pk_bf16_f32 v36, v28, v29
	v_cvt_pk_bf16_f32 v37, v30, v31
	v_cvt_pk_bf16_f32 v38, v24, v25
	v_cvt_pk_bf16_f32 v39, v26, v27
	flat_store_dwordx4 v[34:35], v[36:39] sc1
	s_cbranch_vccnz .LBB0_262
	s_nop 0
	v_pk_mul_f32 v[36:37], v[20:21], v[20:21]
	s_nop 0
	v_pk_fma_f32 v[36:37], v[36:37], s[46:47], v[146:147] op_sel_hi:[1,0,0]
	s_nop 0
	v_pk_mul_f32 v[36:37], v[20:21], v[36:37]
	s_nop 0
	v_exp_f32_e32 v36, v36
	v_exp_f32_e32 v37, v37
	s_nop 0
	v_pk_add_f32 v[36:37], v[36:37], 1.0 op_sel_hi:[1,0]
	s_nop 0
	v_rcp_f32_e32 v36, v36
	v_rcp_f32_e32 v37, v37
	s_nop 0
	v_pk_mul_f32 v[20:21], v[20:21], v[36:37]

.LBB0_268:
	s_and_b64 vcc, exec, s[14:15]
	v_cvt_pk_bf16_f32 v36, v20, v21
	v_cvt_pk_bf16_f32 v37, v22, v23
	v_cvt_pk_bf16_f32 v38, v16, v17
	v_cvt_pk_bf16_f32 v39, v18, v19
	flat_store_dwordx4 v[34:35], v[36:39] offset:256 sc1
	s_cbranch_vccnz .LBB0_272
	v_pk_mul_f32 v[28:29], v[28:29], v[28:29]
	v_pk_mul_f32 v[30:31], v[30:31], v[30:31]
	v_pk_mul_f32 v[24:25], v[24:25], v[24:25]
	v_add_f32_e32 v30, v30, v31
	v_add_f32_e32 v28, v28, v29
	v_pk_mul_f32 v[26:27], v[26:27], v[26:27]
	v_add_f32_e32 v28, v28, v30
	v_add_f32_e32 v24, v24, v25
	v_pk_mul_f32 v[20:21], v[20:21], v[20:21]
	v_add_f32_e32 v24, v28, v24
	v_add_f32_e32 v25, v26, v27
	v_pk_mul_f32 v[22:23], v[22:23], v[22:23]
	v_add_f32_e32 v24, v24, v25
	v_add_f32_e32 v20, v20, v21
	v_pk_mul_f32 v[16:17], v[16:17], v[16:17]
	v_add_f32_e32 v20, v24, v20
	v_add_f32_e32 v21, v22, v23
	v_pk_mul_f32 v[18:19], v[18:19], v[18:19]
	v_add_f32_e32 v20, v20, v21
	v_add_f32_e32 v16, v16, v17
	v_add_f32_e32 v16, v20, v16
	v_add_f32_e32 v17, v18, v19
	v_and_b32_e32 v18, 64, v159
	v_add_f32_e32 v16, v16, v17
	v_xor_b32_e32 v17, 16, v159
	v_add_u32_e32 v18, 64, v18
	v_cmp_lt_i32_e32 vcc, v17, v18
	s_nop 1
	v_cndmask_b32_e32 v17, v159, v17, vcc
	v_lshlrev_b32_e32 v17, 2, v17
	ds_bpermute_b32 v17, v17, v16
	s_waitcnt lgkmcnt(0)
	v_add_f32_e32 v16, v16, v17
	v_xor_b32_e32 v17, 32, v159
	v_cmp_lt_i32_e32 vcc, v17, v18
	s_nop 1
	v_cndmask_b32_e32 v17, v159, v17, vcc
	v_lshlrev_b32_e32 v17, 2, v17
	ds_bpermute_b32 v17, v17, v16
	s_and_saveexec_b64 s[58:59], s[10:11]
	s_cbranch_execz .LBB0_271
	v_ashrrev_i32_e32 v33, 31, v32
	v_lshlrev_b64 v[18:19], 6, v[32:33]
	v_lshl_add_u64 v[18:19], s[30:31], 0, v[18:19]
	v_lshl_add_u64 v[18:19], s[56:57], 2, v[18:19]
	s_lshl_b32 s22, s65, 2
	v_lshl_add_u64 v[18:19], v[18:19], 0, s[22:23]
	s_waitcnt lgkmcnt(0)
	v_add_f32_e32 v16, v16, v17
	flat_store_dword v[18:19], v16 sc1

.LBB0_280:
	v_add_u32_e32 v16, 0xb0, v150
	s_waitcnt lgkmcnt(0)
	v_add_u32_e32 v17, 0xffff00b0, v150
	v_mov_b64_e32 v[18:19], s[26:27]
	v_mov_b64_e32 v[24:25], s[28:29]
	v_mad_i64_i32 v[18:19], s[4:5], v16, s73, v[18:19]
	v_mad_i64_i32 v[24:25], s[4:5], v17, s72, v[24:25]
	v_cndmask_b32_e64 v19, v25, v19, s[12:13]
	v_cndmask_b32_e64 v18, v24, v18, s[12:13]
	v_lshl_add_u64 v[18:19], v[148:149], 1, v[18:19]
	s_and_b64 vcc, exec, s[8:9]
	v_cvt_pk_bf16_f32 v20, v12, v13
	v_cvt_pk_bf16_f32 v21, v14, v15
	v_cvt_pk_bf16_f32 v22, v8, v9
	v_cvt_pk_bf16_f32 v23, v10, v11
	flat_store_dwordx4 v[18:19], v[20:23] sc1
	s_cbranch_vccnz .LBB0_282
	s_nop 0
	v_pk_mul_f32 v[20:21], v[4:5], v[4:5]
	s_nop 0
	v_pk_fma_f32 v[20:21], v[20:21], s[46:47], v[146:147] op_sel_hi:[1,0,0]
	s_nop 0
	v_pk_mul_f32 v[20:21], v[4:5], v[20:21]
	s_nop 0
	v_exp_f32_e32 v20, v20
	v_exp_f32_e32 v21, v21
	s_nop 0
	v_pk_add_f32 v[20:21], v[20:21], 1.0 op_sel_hi:[1,0]
	s_nop 0
	v_rcp_f32_e32 v20, v20
	v_rcp_f32_e32 v21, v21
	s_nop 0
	v_pk_mul_f32 v[4:5], v[4:5], v[20:21]

.LBB0_288:
	s_and_b64 vcc, exec, s[14:15]
	v_cvt_pk_bf16_f32 v20, v4, v5
	v_cvt_pk_bf16_f32 v21, v6, v7
	v_cvt_pk_bf16_f32 v22, v0, v1
	v_cvt_pk_bf16_f32 v23, v2, v3
	flat_store_dwordx4 v[18:19], v[20:23] offset:256 sc1
	s_cbranch_vccnz .LBB0_292
	v_pk_mul_f32 v[12:13], v[12:13], v[12:13]
	v_pk_mul_f32 v[14:15], v[14:15], v[14:15]
	v_pk_mul_f32 v[8:9], v[8:9], v[8:9]
	v_add_f32_e32 v14, v14, v15
	v_add_f32_e32 v12, v12, v13
	v_pk_mul_f32 v[10:11], v[10:11], v[10:11]
	v_add_f32_e32 v12, v12, v14
	v_add_f32_e32 v8, v8, v9
	v_pk_mul_f32 v[4:5], v[4:5], v[4:5]
	v_add_f32_e32 v8, v12, v8
	v_add_f32_e32 v9, v10, v11
	v_pk_mul_f32 v[6:7], v[6:7], v[6:7]
	v_add_f32_e32 v8, v8, v9
	v_add_f32_e32 v4, v4, v5
	v_pk_mul_f32 v[0:1], v[0:1], v[0:1]
	v_add_f32_e32 v4, v8, v4
	v_add_f32_e32 v5, v6, v7
	v_pk_mul_f32 v[2:3], v[2:3], v[2:3]
	v_add_f32_e32 v4, v4, v5
	v_add_f32_e32 v0, v0, v1
	v_add_f32_e32 v0, v4, v0
	v_add_f32_e32 v1, v2, v3
	v_and_b32_e32 v2, 64, v159
	v_add_f32_e32 v0, v0, v1
	v_xor_b32_e32 v1, 16, v159
	v_add_u32_e32 v2, 64, v2
	v_cmp_lt_i32_e32 vcc, v1, v2
	s_nop 1
	v_cndmask_b32_e32 v1, v159, v1, vcc
	v_lshlrev_b32_e32 v1, 2, v1
	ds_bpermute_b32 v1, v1, v0
	s_waitcnt lgkmcnt(0)
	v_add_f32_e32 v0, v0, v1
	v_xor_b32_e32 v1, 32, v159
	v_cmp_lt_i32_e32 vcc, v1, v2
	s_nop 1
	v_cndmask_b32_e32 v1, v159, v1, vcc
	v_lshlrev_b32_e32 v1, 2, v1
	ds_bpermute_b32 v1, v1, v0
	s_and_saveexec_b64 s[8:9], s[10:11]
	s_cbranch_execz .LBB0_291
	v_ashrrev_i32_e32 v17, 31, v16
	v_lshlrev_b64 v[2:3], 6, v[16:17]
	v_lshl_add_u64 v[2:3], s[30:31], 0, v[2:3]
	v_lshl_add_u64 v[2:3], s[56:57], 2, v[2:3]
	s_lshl_b32 s22, s65, 2
	v_lshl_add_u64 v[2:3], v[2:3], 0, s[22:23]
	s_waitcnt lgkmcnt(0)
	v_add_f32_e32 v0, v0, v1
	flat_store_dword v[2:3], v0 sc1

.LBB0_349:
	v_or_b32_e32 v0, s50, v20
	v_mov_b64_e32 v[54:55], s[46:47]
	s_mul_i32 s33, s51, 0x3400
	v_mad_u64_u32 v[0:1], s[4:5], v0, s54, v[54:55]
	v_add_u32_e32 v1, s33, v1
	s_lshl_b32 s16, s52, 8
	v_or_b32_e32 v2, s50, v28
	v_lshl_add_u64 v[0:1], v[0:1], 0, s[16:17]
	v_mad_u64_u32 v[2:3], s[4:5], v2, s54, v[54:55]
	v_lshl_add_u64 v[0:1], v[0:1], 0, v[22:23]
	v_add_u32_e32 v3, s33, v3
	v_add_co_u32_e32 v0, vcc, s27, v0
	v_lshl_add_u64 v[2:3], v[2:3], 0, s[16:17]
	s_nop 0
	v_addc_co_u32_e32 v1, vcc, 0, v1, vcc
	v_lshl_add_u64 v[2:3], v[2:3], 0, v[22:23]
	v_add_co_u32_e32 v2, vcc, s27, v2
	v_mov_b32_e32 v51, v23
	s_nop 0
	v_addc_co_u32_e32 v3, vcc, 0, v3, vcc
	flat_load_dwordx4 v[4:7], v[0:1] offset:3072
	flat_load_dwordx4 v[8:11], v[2:3] offset:3072
	v_lshl_add_u64 v[2:3], s[50:51], 0, v[32:33]
	v_mad_u64_u32 v[16:17], s[4:5], v2, s54, v[54:55]
	v_mov_b32_e32 v2, v17
	v_mad_u64_u32 v[2:3], s[4:5], v3, s54, v[2:3]
	v_or_b32_e32 v0, s50, v30
	v_mov_b32_e32 v17, v2
	v_mad_u64_u32 v[0:1], s[4:5], v0, s54, v[54:55]
	v_lshl_add_u64 v[2:3], v[16:17], 0, s[16:17]
	v_lshl_add_u64 v[16:17], s[50:51], 0, v[26:27]
	v_add_u32_e32 v1, s33, v1
	v_mad_u64_u32 v[18:19], s[4:5], v16, s54, v[54:55]
	v_lshl_add_u64 v[0:1], v[0:1], 0, s[16:17]
	v_mov_b32_e32 v16, v19
	v_lshl_add_u64 v[0:1], v[0:1], 0, v[22:23]
	v_mad_u64_u32 v[16:17], s[4:5], v17, s54, v[16:17]
	v_add_co_u32_e32 v0, vcc, s27, v0
	v_mov_b32_e32 v19, v16
	s_nop 0
	v_addc_co_u32_e32 v1, vcc, 0, v1, vcc
	v_lshl_add_u64 v[2:3], v[2:3], 0, v[22:23]
	v_lshl_add_u64 v[16:17], v[18:19], 0, s[16:17]
	v_add_co_u32_e32 v2, vcc, s27, v2
	v_mov_b32_e32 v53, v23
	v_lshl_add_u64 v[16:17], v[16:17], 0, v[50:51]
	v_addc_co_u32_e32 v3, vcc, 0, v3, vcc
	v_lshl_add_u64 v[16:17], v[16:17], 0, v[52:53]
	v_add_co_u32_e32 v62, vcc, s27, v16
	v_lshl_add_u64 v[60:61], v[16:17], 0, s[22:23]
	s_nop 0
	v_addc_co_u32_e32 v63, vcc, 0, v17, vcc
	v_lshl_add_u64 v[64:65], v[16:17], 0, s[24:25]
	v_add_co_u32_e32 v16, vcc, s57, v16
	s_lshl_b32 s4, s52, 9
	s_nop 0
	v_addc_co_u32_e32 v17, vcc, 0, v17, vcc
	s_mov_b32 s5, s17
	flat_load_dwordx4 v[112:115], v[0:1] offset:3072
	s_nop 0
	flat_load_dwordx4 v[0:3], v[2:3] offset:3072
	s_nop 0
	flat_load_dwordx2 v[72:73], v[62:63] offset:1024
	flat_load_dwordx2 v[70:71], v[60:61] offset:32
	flat_load_dwordx2 v[68:69], v[60:61] offset:64
	flat_load_dwordx2 v[66:67], v[60:61] offset:96
	flat_load_dwordx2 v[58:59], v[16:17] offset:1024
	flat_load_dwordx2 v[56:57], v[64:65] offset:32
	flat_load_dwordx2 v[18:19], v[64:65] offset:64
	s_nop 0
	flat_load_dwordx2 v[16:17], v[64:65] offset:96
	v_lshl_add_u64 v[64:65], v[14:15], 0, s[4:5]
	s_waitcnt lgkmcnt(0)
	s_barrier
	flat_load_dwordx4 v[116:119], v[64:65]
	flat_load_dwordx4 v[120:123], v[64:65] offset:16
	ds_read_b32 v43, v25
	ds_read_b32 v47, v94
	ds_read_b32 v49, v97
	ds_read_b32 v111, v100
	s_add_i32 s60, s60, s38
	s_add_i32 s59, s59, s39
	s_cmpk_lt_i32 s60, 0x1000
	s_waitcnt vmcnt(0)
	v_lshlrev_b32_e32 v45, 16, v4
	v_and_b32_e32 v4, 0xffff0000, v4
	s_waitcnt lgkmcnt(0)
	v_mul_f32_e32 v4, v43, v4
	v_mul_f32_e32 v45, v43, v45
	v_lshlrev_b32_e32 v74, 16, v5
	v_and_b32_e32 v5, 0xffff0000, v5
	v_mul_f32_e32 v74, v43, v74
	v_mul_f32_e32 v5, v43, v5
	v_lshlrev_b32_e32 v75, 16, v6
	v_and_b32_e32 v6, 0xffff0000, v6
	v_mul_f32_e32 v75, v43, v75
	v_mul_f32_e32 v6, v43, v6
	v_lshlrev_b32_e32 v176, 16, v70
	v_and_b32_e32 v177, 0xffff0000, v70
	v_lshlrev_b32_e32 v178, 16, v71
	v_and_b32_e32 v179, 0xffff0000, v71
	v_lshlrev_b32_e32 v182, 16, v69
	v_and_b32_e32 v183, 0xffff0000, v69
	v_lshlrev_b32_e32 v180, 16, v68
	v_mul_f32_e32 v4, v4, v117
	v_mul_f32_e32 v45, v45, v116
	v_cvt_pk_bf16_f32 v4, v45, v4
	v_mul_f32_e32 v74, v74, v118
	v_mul_f32_e32 v5, v5, v119
	v_lshlrev_b32_e32 v116, 16, v7
	v_and_b32_e32 v7, 0xffff0000, v7
	ds_write_b16 v29, v4 offset:34816
	ds_write_b16_d16_hi v31, v4 offset:35088
	v_cvt_pk_bf16_f32 v4, v74, v5
	v_mul_f32_e32 v75, v75, v120
	v_mul_f32_e32 v6, v6, v121
	v_mul_f32_e32 v116, v43, v116
	v_mul_f32_e32 v7, v43, v7
	ds_write_b16 v29, v4 offset:35360
	ds_write_b16_d16_hi v31, v4 offset:35632
	v_cvt_pk_bf16_f32 v4, v75, v6
	v_mul_f32_e32 v116, v116, v122
	v_mul_f32_e32 v7, v7, v123
	ds_write_b16 v29, v4 offset:35904
	ds_write_b16_d16_hi v31, v4 offset:36176
	v_cvt_pk_bf16_f32 v4, v116, v7
	ds_write_b16 v29, v4 offset:36448
	ds_write_b16_d16_hi v31, v4 offset:36720
	flat_load_dwordx4 v[4:7], v[64:65]
	flat_load_dwordx4 v[116:119], v[64:65] offset:16
	v_lshlrev_b32_e32 v43, 16, v8
	v_and_b32_e32 v8, 0xffff0000, v8
	v_lshlrev_b32_e32 v45, 16, v9
	v_and_b32_e32 v9, 0xffff0000, v9
	v_mul_f32_e32 v43, v47, v43
	v_lshlrev_b32_e32 v74, 16, v10
	v_and_b32_e32 v10, 0xffff0000, v10
	v_lshlrev_b32_e32 v75, 16, v11
	v_and_b32_e32 v11, 0xffff0000, v11
	v_mul_f32_e32 v8, v47, v8
	v_mul_f32_e32 v45, v47, v45
	v_mul_f32_e32 v9, v47, v9
	v_mul_f32_e32 v74, v47, v74
	v_mul_f32_e32 v10, v47, v10
	v_mul_f32_e32 v75, v47, v75
	v_mul_f32_e32 v11, v47, v11
	v_lshlrev_b32_e32 v47, 16, v113
	v_mul_f32_e32 v47, v49, v47
	v_lshlrev_b32_e32 v120, 16, v2
	v_and_b32_e32 v121, 0xffff0000, v2
	v_lshlrev_b32_e32 v122, 16, v3
	v_and_b32_e32 v123, 0xffff0000, v3
	v_mul_f32_e32 v124, v111, v120
	v_mul_f32_e32 v125, v111, v121
	v_mul_f32_e32 v122, v111, v122
	v_and_b32_e32 v181, 0xffff0000, v68
	v_lshlrev_b32_e32 v184, 16, v66
	v_and_b32_e32 v185, 0xffff0000, v66
	v_lshlrev_b32_e32 v186, 16, v67
	v_and_b32_e32 v187, 0xffff0000, v67
	v_pk_mul_f32 v[66:67], v[176:177], v[176:177]
	v_pk_mul_f32 v[68:69], v[178:179], v[178:179]
	v_pk_mul_f32 v[70:71], v[180:181], v[180:181]
	s_waitcnt vmcnt(0) lgkmcnt(0)
	v_mul_f32_e32 v4, v43, v4
	v_mul_f32_e32 v5, v8, v5
	v_mul_f32_e32 v6, v45, v6
	v_mul_f32_e32 v7, v9, v7
	v_cvt_pk_bf16_f32 v4, v4, v5
	v_mul_f32_e32 v8, v74, v116
	v_mul_f32_e32 v9, v10, v117
	v_mul_f32_e32 v10, v75, v118
	v_mul_f32_e32 v11, v11, v119
	v_cvt_pk_bf16_f32 v5, v6, v7
	v_cvt_pk_bf16_f32 v6, v8, v9
	v_cvt_pk_bf16_f32 v7, v10, v11
	ds_write_b16 v95, v4 offset:34816
	ds_write_b16_d16_hi v96, v4 offset:35088
	ds_write_b16 v95, v5 offset:35360
	ds_write_b16_d16_hi v96, v5 offset:35632
	ds_write_b16 v95, v6 offset:35904
	ds_write_b16_d16_hi v96, v6 offset:36176
	ds_write_b16 v95, v7 offset:36448
	ds_write_b16_d16_hi v96, v7 offset:36720
	flat_load_dwordx4 v[4:7], v[64:65]
	flat_load_dwordx4 v[8:11], v[64:65] offset:16
	v_lshlrev_b32_e32 v43, 16, v112
	v_and_b32_e32 v45, 0xffff0000, v112
	v_and_b32_e32 v74, 0xffff0000, v113
	v_mul_f32_e32 v43, v49, v43
	v_lshlrev_b32_e32 v75, 16, v114
	v_and_b32_e32 v112, 0xffff0000, v114
	v_lshlrev_b32_e32 v113, 16, v115
	v_and_b32_e32 v114, 0xffff0000, v115
	v_mul_f32_e32 v45, v49, v45
	v_mul_f32_e32 v74, v49, v74
	v_mul_f32_e32 v75, v49, v75
	v_mul_f32_e32 v112, v49, v112
	v_mul_f32_e32 v113, v49, v113
	v_mul_f32_e32 v49, v49, v114
	v_pk_mul_f32 v[114:115], v[182:183], v[182:183]
	v_pk_mul_f32 v[118:119], v[186:187], v[186:187]
	v_pk_mul_f32 v[116:117], v[184:185], v[184:185]
	s_waitcnt vmcnt(0) lgkmcnt(0)
	v_mul_f32_e32 v4, v43, v4
	v_mul_f32_e32 v5, v45, v5
	v_mul_f32_e32 v6, v47, v6
	v_mul_f32_e32 v7, v74, v7
	v_cvt_pk_bf16_f32 v4, v4, v5
	v_mul_f32_e32 v8, v75, v8
	v_mul_f32_e32 v9, v112, v9
	v_mul_f32_e32 v10, v113, v10
	v_mul_f32_e32 v11, v49, v11
	v_cvt_pk_bf16_f32 v5, v6, v7
	v_cvt_pk_bf16_f32 v6, v8, v9
	v_cvt_pk_bf16_f32 v7, v10, v11
	ds_write_b16 v98, v4 offset:34816
	ds_write_b16_d16_hi v99, v4 offset:35088
	ds_write_b16 v98, v5 offset:35360
	ds_write_b16_d16_hi v99, v5 offset:35632
	ds_write_b16 v98, v6 offset:35904
	ds_write_b16_d16_hi v99, v6 offset:36176
	ds_write_b16 v98, v7 offset:36448
	ds_write_b16_d16_hi v99, v7 offset:36720
	flat_load_dwordx4 v[8:11], v[64:65]
	flat_load_dwordx4 v[4:7], v[64:65] offset:16
	v_or_b32_e32 v43, s52, v92
	v_mov_b32_e32 v75, v23
	v_lshlrev_b32_e32 v74, 2, v43
	v_lshl_add_u64 v[112:113], s[36:37], 0, v[74:75]
	v_lshlrev_b32_e32 v74, 16, v72
	v_and_b32_e32 v75, 0xffff0000, v72
	v_lshlrev_b32_e32 v72, 16, v73
	v_and_b32_e32 v73, 0xffff0000, v73
	v_mov_b64_e32 v[64:65], s[28:29]
	v_pk_mul_f32 v[2:3], v[72:73], v[72:73]
	v_lshlrev_b32_e32 v43, 16, v0
	v_pk_fma_f32 v[2:3], v[2:3], s[26:27], v[64:65] op_sel_hi:[1,0,0] neg_lo:[1,0,0] neg_hi:[1,0,0]
	v_and_b32_e32 v45, 0xffff0000, v0
	v_mul_f32_e32 v43, v111, v43
	v_pk_mul_f32 v[2:3], v[2:3], v[72:73]
	v_lshlrev_b32_e32 v47, 16, v1
	v_and_b32_e32 v49, 0xffff0000, v1
	v_mul_f32_e32 v45, v111, v45
	v_exp_f32_e32 v120, v2
	v_mul_f32_e32 v47, v111, v47
	v_mul_f32_e32 v49, v111, v49
	v_mul_f32_e32 v111, v111, v123
	v_exp_f32_e32 v121, v3
	v_pk_mul_f32 v[0:1], v[74:75], v[74:75]
	v_pk_fma_f32 v[66:67], v[66:67], s[26:27], v[64:65] op_sel_hi:[1,0,0] neg_lo:[1,0,0] neg_hi:[1,0,0]
	v_pk_fma_f32 v[0:1], v[0:1], s[26:27], v[64:65] op_sel_hi:[1,0,0] neg_lo:[1,0,0] neg_hi:[1,0,0]
	v_pk_fma_f32 v[68:69], v[68:69], s[26:27], v[64:65] op_sel_hi:[1,0,0] neg_lo:[1,0,0] neg_hi:[1,0,0]
	v_pk_fma_f32 v[114:115], v[114:115], s[26:27], v[64:65] op_sel_hi:[1,0,0] neg_lo:[1,0,0] neg_hi:[1,0,0]
	v_pk_mul_f32 v[0:1], v[0:1], v[74:75]
	v_pk_mul_f32 v[66:67], v[66:67], v[176:177]
	v_pk_mul_f32 v[68:69], v[68:69], v[178:179]
	v_pk_mul_f32 v[114:115], v[114:115], v[182:183]
	v_exp_f32_e32 v0, v0
	v_exp_f32_e32 v1, v1
	v_exp_f32_e32 v66, v66
	v_exp_f32_e32 v67, v67
	v_exp_f32_e32 v68, v68
	v_exp_f32_e32 v69, v69
	v_exp_f32_e32 v123, v115
	v_pk_fma_f32 v[118:119], v[118:119], s[26:27], v[64:65] op_sel_hi:[1,0,0] neg_lo:[1,0,0] neg_hi:[1,0,0]
	v_pk_add_f32 v[136:137], v[0:1], 1.0 op_sel_hi:[1,0]
	v_pk_mul_f32 v[118:119], v[118:119], v[186:187]
	v_pk_add_f32 v[140:141], v[120:121], 1.0 op_sel_hi:[1,0]
	v_exp_f32_e32 v128, v118
	v_exp_f32_e32 v129, v119
	v_pk_add_f32 v[144:145], v[66:67], 1.0 op_sel_hi:[1,0]
	v_pk_add_f32 v[148:149], v[68:69], 1.0 op_sel_hi:[1,0]
	v_pk_fma_f32 v[116:117], v[116:117], s[26:27], v[64:65] op_sel_hi:[1,0,0] neg_lo:[1,0,0] neg_hi:[1,0,0]
	v_pk_add_f32 v[172:173], v[128:129], 1.0 op_sel_hi:[1,0]
	v_pk_mul_f32 v[116:117], v[116:117], v[184:185]
	v_rcp_f32_e32 v174, v136
	v_rcp_f32_e32 v175, v137
	v_rcp_f32_e32 v188, v140
	v_rcp_f32_e32 v189, v141
	v_rcp_f32_e32 v190, v144
	v_rcp_f32_e32 v191, v145
	v_rcp_f32_e32 v192, v148
	v_rcp_f32_e32 v193, v149
	v_pk_fma_f32 v[70:71], v[70:71], s[26:27], v[64:65] op_sel_hi:[1,0,0] neg_lo:[1,0,0] neg_hi:[1,0,0]
	v_rcp_f32_e32 v202, v172
	v_pk_mul_f32 v[70:71], v[70:71], v[180:181]
	v_rcp_f32_e32 v203, v173
	v_exp_f32_e32 v70, v70
	v_exp_f32_e32 v71, v71
	v_pk_mul_f32 v[74:75], v[174:175], v[74:75]
	v_pk_mul_f32 v[204:205], v[188:189], v[72:73]
	v_pk_mul_f32 v[206:207], v[190:191], v[176:177]
	v_pk_add_f32 v[70:71], v[70:71], 1.0 op_sel_hi:[1,0]
	v_pk_mul_f32 v[192:193], v[192:193], v[178:179]
	v_rcp_f32_e32 v194, v70
	v_rcp_f32_e32 v195, v71
	v_pk_mul_f32 v[202:203], v[202:203], v[186:187]
	v_pk_mul_f32 v[194:195], v[194:195], v[180:181]
	s_waitcnt vmcnt(0) lgkmcnt(0)
	v_mul_f32_e32 v2, v43, v8
	v_mul_f32_e32 v3, v45, v9
	v_mul_f32_e32 v4, v124, v4
	v_mul_f32_e32 v5, v125, v5
	v_cvt_pk_bf16_f32 v2, v2, v3
	v_mul_f32_e32 v8, v47, v10
	v_mul_f32_e32 v9, v49, v11
	v_mul_f32_e32 v6, v122, v6
	v_mul_f32_e32 v7, v111, v7
	v_cvt_pk_bf16_f32 v3, v8, v9
	v_cvt_pk_bf16_f32 v4, v4, v5
	v_cvt_pk_bf16_f32 v5, v6, v7
	ds_write_b16 v101, v2 offset:34816
	ds_write_b16_d16_hi v102, v2 offset:35088
	ds_write_b16 v101, v3 offset:35360
	ds_write_b16_d16_hi v102, v3 offset:35632
	ds_write_b16 v101, v4 offset:35904
	ds_write_b16_d16_hi v102, v4 offset:36176
	ds_write_b16 v101, v5 offset:36448
	ds_write_b16_d16_hi v102, v5 offset:36720
	s_waitcnt lgkmcnt(0)
	s_barrier
	flat_load_dword v43, v[112:113]
	v_exp_f32_e32 v122, v114
	ds_read_b128 v[0:3], v76 offset:34816
	ds_read_b128 v[4:7], v110
	ds_read_b128 v[8:11], v77 offset:34816
	ds_read_b128 v[66:69], v78 offset:34816
	ds_read_b128 v[112:115], v110 offset:64
	v_pk_add_f32 v[164:165], v[122:123], 1.0 op_sel_hi:[1,0]
	ds_read_b128 v[120:123], v79 offset:34816
	ds_read_b128 v[128:131], v80 offset:34816
	ds_read_b128 v[136:139], v81 offset:34816
	ds_read_b128 v[140:143], v82 offset:34816
	ds_read_b128 v[144:147], v83 offset:34816
	ds_read_b128 v[148:151], v84 offset:34816
	v_exp_f32_e32 v124, v116
	v_exp_f32_e32 v125, v117
	s_waitcnt lgkmcnt(0)
	v_mfma_f32_16x16x32_bf16 v[116:119], v[0:3], v[4:7], 0
	ds_read_b128 v[152:155], v110 offset:128
	ds_read_b128 v[156:159], v85 offset:34816
	v_rcp_f32_e32 v198, v164
	v_pk_add_f32 v[168:169], v[124:125], 1.0 op_sel_hi:[1,0]
	v_mfma_f32_16x16x32_bf16 v[124:127], v[8:11], v[4:7], 0
	v_rcp_f32_e32 v199, v165
	v_rcp_f32_e32 v200, v168
	v_rcp_f32_e32 v201, v169
	v_mfma_f32_16x16x32_bf16 v[132:135], v[66:69], v[4:7], 0
	v_mul_f32_e64 v198, v198, v182
	v_mul_f32_e64 v199, v199, v183
	v_pk_mul_f32 v[200:201], v[200:201], v[184:185]
	v_mfma_f32_16x16x32_bf16 v[4:7], v[120:123], v[4:7], 0
	v_mfma_f32_16x16x32_bf16 v[116:119], v[128:131], v[112:115], v[116:119]
	v_mfma_f32_16x16x32_bf16 v[124:127], v[136:139], v[112:115], v[124:127]
	v_mfma_f32_16x16x32_bf16 v[132:135], v[140:143], v[112:115], v[132:135]
	v_mfma_f32_16x16x32_bf16 v[4:7], v[144:147], v[112:115], v[4:7]
	ds_read_b128 v[112:115], v86 offset:34816
	ds_read_b128 v[160:163], v110 offset:192
	ds_read_b128 v[164:167], v87 offset:34816
	ds_read_b128 v[168:171], v88 offset:34816
	s_waitcnt lgkmcnt(0)
	v_mfma_f32_16x16x32_bf16 v[116:119], v[148:151], v[152:155], v[116:119]
	ds_read_b128 v[172:175], v89 offset:34816
	ds_read_b128 v[70:73], v90 offset:34816
	v_mfma_f32_16x16x32_bf16 v[124:127], v[156:159], v[152:155], v[124:127]
	v_mfma_f32_16x16x32_bf16 v[132:135], v[112:115], v[152:155], v[132:135]
	v_mfma_f32_16x16x32_bf16 v[4:7], v[164:167], v[152:155], v[4:7]
	ds_read_b128 v[152:155], v91 offset:34816
	ds_read_b128 v[176:179], v110 offset:4352
	ds_read_b128 v[180:183], v110 offset:4416
	ds_read_b128 v[184:187], v110 offset:4480
	ds_read_b128 v[188:191], v110 offset:4544
	v_mfma_f32_16x16x32_bf16 v[116:119], v[168:171], v[160:163], v[116:119]
	s_waitcnt lgkmcnt(0)
	v_mfma_f32_16x16x32_bf16 v[124:127], v[172:175], v[160:163], v[124:127]
	v_mfma_f32_16x16x32_bf16 v[132:135], v[70:73], v[160:163], v[132:135]
	s_waitcnt vmcnt(0)
	s_nop 3
	v_add_f32_e32 v45, v116, v43
	v_mfma_f32_16x16x32_bf16 v[4:7], v[152:155], v[160:163], v[4:7]
	v_add_f32_e32 v47, v117, v43
	v_add_f32_e32 v49, v118, v43
	v_add_f32_e32 v111, v119, v43
	v_add_f32_e32 v116, v124, v43
	v_add_f32_e32 v117, v125, v43
	v_add_f32_e32 v118, v126, v43
	v_add_f32_e32 v119, v127, v43
	v_add_f32_e32 v125, v133, v43
	v_add_f32_e32 v126, v134, v43
	v_add_f32_e32 v4, v4, v43
	v_add_f32_e32 v5, v5, v43
	v_add_f32_e32 v124, v132, v43
	v_add_f32_e32 v127, v135, v43
	v_add_f32_e32 v6, v6, v43
	v_add_f32_e32 v7, v7, v43
	v_mul_f32_e32 v43, v74, v45
	v_mul_f32_e32 v45, v75, v47
	v_mul_f32_e32 v47, v204, v49
	v_mul_f32_e32 v49, v205, v111
	v_mul_f32_e32 v74, v206, v116
	v_mul_f32_e32 v75, v207, v117
	v_mul_f32_e32 v111, v192, v118
	v_mul_f32_e32 v116, v193, v119
	v_mul_f32_e32 v118, v195, v125
	v_mul_f32_e32 v119, v198, v126
	v_mul_f32_e32 v125, v200, v4
	v_mul_f32_e32 v126, v201, v5
	v_cvt_pk_bf16_f32 v4, v43, v45
	v_cvt_pk_bf16_f32 v5, v47, v49
	v_mul_f32_e32 v117, v194, v124
	v_mul_f32_e32 v124, v199, v127
	v_mul_f32_e32 v127, v202, v6
	v_mul_f32_e32 v132, v203, v7
	v_cvt_pk_bf16_f32 v6, v74, v75
	v_cvt_pk_bf16_f32 v7, v111, v116
	v_cvt_pk_bf16_f32 v74, v117, v118
	v_cvt_pk_bf16_f32 v75, v119, v124
	flat_store_dwordx2 v[62:63], v[4:5] offset:1024 sc1
	flat_store_dwordx2 v[60:61], v[6:7] offset:32 sc1
	flat_store_dwordx2 v[60:61], v[74:75] offset:64 sc1
	v_or_b32_e32 v4, s52, v93
	v_lshlrev_b32_e32 v4, 2, v4
	v_mov_b32_e32 v5, v23
	v_cvt_pk_bf16_f32 v116, v125, v126
	v_cvt_pk_bf16_f32 v117, v127, v132
	flat_store_dwordx2 v[60:61], v[116:117] offset:96 sc1
	v_lshl_add_u64 v[4:5], s[36:37], 0, v[4:5]
	flat_load_dword v43, v[4:5]
	v_lshl_add_u64 v[6:7], s[50:51], 0, v[34:35]
	v_mfma_f32_16x16x32_bf16 v[2:5], v[0:3], v[176:179], 0
	v_mad_u64_u32 v[54:55], s[4:5], v6, s54, v[54:55]
	v_mov_b32_e32 v6, v55
	v_mfma_f32_16x16x32_bf16 v[60:63], v[66:69], v[176:179], 0
	v_mad_u64_u32 v[0:1], s[4:5], v7, s54, v[6:7]
	v_lshlrev_b32_e32 v74, 16, v58
	v_mfma_f32_16x16x32_bf16 v[66:69], v[120:123], v[176:179], 0
	v_and_b32_e32 v75, 0xffff0000, v58
	v_lshlrev_b32_e32 v116, 16, v59
	v_and_b32_e32 v117, 0xffff0000, v59
	v_mov_b32_e32 v55, v0
	v_mfma_f32_16x16x32_bf16 v[6:9], v[8:11], v[176:179], 0
	v_mul_f32_e64 v58, v74, v74
	v_mul_f32_e64 v59, v75, v75
	v_pk_mul_f32 v[122:123], v[116:117], v[116:117]
	v_lshl_add_u64 v[0:1], v[54:55], 0, s[16:17]
	v_mfma_f32_16x16x32_bf16 v[2:5], v[128:131], v[180:183], v[2:5]
	v_lshlrev_b32_e32 v118, 16, v56
	v_and_b32_e32 v119, 0xffff0000, v56
	v_lshlrev_b32_e32 v120, 16, v57
	v_and_b32_e32 v121, 0xffff0000, v57
	v_mfma_f32_16x16x32_bf16 v[54:57], v[140:143], v[180:183], v[60:63]
	v_fma_f32 v122, -v122, s26, v64
	v_fma_f32 v123, -v123, s26, v64
	v_pk_mul_f32 v[124:125], v[118:119], v[118:119]
	v_pk_mul_f32 v[126:127], v[120:121], v[120:121]
	v_pk_fma_f32 v[62:63], v[58:59], s[26:27], v[64:65] op_sel_hi:[1,0,0] neg_lo:[1,0,0] neg_hi:[1,0,0]
	v_mfma_f32_16x16x32_bf16 v[58:61], v[144:147], v[180:183], v[66:69]
	v_mul_f32_e64 v62, v62, v74
	v_mul_f32_e64 v63, v63, v75
	v_pk_fma_f32 v[124:125], v[124:125], s[26:27], v[64:65] op_sel_hi:[1,0,0] neg_lo:[1,0,0] neg_hi:[1,0,0]
	v_exp_f32_e32 v62, v62
	v_pk_mul_f32 v[68:69], v[122:123], v[116:117]
	v_exp_f32_e32 v63, v63
	v_exp_f32_e32 v68, v68
	v_exp_f32_e32 v69, v69
	v_mfma_f32_16x16x32_bf16 v[6:9], v[136:139], v[180:183], v[6:9]
	v_mul_f32_e64 v122, v124, v118
	v_mul_f32_e64 v123, v125, v119
	v_pk_add_f32 v[62:63], v[62:63], 1.0 op_sel_hi:[1,0]
	v_pk_add_f32 v[68:69], v[68:69], 1.0 op_sel_hi:[1,0]
	v_mfma_f32_16x16x32_bf16 v[2:5], v[148:151], v[184:187], v[2:5]
	v_fma_f32 v66, -v126, s26, v64
	v_fma_f32 v67, -v127, s26, v64
	v_rcp_f32_e32 v62, v62
	v_rcp_f32_e32 v63, v63
	v_mfma_f32_16x16x32_bf16 v[54:57], v[112:115], v[184:187], v[54:57]
	v_exp_f32_e32 v112, v122
	v_exp_f32_e32 v113, v123
	v_rcp_f32_e32 v68, v68
	v_mfma_f32_16x16x32_bf16 v[6:9], v[156:159], v[184:187], v[6:9]
	v_rcp_f32_e32 v69, v69
	v_pk_mul_f32 v[66:67], v[66:67], v[120:121]
	v_pk_add_f32 v[112:113], v[112:113], 1.0 op_sel_hi:[1,0]
	v_mfma_f32_16x16x32_bf16 v[2:5], v[168:171], v[188:191], v[2:5]
	v_exp_f32_e32 v66, v66
	v_exp_f32_e32 v67, v67
	v_lshl_add_u64 v[0:1], v[0:1], 0, v[50:51]
	v_mfma_f32_16x16x32_bf16 v[6:9], v[172:175], v[188:191], v[6:9]
	v_rcp_f32_e32 v112, v112
	v_rcp_f32_e32 v113, v113
	v_pk_mul_f32 v[62:63], v[62:63], v[74:75]
	v_pk_mul_f32 v[68:69], v[68:69], v[116:117]
	v_lshl_add_u64 v[10:11], v[0:1], 0, v[52:53]
	v_lshl_add_u64 v[0:1], v[10:11], 0, s[22:23]
	v_add_co_u32_e32 v10, vcc, s27, v10
	v_mfma_f32_16x16x32_bf16 v[54:57], v[70:73], v[188:191], v[54:57]
	s_nop 0
	v_addc_co_u32_e32 v11, vcc, 0, v11, vcc
	s_waitcnt vmcnt(0) lgkmcnt(0)
	v_add_f32_e32 v2, v2, v43
	v_add_f32_e32 v3, v3, v43
	v_add_f32_e32 v4, v4, v43
	v_add_f32_e32 v5, v5, v43
	v_mul_f32_e32 v2, v62, v2
	v_mul_f32_e32 v3, v63, v3
	v_mul_f32_e32 v4, v68, v4
	v_mul_f32_e32 v5, v69, v5
	v_cvt_pk_bf16_f32 v2, v2, v3
	v_cvt_pk_bf16_f32 v3, v4, v5
	v_pk_add_f32 v[4:5], v[66:67], 1.0 op_sel_hi:[1,0]
	flat_store_dwordx2 v[10:11], v[2:3] offset:1024 sc1
	v_rcp_f32_e32 v4, v4
	v_rcp_f32_e32 v5, v5
	v_pk_mul_f32 v[2:3], v[112:113], v[118:119]
	v_add_f32_e32 v6, v6, v43
	v_mul_f32_e32 v2, v2, v6
	v_add_f32_e32 v6, v7, v43
	v_mul_f32_e32 v3, v3, v6
	v_pk_mul_f32 v[4:5], v[4:5], v[120:121]
	v_cvt_pk_bf16_f32 v2, v2, v3
	v_add_f32_e32 v3, v8, v43
	v_mul_f32_e32 v3, v4, v3
	v_add_f32_e32 v4, v9, v43
	v_mul_f32_e32 v45, v5, v4
	v_lshlrev_b32_e32 v4, 16, v18
	v_and_b32_e32 v5, 0xffff0000, v18
	v_pk_mul_f32 v[6:7], v[4:5], v[4:5]
	v_lshlrev_b32_e32 v8, 16, v19
	v_pk_fma_f32 v[6:7], v[6:7], s[26:27], v[64:65] op_sel_hi:[1,0,0] neg_lo:[1,0,0] neg_hi:[1,0,0]
	v_and_b32_e32 v9, 0xffff0000, v19
	v_pk_mul_f32 v[6:7], v[6:7], v[4:5]
	v_pk_mul_f32 v[10:11], v[8:9], v[8:9]
	v_exp_f32_e32 v6, v6
	v_exp_f32_e32 v7, v7
	v_pk_fma_f32 v[10:11], v[10:11], s[26:27], v[64:65] op_sel_hi:[1,0,0] neg_lo:[1,0,0] neg_hi:[1,0,0]
	v_cvt_pk_bf16_f32 v3, v3, v45
	flat_store_dwordx2 v[0:1], v[2:3] offset:32 sc1
	v_pk_mul_f32 v[10:11], v[10:11], v[8:9]
	v_pk_add_f32 v[6:7], v[6:7], 1.0 op_sel_hi:[1,0]
	v_exp_f32_e32 v10, v10
	v_exp_f32_e32 v11, v11
	v_rcp_f32_e32 v6, v6
	v_rcp_f32_e32 v7, v7
	v_mfma_f32_16x16x32_bf16 v[58:61], v[164:167], v[184:187], v[58:61]
	v_add_f32_e64 v10, v10, 1.0
	v_add_f32_e64 v11, v11, 1.0
	v_pk_mul_f32 v[2:3], v[6:7], v[4:5]
	v_rcp_f32_e32 v10, v10
	v_rcp_f32_e32 v11, v11
	v_add_f32_e32 v6, v54, v43
	v_mul_f32_e32 v2, v2, v6
	v_add_f32_e32 v6, v55, v43
	v_mul_f32_e32 v3, v3, v6
	v_pk_mul_f32 v[4:5], v[10:11], v[8:9]
	v_cvt_pk_bf16_f32 v2, v2, v3
	v_add_f32_e32 v3, v56, v43
	v_mul_f32_e32 v3, v4, v3
	v_add_f32_e32 v4, v57, v43
	v_mul_f32_e32 v18, v5, v4
	v_lshlrev_b32_e32 v4, 16, v16
	v_and_b32_e32 v5, 0xffff0000, v16
	v_pk_mul_f32 v[6:7], v[4:5], v[4:5]
	v_lshlrev_b32_e32 v8, 16, v17
	v_pk_fma_f32 v[6:7], v[6:7], s[26:27], v[64:65] op_sel_hi:[1,0,0] neg_lo:[1,0,0] neg_hi:[1,0,0]
	v_and_b32_e32 v9, 0xffff0000, v17
	v_pk_mul_f32 v[6:7], v[6:7], v[4:5]
	v_pk_mul_f32 v[10:11], v[8:9], v[8:9]
	v_exp_f32_e32 v6, v6
	v_exp_f32_e32 v7, v7
	v_pk_fma_f32 v[10:11], v[10:11], s[26:27], v[64:65] op_sel_hi:[1,0,0] neg_lo:[1,0,0] neg_hi:[1,0,0]
	v_mfma_f32_16x16x32_bf16 v[58:61], v[152:155], v[188:191], v[58:61]
	v_mul_f32_e64 v10, v10, v8
	v_mul_f32_e64 v11, v11, v9
	v_pk_add_f32 v[6:7], v[6:7], 1.0 op_sel_hi:[1,0]
	v_exp_f32_e32 v10, v10
	v_exp_f32_e32 v11, v11
	v_rcp_f32_e32 v6, v6
	v_rcp_f32_e32 v7, v7
	v_cvt_pk_bf16_f32 v3, v3, v18
	v_pk_add_f32 v[10:11], v[10:11], 1.0 op_sel_hi:[1,0]
	flat_store_dwordx2 v[0:1], v[2:3] offset:64 sc1
	v_rcp_f32_e32 v10, v10
	v_rcp_f32_e32 v11, v11
	v_pk_mul_f32 v[2:3], v[6:7], v[4:5]
	v_add_f32_e32 v6, v58, v43
	v_mul_f32_e32 v2, v2, v6
	v_add_f32_e32 v6, v59, v43
	v_mul_f32_e32 v3, v3, v6
	v_pk_mul_f32 v[4:5], v[10:11], v[8:9]
	v_cvt_pk_bf16_f32 v2, v2, v3
	v_add_f32_e32 v3, v60, v43
	v_mul_f32_e32 v3, v4, v3
	v_add_f32_e32 v4, v61, v43
	v_mul_f32_e32 v4, v5, v4
	v_cvt_pk_bf16_f32 v3, v3, v4
	flat_store_dwordx2 v[0:1], v[2:3] offset:96 sc1
	s_cbranch_scc0 .LBB0_354

.LBB0_359:
	s_or_b64 exec, exec, s[50:51]
	s_waitcnt vmcnt(0) lgkmcnt(0)
	v_lshlrev_b32_e32 v62, 16, v60
	v_and_b32_e32 v63, 0xffff0000, v60
	v_lshlrev_b32_e32 v60, 16, v61
	v_and_b32_e32 v61, 0xffff0000, v61
	v_pk_fma_f32 v[62:63], v[0:1], v[62:63], v[16:17]
	v_pk_fma_f32 v[60:61], v[2:3], v[60:61], v[18:19]
	v_lshlrev_b32_e32 v68, 16, v58
	v_and_b32_e32 v69, 0xffff0000, v58
	v_lshlrev_b32_e32 v58, 16, v59
	v_and_b32_e32 v59, 0xffff0000, v59
	v_pk_fma_f32 v[58:59], v[6:7], v[58:59], v[60:61]
	v_pk_fma_f32 v[60:61], v[4:5], v[68:69], v[62:63]
	v_lshlrev_b32_e32 v62, 16, v66
	v_and_b32_e32 v63, 0xffff0000, v66
	v_lshlrev_b32_e32 v66, 16, v67
	v_and_b32_e32 v67, 0xffff0000, v67
	v_pk_fma_f32 v[60:61], v[8:9], v[62:63], v[60:61]
	v_lshlrev_b32_e32 v62, 16, v64
	v_and_b32_e32 v63, 0xffff0000, v64
	v_add_u32_e32 v43, 1, v43
	v_pk_fma_f32 v[58:59], v[10:11], v[66:67], v[58:59]
	v_lshlrev_b32_e32 v64, 16, v65
	v_and_b32_e32 v65, 0xffff0000, v65
	v_pk_fma_f32 v[60:61], v[12:13], v[62:63], v[60:61]
	v_cmp_ge_i32_e32 vcc, v43, v104
	v_pk_fma_f32 v[58:59], v[14:15], v[64:65], v[58:59]
	v_cvt_pk_bf16_f32 v60, v60, v61
	v_lshl_add_u64 v[54:55], v[54:55], 0, s[30:31]
	v_cvt_pk_bf16_f32 v61, v58, v59
	flat_store_dwordx2 v[56:57], v[60:61] sc1
	s_or_b64 s[48:49], vcc, s[48:49]
	v_lshl_add_u64 v[56:57], v[56:57], 0, s[34:35]
	s_andn2_b64 exec, exec, s[48:49]
	s_cbranch_execz .LBB0_344
.Lc1_top:
	v_readfirstlane_b32 s84, v43
	v_readfirstlane_b32 s85, v104
	v_readfirstlane_b32 s88, v36
	v_readfirstlane_b32 s94, v56
	v_readfirstlane_b32 s95, v57
	v_lshlrev_b32_e32 v252, 1, v36
	s_nop 1
	s_lshl_b32 s88, s88, 1
	v_subrev_u32_e32 v252, s88, v252
	s_add_u32 s91, s84, 8
	s_cmp_gt_u32 s91, s85
	s_cbranch_scc1 .LBB0_360
	s_cmp_ge_u32 s84, 0x10000
	s_cbranch_scc1 .Lc1_ctx
	s_cmp_gt_u32 s91, 0x10000
	s_cbranch_scc1 .LBB0_360
	s_and_b32 s91, s84, 0x1fff
	s_cmp_lt_u32 s91, 2
	s_cbranch_scc1 .LBB0_360
	s_cmp_gt_u32 s91, 0x1ff7
	s_cbranch_scc1 .LBB0_360
	v_readfirstlane_b32 s86, v54
	v_readfirstlane_b32 s87, v55
	s_nop 1
	s_add_u32 s86, s86, s88
	s_addc_u32 s87, s87, 0
	s_sub_u32 s92, s86, 0x6800
	s_subb_u32 s93, s87, 0
	global_load_dwordx2 v[208:209], v252, s[92:93]
	s_add_u32 s92, s92, 0x3400
	s_addc_u32 s93, s93, 0
	global_load_dwordx2 v[212:213], v252, s[92:93]
	s_add_u32 s92, s92, 0x3400
	s_addc_u32 s93, s93, 0
	global_load_dwordx2 v[216:217], v252, s[92:93]
	s_add_u32 s92, s92, 0x3400
	s_addc_u32 s93, s93, 0
	global_load_dwordx2 v[220:221], v252, s[92:93]
	s_add_u32 s92, s92, 0x3400
	s_addc_u32 s93, s93, 0
	global_load_dwordx2 v[224:225], v252, s[92:93]
	s_add_u32 s92, s92, 0x3400
	s_addc_u32 s93, s93, 0
	global_load_dwordx2 v[228:229], v252, s[92:93]
	s_add_u32 s92, s92, 0x3400
	s_addc_u32 s93, s93, 0
	global_load_dwordx2 v[232:233], v252, s[92:93]
	s_add_u32 s92, s92, 0x3400
	s_addc_u32 s93, s93, 0
	global_load_dwordx2 v[236:237], v252, s[92:93]
	s_add_u32 s92, s92, 0x3400
	s_addc_u32 s93, s93, 0
	global_load_dwordx2 v[240:241], v252, s[92:93]
	s_add_u32 s92, s92, 0x3400
	s_addc_u32 s93, s93, 0
	global_load_dwordx2 v[244:245], v252, s[92:93]
	s_add_u32 s92, s92, 0x3400
	s_addc_u32 s93, s93, 0
	global_load_dwordx2 v[248:249], v252, s[92:93]
	s_waitcnt vmcnt(0)
	v_lshlrev_b32_e32 v210, 16, v209
	v_and_b32_e32 v211, 0xffff0000, v209
	v_and_b32_e32 v209, 0xffff0000, v208
	v_lshlrev_b32_e32 v208, 16, v208
	v_lshlrev_b32_e32 v214, 16, v213
	v_and_b32_e32 v215, 0xffff0000, v213
	v_and_b32_e32 v213, 0xffff0000, v212
	v_lshlrev_b32_e32 v212, 16, v212
	v_lshlrev_b32_e32 v218, 16, v217
	v_and_b32_e32 v219, 0xffff0000, v217
	v_and_b32_e32 v217, 0xffff0000, v216
	v_lshlrev_b32_e32 v216, 16, v216
	v_lshlrev_b32_e32 v222, 16, v221
	v_and_b32_e32 v223, 0xffff0000, v221
	v_and_b32_e32 v221, 0xffff0000, v220
	v_lshlrev_b32_e32 v220, 16, v220
	v_lshlrev_b32_e32 v226, 16, v225
	v_and_b32_e32 v227, 0xffff0000, v225
	v_and_b32_e32 v225, 0xffff0000, v224
	v_lshlrev_b32_e32 v224, 16, v224
	v_lshlrev_b32_e32 v230, 16, v229
	v_and_b32_e32 v231, 0xffff0000, v229
	v_and_b32_e32 v229, 0xffff0000, v228
	v_lshlrev_b32_e32 v228, 16, v228
	v_lshlrev_b32_e32 v234, 16, v233
	v_and_b32_e32 v235, 0xffff0000, v233
	v_and_b32_e32 v233, 0xffff0000, v232
	v_lshlrev_b32_e32 v232, 16, v232
	v_lshlrev_b32_e32 v238, 16, v237
	v_and_b32_e32 v239, 0xffff0000, v237
	v_and_b32_e32 v237, 0xffff0000, v236
	v_lshlrev_b32_e32 v236, 16, v236
	v_lshlrev_b32_e32 v242, 16, v241
	v_and_b32_e32 v243, 0xffff0000, v241
	v_and_b32_e32 v241, 0xffff0000, v240
	v_lshlrev_b32_e32 v240, 16, v240
	v_lshlrev_b32_e32 v246, 16, v245
	v_and_b32_e32 v247, 0xffff0000, v245
	v_and_b32_e32 v245, 0xffff0000, v244
	v_lshlrev_b32_e32 v244, 16, v244
	v_lshlrev_b32_e32 v250, 16, v249
	v_and_b32_e32 v251, 0xffff0000, v249
	v_and_b32_e32 v249, 0xffff0000, v248
	v_lshlrev_b32_e32 v248, 16, v248
	v_pk_fma_f32 v[208:209], v[0:1], v[208:209], v[16:17]
	v_pk_fma_f32 v[210:211], v[2:3], v[210:211], v[18:19]
	v_pk_fma_f32 v[208:209], v[4:5], v[212:213], v[208:209]
	v_pk_fma_f32 v[210:211], v[6:7], v[214:215], v[210:211]
	v_pk_fma_f32 v[208:209], v[8:9], v[216:217], v[208:209]
	v_pk_fma_f32 v[210:211], v[10:11], v[218:219], v[210:211]
	v_pk_fma_f32 v[208:209], v[12:13], v[220:221], v[208:209]
	v_pk_fma_f32 v[210:211], v[14:15], v[222:223], v[210:211]
	v_cvt_pk_bf16_f32 v208, v208, v209
	v_cvt_pk_bf16_f32 v209, v210, v211
	global_store_dwordx2 v252, v[208:209], s[94:95] sc1
	s_add_u32 s94, s94, 0xa00
	s_addc_u32 s95, s95, 0
	v_pk_fma_f32 v[212:213], v[0:1], v[212:213], v[16:17]
	v_pk_fma_f32 v[214:215], v[2:3], v[214:215], v[18:19]
	v_pk_fma_f32 v[212:213], v[4:5], v[216:217], v[212:213]
	v_pk_fma_f32 v[214:215], v[6:7], v[218:219], v[214:215]
	v_pk_fma_f32 v[212:213], v[8:9], v[220:221], v[212:213]
	v_pk_fma_f32 v[214:215], v[10:11], v[222:223], v[214:215]
	v_pk_fma_f32 v[212:213], v[12:13], v[224:225], v[212:213]
	v_pk_fma_f32 v[214:215], v[14:15], v[226:227], v[214:215]
	v_cvt_pk_bf16_f32 v212, v212, v213
	v_cvt_pk_bf16_f32 v213, v214, v215
	global_store_dwordx2 v252, v[212:213], s[94:95] sc1
	s_add_u32 s94, s94, 0xa00
	s_addc_u32 s95, s95, 0
	v_pk_fma_f32 v[216:217], v[0:1], v[216:217], v[16:17]
	v_pk_fma_f32 v[218:219], v[2:3], v[218:219], v[18:19]
	v_pk_fma_f32 v[216:217], v[4:5], v[220:221], v[216:217]
	v_pk_fma_f32 v[218:219], v[6:7], v[222:223], v[218:219]
	v_pk_fma_f32 v[216:217], v[8:9], v[224:225], v[216:217]
	v_pk_fma_f32 v[218:219], v[10:11], v[226:227], v[218:219]
	v_pk_fma_f32 v[216:217], v[12:13], v[228:229], v[216:217]
	v_pk_fma_f32 v[218:219], v[14:15], v[230:231], v[218:219]
	v_cvt_pk_bf16_f32 v216, v216, v217
	v_cvt_pk_bf16_f32 v217, v218, v219
	global_store_dwordx2 v252, v[216:217], s[94:95] sc1
	s_add_u32 s94, s94, 0xa00
	s_addc_u32 s95, s95, 0
	v_pk_fma_f32 v[220:221], v[0:1], v[220:221], v[16:17]
	v_pk_fma_f32 v[222:223], v[2:3], v[222:223], v[18:19]
	v_pk_fma_f32 v[220:221], v[4:5], v[224:225], v[220:221]
	v_pk_fma_f32 v[222:223], v[6:7], v[226:227], v[222:223]
	v_pk_fma_f32 v[220:221], v[8:9], v[228:229], v[220:221]
	v_pk_fma_f32 v[222:223], v[10:11], v[230:231], v[222:223]
	v_pk_fma_f32 v[220:221], v[12:13], v[232:233], v[220:221]
	v_pk_fma_f32 v[222:223], v[14:15], v[234:235], v[222:223]
	v_cvt_pk_bf16_f32 v220, v220, v221
	v_cvt_pk_bf16_f32 v221, v222, v223
	global_store_dwordx2 v252, v[220:221], s[94:95] sc1
	s_add_u32 s94, s94, 0xa00
	s_addc_u32 s95, s95, 0
	v_pk_fma_f32 v[224:225], v[0:1], v[224:225], v[16:17]
	v_pk_fma_f32 v[226:227], v[2:3], v[226:227], v[18:19]
	v_pk_fma_f32 v[224:225], v[4:5], v[228:229], v[224:225]
	v_pk_fma_f32 v[226:227], v[6:7], v[230:231], v[226:227]
	v_pk_fma_f32 v[224:225], v[8:9], v[232:233], v[224:225]
	v_pk_fma_f32 v[226:227], v[10:11], v[234:235], v[226:227]
	v_pk_fma_f32 v[224:225], v[12:13], v[236:237], v[224:225]
	v_pk_fma_f32 v[226:227], v[14:15], v[238:239], v[226:227]
	v_cvt_pk_bf16_f32 v224, v224, v225
	v_cvt_pk_bf16_f32 v225, v226, v227
	global_store_dwordx2 v252, v[224:225], s[94:95] sc1
	s_add_u32 s94, s94, 0xa00
	s_addc_u32 s95, s95, 0
	v_pk_fma_f32 v[228:229], v[0:1], v[228:229], v[16:17]
	v_pk_fma_f32 v[230:231], v[2:3], v[230:231], v[18:19]
	v_pk_fma_f32 v[228:229], v[4:5], v[232:233], v[228:229]
	v_pk_fma_f32 v[230:231], v[6:7], v[234:235], v[230:231]
	v_pk_fma_f32 v[228:229], v[8:9], v[236:237], v[228:229]
	v_pk_fma_f32 v[230:231], v[10:11], v[238:239], v[230:231]
	v_pk_fma_f32 v[228:229], v[12:13], v[240:241], v[228:229]
	v_pk_fma_f32 v[230:231], v[14:15], v[242:243], v[230:231]
	v_cvt_pk_bf16_f32 v228, v228, v229
	v_cvt_pk_bf16_f32 v229, v230, v231
	global_store_dwordx2 v252, v[228:229], s[94:95] sc1
	s_add_u32 s94, s94, 0xa00
	s_addc_u32 s95, s95, 0
	v_pk_fma_f32 v[232:233], v[0:1], v[232:233], v[16:17]
	v_pk_fma_f32 v[234:235], v[2:3], v[234:235], v[18:19]
	v_pk_fma_f32 v[232:233], v[4:5], v[236:237], v[232:233]
	v_pk_fma_f32 v[234:235], v[6:7], v[238:239], v[234:235]
	v_pk_fma_f32 v[232:233], v[8:9], v[240:241], v[232:233]
	v_pk_fma_f32 v[234:235], v[10:11], v[242:243], v[234:235]
	v_pk_fma_f32 v[232:233], v[12:13], v[244:245], v[232:233]
	v_pk_fma_f32 v[234:235], v[14:15], v[246:247], v[234:235]
	v_cvt_pk_bf16_f32 v232, v232, v233
	v_cvt_pk_bf16_f32 v233, v234, v235
	global_store_dwordx2 v252, v[232:233], s[94:95] sc1
	s_add_u32 s94, s94, 0xa00
	s_addc_u32 s95, s95, 0
	v_pk_fma_f32 v[236:237], v[0:1], v[236:237], v[16:17]
	v_pk_fma_f32 v[238:239], v[2:3], v[238:239], v[18:19]
	v_pk_fma_f32 v[236:237], v[4:5], v[240:241], v[236:237]
	v_pk_fma_f32 v[238:239], v[6:7], v[242:243], v[238:239]
	v_pk_fma_f32 v[236:237], v[8:9], v[244:245], v[236:237]
	v_pk_fma_f32 v[238:239], v[10:11], v[246:247], v[238:239]
	v_pk_fma_f32 v[236:237], v[12:13], v[248:249], v[236:237]
	v_pk_fma_f32 v[238:239], v[14:15], v[250:251], v[238:239]
	v_cvt_pk_bf16_f32 v236, v236, v237
	v_cvt_pk_bf16_f32 v237, v238, v239
	global_store_dwordx2 v252, v[236:237], s[94:95] sc1
	s_mov_b32 s66, 0x1a000
	s_mov_b32 s67, 0
	s_mov_b32 s68, 0x5000
	s_mov_b32 s69, 0
	v_add_u32_e32 v43, 8, v43
	v_lshl_add_u64 v[54:55], v[54:55], 0, s[66:67]
	v_lshl_add_u64 v[56:57], v[56:57], 0, s[68:69]
	s_add_u32 s84, s84, 8
	s_cmp_lt_u32 s84, s85
	s_cbranch_scc1 .Lc1_top
	s_branch .LBB0_344
.Lc1_ctx:
	s_and_b32 s91, s84, 0xff
	s_cmp_lt_u32 s91, 2
	s_cbranch_scc1 .LBB0_360
	s_cmp_gt_u32 s91, 0xf7
	s_cbranch_scc1 .LBB0_360
	s_sub_u32 s91, s84, 0x10002
	s_mul_i32 s91, s91, 0xa00
	s_add_u32 s92, s46, s91
	s_addc_u32 s93, s47, 0
	s_add_u32 s92, s92, s88
	s_addc_u32 s93, s93, 0
	global_load_dwordx2 v[208:209], v252, s[92:93]
	s_add_u32 s92, s92, 0xa00
	s_addc_u32 s93, s93, 0
	global_load_dwordx2 v[212:213], v252, s[92:93]
	s_add_u32 s92, s92, 0xa00
	s_addc_u32 s93, s93, 0
	global_load_dwordx2 v[216:217], v252, s[92:93]
	s_add_u32 s92, s92, 0xa00
	s_addc_u32 s93, s93, 0
	global_load_dwordx2 v[220:221], v252, s[92:93]
	s_add_u32 s92, s92, 0xa00
	s_addc_u32 s93, s93, 0
	global_load_dwordx2 v[224:225], v252, s[92:93]
	s_add_u32 s92, s92, 0xa00
	s_addc_u32 s93, s93, 0
	global_load_dwordx2 v[228:229], v252, s[92:93]
	s_add_u32 s92, s92, 0xa00
	s_addc_u32 s93, s93, 0
	global_load_dwordx2 v[232:233], v252, s[92:93]
	s_add_u32 s92, s92, 0xa00
	s_addc_u32 s93, s93, 0
	global_load_dwordx2 v[236:237], v252, s[92:93]
	s_add_u32 s92, s92, 0xa00
	s_addc_u32 s93, s93, 0
	global_load_dwordx2 v[240:241], v252, s[92:93]
	s_add_u32 s92, s92, 0xa00
	s_addc_u32 s93, s93, 0
	global_load_dwordx2 v[244:245], v252, s[92:93]
	s_add_u32 s92, s92, 0xa00
	s_addc_u32 s93, s93, 0
	global_load_dwordx2 v[248:249], v252, s[92:93]
	s_waitcnt vmcnt(0)
	v_lshlrev_b32_e32 v210, 16, v209
	v_and_b32_e32 v211, 0xffff0000, v209
	v_and_b32_e32 v209, 0xffff0000, v208
	v_lshlrev_b32_e32 v208, 16, v208
	v_lshlrev_b32_e32 v214, 16, v213
	v_and_b32_e32 v215, 0xffff0000, v213
	v_and_b32_e32 v213, 0xffff0000, v212
	v_lshlrev_b32_e32 v212, 16, v212
	v_lshlrev_b32_e32 v218, 16, v217
	v_and_b32_e32 v219, 0xffff0000, v217
	v_and_b32_e32 v217, 0xffff0000, v216
	v_lshlrev_b32_e32 v216, 16, v216
	v_lshlrev_b32_e32 v222, 16, v221
	v_and_b32_e32 v223, 0xffff0000, v221
	v_and_b32_e32 v221, 0xffff0000, v220
	v_lshlrev_b32_e32 v220, 16, v220
	v_lshlrev_b32_e32 v226, 16, v225
	v_and_b32_e32 v227, 0xffff0000, v225
	v_and_b32_e32 v225, 0xffff0000, v224
	v_lshlrev_b32_e32 v224, 16, v224
	v_lshlrev_b32_e32 v230, 16, v229
	v_and_b32_e32 v231, 0xffff0000, v229
	v_and_b32_e32 v229, 0xffff0000, v228
	v_lshlrev_b32_e32 v228, 16, v228
	v_lshlrev_b32_e32 v234, 16, v233
	v_and_b32_e32 v235, 0xffff0000, v233
	v_and_b32_e32 v233, 0xffff0000, v232
	v_lshlrev_b32_e32 v232, 16, v232
	v_lshlrev_b32_e32 v238, 16, v237
	v_and_b32_e32 v239, 0xffff0000, v237
	v_and_b32_e32 v237, 0xffff0000, v236
	v_lshlrev_b32_e32 v236, 16, v236
	v_lshlrev_b32_e32 v242, 16, v241
	v_and_b32_e32 v243, 0xffff0000, v241
	v_and_b32_e32 v241, 0xffff0000, v240
	v_lshlrev_b32_e32 v240, 16, v240
	v_lshlrev_b32_e32 v246, 16, v245
	v_and_b32_e32 v247, 0xffff0000, v245
	v_and_b32_e32 v245, 0xffff0000, v244
	v_lshlrev_b32_e32 v244, 16, v244
	v_lshlrev_b32_e32 v250, 16, v249
	v_and_b32_e32 v251, 0xffff0000, v249
	v_and_b32_e32 v249, 0xffff0000, v248
	v_lshlrev_b32_e32 v248, 16, v248
	v_pk_fma_f32 v[208:209], v[0:1], v[208:209], v[16:17]
	v_pk_fma_f32 v[210:211], v[2:3], v[210:211], v[18:19]
	v_pk_fma_f32 v[208:209], v[4:5], v[212:213], v[208:209]
	v_pk_fma_f32 v[210:211], v[6:7], v[214:215], v[210:211]
	v_pk_fma_f32 v[208:209], v[8:9], v[216:217], v[208:209]
	v_pk_fma_f32 v[210:211], v[10:11], v[218:219], v[210:211]
	v_pk_fma_f32 v[208:209], v[12:13], v[220:221], v[208:209]
	v_pk_fma_f32 v[210:211], v[14:15], v[222:223], v[210:211]
	v_cvt_pk_bf16_f32 v208, v208, v209
	v_cvt_pk_bf16_f32 v209, v210, v211
	global_store_dwordx2 v252, v[208:209], s[94:95] sc1
	s_add_u32 s94, s94, 0xa00
	s_addc_u32 s95, s95, 0
	v_pk_fma_f32 v[212:213], v[0:1], v[212:213], v[16:17]
	v_pk_fma_f32 v[214:215], v[2:3], v[214:215], v[18:19]
	v_pk_fma_f32 v[212:213], v[4:5], v[216:217], v[212:213]
	v_pk_fma_f32 v[214:215], v[6:7], v[218:219], v[214:215]
	v_pk_fma_f32 v[212:213], v[8:9], v[220:221], v[212:213]
	v_pk_fma_f32 v[214:215], v[10:11], v[222:223], v[214:215]
	v_pk_fma_f32 v[212:213], v[12:13], v[224:225], v[212:213]
	v_pk_fma_f32 v[214:215], v[14:15], v[226:227], v[214:215]
	v_cvt_pk_bf16_f32 v212, v212, v213
	v_cvt_pk_bf16_f32 v213, v214, v215
	global_store_dwordx2 v252, v[212:213], s[94:95] sc1
	s_add_u32 s94, s94, 0xa00
	s_addc_u32 s95, s95, 0
	v_pk_fma_f32 v[216:217], v[0:1], v[216:217], v[16:17]
	v_pk_fma_f32 v[218:219], v[2:3], v[218:219], v[18:19]
	v_pk_fma_f32 v[216:217], v[4:5], v[220:221], v[216:217]
	v_pk_fma_f32 v[218:219], v[6:7], v[222:223], v[218:219]
	v_pk_fma_f32 v[216:217], v[8:9], v[224:225], v[216:217]
	v_pk_fma_f32 v[218:219], v[10:11], v[226:227], v[218:219]
	v_pk_fma_f32 v[216:217], v[12:13], v[228:229], v[216:217]
	v_pk_fma_f32 v[218:219], v[14:15], v[230:231], v[218:219]
	v_cvt_pk_bf16_f32 v216, v216, v217
	v_cvt_pk_bf16_f32 v217, v218, v219
	global_store_dwordx2 v252, v[216:217], s[94:95] sc1
	s_add_u32 s94, s94, 0xa00
	s_addc_u32 s95, s95, 0
	v_pk_fma_f32 v[220:221], v[0:1], v[220:221], v[16:17]
	v_pk_fma_f32 v[222:223], v[2:3], v[222:223], v[18:19]
	v_pk_fma_f32 v[220:221], v[4:5], v[224:225], v[220:221]
	v_pk_fma_f32 v[222:223], v[6:7], v[226:227], v[222:223]
	v_pk_fma_f32 v[220:221], v[8:9], v[228:229], v[220:221]
	v_pk_fma_f32 v[222:223], v[10:11], v[230:231], v[222:223]
	v_pk_fma_f32 v[220:221], v[12:13], v[232:233], v[220:221]
	v_pk_fma_f32 v[222:223], v[14:15], v[234:235], v[222:223]
	v_cvt_pk_bf16_f32 v220, v220, v221
	v_cvt_pk_bf16_f32 v221, v222, v223
	global_store_dwordx2 v252, v[220:221], s[94:95] sc1
	s_add_u32 s94, s94, 0xa00
	s_addc_u32 s95, s95, 0
	v_pk_fma_f32 v[224:225], v[0:1], v[224:225], v[16:17]
	v_pk_fma_f32 v[226:227], v[2:3], v[226:227], v[18:19]
	v_pk_fma_f32 v[224:225], v[4:5], v[228:229], v[224:225]
	v_pk_fma_f32 v[226:227], v[6:7], v[230:231], v[226:227]
	v_pk_fma_f32 v[224:225], v[8:9], v[232:233], v[224:225]
	v_pk_fma_f32 v[226:227], v[10:11], v[234:235], v[226:227]
	v_pk_fma_f32 v[224:225], v[12:13], v[236:237], v[224:225]
	v_pk_fma_f32 v[226:227], v[14:15], v[238:239], v[226:227]
	v_cvt_pk_bf16_f32 v224, v224, v225
	v_cvt_pk_bf16_f32 v225, v226, v227
	global_store_dwordx2 v252, v[224:225], s[94:95] sc1
	s_add_u32 s94, s94, 0xa00
	s_addc_u32 s95, s95, 0
	v_pk_fma_f32 v[228:229], v[0:1], v[228:229], v[16:17]
	v_pk_fma_f32 v[230:231], v[2:3], v[230:231], v[18:19]
	v_pk_fma_f32 v[228:229], v[4:5], v[232:233], v[228:229]
	v_pk_fma_f32 v[230:231], v[6:7], v[234:235], v[230:231]
	v_pk_fma_f32 v[228:229], v[8:9], v[236:237], v[228:229]
	v_pk_fma_f32 v[230:231], v[10:11], v[238:239], v[230:231]
	v_pk_fma_f32 v[228:229], v[12:13], v[240:241], v[228:229]
	v_pk_fma_f32 v[230:231], v[14:15], v[242:243], v[230:231]
	v_cvt_pk_bf16_f32 v228, v228, v229
	v_cvt_pk_bf16_f32 v229, v230, v231
	global_store_dwordx2 v252, v[228:229], s[94:95] sc1
	s_add_u32 s94, s94, 0xa00
	s_addc_u32 s95, s95, 0
	v_pk_fma_f32 v[232:233], v[0:1], v[232:233], v[16:17]
	v_pk_fma_f32 v[234:235], v[2:3], v[234:235], v[18:19]
	v_pk_fma_f32 v[232:233], v[4:5], v[236:237], v[232:233]
	v_pk_fma_f32 v[234:235], v[6:7], v[238:239], v[234:235]
	v_pk_fma_f32 v[232:233], v[8:9], v[240:241], v[232:233]
	v_pk_fma_f32 v[234:235], v[10:11], v[242:243], v[234:235]
	v_pk_fma_f32 v[232:233], v[12:13], v[244:245], v[232:233]
	v_pk_fma_f32 v[234:235], v[14:15], v[246:247], v[234:235]
	v_cvt_pk_bf16_f32 v232, v232, v233
	v_cvt_pk_bf16_f32 v233, v234, v235
	global_store_dwordx2 v252, v[232:233], s[94:95] sc1
	s_add_u32 s94, s94, 0xa00
	s_addc_u32 s95, s95, 0
	v_pk_fma_f32 v[236:237], v[0:1], v[236:237], v[16:17]
	v_pk_fma_f32 v[238:239], v[2:3], v[238:239], v[18:19]
	v_pk_fma_f32 v[236:237], v[4:5], v[240:241], v[236:237]
	v_pk_fma_f32 v[238:239], v[6:7], v[242:243], v[238:239]
	v_pk_fma_f32 v[236:237], v[8:9], v[244:245], v[236:237]
	v_pk_fma_f32 v[238:239], v[10:11], v[246:247], v[238:239]
	v_pk_fma_f32 v[236:237], v[12:13], v[248:249], v[236:237]
	v_pk_fma_f32 v[238:239], v[14:15], v[250:251], v[238:239]
	v_cvt_pk_bf16_f32 v236, v236, v237
	v_cvt_pk_bf16_f32 v237, v238, v239
	global_store_dwordx2 v252, v[236:237], s[94:95] sc1
	s_mov_b32 s66, 0x1a000
	s_mov_b32 s67, 0
	s_mov_b32 s68, 0x5000
	s_mov_b32 s69, 0
	v_add_u32_e32 v43, 8, v43
	v_lshl_add_u64 v[54:55], v[54:55], 0, s[66:67]
	v_lshl_add_u64 v[56:57], v[56:57], 0, s[68:69]
	s_add_u32 s84, s84, 8
	s_cmp_lt_u32 s84, s85
	s_cbranch_scc1 .Lc1_top
	s_branch .LBB0_344

.LBB0_435:
	s_waitcnt vmcnt(0) lgkmcnt(0)
	v_pk_fma_f32 v[150:151], v[150:151], s[36:37], v[94:95] op_sel_hi:[1,0,1] neg_lo:[1,0,0] neg_hi:[1,0,0]
	v_pk_fma_f32 v[148:149], v[148:149], s[36:37], v[92:93] op_sel_hi:[1,0,1] neg_lo:[1,0,0] neg_hi:[1,0,0]
	v_exp_f32_e32 v150, v150
	v_exp_f32_e32 v151, v151
	v_exp_f32_e32 v148, v148
	v_exp_f32_e32 v149, v149
	v_pk_fma_f32 v[146:147], v[146:147], s[36:37], v[86:87] op_sel_hi:[1,0,1] neg_lo:[1,0,0] neg_hi:[1,0,0]
	v_pk_add_f32 v[150:151], v[150:151], 1.0 op_sel_hi:[1,0]
	v_exp_f32_e32 v146, v146
	v_exp_f32_e32 v147, v147
	v_rcp_f32_e32 v150, v150
	v_rcp_f32_e32 v151, v151
	v_pk_add_f32 v[148:149], v[148:149], 1.0 op_sel_hi:[1,0]
	v_pk_add_f32 v[146:147], v[146:147], 1.0 op_sel_hi:[1,0]
	v_rcp_f32_e32 v148, v148
	v_rcp_f32_e32 v149, v149
	v_rcp_f32_e32 v202, v146
	v_rcp_f32_e32 v203, v147
	v_pk_mul_f32 v[146:147], v[90:91], v[150:151]
	v_pk_fma_f32 v[144:145], v[144:145], s[36:37], v[84:85] op_sel_hi:[1,0,1] neg_lo:[1,0,0] neg_hi:[1,0,0]
	v_pk_fma_f32 v[140:141], v[140:141], s[36:37], v[92:93] op_sel_hi:[1,0,1] neg_lo:[1,0,0] neg_hi:[1,0,0]
	v_exp_f32_e32 v146, v146
	v_exp_f32_e32 v147, v147
	v_exp_f32_e32 v204, v144
	v_exp_f32_e32 v205, v145
	v_pk_mul_f32 v[144:145], v[88:89], v[148:149]
	v_exp_f32_e32 v140, v140
	v_exp_f32_e32 v141, v141
	v_exp_f32_e32 v144, v144
	v_exp_f32_e32 v145, v145
	v_pk_fma_f32 v[150:151], v[146:147], v[146:147], 1.0 op_sel_hi:[1,1,0] neg_lo:[1,0,0] neg_hi:[1,0,0]
	v_pk_add_f32 v[148:149], v[204:205], 1.0 op_sel_hi:[1,0]
	v_pk_add_f32 v[140:141], v[140:141], 1.0 op_sel_hi:[1,0]
	v_sqrt_f32_e32 v150, v150
	v_sqrt_f32_e32 v151, v151
	v_rcp_f32_e32 v204, v148
	v_rcp_f32_e32 v205, v149
	v_pk_fma_f32 v[148:149], v[144:145], v[144:145], 1.0 op_sel_hi:[1,1,0] neg_lo:[1,0,0] neg_hi:[1,0,0]
	v_rcp_f32_e32 v140, v140
	v_rcp_f32_e32 v141, v141
	v_lshl_add_u32 v200, v217, 4, v215
	v_sqrt_f32_e32 v206, v148
	v_sqrt_f32_e32 v207, v149
	v_pk_fma_f32 v[142:143], v[142:143], s[36:37], v[94:95] op_sel_hi:[1,0,1] neg_lo:[1,0,0] neg_hi:[1,0,0]
	v_and_b32_e32 v223, 48, v200
	v_lshlrev_b32_e32 v200, 16, v188
	v_and_b32_e32 v201, 0xffff0000, v188
	v_lshlrev_b32_e32 v188, 16, v189
	v_and_b32_e32 v189, 0xffff0000, v189
	v_exp_f32_e32 v142, v142
	v_exp_f32_e32 v143, v143
	v_pk_mul_f32 v[148:149], v[202:203], v[188:189]
	v_pk_fma_f32 v[138:139], v[138:139], s[36:37], v[86:87] op_sel_hi:[1,0,1] neg_lo:[1,0,0] neg_hi:[1,0,0]
	v_pk_fma_f32 v[136:137], v[136:137], s[36:37], v[84:85] op_sel_hi:[1,0,1] neg_lo:[1,0,0] neg_hi:[1,0,0]
	v_pk_fma_f32 v[134:135], v[134:135], s[36:37], v[94:95] op_sel_hi:[1,0,1] neg_lo:[1,0,0] neg_hi:[1,0,0]
	v_pk_mul_f32 v[148:149], v[148:149], v[150:151]
	v_pk_mul_f32 v[150:151], v[204:205], v[200:201]
	v_exp_f32_e32 v138, v138
	v_exp_f32_e32 v139, v139
	v_exp_f32_e32 v136, v136
	v_exp_f32_e32 v137, v137
	v_pk_mul_f32 v[140:141], v[88:89], v[140:141]
	v_exp_f32_e32 v134, v134
	v_exp_f32_e32 v135, v135
	v_pk_mul_f32 v[150:151], v[150:151], v[206:207]
	v_exp_f32_e32 v206, v140
	v_exp_f32_e32 v207, v141
	v_pk_add_f32 v[142:143], v[142:143], 1.0 op_sel_hi:[1,0]
	v_pk_fma_f32 v[132:133], v[132:133], s[36:37], v[92:93] op_sel_hi:[1,0,1] neg_lo:[1,0,0] neg_hi:[1,0,0]
	v_rcp_f32_e32 v142, v142
	v_rcp_f32_e32 v143, v143
	v_exp_f32_e32 v132, v132
	v_exp_f32_e32 v133, v133
	v_pk_add_f32 v[138:139], v[138:139], 1.0 op_sel_hi:[1,0]
	v_pk_add_f32 v[136:137], v[136:137], 1.0 op_sel_hi:[1,0]
	v_pk_add_f32 v[134:135], v[134:135], 1.0 op_sel_hi:[1,0]
	v_pk_fma_f32 v[124:125], v[124:125], s[36:37], v[92:93] op_sel_hi:[1,0,1] neg_lo:[1,0,0] neg_hi:[1,0,0]
	v_rcp_f32_e32 v138, v138
	v_rcp_f32_e32 v139, v139
	v_rcp_f32_e32 v140, v136
	v_rcp_f32_e32 v141, v137
	v_pk_fma_f32 v[136:137], v[206:207], v[206:207], 1.0 op_sel_hi:[1,1,0] neg_lo:[1,0,0] neg_hi:[1,0,0]
	v_rcp_f32_e32 v134, v134
	v_rcp_f32_e32 v135, v135
	v_exp_f32_e32 v124, v124
	v_exp_f32_e32 v125, v125
	v_sqrt_f32_e32 v220, v136
	v_sqrt_f32_e32 v221, v137
	v_pk_fma_f32 v[126:127], v[126:127], s[36:37], v[94:95] op_sel_hi:[1,0,1] neg_lo:[1,0,0] neg_hi:[1,0,0]
	v_pk_mul_f32 v[142:143], v[90:91], v[142:143]
	v_pk_add_f32 v[132:133], v[132:133], 1.0 op_sel_hi:[1,0]
	v_exp_f32_e32 v126, v126
	v_exp_f32_e32 v127, v127
	v_lshlrev_b32_e32 v202, 16, v186
	v_and_b32_e32 v203, 0xffff0000, v186
	v_lshlrev_b32_e32 v186, 16, v187
	v_and_b32_e32 v187, 0xffff0000, v187
	v_exp_f32_e32 v204, v142
	v_exp_f32_e32 v205, v143
	v_pk_fma_f32 v[130:131], v[130:131], s[36:37], v[86:87] op_sel_hi:[1,0,1] neg_lo:[1,0,0] neg_hi:[1,0,0]
	v_rcp_f32_e32 v132, v132
	v_rcp_f32_e32 v133, v133
	v_pk_mul_f32 v[136:137], v[138:139], v[186:187]
	v_pk_mul_f32 v[138:139], v[140:141], v[202:203]
	v_exp_f32_e32 v130, v130
	v_exp_f32_e32 v131, v131
	v_pk_mul_f32 v[134:135], v[90:91], v[134:135]
	v_pk_add_f32 v[124:125], v[124:125], 1.0 op_sel_hi:[1,0]
	v_pk_mul_f32 v[138:139], v[138:139], v[220:221]
	v_exp_f32_e32 v220, v134
	v_exp_f32_e32 v221, v135
	v_rcp_f32_e32 v124, v124
	v_rcp_f32_e32 v125, v125
	v_pk_fma_f32 v[128:129], v[128:129], s[36:37], v[84:85] op_sel_hi:[1,0,1] neg_lo:[1,0,0] neg_hi:[1,0,0]
	v_pk_add_f32 v[126:127], v[126:127], 1.0 op_sel_hi:[1,0]
	v_pk_fma_f32 v[142:143], v[204:205], v[204:205], 1.0 op_sel_hi:[1,1,0] neg_lo:[1,0,0] neg_hi:[1,0,0]
	v_exp_f32_e32 v128, v128
	v_exp_f32_e32 v129, v129
	v_pk_mul_f32 v[132:133], v[88:89], v[132:133]
	v_rcp_f32_e32 v126, v126
	v_rcp_f32_e32 v127, v127
	v_sqrt_f32_e32 v142, v142
	v_sqrt_f32_e32 v143, v143
	v_pk_add_f32 v[130:131], v[130:131], 1.0 op_sel_hi:[1,0]
	v_exp_f32_e32 v224, v132
	v_exp_f32_e32 v225, v133
	v_pk_fma_f32 v[120:121], v[120:121], s[36:37], v[84:85] op_sel_hi:[1,0,1] neg_lo:[1,0,0] neg_hi:[1,0,0]
	v_rcp_f32_e32 v130, v130
	v_rcp_f32_e32 v131, v131
	v_pk_fma_f32 v[134:135], v[220:221], v[220:221], 1.0 op_sel_hi:[1,1,0] neg_lo:[1,0,0] neg_hi:[1,0,0]
	v_exp_f32_e32 v120, v120
	v_exp_f32_e32 v121, v121
	v_pk_mul_f32 v[124:125], v[88:89], v[124:125]
	v_sqrt_f32_e32 v134, v134
	v_sqrt_f32_e32 v135, v135
	v_pk_fma_f32 v[122:123], v[122:123], s[36:37], v[86:87] op_sel_hi:[1,0,1] neg_lo:[1,0,0] neg_hi:[1,0,0]
	v_exp_f32_e32 v124, v124
	v_exp_f32_e32 v125, v125
	v_pk_add_f32 v[128:129], v[128:129], 1.0 op_sel_hi:[1,0]
	v_exp_f32_e32 v122, v122
	v_exp_f32_e32 v123, v123
	v_pk_mul_f32 v[126:127], v[90:91], v[126:127]
	v_pk_mul_f32 v[136:137], v[136:137], v[142:143]
	v_lshlrev_b32_e32 v142, 16, v185
	v_and_b32_e32 v143, 0xffff0000, v185
	v_rcp_f32_e32 v132, v128
	v_rcp_f32_e32 v133, v129
	v_pk_fma_f32 v[128:129], v[224:225], v[224:225], 1.0 op_sel_hi:[1,1,0] neg_lo:[1,0,0] neg_hi:[1,0,0]
	v_exp_f32_e32 v126, v126
	v_exp_f32_e32 v127, v127
	v_lshlrev_b32_e32 v140, 16, v184
	v_and_b32_e32 v141, 0xffff0000, v184
	v_sqrt_f32_e32 v184, v128
	v_sqrt_f32_e32 v185, v129
	v_pk_mul_f32 v[128:129], v[130:131], v[142:143]
	v_pk_add_f32 v[120:121], v[120:121], 1.0 op_sel_hi:[1,0]
	v_pk_mul_f32 v[128:129], v[128:129], v[134:135]
	v_rcp_f32_e32 v120, v120
	v_rcp_f32_e32 v121, v121
	v_pk_fma_f32 v[134:135], v[124:125], v[124:125], 1.0 op_sel_hi:[1,1,0] neg_lo:[1,0,0] neg_hi:[1,0,0]
	v_pk_add_f32 v[122:123], v[122:123], 1.0 op_sel_hi:[1,0]
	v_sqrt_f32_e32 v134, v134
	v_sqrt_f32_e32 v135, v135
	v_pk_mul_f32 v[130:131], v[132:133], v[140:141]
	v_rcp_f32_e32 v122, v122
	v_rcp_f32_e32 v123, v123
	v_pk_fma_f32 v[132:133], v[126:127], v[126:127], 1.0 op_sel_hi:[1,1,0] neg_lo:[1,0,0] neg_hi:[1,0,0]
	v_pk_mul_f32 v[130:131], v[130:131], v[184:185]
	v_lshlrev_b32_e32 v184, 16, v182
	v_and_b32_e32 v185, 0xffff0000, v182
	v_sqrt_f32_e32 v132, v132
	v_sqrt_f32_e32 v133, v133
	v_mov_b32_e32 v219, v144
	v_pk_mul_f32 v[120:121], v[120:121], v[184:185]
	s_nop 1
v_fmac_f32_dpp v150, v150, v219 row_shr:1 row_mask:0xf bank_mask:0xf
v_fmac_f32_dpp v151, v151, v145 row_shr:1 row_mask:0xf bank_mask:0xf
v_fmac_f32_dpp v148, v148, v146 row_shr:1 row_mask:0xf bank_mask:0xf
v_fmac_f32_dpp v149, v149, v147 row_shr:1 row_mask:0xf bank_mask:0xf
v_mul_f32_dpp v219, v219, v219 row_shr:1 row_mask:0xf bank_mask:0xf
v_mul_f32_dpp v145, v145, v145 row_shr:1 row_mask:0xf bank_mask:0xf
v_mul_f32_dpp v146, v146, v146 row_shr:1 row_mask:0xf bank_mask:0xf
v_mul_f32_dpp v147, v147, v147 row_shr:1 row_mask:0xf bank_mask:0xf
v_fmac_f32_dpp v150, v150, v219 row_shr:2 row_mask:0xf bank_mask:0xf
v_fmac_f32_dpp v151, v151, v145 row_shr:2 row_mask:0xf bank_mask:0xf
v_fmac_f32_dpp v148, v148, v146 row_shr:2 row_mask:0xf bank_mask:0xf
v_fmac_f32_dpp v149, v149, v147 row_shr:2 row_mask:0xf bank_mask:0xf
v_mul_f32_dpp v219, v219, v219 row_shr:2 row_mask:0xf bank_mask:0xf
v_mul_f32_dpp v145, v145, v145 row_shr:2 row_mask:0xf bank_mask:0xf
v_mul_f32_dpp v146, v146, v146 row_shr:2 row_mask:0xf bank_mask:0xf
v_mul_f32_dpp v147, v147, v147 row_shr:2 row_mask:0xf bank_mask:0xf
v_fmac_f32_dpp v150, v150, v219 row_shr:4 row_mask:0xf bank_mask:0xf
v_fmac_f32_dpp v151, v151, v145 row_shr:4 row_mask:0xf bank_mask:0xf
v_fmac_f32_dpp v148, v148, v146 row_shr:4 row_mask:0xf bank_mask:0xf
v_fmac_f32_dpp v149, v149, v147 row_shr:4 row_mask:0xf bank_mask:0xf
v_mul_f32_dpp v219, v219, v219 row_shr:4 row_mask:0xf bank_mask:0xf
v_mul_f32_dpp v145, v145, v145 row_shr:4 row_mask:0xf bank_mask:0xf
v_mul_f32_dpp v146, v146, v146 row_shr:4 row_mask:0xf bank_mask:0xf
v_mul_f32_dpp v147, v147, v147 row_shr:4 row_mask:0xf bank_mask:0xf
v_fmac_f32_dpp v150, v150, v219 row_shr:8 row_mask:0xf bank_mask:0xf
v_fmac_f32_dpp v151, v151, v145 row_shr:8 row_mask:0xf bank_mask:0xf
v_fmac_f32_dpp v148, v148, v146 row_shr:8 row_mask:0xf bank_mask:0xf
v_fmac_f32_dpp v149, v149, v147 row_shr:8 row_mask:0xf bank_mask:0xf
v_mul_f32_dpp v219, v219, v219 row_shr:8 row_mask:0xf bank_mask:0xf
v_mul_f32_dpp v145, v145, v145 row_shr:8 row_mask:0xf bank_mask:0xf
v_mul_f32_dpp v146, v146, v146 row_shr:8 row_mask:0xf bank_mask:0xf
v_mul_f32_dpp v147, v147, v147 row_shr:8 row_mask:0xf bank_mask:0xf

	v_lshlrev_b32_e32 v182, 16, v183
	v_and_b32_e32 v183, 0xffff0000, v183
	v_pk_mul_f32 v[134:135], v[120:121], v[134:135]
	v_and_or_b32 v121, v214, 64, v223
	v_pk_mul_f32 v[122:123], v[122:123], v[182:183]
	v_lshlrev_b32_e32 v144, 2, v121
	v_fmac_f32_e32 v150, 0, v219
	v_fmac_f32_e32 v151, 0, v145
	v_fmac_f32_e32 v148, 0, v146
	v_fmac_f32_e32 v149, 0, v147
	v_pk_mul_f32 v[132:133], v[122:123], v[132:133]
	v_mov_b32_e32 v120, v124
	v_mov_b32_e32 v124, v126
	ds_bpermute_b32 v121, v144, v150 offset:60
	ds_bpermute_b32 v122, v144, v219 offset:60
	ds_bpermute_b32 v123, v144, v151 offset:60
	ds_bpermute_b32 v126, v144, v145 offset:60
	ds_bpermute_b32 v223, v144, v148 offset:60
	ds_bpermute_b32 v227, v144, v146 offset:60
	ds_bpermute_b32 v228, v144, v149 offset:60
	ds_bpermute_b32 v230, v144, v147 offset:60
	s_nop 1
v_fmac_f32_dpp v138, v138, v206 row_shr:1 row_mask:0xf bank_mask:0xf
v_fmac_f32_dpp v139, v139, v207 row_shr:1 row_mask:0xf bank_mask:0xf
v_fmac_f32_dpp v136, v136, v204 row_shr:1 row_mask:0xf bank_mask:0xf
v_fmac_f32_dpp v137, v137, v205 row_shr:1 row_mask:0xf bank_mask:0xf
v_mul_f32_dpp v206, v206, v206 row_shr:1 row_mask:0xf bank_mask:0xf
v_mul_f32_dpp v207, v207, v207 row_shr:1 row_mask:0xf bank_mask:0xf
v_mul_f32_dpp v204, v204, v204 row_shr:1 row_mask:0xf bank_mask:0xf
v_mul_f32_dpp v205, v205, v205 row_shr:1 row_mask:0xf bank_mask:0xf
v_fmac_f32_dpp v138, v138, v206 row_shr:2 row_mask:0xf bank_mask:0xf
v_fmac_f32_dpp v139, v139, v207 row_shr:2 row_mask:0xf bank_mask:0xf
v_fmac_f32_dpp v136, v136, v204 row_shr:2 row_mask:0xf bank_mask:0xf
v_fmac_f32_dpp v137, v137, v205 row_shr:2 row_mask:0xf bank_mask:0xf
v_mul_f32_dpp v206, v206, v206 row_shr:2 row_mask:0xf bank_mask:0xf
v_mul_f32_dpp v207, v207, v207 row_shr:2 row_mask:0xf bank_mask:0xf
v_mul_f32_dpp v204, v204, v204 row_shr:2 row_mask:0xf bank_mask:0xf
v_mul_f32_dpp v205, v205, v205 row_shr:2 row_mask:0xf bank_mask:0xf
v_fmac_f32_dpp v138, v138, v206 row_shr:4 row_mask:0xf bank_mask:0xf
v_fmac_f32_dpp v139, v139, v207 row_shr:4 row_mask:0xf bank_mask:0xf
v_fmac_f32_dpp v136, v136, v204 row_shr:4 row_mask:0xf bank_mask:0xf
v_fmac_f32_dpp v137, v137, v205 row_shr:4 row_mask:0xf bank_mask:0xf
v_mul_f32_dpp v206, v206, v206 row_shr:4 row_mask:0xf bank_mask:0xf
v_mul_f32_dpp v207, v207, v207 row_shr:4 row_mask:0xf bank_mask:0xf
v_mul_f32_dpp v204, v204, v204 row_shr:4 row_mask:0xf bank_mask:0xf
v_mul_f32_dpp v205, v205, v205 row_shr:4 row_mask:0xf bank_mask:0xf
v_fmac_f32_dpp v138, v138, v206 row_shr:8 row_mask:0xf bank_mask:0xf
v_fmac_f32_dpp v139, v139, v207 row_shr:8 row_mask:0xf bank_mask:0xf
v_fmac_f32_dpp v136, v136, v204 row_shr:8 row_mask:0xf bank_mask:0xf
v_fmac_f32_dpp v137, v137, v205 row_shr:8 row_mask:0xf bank_mask:0xf
v_mul_f32_dpp v206, v206, v206 row_shr:8 row_mask:0xf bank_mask:0xf
v_mul_f32_dpp v207, v207, v207 row_shr:8 row_mask:0xf bank_mask:0xf
v_mul_f32_dpp v204, v204, v204 row_shr:8 row_mask:0xf bank_mask:0xf
v_mul_f32_dpp v205, v205, v205 row_shr:8 row_mask:0xf bank_mask:0xf

	v_mov_b32_e32 v229, v220
	v_mov_b32_e32 v220, v225
	s_waitcnt lgkmcnt(7)
	v_fmac_f32_e32 v138, v206, v121
	s_waitcnt lgkmcnt(6)
	v_mul_f32_e32 v225, v206, v122
	s_waitcnt lgkmcnt(5)
	v_fmac_f32_e32 v139, v207, v123
	s_waitcnt lgkmcnt(4)
	v_mul_f32_e32 v226, v207, v126
	s_waitcnt lgkmcnt(3)
	v_fmac_f32_e32 v136, v204, v223
	s_waitcnt lgkmcnt(2)
	v_mul_f32_e32 v227, v204, v227
	s_waitcnt lgkmcnt(1)
	v_fmac_f32_e32 v137, v205, v228
	s_waitcnt lgkmcnt(0)
	v_mul_f32_e32 v228, v205, v230
	ds_bpermute_b32 v121, v144, v138 offset:60
	ds_bpermute_b32 v122, v144, v225 offset:60
	ds_bpermute_b32 v123, v144, v139 offset:60
	ds_bpermute_b32 v126, v144, v226 offset:60
	ds_bpermute_b32 v204, v144, v136 offset:60
	ds_bpermute_b32 v207, v144, v227 offset:60
	ds_bpermute_b32 v205, v144, v137 offset:60
	ds_bpermute_b32 v230, v144, v228 offset:60
	s_nop 1
v_fmac_f32_dpp v130, v130, v224 row_shr:1 row_mask:0xf bank_mask:0xf
v_fmac_f32_dpp v131, v131, v220 row_shr:1 row_mask:0xf bank_mask:0xf
v_fmac_f32_dpp v128, v128, v229 row_shr:1 row_mask:0xf bank_mask:0xf
v_fmac_f32_dpp v129, v129, v221 row_shr:1 row_mask:0xf bank_mask:0xf
v_mul_f32_dpp v224, v224, v224 row_shr:1 row_mask:0xf bank_mask:0xf
v_mul_f32_dpp v220, v220, v220 row_shr:1 row_mask:0xf bank_mask:0xf
v_mul_f32_dpp v229, v229, v229 row_shr:1 row_mask:0xf bank_mask:0xf
v_mul_f32_dpp v221, v221, v221 row_shr:1 row_mask:0xf bank_mask:0xf
v_fmac_f32_dpp v130, v130, v224 row_shr:2 row_mask:0xf bank_mask:0xf
v_fmac_f32_dpp v131, v131, v220 row_shr:2 row_mask:0xf bank_mask:0xf
v_fmac_f32_dpp v128, v128, v229 row_shr:2 row_mask:0xf bank_mask:0xf
v_fmac_f32_dpp v129, v129, v221 row_shr:2 row_mask:0xf bank_mask:0xf
v_mul_f32_dpp v224, v224, v224 row_shr:2 row_mask:0xf bank_mask:0xf
v_mul_f32_dpp v220, v220, v220 row_shr:2 row_mask:0xf bank_mask:0xf
v_mul_f32_dpp v229, v229, v229 row_shr:2 row_mask:0xf bank_mask:0xf
v_mul_f32_dpp v221, v221, v221 row_shr:2 row_mask:0xf bank_mask:0xf
v_fmac_f32_dpp v130, v130, v224 row_shr:4 row_mask:0xf bank_mask:0xf
v_fmac_f32_dpp v131, v131, v220 row_shr:4 row_mask:0xf bank_mask:0xf
v_fmac_f32_dpp v128, v128, v229 row_shr:4 row_mask:0xf bank_mask:0xf
v_fmac_f32_dpp v129, v129, v221 row_shr:4 row_mask:0xf bank_mask:0xf
v_mul_f32_dpp v224, v224, v224 row_shr:4 row_mask:0xf bank_mask:0xf
v_mul_f32_dpp v220, v220, v220 row_shr:4 row_mask:0xf bank_mask:0xf
v_mul_f32_dpp v229, v229, v229 row_shr:4 row_mask:0xf bank_mask:0xf
v_mul_f32_dpp v221, v221, v221 row_shr:4 row_mask:0xf bank_mask:0xf
v_fmac_f32_dpp v130, v130, v224 row_shr:8 row_mask:0xf bank_mask:0xf
v_fmac_f32_dpp v131, v131, v220 row_shr:8 row_mask:0xf bank_mask:0xf
v_fmac_f32_dpp v128, v128, v229 row_shr:8 row_mask:0xf bank_mask:0xf
v_fmac_f32_dpp v129, v129, v221 row_shr:8 row_mask:0xf bank_mask:0xf
v_mul_f32_dpp v224, v224, v224 row_shr:8 row_mask:0xf bank_mask:0xf
v_mul_f32_dpp v220, v220, v220 row_shr:8 row_mask:0xf bank_mask:0xf
v_mul_f32_dpp v229, v229, v229 row_shr:8 row_mask:0xf bank_mask:0xf
v_mul_f32_dpp v221, v221, v221 row_shr:8 row_mask:0xf bank_mask:0xf

	s_ashr_i32 s8, s90, 5
	s_waitcnt lgkmcnt(7)
	v_fmac_f32_e32 v130, v224, v121
	s_waitcnt lgkmcnt(6)
	v_mul_f32_e32 v206, v224, v122
	s_waitcnt lgkmcnt(5)
	v_fmac_f32_e32 v131, v220, v123
	s_waitcnt lgkmcnt(4)
	v_mul_f32_e32 v220, v220, v126
	s_waitcnt lgkmcnt(3)
	v_fmac_f32_e32 v128, v229, v204
	s_waitcnt lgkmcnt(2)
	v_mul_f32_e32 v223, v229, v207
	s_waitcnt lgkmcnt(1)
	v_fmac_f32_e32 v129, v221, v205
	s_waitcnt lgkmcnt(0)
	v_mul_f32_e32 v224, v221, v230
	ds_bpermute_b32 v121, v144, v130 offset:60
	ds_bpermute_b32 v122, v144, v206 offset:60
	ds_bpermute_b32 v123, v144, v131 offset:60
	ds_bpermute_b32 v126, v144, v220 offset:60
	ds_bpermute_b32 v207, v144, v128 offset:60
	ds_bpermute_b32 v229, v144, v223 offset:60
	ds_bpermute_b32 v221, v144, v129 offset:60
	ds_bpermute_b32 v230, v144, v224 offset:60
	s_add_i32 s9, s90, 0xffffff00
	s_and_b64 s[4:5], exec, s[54:55]
	s_cselect_b32 s4, s9, s8
	s_nop 1
v_fmac_f32_dpp v134, v134, v120 row_shr:1 row_mask:0xf bank_mask:0xf
v_fmac_f32_dpp v135, v135, v125 row_shr:1 row_mask:0xf bank_mask:0xf
v_fmac_f32_dpp v132, v132, v124 row_shr:1 row_mask:0xf bank_mask:0xf
v_fmac_f32_dpp v133, v133, v127 row_shr:1 row_mask:0xf bank_mask:0xf
v_mul_f32_dpp v120, v120, v120 row_shr:1 row_mask:0xf bank_mask:0xf
v_mul_f32_dpp v125, v125, v125 row_shr:1 row_mask:0xf bank_mask:0xf
v_mul_f32_dpp v124, v124, v124 row_shr:1 row_mask:0xf bank_mask:0xf
v_mul_f32_dpp v127, v127, v127 row_shr:1 row_mask:0xf bank_mask:0xf
v_fmac_f32_dpp v134, v134, v120 row_shr:2 row_mask:0xf bank_mask:0xf
v_fmac_f32_dpp v135, v135, v125 row_shr:2 row_mask:0xf bank_mask:0xf
v_fmac_f32_dpp v132, v132, v124 row_shr:2 row_mask:0xf bank_mask:0xf
v_fmac_f32_dpp v133, v133, v127 row_shr:2 row_mask:0xf bank_mask:0xf
v_mul_f32_dpp v120, v120, v120 row_shr:2 row_mask:0xf bank_mask:0xf
v_mul_f32_dpp v125, v125, v125 row_shr:2 row_mask:0xf bank_mask:0xf
v_mul_f32_dpp v124, v124, v124 row_shr:2 row_mask:0xf bank_mask:0xf
v_mul_f32_dpp v127, v127, v127 row_shr:2 row_mask:0xf bank_mask:0xf
v_fmac_f32_dpp v134, v134, v120 row_shr:4 row_mask:0xf bank_mask:0xf
v_fmac_f32_dpp v135, v135, v125 row_shr:4 row_mask:0xf bank_mask:0xf
v_fmac_f32_dpp v132, v132, v124 row_shr:4 row_mask:0xf bank_mask:0xf
v_fmac_f32_dpp v133, v133, v127 row_shr:4 row_mask:0xf bank_mask:0xf
v_mul_f32_dpp v120, v120, v120 row_shr:4 row_mask:0xf bank_mask:0xf
v_mul_f32_dpp v125, v125, v125 row_shr:4 row_mask:0xf bank_mask:0xf
v_mul_f32_dpp v124, v124, v124 row_shr:4 row_mask:0xf bank_mask:0xf
v_mul_f32_dpp v127, v127, v127 row_shr:4 row_mask:0xf bank_mask:0xf
v_fmac_f32_dpp v134, v134, v120 row_shr:8 row_mask:0xf bank_mask:0xf
v_fmac_f32_dpp v135, v135, v125 row_shr:8 row_mask:0xf bank_mask:0xf
v_fmac_f32_dpp v132, v132, v124 row_shr:8 row_mask:0xf bank_mask:0xf
v_fmac_f32_dpp v133, v133, v127 row_shr:8 row_mask:0xf bank_mask:0xf
v_mul_f32_dpp v120, v120, v120 row_shr:8 row_mask:0xf bank_mask:0xf
v_mul_f32_dpp v125, v125, v125 row_shr:8 row_mask:0xf bank_mask:0xf
v_mul_f32_dpp v124, v124, v124 row_shr:8 row_mask:0xf bank_mask:0xf
v_mul_f32_dpp v127, v127, v127 row_shr:8 row_mask:0xf bank_mask:0xf

	s_lshl_b32 s47, s4, 1
	s_lshl_b32 s4, s90, 2
	s_waitcnt lgkmcnt(7)
	v_fmac_f32_e32 v134, v120, v121
	s_waitcnt lgkmcnt(6)
	v_mul_f32_e32 v204, v120, v122
	s_waitcnt lgkmcnt(5)
	v_fmac_f32_e32 v135, v125, v123
	s_waitcnt lgkmcnt(4)
	v_mul_f32_e32 v205, v125, v126
	s_waitcnt lgkmcnt(3)
	v_fmac_f32_e32 v132, v124, v207
	s_waitcnt lgkmcnt(2)
	v_mul_f32_e32 v207, v124, v229
	s_waitcnt lgkmcnt(1)
	v_fmac_f32_e32 v133, v127, v221
	s_waitcnt lgkmcnt(0)
	v_mul_f32_e32 v221, v127, v230
	s_and_b32 s49, s4, 0x7c
	ds_bpermute_b32 v121, v144, v134 offset:60
	ds_bpermute_b32 v120, v144, v204 offset:60
	ds_bpermute_b32 v123, v144, v135 offset:60
	ds_bpermute_b32 v122, v144, v205 offset:60
	ds_bpermute_b32 v125, v144, v132 offset:60
	ds_bpermute_b32 v124, v144, v207 offset:60
	ds_bpermute_b32 v127, v144, v133 offset:60
	ds_bpermute_b32 v126, v144, v221 offset:60
	s_add_i32 s8, s49, 4
	s_and_b64 s[4:5], exec, s[54:55]
	s_cselect_b32 s14, 0, s8
	s_add_i32 s14, s14, s66
	v_cmp_eq_u32_e64 s[10:11], 15, v215
	s_mul_hi_i32 s58, s47, 0x84
	s_mul_i32 s59, s47, 0x84
	s_and_saveexec_b64 s[8:9], s[10:11]
	s_cbranch_execz .LBB0_437
	s_add_u32 s4, s59, s14
	s_addc_u32 s5, s58, 0
	s_mulk_i32 s5, 0x2800
	s_mul_hi_u32 s12, s4, 0x2800
	s_add_i32 s12, s12, s5
	s_mulk_i32 s4, 0x2800
	s_add_u32 s4, s77, s4
	s_addc_u32 s5, s78, s12
	v_lshl_add_u64 v[230:231], v[176:177], 3, s[4:5]
	s_waitcnt lgkmcnt(4)
	flat_store_dwordx4 v[230:231], v[120:123] sc1
	s_waitcnt lgkmcnt(0)
	flat_store_dwordx4 v[230:231], v[124:127] offset:16 sc1
.LBB0_437:
	s_or_b64 exec, exec, s[8:9]
	v_pk_fma_f32 v[116:117], v[116:117], s[36:37], v[72:73] op_sel_hi:[1,0,1] neg_lo:[1,0,0] neg_hi:[1,0,0]
	v_pk_fma_f32 v[108:109], v[108:109], s[36:37], v[72:73] op_sel_hi:[1,0,1] neg_lo:[1,0,0] neg_hi:[1,0,0]
	v_exp_f32_e32 v116, v116
	v_exp_f32_e32 v117, v117
	v_pk_fma_f32 v[114:115], v[114:115], s[36:37], v[70:71] op_sel_hi:[1,0,1] neg_lo:[1,0,0] neg_hi:[1,0,0]
	v_pk_fma_f32 v[112:113], v[112:113], s[36:37], v[68:69] op_sel_hi:[1,0,1] neg_lo:[1,0,0] neg_hi:[1,0,0]
	v_exp_f32_e32 v108, v108
	v_pk_add_f32 v[116:117], v[116:117], 1.0 op_sel_hi:[1,0]
	v_exp_f32_e32 v109, v109
	v_rcp_f32_e32 v116, v116
	v_rcp_f32_e32 v117, v117
	v_exp_f32_e32 v114, v114
	v_exp_f32_e32 v115, v115
	v_exp_f32_e32 v112, v112
	v_exp_f32_e32 v113, v113
	v_pk_mul_f32 v[116:117], v[64:65], v[116:117]
	v_pk_add_f32 v[108:109], v[108:109], 1.0 op_sel_hi:[1,0]
	v_pk_add_f32 v[114:115], v[114:115], 1.0 op_sel_hi:[1,0]
	v_exp_f32_e32 v116, v116
	v_exp_f32_e32 v117, v117
	v_pk_add_f32 v[112:113], v[112:113], 1.0 op_sel_hi:[1,0]
	v_rcp_f32_e32 v108, v108
	v_rcp_f32_e32 v109, v109
	v_rcp_f32_e32 v114, v114
	v_rcp_f32_e32 v115, v115
	s_waitcnt lgkmcnt(0)
	v_rcp_f32_e32 v122, v112
	v_rcp_f32_e32 v123, v113
	v_pk_fma_f32 v[106:107], v[106:107], s[36:37], v[70:71] op_sel_hi:[1,0,1] neg_lo:[1,0,0] neg_hi:[1,0,0]
	v_pk_fma_f32 v[104:105], v[104:105], s[36:37], v[68:69] op_sel_hi:[1,0,1] neg_lo:[1,0,0] neg_hi:[1,0,0]
	v_pk_fma_f32 v[102:103], v[102:103], s[36:37], v[74:75] op_sel_hi:[1,0,1] neg_lo:[1,0,0] neg_hi:[1,0,0]
	v_pk_fma_f32 v[112:113], v[116:117], v[116:117], 1.0 op_sel_hi:[1,1,0] neg_lo:[1,0,0] neg_hi:[1,0,0]
	v_exp_f32_e32 v106, v106
	v_exp_f32_e32 v107, v107
	v_exp_f32_e32 v104, v104
	v_exp_f32_e32 v105, v105
	v_pk_mul_f32 v[108:109], v[64:65], v[108:109]
	v_exp_f32_e32 v102, v102
	v_exp_f32_e32 v103, v103
	v_sqrt_f32_e32 v124, v112
	v_sqrt_f32_e32 v125, v113
	v_pk_mul_f32 v[112:113], v[114:115], v[188:189]
	v_pk_mul_f32 v[114:115], v[122:123], v[200:201]
	v_exp_f32_e32 v122, v108
	v_exp_f32_e32 v123, v109
	v_pk_fma_f32 v[100:101], v[100:101], s[36:37], v[72:73] op_sel_hi:[1,0,1] neg_lo:[1,0,0] neg_hi:[1,0,0]
	v_pk_fma_f32 v[118:119], v[118:119], s[36:37], v[74:75] op_sel_hi:[1,0,1] neg_lo:[1,0,0] neg_hi:[1,0,0]
	v_exp_f32_e32 v100, v100
	v_exp_f32_e32 v101, v101
	v_exp_f32_e32 v118, v118
	v_exp_f32_e32 v119, v119
	v_pk_add_f32 v[106:107], v[106:107], 1.0 op_sel_hi:[1,0]
	v_pk_add_f32 v[104:105], v[104:105], 1.0 op_sel_hi:[1,0]
	v_pk_add_f32 v[102:103], v[102:103], 1.0 op_sel_hi:[1,0]
	v_rcp_f32_e32 v106, v106
	v_rcp_f32_e32 v107, v107
	v_rcp_f32_e32 v108, v104
	v_rcp_f32_e32 v109, v105
	v_pk_fma_f32 v[104:105], v[122:123], v[122:123], 1.0 op_sel_hi:[1,1,0] neg_lo:[1,0,0] neg_hi:[1,0,0]
	v_rcp_f32_e32 v102, v102
	v_rcp_f32_e32 v103, v103
	v_pk_mul_f32 v[114:115], v[114:115], v[124:125]
	v_sqrt_f32_e32 v124, v104
	v_sqrt_f32_e32 v125, v105
	v_pk_add_f32 v[100:101], v[100:101], 1.0 op_sel_hi:[1,0]
	v_pk_add_f32 v[118:119], v[118:119], 1.0 op_sel_hi:[1,0]
	v_pk_fma_f32 v[110:111], v[110:111], s[36:37], v[74:75] op_sel_hi:[1,0,1] neg_lo:[1,0,0] neg_hi:[1,0,0]
	v_pk_fma_f32 v[98:99], v[98:99], s[36:37], v[70:71] op_sel_hi:[1,0,1] neg_lo:[1,0,0] neg_hi:[1,0,0]
	v_rcp_f32_e32 v100, v100
	v_rcp_f32_e32 v101, v101
	v_pk_fma_f32 v[82:83], v[82:83], s[36:37], v[74:75] op_sel_hi:[1,0,1] neg_lo:[1,0,0] neg_hi:[1,0,0]
	v_pk_fma_f32 v[80:81], v[80:81], s[36:37], v[72:73] op_sel_hi:[1,0,1] neg_lo:[1,0,0] neg_hi:[1,0,0]
	v_rcp_f32_e32 v118, v118
	v_rcp_f32_e32 v119, v119
	v_exp_f32_e32 v110, v110
	v_exp_f32_e32 v111, v111
	v_pk_mul_f32 v[104:105], v[106:107], v[186:187]
	v_pk_mul_f32 v[106:107], v[108:109], v[202:203]
	v_exp_f32_e32 v98, v98
	v_exp_f32_e32 v99, v99
	v_pk_mul_f32 v[102:103], v[66:67], v[102:103]
	v_pk_fma_f32 v[96:97], v[96:97], s[36:37], v[68:69] op_sel_hi:[1,0,1] neg_lo:[1,0,0] neg_hi:[1,0,0]
	v_exp_f32_e32 v82, v82
	v_exp_f32_e32 v83, v83
	v_exp_f32_e32 v80, v80
	v_exp_f32_e32 v81, v81
	v_pk_mul_f32 v[106:107], v[106:107], v[124:125]
	v_exp_f32_e32 v124, v102
	v_exp_f32_e32 v125, v103
	v_exp_f32_e32 v96, v96
	v_exp_f32_e32 v97, v97
	v_pk_mul_f32 v[100:101], v[64:65], v[100:101]
	v_pk_mul_f32 v[118:119], v[66:67], v[118:119]
	v_pk_add_f32 v[110:111], v[110:111], 1.0 op_sel_hi:[1,0]
	v_pk_add_f32 v[98:99], v[98:99], 1.0 op_sel_hi:[1,0]
	v_exp_f32_e32 v126, v100
	v_exp_f32_e32 v127, v101
	v_pk_add_f32 v[82:83], v[82:83], 1.0 op_sel_hi:[1,0]
	v_pk_add_f32 v[80:81], v[80:81], 1.0 op_sel_hi:[1,0]
	v_exp_f32_e32 v118, v118
	v_exp_f32_e32 v119, v119
	v_rcp_f32_e32 v110, v110
	v_rcp_f32_e32 v111, v111
	v_rcp_f32_e32 v98, v98
	v_rcp_f32_e32 v99, v99
	v_pk_fma_f32 v[102:103], v[124:125], v[124:125], 1.0 op_sel_hi:[1,1,0] neg_lo:[1,0,0] neg_hi:[1,0,0]
	v_pk_add_f32 v[96:97], v[96:97], 1.0 op_sel_hi:[1,0]
	v_rcp_f32_e32 v82, v82
	v_rcp_f32_e32 v83, v83
	v_rcp_f32_e32 v80, v80
	v_rcp_f32_e32 v81, v81
	v_sqrt_f32_e32 v102, v102
	v_sqrt_f32_e32 v103, v103
	v_rcp_f32_e32 v100, v96
	v_rcp_f32_e32 v101, v97
	v_pk_fma_f32 v[96:97], v[126:127], v[126:127], 1.0 op_sel_hi:[1,1,0] neg_lo:[1,0,0] neg_hi:[1,0,0]
	v_pk_fma_f32 v[78:79], v[78:79], s[36:37], v[70:71] op_sel_hi:[1,0,1] neg_lo:[1,0,0] neg_hi:[1,0,0]
	v_pk_fma_f32 v[76:77], v[76:77], s[36:37], v[68:69] op_sel_hi:[1,0,1] neg_lo:[1,0,0] neg_hi:[1,0,0]
	v_pk_fma_f32 v[120:121], v[118:119], v[118:119], 1.0 op_sel_hi:[1,1,0] neg_lo:[1,0,0] neg_hi:[1,0,0]
	v_pk_mul_f32 v[110:111], v[66:67], v[110:111]
	v_sqrt_f32_e32 v108, v96
	v_sqrt_f32_e32 v109, v97
	v_pk_mul_f32 v[96:97], v[98:99], v[142:143]
	v_exp_f32_e32 v78, v78
	v_exp_f32_e32 v79, v79
	v_pk_mul_f32 v[82:83], v[66:67], v[82:83]
	v_exp_f32_e32 v76, v76
	v_exp_f32_e32 v77, v77
	v_pk_mul_f32 v[80:81], v[64:65], v[80:81]
	v_sqrt_f32_e32 v120, v120
	v_sqrt_f32_e32 v121, v121
	v_exp_f32_e32 v110, v110
	v_exp_f32_e32 v111, v111
	v_pk_mul_f32 v[96:97], v[96:97], v[102:103]
	v_pk_mul_f32 v[98:99], v[100:101], v[140:141]
	v_exp_f32_e32 v100, v82
	v_exp_f32_e32 v101, v83
	v_exp_f32_e32 v102, v80
	v_exp_f32_e32 v103, v81
	v_pk_add_f32 v[78:79], v[78:79], 1.0 op_sel_hi:[1,0]
	v_pk_add_f32 v[76:77], v[76:77], 1.0 op_sel_hi:[1,0]
	v_pk_mul_f32 v[112:113], v[112:113], v[120:121]
	v_pk_fma_f32 v[120:121], v[110:111], v[110:111], 1.0 op_sel_hi:[1,1,0] neg_lo:[1,0,0] neg_hi:[1,0,0]
	v_rcp_f32_e32 v78, v78
	v_rcp_f32_e32 v79, v79
	v_pk_fma_f32 v[82:83], v[100:101], v[100:101], 1.0 op_sel_hi:[1,1,0] neg_lo:[1,0,0] neg_hi:[1,0,0]
	v_rcp_f32_e32 v76, v76
	v_rcp_f32_e32 v77, v77
	v_pk_fma_f32 v[80:81], v[102:103], v[102:103], 1.0 op_sel_hi:[1,1,0] neg_lo:[1,0,0] neg_hi:[1,0,0]
	v_sqrt_f32_e32 v120, v120
	v_sqrt_f32_e32 v121, v121
	v_sqrt_f32_e32 v82, v82
	v_sqrt_f32_e32 v83, v83
	v_sqrt_f32_e32 v80, v80
	v_sqrt_f32_e32 v81, v81
	v_pk_mul_f32 v[78:79], v[78:79], v[182:183]
	v_pk_mul_f32 v[76:77], v[76:77], v[184:185]
	v_mov_b32_e32 v188, v118
	v_mov_b32_e32 v189, v117
	v_pk_mul_f32 v[104:105], v[104:105], v[120:121]
	v_mov_b32_e32 v186, v122
	v_pk_mul_f32 v[98:99], v[98:99], v[108:109]
	v_mov_b32_e32 v117, v126
	v_mov_b32_e32 v122, v124
	v_pk_mul_f32 v[108:109], v[78:79], v[82:83]
	v_pk_mul_f32 v[120:121], v[76:77], v[80:81]
	s_nop 1
v_fmac_f32_dpp v114, v114, v116 row_shl:1 row_mask:0xf bank_mask:0xf
v_fmac_f32_dpp v115, v115, v189 row_shl:1 row_mask:0xf bank_mask:0xf
v_fmac_f32_dpp v112, v112, v188 row_shl:1 row_mask:0xf bank_mask:0xf
v_fmac_f32_dpp v113, v113, v119 row_shl:1 row_mask:0xf bank_mask:0xf
v_mul_f32_dpp v116, v116, v116 row_shl:1 row_mask:0xf bank_mask:0xf
v_mul_f32_dpp v189, v189, v189 row_shl:1 row_mask:0xf bank_mask:0xf
v_mul_f32_dpp v188, v188, v188 row_shl:1 row_mask:0xf bank_mask:0xf
v_mul_f32_dpp v119, v119, v119 row_shl:1 row_mask:0xf bank_mask:0xf
v_fmac_f32_dpp v114, v114, v116 row_shl:2 row_mask:0xf bank_mask:0xf
v_fmac_f32_dpp v115, v115, v189 row_shl:2 row_mask:0xf bank_mask:0xf
v_fmac_f32_dpp v112, v112, v188 row_shl:2 row_mask:0xf bank_mask:0xf
v_fmac_f32_dpp v113, v113, v119 row_shl:2 row_mask:0xf bank_mask:0xf
v_mul_f32_dpp v116, v116, v116 row_shl:2 row_mask:0xf bank_mask:0xf
v_mul_f32_dpp v189, v189, v189 row_shl:2 row_mask:0xf bank_mask:0xf
v_mul_f32_dpp v188, v188, v188 row_shl:2 row_mask:0xf bank_mask:0xf
v_mul_f32_dpp v119, v119, v119 row_shl:2 row_mask:0xf bank_mask:0xf
v_fmac_f32_dpp v114, v114, v116 row_shl:4 row_mask:0xf bank_mask:0xf
v_fmac_f32_dpp v115, v115, v189 row_shl:4 row_mask:0xf bank_mask:0xf
v_fmac_f32_dpp v112, v112, v188 row_shl:4 row_mask:0xf bank_mask:0xf
v_fmac_f32_dpp v113, v113, v119 row_shl:4 row_mask:0xf bank_mask:0xf
v_mul_f32_dpp v116, v116, v116 row_shl:4 row_mask:0xf bank_mask:0xf
v_mul_f32_dpp v189, v189, v189 row_shl:4 row_mask:0xf bank_mask:0xf
v_mul_f32_dpp v188, v188, v188 row_shl:4 row_mask:0xf bank_mask:0xf
v_mul_f32_dpp v119, v119, v119 row_shl:4 row_mask:0xf bank_mask:0xf
v_fmac_f32_dpp v114, v114, v116 row_shl:8 row_mask:0xf bank_mask:0xf
v_fmac_f32_dpp v115, v115, v189 row_shl:8 row_mask:0xf bank_mask:0xf
v_fmac_f32_dpp v112, v112, v188 row_shl:8 row_mask:0xf bank_mask:0xf
v_fmac_f32_dpp v113, v113, v119 row_shl:8 row_mask:0xf bank_mask:0xf
v_mul_f32_dpp v116, v116, v116 row_shl:8 row_mask:0xf bank_mask:0xf
v_mul_f32_dpp v189, v189, v189 row_shl:8 row_mask:0xf bank_mask:0xf
v_mul_f32_dpp v188, v188, v188 row_shl:8 row_mask:0xf bank_mask:0xf
v_mul_f32_dpp v119, v119, v119 row_shl:8 row_mask:0xf bank_mask:0xf

	s_nop 1
v_fmac_f32_dpp v106, v106, v186 row_shl:1 row_mask:0xf bank_mask:0xf
v_fmac_f32_dpp v107, v107, v123 row_shl:1 row_mask:0xf bank_mask:0xf
v_fmac_f32_dpp v104, v104, v110 row_shl:1 row_mask:0xf bank_mask:0xf
v_fmac_f32_dpp v105, v105, v111 row_shl:1 row_mask:0xf bank_mask:0xf
v_mul_f32_dpp v186, v186, v186 row_shl:1 row_mask:0xf bank_mask:0xf
v_mul_f32_dpp v123, v123, v123 row_shl:1 row_mask:0xf bank_mask:0xf
v_mul_f32_dpp v110, v110, v110 row_shl:1 row_mask:0xf bank_mask:0xf
v_mul_f32_dpp v111, v111, v111 row_shl:1 row_mask:0xf bank_mask:0xf
v_fmac_f32_dpp v106, v106, v186 row_shl:2 row_mask:0xf bank_mask:0xf
v_fmac_f32_dpp v107, v107, v123 row_shl:2 row_mask:0xf bank_mask:0xf
v_fmac_f32_dpp v104, v104, v110 row_shl:2 row_mask:0xf bank_mask:0xf
v_fmac_f32_dpp v105, v105, v111 row_shl:2 row_mask:0xf bank_mask:0xf
v_mul_f32_dpp v186, v186, v186 row_shl:2 row_mask:0xf bank_mask:0xf
v_mul_f32_dpp v123, v123, v123 row_shl:2 row_mask:0xf bank_mask:0xf
v_mul_f32_dpp v110, v110, v110 row_shl:2 row_mask:0xf bank_mask:0xf
v_mul_f32_dpp v111, v111, v111 row_shl:2 row_mask:0xf bank_mask:0xf
v_fmac_f32_dpp v106, v106, v186 row_shl:4 row_mask:0xf bank_mask:0xf
v_fmac_f32_dpp v107, v107, v123 row_shl:4 row_mask:0xf bank_mask:0xf
v_fmac_f32_dpp v104, v104, v110 row_shl:4 row_mask:0xf bank_mask:0xf
v_fmac_f32_dpp v105, v105, v111 row_shl:4 row_mask:0xf bank_mask:0xf
v_mul_f32_dpp v186, v186, v186 row_shl:4 row_mask:0xf bank_mask:0xf
v_mul_f32_dpp v123, v123, v123 row_shl:4 row_mask:0xf bank_mask:0xf
v_mul_f32_dpp v110, v110, v110 row_shl:4 row_mask:0xf bank_mask:0xf
v_mul_f32_dpp v111, v111, v111 row_shl:4 row_mask:0xf bank_mask:0xf
v_fmac_f32_dpp v106, v106, v186 row_shl:8 row_mask:0xf bank_mask:0xf
v_fmac_f32_dpp v107, v107, v123 row_shl:8 row_mask:0xf bank_mask:0xf
v_fmac_f32_dpp v104, v104, v110 row_shl:8 row_mask:0xf bank_mask:0xf
v_fmac_f32_dpp v105, v105, v111 row_shl:8 row_mask:0xf bank_mask:0xf
v_mul_f32_dpp v186, v186, v186 row_shl:8 row_mask:0xf bank_mask:0xf
v_mul_f32_dpp v123, v123, v123 row_shl:8 row_mask:0xf bank_mask:0xf
v_mul_f32_dpp v110, v110, v110 row_shl:8 row_mask:0xf bank_mask:0xf
v_mul_f32_dpp v111, v111, v111 row_shl:8 row_mask:0xf bank_mask:0xf

	s_nop 1
v_fmac_f32_dpp v98, v98, v117 row_shl:1 row_mask:0xf bank_mask:0xf
v_fmac_f32_dpp v99, v99, v127 row_shl:1 row_mask:0xf bank_mask:0xf
v_fmac_f32_dpp v96, v96, v122 row_shl:1 row_mask:0xf bank_mask:0xf
v_fmac_f32_dpp v97, v97, v125 row_shl:1 row_mask:0xf bank_mask:0xf
v_mul_f32_dpp v117, v117, v117 row_shl:1 row_mask:0xf bank_mask:0xf
v_mul_f32_dpp v127, v127, v127 row_shl:1 row_mask:0xf bank_mask:0xf
v_mul_f32_dpp v122, v122, v122 row_shl:1 row_mask:0xf bank_mask:0xf
v_mul_f32_dpp v125, v125, v125 row_shl:1 row_mask:0xf bank_mask:0xf
v_fmac_f32_dpp v98, v98, v117 row_shl:2 row_mask:0xf bank_mask:0xf
v_fmac_f32_dpp v99, v99, v127 row_shl:2 row_mask:0xf bank_mask:0xf
v_fmac_f32_dpp v96, v96, v122 row_shl:2 row_mask:0xf bank_mask:0xf
v_fmac_f32_dpp v97, v97, v125 row_shl:2 row_mask:0xf bank_mask:0xf
v_mul_f32_dpp v117, v117, v117 row_shl:2 row_mask:0xf bank_mask:0xf
v_mul_f32_dpp v127, v127, v127 row_shl:2 row_mask:0xf bank_mask:0xf
v_mul_f32_dpp v122, v122, v122 row_shl:2 row_mask:0xf bank_mask:0xf
v_mul_f32_dpp v125, v125, v125 row_shl:2 row_mask:0xf bank_mask:0xf
v_fmac_f32_dpp v98, v98, v117 row_shl:4 row_mask:0xf bank_mask:0xf
v_fmac_f32_dpp v99, v99, v127 row_shl:4 row_mask:0xf bank_mask:0xf
v_fmac_f32_dpp v96, v96, v122 row_shl:4 row_mask:0xf bank_mask:0xf
v_fmac_f32_dpp v97, v97, v125 row_shl:4 row_mask:0xf bank_mask:0xf
v_mul_f32_dpp v117, v117, v117 row_shl:4 row_mask:0xf bank_mask:0xf
v_mul_f32_dpp v127, v127, v127 row_shl:4 row_mask:0xf bank_mask:0xf
v_mul_f32_dpp v122, v122, v122 row_shl:4 row_mask:0xf bank_mask:0xf
v_mul_f32_dpp v125, v125, v125 row_shl:4 row_mask:0xf bank_mask:0xf
v_fmac_f32_dpp v98, v98, v117 row_shl:8 row_mask:0xf bank_mask:0xf
v_fmac_f32_dpp v99, v99, v127 row_shl:8 row_mask:0xf bank_mask:0xf
v_fmac_f32_dpp v96, v96, v122 row_shl:8 row_mask:0xf bank_mask:0xf
v_fmac_f32_dpp v97, v97, v125 row_shl:8 row_mask:0xf bank_mask:0xf
v_mul_f32_dpp v117, v117, v117 row_shl:8 row_mask:0xf bank_mask:0xf
v_mul_f32_dpp v127, v127, v127 row_shl:8 row_mask:0xf bank_mask:0xf
v_mul_f32_dpp v122, v122, v122 row_shl:8 row_mask:0xf bank_mask:0xf
v_mul_f32_dpp v125, v125, v125 row_shl:8 row_mask:0xf bank_mask:0xf

	v_cmp_eq_u32_e64 s[12:13], 0, v215
	s_nop 1
v_fmac_f32_dpp v120, v120, v102 row_shl:1 row_mask:0xf bank_mask:0xf
v_fmac_f32_dpp v121, v121, v103 row_shl:1 row_mask:0xf bank_mask:0xf
v_fmac_f32_dpp v108, v108, v100 row_shl:1 row_mask:0xf bank_mask:0xf
v_fmac_f32_dpp v109, v109, v101 row_shl:1 row_mask:0xf bank_mask:0xf
v_mul_f32_dpp v102, v102, v102 row_shl:1 row_mask:0xf bank_mask:0xf
v_mul_f32_dpp v103, v103, v103 row_shl:1 row_mask:0xf bank_mask:0xf
v_mul_f32_dpp v100, v100, v100 row_shl:1 row_mask:0xf bank_mask:0xf
v_mul_f32_dpp v101, v101, v101 row_shl:1 row_mask:0xf bank_mask:0xf
v_fmac_f32_dpp v120, v120, v102 row_shl:2 row_mask:0xf bank_mask:0xf
v_fmac_f32_dpp v121, v121, v103 row_shl:2 row_mask:0xf bank_mask:0xf
v_fmac_f32_dpp v108, v108, v100 row_shl:2 row_mask:0xf bank_mask:0xf
v_fmac_f32_dpp v109, v109, v101 row_shl:2 row_mask:0xf bank_mask:0xf
v_mul_f32_dpp v102, v102, v102 row_shl:2 row_mask:0xf bank_mask:0xf
v_mul_f32_dpp v103, v103, v103 row_shl:2 row_mask:0xf bank_mask:0xf
v_mul_f32_dpp v100, v100, v100 row_shl:2 row_mask:0xf bank_mask:0xf
v_mul_f32_dpp v101, v101, v101 row_shl:2 row_mask:0xf bank_mask:0xf
v_fmac_f32_dpp v120, v120, v102 row_shl:4 row_mask:0xf bank_mask:0xf
v_fmac_f32_dpp v121, v121, v103 row_shl:4 row_mask:0xf bank_mask:0xf
v_fmac_f32_dpp v108, v108, v100 row_shl:4 row_mask:0xf bank_mask:0xf
v_fmac_f32_dpp v109, v109, v101 row_shl:4 row_mask:0xf bank_mask:0xf
v_mul_f32_dpp v102, v102, v102 row_shl:4 row_mask:0xf bank_mask:0xf
v_mul_f32_dpp v103, v103, v103 row_shl:4 row_mask:0xf bank_mask:0xf
v_mul_f32_dpp v100, v100, v100 row_shl:4 row_mask:0xf bank_mask:0xf
v_mul_f32_dpp v101, v101, v101 row_shl:4 row_mask:0xf bank_mask:0xf
v_fmac_f32_dpp v120, v120, v102 row_shl:8 row_mask:0xf bank_mask:0xf
v_fmac_f32_dpp v121, v121, v103 row_shl:8 row_mask:0xf bank_mask:0xf
v_fmac_f32_dpp v108, v108, v100 row_shl:8 row_mask:0xf bank_mask:0xf
v_fmac_f32_dpp v109, v109, v101 row_shl:8 row_mask:0xf bank_mask:0xf
v_mul_f32_dpp v102, v102, v102 row_shl:8 row_mask:0xf bank_mask:0xf
v_mul_f32_dpp v103, v103, v103 row_shl:8 row_mask:0xf bank_mask:0xf
v_mul_f32_dpp v100, v100, v100 row_shl:8 row_mask:0xf bank_mask:0xf
v_mul_f32_dpp v101, v101, v101 row_shl:8 row_mask:0xf bank_mask:0xf

	ds_bpermute_b32 v77, v144, v102
	v_fmac_f32_e32 v120, 0, v102
	v_fmac_f32_e32 v121, 0, v103
	v_fmac_f32_e32 v108, 0, v100
	v_fmac_f32_e32 v109, 0, v101
	ds_bpermute_b32 v76, v144, v120
	ds_bpermute_b32 v78, v144, v121
	ds_bpermute_b32 v79, v144, v103
	ds_bpermute_b32 v80, v144, v108
	ds_bpermute_b32 v81, v144, v100
	ds_bpermute_b32 v82, v144, v109
	ds_bpermute_b32 v83, v144, v101
	s_waitcnt lgkmcnt(0)
	v_fmac_f32_e32 v98, v117, v76
	v_mul_f32_e32 v117, v117, v77
	v_fmac_f32_e32 v99, v127, v78
	v_mul_f32_e32 v118, v127, v79
	v_fmac_f32_e32 v96, v122, v80
	v_mul_f32_e32 v122, v122, v81
	v_fmac_f32_e32 v97, v125, v82
	v_mul_f32_e32 v124, v125, v83
	ds_bpermute_b32 v76, v144, v98
	ds_bpermute_b32 v77, v144, v117
	ds_bpermute_b32 v78, v144, v99
	ds_bpermute_b32 v79, v144, v118
	ds_bpermute_b32 v80, v144, v96
	ds_bpermute_b32 v81, v144, v122
	ds_bpermute_b32 v82, v144, v97
	ds_bpermute_b32 v83, v144, v124
	s_waitcnt lgkmcnt(0)
	v_fmac_f32_e32 v106, v186, v76
	v_mul_f32_e32 v125, v186, v77
	v_fmac_f32_e32 v107, v123, v78
	v_mul_f32_e32 v123, v123, v79
	v_fmac_f32_e32 v104, v110, v80
	v_mul_f32_e32 v126, v110, v81
	v_fmac_f32_e32 v105, v111, v82
	v_mul_f32_e32 v127, v111, v83
	ds_bpermute_b32 v76, v144, v106
	ds_bpermute_b32 v77, v144, v125
	ds_bpermute_b32 v78, v144, v107
	ds_bpermute_b32 v79, v144, v123
	ds_bpermute_b32 v80, v144, v104
	ds_bpermute_b32 v81, v144, v126
	ds_bpermute_b32 v82, v144, v105
	ds_bpermute_b32 v83, v144, v127
	s_waitcnt lgkmcnt(0)
	v_fmac_f32_e32 v114, v116, v76
	v_mul_f32_e32 v140, v116, v77
	v_fmac_f32_e32 v115, v189, v78
	v_mul_f32_e32 v141, v189, v79
	v_fmac_f32_e32 v112, v188, v80
	v_mul_f32_e32 v142, v188, v81
	v_fmac_f32_e32 v113, v119, v82
	v_mul_f32_e32 v119, v119, v83
	ds_bpermute_b32 v77, v144, v114
	ds_bpermute_b32 v76, v144, v140
	ds_bpermute_b32 v79, v144, v115
	ds_bpermute_b32 v78, v144, v141
	ds_bpermute_b32 v81, v144, v112
	ds_bpermute_b32 v80, v144, v142
	ds_bpermute_b32 v83, v144, v113
	ds_bpermute_b32 v82, v144, v119
	s_and_saveexec_b64 s[8:9], s[12:13]
	s_cbranch_execz .LBB0_439
	s_or_b32 s4, s47, 1
	s_mul_hi_i32 s5, s4, 0x84
	s_mulk_i32 s4, 0x84
	s_add_u32 s4, s4, s14
	s_addc_u32 s5, s5, 0
	s_mulk_i32 s5, 0x2800
	s_mul_hi_u32 s14, s4, 0x2800
	s_add_i32 s14, s14, s5
	s_mulk_i32 s4, 0x2800
	s_add_u32 s4, s77, s4
	s_addc_u32 s5, s78, s14
	v_lshl_add_u64 v[110:111], v[176:177], 3, s[4:5]
	s_waitcnt lgkmcnt(0)
	flat_store_dwordx4 v[110:111], v[76:79] sc1
	flat_store_dwordx4 v[110:111], v[80:83] offset:16 sc1
.LBB0_439:
	s_or_b64 exec, exec, s[8:9]
	s_waitcnt lgkmcnt(0)
	v_and_b32_e32 v77, 1, v217
	v_and_b32_e32 v76, -8, v176
	v_cndmask_b32_e64 v78, 0, 1, s[56:57]
	v_cmp_eq_u32_e64 s[8:9], 0, v77
	v_lshl_add_u32 v110, v77, 4, v218
	v_ashrrev_i32_e32 v77, 31, v76
	v_cmp_ne_u32_e64 s[14:15], 1, v78
	v_and_b32_e32 v78, 64, v214
	s_andn2_b64 vcc, exec, s[56:57]
	v_xor_b32_e32 v111, 16, v214
	v_lshlrev_b64 v[76:77], 1, v[76:77]
	v_add_u32_e32 v116, 64, v78
	s_cbranch_vccnz .LBB0_441
	v_lshlrev_b32_e32 v78, 16, v198
	v_and_b32_e32 v79, 0xffff0000, v198
	v_add_f32_e32 v82, v150, v114
	v_add_f32_e32 v83, v151, v115
	v_mul_f32_e32 v82, v82, v78
	v_mul_f32_e32 v83, v83, v79
	v_lshlrev_b32_e32 v80, 16, v199
	v_and_b32_e32 v81, 0xffff0000, v199
	v_cvt_pk_bf16_f32 v82, v82, v83
	v_add_f32_e32 v83, v148, v112
	v_add_f32_e32 v112, v149, v113
	v_mul_f32_e32 v83, v83, v80
	v_mul_f32_e32 v112, v112, v81
	v_cvt_pk_bf16_f32 v83, v83, v112
	v_mul_f32_e32 v112, v219, v78
	v_mul_f32_e32 v113, v145, v79
	v_mul_f32_e32 v78, v140, v78
	v_mul_f32_e32 v79, v141, v79
	v_cvt_pk_bf16_f32 v112, v112, v113
	v_mul_f32_e32 v113, v146, v80
	v_mul_f32_e32 v114, v147, v81
	v_cvt_pk_bf16_f32 v78, v78, v79
	v_mul_f32_e32 v79, v142, v80
	v_mul_f32_e32 v80, v119, v81
	v_cvt_pk_bf16_f32 v113, v113, v114
	v_cvt_pk_bf16_f32 v79, v79, v80
	v_lshlrev_b32_e32 v80, 16, v194
	v_and_b32_e32 v81, 0xffff0000, v194
	v_lshlrev_b32_e32 v114, 16, v195
	v_and_b32_e32 v115, 0xffff0000, v195
	v_add_f32_e32 v106, v138, v106
	v_add_f32_e32 v107, v139, v107
	v_add_f32_e32 v104, v136, v104
	v_add_f32_e32 v105, v137, v105
	v_mul_f32_e32 v106, v106, v80
	v_mul_f32_e32 v107, v107, v81
	v_mul_f32_e32 v104, v104, v114
	v_mul_f32_e32 v105, v105, v115
	v_cvt_pk_bf16_f32 v106, v106, v107
	v_cvt_pk_bf16_f32 v104, v104, v105
	v_mul_f32_e32 v105, v225, v80
	v_mul_f32_e32 v107, v226, v81
	v_mul_f32_e32 v80, v125, v80
	v_mul_f32_e32 v81, v123, v81
	v_cvt_pk_bf16_f32 v105, v105, v107
	v_mul_f32_e32 v107, v227, v114
	v_cvt_pk_bf16_f32 v80, v80, v81
	v_mul_f32_e32 v81, v126, v114
	v_mul_f32_e32 v114, v127, v115
	v_cmp_lt_i32_e32 vcc, v111, v116
	v_cvt_pk_bf16_f32 v81, v81, v114
	v_cndmask_b32_e64 v114, v83, v104, s[8:9]
	v_cndmask_b32_e64 v123, v112, v105, s[8:9]
	v_cndmask_b32_e64 v126, v78, v80, s[8:9]
	v_cndmask_b32_e64 v83, v104, v83, s[8:9]
	v_cndmask_b32_e64 v104, v105, v112, s[8:9]
	v_cndmask_b32_e64 v112, v80, v78, s[8:9]
	v_cndmask_b32_e32 v78, v214, v111, vcc
	v_mul_f32_e32 v119, v228, v115
	v_cndmask_b32_e64 v115, v82, v106, s[8:9]
	v_lshlrev_b32_e32 v136, 2, v78
	v_cvt_pk_bf16_f32 v107, v107, v119
	v_cndmask_b32_e64 v125, v79, v81, s[8:9]
	v_cndmask_b32_e64 v119, v113, v107, s[8:9]
	v_cndmask_b32_e64 v105, v107, v113, s[8:9]
	v_cndmask_b32_e64 v113, v81, v79, s[8:9]
	ds_bpermute_b32 v78, v136, v115
	ds_bpermute_b32 v79, v136, v114
	ds_bpermute_b32 v114, v136, v123
	ds_bpermute_b32 v115, v136, v119
	v_cndmask_b32_e64 v82, v106, v82, s[8:9]
	ds_bpermute_b32 v119, v136, v126
	s_waitcnt lgkmcnt(0)
	v_cndmask_b32_e64 v81, v83, v79, s[8:9]
	v_cndmask_b32_e64 v80, v82, v78, s[8:9]
	v_cndmask_b32_e64 v79, v79, v83, s[8:9]
	v_cndmask_b32_e64 v78, v78, v82, s[8:9]
	v_mov_b64_e32 v[82:83], s[24:25]
	v_mad_i64_i32 v[126:127], s[4:5], v110, s88, v[82:83]
	ds_bpermute_b32 v123, v136, v125
	v_cndmask_b32_e64 v107, v105, v115, s[8:9]
	v_cndmask_b32_e64 v106, v104, v114, s[8:9]
	v_cndmask_b32_e64 v105, v115, v105, s[8:9]
	v_cndmask_b32_e64 v104, v114, v104, s[8:9]
	v_lshl_add_u64 v[126:127], v[126:127], 0, v[76:77]
	flat_store_dwordx4 v[126:127], v[78:81] offset:2560 sc1
	flat_store_dwordx4 v[126:127], v[104:107] sc1
	v_cmp_gt_i32_e32 vcc, s85, v110
	v_add_u32_e32 v78, 0xffff8000, v110
	v_mov_b32_e32 v104, s82
	v_mov_b32_e32 v105, s80
	v_mov_b32_e32 v106, s81
	v_mov_b32_e32 v107, s79
	v_cndmask_b32_e64 v114, v112, v119, s[8:9]
	v_cndmask_b32_e64 v112, v119, v112, s[8:9]
	v_ashrrev_i32_e32 v119, 31, v110
	v_cndmask_b32_e32 v81, v78, v110, vcc
	v_cndmask_b32_e32 v79, v104, v105, vcc
	v_cndmask_b32_e32 v78, v106, v107, vcc
	v_cndmask_b32_e32 v80, 0, v119, vcc
	v_mad_u64_u32 v[78:79], s[4:5], v81, s3, v[78:79]
	v_mad_i32_i24 v79, v80, s3, v79
	s_waitcnt lgkmcnt(0)
	v_cndmask_b32_e64 v115, v113, v123, s[8:9]
	v_cndmask_b32_e64 v113, v123, v113, s[8:9]
	v_lshl_add_u64 v[78:79], v[78:79], 0, v[76:77]
	flat_store_dwordx4 v[78:79], v[112:115] sc1
	v_lshlrev_b32_e32 v78, 16, v192
	v_and_b32_e32 v79, 0xffff0000, v192
	v_lshlrev_b32_e32 v80, 16, v193
	v_and_b32_e32 v81, 0xffff0000, v193
	v_add_f32_e32 v98, v130, v98
	v_add_f32_e32 v99, v131, v99
	v_add_f32_e32 v96, v128, v96
	v_add_f32_e32 v97, v129, v97
	v_mul_f32_e32 v98, v98, v78
	v_mul_f32_e32 v99, v99, v79
	v_mul_f32_e32 v96, v96, v80
	v_mul_f32_e32 v97, v97, v81
	v_cvt_pk_bf16_f32 v98, v98, v99
	v_cvt_pk_bf16_f32 v96, v96, v97
	v_mul_f32_e32 v97, v206, v78
	v_mul_f32_e32 v99, v220, v79
	v_mul_f32_e32 v78, v117, v78
	v_mul_f32_e32 v79, v118, v79
	v_cvt_pk_bf16_f32 v97, v97, v99
	v_mul_f32_e32 v99, v223, v80
	v_mul_f32_e32 v112, v224, v81
	v_cvt_pk_bf16_f32 v78, v78, v79
	v_mul_f32_e32 v79, v122, v80
	v_mul_f32_e32 v80, v124, v81
	v_cvt_pk_bf16_f32 v99, v99, v112
	v_cvt_pk_bf16_f32 v79, v79, v80
	v_lshlrev_b32_e32 v80, 16, v190
	v_and_b32_e32 v81, 0xffff0000, v190
	v_lshlrev_b32_e32 v112, 16, v191
	v_and_b32_e32 v113, 0xffff0000, v191
	v_add_f32_e32 v114, v134, v120
	v_add_f32_e32 v115, v135, v121
	v_add_f32_e32 v108, v132, v108
	v_add_f32_e32 v109, v133, v109
	v_mul_f32_e32 v114, v114, v80
	v_mul_f32_e32 v115, v115, v81
	v_mul_f32_e32 v108, v108, v112
	v_mul_f32_e32 v109, v109, v113
	v_cvt_pk_bf16_f32 v114, v114, v115
	v_cvt_pk_bf16_f32 v108, v108, v109
	v_mul_f32_e32 v109, v204, v80
	v_mul_f32_e32 v115, v205, v81
	v_mul_f32_e32 v80, v102, v80
	v_mul_f32_e32 v81, v103, v81
	v_cvt_pk_bf16_f32 v80, v80, v81
	v_mul_f32_e32 v81, v100, v112
	v_mul_f32_e32 v100, v101, v113
	v_cvt_pk_bf16_f32 v109, v109, v115
	v_mul_f32_e32 v115, v207, v112
	v_mul_f32_e32 v117, v221, v113
	v_cvt_pk_bf16_f32 v81, v81, v100
	v_cndmask_b32_e64 v100, v96, v108, s[8:9]
	v_cndmask_b32_e64 v101, v98, v114, s[8:9]
	v_cvt_pk_bf16_f32 v115, v115, v117
	v_cndmask_b32_e64 v103, v97, v109, s[8:9]
	v_cndmask_b32_e64 v102, v99, v115, s[8:9]
	v_cndmask_b32_e64 v113, v79, v81, s[8:9]
	v_cndmask_b32_e64 v117, v78, v80, s[8:9]
	v_cndmask_b32_e64 v98, v114, v98, s[8:9]
	v_cndmask_b32_e64 v96, v108, v96, s[8:9]
	v_cndmask_b32_e64 v108, v109, v97, s[8:9]
	v_cndmask_b32_e64 v109, v80, v78, s[8:9]
	v_cndmask_b32_e64 v114, v81, v79, s[8:9]
	ds_bpermute_b32 v78, v136, v101
	ds_bpermute_b32 v79, v136, v100
	ds_bpermute_b32 v100, v136, v103
	ds_bpermute_b32 v101, v136, v102
	v_add_u32_e32 v112, 32, v110
	v_mad_i64_i32 v[82:83], s[4:5], v112, s88, v[82:83]
	v_cndmask_b32_e64 v97, v115, v99, s[8:9]
	ds_bpermute_b32 v115, v136, v117
	ds_bpermute_b32 v113, v136, v113
	s_waitcnt lgkmcnt(0)
	v_cndmask_b32_e64 v81, v96, v79, s[8:9]
	v_cndmask_b32_e64 v80, v98, v78, s[8:9]
	v_cndmask_b32_e64 v79, v79, v96, s[8:9]
	v_cndmask_b32_e64 v78, v78, v98, s[8:9]
	v_lshl_add_u64 v[82:83], v[82:83], 0, v[76:77]
	v_cndmask_b32_e64 v99, v97, v101, s[8:9]
	v_cndmask_b32_e64 v98, v108, v100, s[8:9]
	v_cndmask_b32_e64 v97, v101, v97, s[8:9]
	v_cndmask_b32_e64 v96, v100, v108, s[8:9]
	flat_store_dwordx4 v[82:83], v[78:81] offset:2560 sc1
	flat_store_dwordx4 v[82:83], v[96:99] sc1
	v_cmp_gt_i32_e32 vcc, s85, v112
	v_add_u32_e32 v78, 0xffff8020, v110
	v_ashrrev_i32_e32 v108, 31, v112
	v_cndmask_b32_e32 v81, v78, v112, vcc
	v_cndmask_b32_e32 v79, v104, v105, vcc
	v_cndmask_b32_e32 v78, v106, v107, vcc
	v_cndmask_b32_e32 v80, 0, v108, vcc
	v_mad_u64_u32 v[78:79], s[4:5], v81, s3, v[78:79]
	v_mad_i32_i24 v79, v80, s3, v79
	v_cndmask_b32_e64 v103, v114, v113, s[8:9]
	v_cndmask_b32_e64 v102, v109, v115, s[8:9]
	v_cndmask_b32_e64 v101, v113, v114, s[8:9]
	v_cndmask_b32_e64 v100, v115, v109, s[8:9]
	v_lshl_add_u64 v[78:79], v[78:79], 0, v[76:77]
	flat_store_dwordx4 v[78:79], v[100:103] sc1
.LBB0_441:
	v_pk_fma_f32 v[62:63], v[62:63], s[36:37], v[94:95] op_sel_hi:[1,0,1] neg_lo:[1,0,0] neg_hi:[1,0,0]
	v_pk_fma_f32 v[60:61], v[60:61], s[36:37], v[92:93] op_sel_hi:[1,0,1] neg_lo:[1,0,0] neg_hi:[1,0,0]
	v_exp_f32_e32 v62, v62
	v_exp_f32_e32 v63, v63
	v_exp_f32_e32 v60, v60
	v_exp_f32_e32 v61, v61
	v_pk_fma_f32 v[58:59], v[58:59], s[36:37], v[86:87] op_sel_hi:[1,0,1] neg_lo:[1,0,0] neg_hi:[1,0,0]
	v_pk_fma_f32 v[54:55], v[54:55], s[36:37], v[94:95] op_sel_hi:[1,0,1] neg_lo:[1,0,0] neg_hi:[1,0,0]
	v_exp_f32_e32 v58, v58
	v_exp_f32_e32 v59, v59
	v_pk_add_f32 v[62:63], v[62:63], 1.0 op_sel_hi:[1,0]
	v_exp_f32_e32 v54, v54
	v_exp_f32_e32 v55, v55
	v_pk_fma_f32 v[52:53], v[52:53], s[36:37], v[92:93] op_sel_hi:[1,0,1] neg_lo:[1,0,0] neg_hi:[1,0,0]
	v_rcp_f32_e32 v62, v62
	v_rcp_f32_e32 v63, v63
	v_pk_add_f32 v[60:61], v[60:61], 1.0 op_sel_hi:[1,0]
	v_exp_f32_e32 v52, v52
	v_exp_f32_e32 v53, v53
	v_pk_fma_f32 v[46:47], v[46:47], s[36:37], v[94:95] op_sel_hi:[1,0,1] neg_lo:[1,0,0] neg_hi:[1,0,0]
	v_rcp_f32_e32 v60, v60
	v_rcp_f32_e32 v61, v61
	v_exp_f32_e32 v46, v46
	v_exp_f32_e32 v47, v47
	v_pk_add_f32 v[58:59], v[58:59], 1.0 op_sel_hi:[1,0]
	v_pk_add_f32 v[54:55], v[54:55], 1.0 op_sel_hi:[1,0]
	v_pk_fma_f32 v[44:45], v[44:45], s[36:37], v[92:93] op_sel_hi:[1,0,1] neg_lo:[1,0,0] neg_hi:[1,0,0]
	v_rcp_f32_e32 v82, v58
	v_rcp_f32_e32 v83, v59
	v_pk_mul_f32 v[58:59], v[90:91], v[62:63]
	v_pk_fma_f32 v[56:57], v[56:57], s[36:37], v[84:85] op_sel_hi:[1,0,1] neg_lo:[1,0,0] neg_hi:[1,0,0]
	v_rcp_f32_e32 v54, v54
	v_rcp_f32_e32 v55, v55
	v_pk_add_f32 v[52:53], v[52:53], 1.0 op_sel_hi:[1,0]
	v_exp_f32_e32 v44, v44
	v_exp_f32_e32 v45, v45
	v_exp_f32_e32 v58, v58
	v_exp_f32_e32 v59, v59
	v_exp_f32_e32 v96, v56
	v_exp_f32_e32 v97, v57
	v_pk_mul_f32 v[56:57], v[88:89], v[60:61]
	v_rcp_f32_e32 v52, v52
	v_rcp_f32_e32 v53, v53
	v_pk_add_f32 v[46:47], v[46:47], 1.0 op_sel_hi:[1,0]
	v_pk_fma_f32 v[38:39], v[38:39], s[36:37], v[94:95] op_sel_hi:[1,0,1] neg_lo:[1,0,0] neg_hi:[1,0,0]
	v_pk_fma_f32 v[36:37], v[36:37], s[36:37], v[92:93] op_sel_hi:[1,0,1] neg_lo:[1,0,0] neg_hi:[1,0,0]
	v_exp_f32_e32 v56, v56
	v_exp_f32_e32 v57, v57
	v_rcp_f32_e32 v46, v46
	v_rcp_f32_e32 v47, v47
	v_exp_f32_e32 v38, v38
	v_exp_f32_e32 v39, v39
	v_exp_f32_e32 v36, v36
	v_exp_f32_e32 v37, v37
	v_pk_fma_f32 v[50:51], v[50:51], s[36:37], v[86:87] op_sel_hi:[1,0,1] neg_lo:[1,0,0] neg_hi:[1,0,0]
	v_pk_mul_f32 v[54:55], v[90:91], v[54:55]
	v_exp_f32_e32 v50, v50
	v_exp_f32_e32 v51, v51
	v_pk_fma_f32 v[48:49], v[48:49], s[36:37], v[84:85] op_sel_hi:[1,0,1] neg_lo:[1,0,0] neg_hi:[1,0,0]
	v_pk_add_f32 v[44:45], v[44:45], 1.0 op_sel_hi:[1,0]
	v_pk_fma_f32 v[62:63], v[58:59], v[58:59], 1.0 op_sel_hi:[1,1,0] neg_lo:[1,0,0] neg_hi:[1,0,0]
	v_pk_add_f32 v[60:61], v[96:97], 1.0 op_sel_hi:[1,0]
	v_exp_f32_e32 v102, v54
	v_exp_f32_e32 v103, v55
	v_exp_f32_e32 v48, v48
	v_exp_f32_e32 v49, v49
	v_pk_mul_f32 v[52:53], v[88:89], v[52:53]
	v_pk_fma_f32 v[42:43], v[42:43], s[36:37], v[86:87] op_sel_hi:[1,0,1] neg_lo:[1,0,0] neg_hi:[1,0,0]
	v_rcp_f32_e32 v44, v44
	v_rcp_f32_e32 v45, v45
	v_sqrt_f32_e32 v62, v62
	v_sqrt_f32_e32 v63, v63
	v_rcp_f32_e32 v96, v60
	v_rcp_f32_e32 v97, v61
	v_pk_fma_f32 v[60:61], v[56:57], v[56:57], 1.0 op_sel_hi:[1,1,0] neg_lo:[1,0,0] neg_hi:[1,0,0]
	v_exp_f32_e32 v104, v52
	v_exp_f32_e32 v105, v53
	v_exp_f32_e32 v42, v42
	v_exp_f32_e32 v43, v43
	v_pk_mul_f32 v[46:47], v[90:91], v[46:47]
	v_pk_fma_f32 v[40:41], v[40:41], s[36:37], v[84:85] op_sel_hi:[1,0,1] neg_lo:[1,0,0] neg_hi:[1,0,0]
	v_pk_add_f32 v[38:39], v[38:39], 1.0 op_sel_hi:[1,0]
	v_pk_add_f32 v[36:37], v[36:37], 1.0 op_sel_hi:[1,0]
	v_sqrt_f32_e32 v98, v60
	v_sqrt_f32_e32 v99, v61
	v_exp_f32_e32 v106, v46
	v_exp_f32_e32 v107, v47
	v_exp_f32_e32 v40, v40
	v_exp_f32_e32 v41, v41
	v_rcp_f32_e32 v38, v38
	v_rcp_f32_e32 v39, v39
	v_rcp_f32_e32 v36, v36
	v_rcp_f32_e32 v37, v37
	v_lshlrev_b32_e32 v80, 16, v171
	v_and_b32_e32 v81, 0xffff0000, v171
	v_pk_add_f32 v[50:51], v[50:51], 1.0 op_sel_hi:[1,0]
	v_lshlrev_b32_e32 v78, 16, v170
	v_and_b32_e32 v79, 0xffff0000, v170
	v_pk_mul_f32 v[60:61], v[82:83], v[80:81]
	v_rcp_f32_e32 v50, v50
	v_rcp_f32_e32 v51, v51
	v_pk_fma_f32 v[54:55], v[102:103], v[102:103], 1.0 op_sel_hi:[1,1,0] neg_lo:[1,0,0] neg_hi:[1,0,0]
	v_pk_add_f32 v[48:49], v[48:49], 1.0 op_sel_hi:[1,0]
	v_pk_mul_f32 v[44:45], v[88:89], v[44:45]
	v_pk_mul_f32 v[60:61], v[60:61], v[62:63]
	v_pk_mul_f32 v[62:63], v[96:97], v[78:79]
	v_sqrt_f32_e32 v54, v54
	v_sqrt_f32_e32 v55, v55
	v_rcp_f32_e32 v52, v48
	v_rcp_f32_e32 v53, v49
	v_pk_fma_f32 v[48:49], v[104:105], v[104:105], 1.0 op_sel_hi:[1,1,0] neg_lo:[1,0,0] neg_hi:[1,0,0]
	v_pk_add_f32 v[42:43], v[42:43], 1.0 op_sel_hi:[1,0]
	v_exp_f32_e32 v108, v44
	v_exp_f32_e32 v109, v45
	v_pk_fma_f32 v[34:35], v[34:35], s[36:37], v[86:87] op_sel_hi:[1,0,1] neg_lo:[1,0,0] neg_hi:[1,0,0]
	v_pk_fma_f32 v[32:33], v[32:33], s[36:37], v[84:85] op_sel_hi:[1,0,1] neg_lo:[1,0,0] neg_hi:[1,0,0]
	v_pk_mul_f32 v[62:63], v[62:63], v[98:99]
	v_sqrt_f32_e32 v98, v48
	v_sqrt_f32_e32 v99, v49
	v_rcp_f32_e32 v42, v42
	v_rcp_f32_e32 v43, v43
	v_pk_fma_f32 v[46:47], v[106:107], v[106:107], 1.0 op_sel_hi:[1,1,0] neg_lo:[1,0,0] neg_hi:[1,0,0]
	v_pk_add_f32 v[40:41], v[40:41], 1.0 op_sel_hi:[1,0]
	v_exp_f32_e32 v34, v34
	v_exp_f32_e32 v35, v35
	v_pk_mul_f32 v[38:39], v[90:91], v[38:39]
	v_exp_f32_e32 v32, v32
	v_exp_f32_e32 v33, v33
	v_pk_mul_f32 v[36:37], v[88:89], v[36:37]
	v_lshlrev_b32_e32 v96, 16, v169
	v_and_b32_e32 v97, 0xffff0000, v169
	v_sqrt_f32_e32 v46, v46
	v_sqrt_f32_e32 v47, v47
	v_rcp_f32_e32 v44, v40
	v_rcp_f32_e32 v45, v41
	v_exp_f32_e32 v38, v38
	v_exp_f32_e32 v39, v39
	v_exp_f32_e32 v36, v36
	v_exp_f32_e32 v37, v37
	v_lshlrev_b32_e32 v82, 16, v168
	v_and_b32_e32 v83, 0xffff0000, v168
	v_pk_mul_f32 v[48:49], v[50:51], v[96:97]
	v_pk_mul_f32 v[50:51], v[52:53], v[82:83]
	v_pk_mul_f32 v[48:49], v[48:49], v[54:55]
	v_lshlrev_b32_e32 v54, 16, v167
	v_and_b32_e32 v55, 0xffff0000, v167
	v_pk_fma_f32 v[40:41], v[108:109], v[108:109], 1.0 op_sel_hi:[1,1,0] neg_lo:[1,0,0] neg_hi:[1,0,0]
	v_pk_mul_f32 v[50:51], v[50:51], v[98:99]
	v_lshlrev_b32_e32 v52, 16, v166
	v_and_b32_e32 v53, 0xffff0000, v166
	v_sqrt_f32_e32 v98, v40
	v_sqrt_f32_e32 v99, v41
	v_pk_mul_f32 v[40:41], v[42:43], v[54:55]
	v_pk_add_f32 v[34:35], v[34:35], 1.0 op_sel_hi:[1,0]
	v_pk_add_f32 v[32:33], v[32:33], 1.0 op_sel_hi:[1,0]
	v_pk_mul_f32 v[40:41], v[40:41], v[46:47]
	v_pk_mul_f32 v[42:43], v[44:45], v[52:53]
	v_rcp_f32_e32 v34, v34
	v_rcp_f32_e32 v35, v35
	v_pk_fma_f32 v[44:45], v[38:39], v[38:39], 1.0 op_sel_hi:[1,1,0] neg_lo:[1,0,0] neg_hi:[1,0,0]
	v_rcp_f32_e32 v32, v32
	v_rcp_f32_e32 v33, v33
	v_pk_fma_f32 v[46:47], v[36:37], v[36:37], 1.0 op_sel_hi:[1,1,0] neg_lo:[1,0,0] neg_hi:[1,0,0]
	v_sqrt_f32_e32 v44, v44
	v_sqrt_f32_e32 v45, v45
	v_sqrt_f32_e32 v46, v46
	v_sqrt_f32_e32 v47, v47
	s_nop 1
v_fmac_f32_dpp v62, v62, v56 row_shr:1 row_mask:0xf bank_mask:0xf
v_fmac_f32_dpp v63, v63, v57 row_shr:1 row_mask:0xf bank_mask:0xf
v_fmac_f32_dpp v60, v60, v58 row_shr:1 row_mask:0xf bank_mask:0xf
v_fmac_f32_dpp v61, v61, v59 row_shr:1 row_mask:0xf bank_mask:0xf
v_mul_f32_dpp v56, v56, v56 row_shr:1 row_mask:0xf bank_mask:0xf
v_mul_f32_dpp v57, v57, v57 row_shr:1 row_mask:0xf bank_mask:0xf
v_mul_f32_dpp v58, v58, v58 row_shr:1 row_mask:0xf bank_mask:0xf
v_mul_f32_dpp v59, v59, v59 row_shr:1 row_mask:0xf bank_mask:0xf
v_fmac_f32_dpp v62, v62, v56 row_shr:2 row_mask:0xf bank_mask:0xf
v_fmac_f32_dpp v63, v63, v57 row_shr:2 row_mask:0xf bank_mask:0xf
v_fmac_f32_dpp v60, v60, v58 row_shr:2 row_mask:0xf bank_mask:0xf
v_fmac_f32_dpp v61, v61, v59 row_shr:2 row_mask:0xf bank_mask:0xf
v_mul_f32_dpp v56, v56, v56 row_shr:2 row_mask:0xf bank_mask:0xf
v_mul_f32_dpp v57, v57, v57 row_shr:2 row_mask:0xf bank_mask:0xf
v_mul_f32_dpp v58, v58, v58 row_shr:2 row_mask:0xf bank_mask:0xf
v_mul_f32_dpp v59, v59, v59 row_shr:2 row_mask:0xf bank_mask:0xf
v_fmac_f32_dpp v62, v62, v56 row_shr:4 row_mask:0xf bank_mask:0xf
v_fmac_f32_dpp v63, v63, v57 row_shr:4 row_mask:0xf bank_mask:0xf
v_fmac_f32_dpp v60, v60, v58 row_shr:4 row_mask:0xf bank_mask:0xf
v_fmac_f32_dpp v61, v61, v59 row_shr:4 row_mask:0xf bank_mask:0xf
v_mul_f32_dpp v56, v56, v56 row_shr:4 row_mask:0xf bank_mask:0xf
v_mul_f32_dpp v57, v57, v57 row_shr:4 row_mask:0xf bank_mask:0xf
v_mul_f32_dpp v58, v58, v58 row_shr:4 row_mask:0xf bank_mask:0xf
v_mul_f32_dpp v59, v59, v59 row_shr:4 row_mask:0xf bank_mask:0xf
v_fmac_f32_dpp v62, v62, v56 row_shr:8 row_mask:0xf bank_mask:0xf
v_fmac_f32_dpp v63, v63, v57 row_shr:8 row_mask:0xf bank_mask:0xf
v_fmac_f32_dpp v60, v60, v58 row_shr:8 row_mask:0xf bank_mask:0xf
v_fmac_f32_dpp v61, v61, v59 row_shr:8 row_mask:0xf bank_mask:0xf
v_mul_f32_dpp v56, v56, v56 row_shr:8 row_mask:0xf bank_mask:0xf
v_mul_f32_dpp v57, v57, v57 row_shr:8 row_mask:0xf bank_mask:0xf
v_mul_f32_dpp v58, v58, v58 row_shr:8 row_mask:0xf bank_mask:0xf
v_mul_f32_dpp v59, v59, v59 row_shr:8 row_mask:0xf bank_mask:0xf

	v_pk_mul_f32 v[42:43], v[42:43], v[98:99]
	v_lshlrev_b32_e32 v98, 16, v164
	v_and_b32_e32 v99, 0xffff0000, v164
	v_lshlrev_b32_e32 v100, 16, v165
	v_and_b32_e32 v101, 0xffff0000, v165
	v_or_b32_e32 v112, 60, v144
	v_pk_mul_f32 v[34:35], v[34:35], v[100:101]
	v_pk_mul_f32 v[32:33], v[32:33], v[98:99]
	v_fmac_f32_e32 v62, 0, v56
	v_fmac_f32_e32 v63, 0, v57
	v_fmac_f32_e32 v60, 0, v58
	v_fmac_f32_e32 v61, 0, v59
	v_pk_mul_f32 v[44:45], v[34:35], v[44:45]
	v_pk_mul_f32 v[46:47], v[32:33], v[46:47]
	v_mov_b32_e32 v32, v36
	v_mov_b32_e32 v36, v38
	ds_bpermute_b32 v33, v112, v62
	ds_bpermute_b32 v34, v112, v56
	ds_bpermute_b32 v35, v112, v63
	ds_bpermute_b32 v38, v112, v57
	ds_bpermute_b32 v84, v112, v60
	ds_bpermute_b32 v85, v112, v58
	ds_bpermute_b32 v86, v112, v61
	ds_bpermute_b32 v87, v112, v59
	s_nop 1
v_fmac_f32_dpp v50, v50, v104 row_shr:1 row_mask:0xf bank_mask:0xf
v_fmac_f32_dpp v51, v51, v105 row_shr:1 row_mask:0xf bank_mask:0xf
v_fmac_f32_dpp v48, v48, v102 row_shr:1 row_mask:0xf bank_mask:0xf
v_fmac_f32_dpp v49, v49, v103 row_shr:1 row_mask:0xf bank_mask:0xf
v_mul_f32_dpp v104, v104, v104 row_shr:1 row_mask:0xf bank_mask:0xf
v_mul_f32_dpp v105, v105, v105 row_shr:1 row_mask:0xf bank_mask:0xf
v_mul_f32_dpp v102, v102, v102 row_shr:1 row_mask:0xf bank_mask:0xf
v_mul_f32_dpp v103, v103, v103 row_shr:1 row_mask:0xf bank_mask:0xf
v_fmac_f32_dpp v50, v50, v104 row_shr:2 row_mask:0xf bank_mask:0xf
v_fmac_f32_dpp v51, v51, v105 row_shr:2 row_mask:0xf bank_mask:0xf
v_fmac_f32_dpp v48, v48, v102 row_shr:2 row_mask:0xf bank_mask:0xf
v_fmac_f32_dpp v49, v49, v103 row_shr:2 row_mask:0xf bank_mask:0xf
v_mul_f32_dpp v104, v104, v104 row_shr:2 row_mask:0xf bank_mask:0xf
v_mul_f32_dpp v105, v105, v105 row_shr:2 row_mask:0xf bank_mask:0xf
v_mul_f32_dpp v102, v102, v102 row_shr:2 row_mask:0xf bank_mask:0xf
v_mul_f32_dpp v103, v103, v103 row_shr:2 row_mask:0xf bank_mask:0xf
v_fmac_f32_dpp v50, v50, v104 row_shr:4 row_mask:0xf bank_mask:0xf
v_fmac_f32_dpp v51, v51, v105 row_shr:4 row_mask:0xf bank_mask:0xf
v_fmac_f32_dpp v48, v48, v102 row_shr:4 row_mask:0xf bank_mask:0xf
v_fmac_f32_dpp v49, v49, v103 row_shr:4 row_mask:0xf bank_mask:0xf
v_mul_f32_dpp v104, v104, v104 row_shr:4 row_mask:0xf bank_mask:0xf
v_mul_f32_dpp v105, v105, v105 row_shr:4 row_mask:0xf bank_mask:0xf
v_mul_f32_dpp v102, v102, v102 row_shr:4 row_mask:0xf bank_mask:0xf
v_mul_f32_dpp v103, v103, v103 row_shr:4 row_mask:0xf bank_mask:0xf
v_fmac_f32_dpp v50, v50, v104 row_shr:8 row_mask:0xf bank_mask:0xf
v_fmac_f32_dpp v51, v51, v105 row_shr:8 row_mask:0xf bank_mask:0xf
v_fmac_f32_dpp v48, v48, v102 row_shr:8 row_mask:0xf bank_mask:0xf
v_fmac_f32_dpp v49, v49, v103 row_shr:8 row_mask:0xf bank_mask:0xf
v_mul_f32_dpp v104, v104, v104 row_shr:8 row_mask:0xf bank_mask:0xf
v_mul_f32_dpp v105, v105, v105 row_shr:8 row_mask:0xf bank_mask:0xf
v_mul_f32_dpp v102, v102, v102 row_shr:8 row_mask:0xf bank_mask:0xf
v_mul_f32_dpp v103, v103, v103 row_shr:8 row_mask:0xf bank_mask:0xf

	s_nop 1
v_fmac_f32_dpp v42, v42, v108 row_shr:1 row_mask:0xf bank_mask:0xf
v_fmac_f32_dpp v43, v43, v109 row_shr:1 row_mask:0xf bank_mask:0xf
v_fmac_f32_dpp v40, v40, v106 row_shr:1 row_mask:0xf bank_mask:0xf
v_fmac_f32_dpp v41, v41, v107 row_shr:1 row_mask:0xf bank_mask:0xf
v_mul_f32_dpp v108, v108, v108 row_shr:1 row_mask:0xf bank_mask:0xf
v_mul_f32_dpp v109, v109, v109 row_shr:1 row_mask:0xf bank_mask:0xf
v_mul_f32_dpp v106, v106, v106 row_shr:1 row_mask:0xf bank_mask:0xf
v_mul_f32_dpp v107, v107, v107 row_shr:1 row_mask:0xf bank_mask:0xf
v_fmac_f32_dpp v42, v42, v108 row_shr:2 row_mask:0xf bank_mask:0xf
v_fmac_f32_dpp v43, v43, v109 row_shr:2 row_mask:0xf bank_mask:0xf
v_fmac_f32_dpp v40, v40, v106 row_shr:2 row_mask:0xf bank_mask:0xf
v_fmac_f32_dpp v41, v41, v107 row_shr:2 row_mask:0xf bank_mask:0xf
v_mul_f32_dpp v108, v108, v108 row_shr:2 row_mask:0xf bank_mask:0xf
v_mul_f32_dpp v109, v109, v109 row_shr:2 row_mask:0xf bank_mask:0xf
v_mul_f32_dpp v106, v106, v106 row_shr:2 row_mask:0xf bank_mask:0xf
v_mul_f32_dpp v107, v107, v107 row_shr:2 row_mask:0xf bank_mask:0xf
v_fmac_f32_dpp v42, v42, v108 row_shr:4 row_mask:0xf bank_mask:0xf
v_fmac_f32_dpp v43, v43, v109 row_shr:4 row_mask:0xf bank_mask:0xf
v_fmac_f32_dpp v40, v40, v106 row_shr:4 row_mask:0xf bank_mask:0xf
v_fmac_f32_dpp v41, v41, v107 row_shr:4 row_mask:0xf bank_mask:0xf
v_mul_f32_dpp v108, v108, v108 row_shr:4 row_mask:0xf bank_mask:0xf
v_mul_f32_dpp v109, v109, v109 row_shr:4 row_mask:0xf bank_mask:0xf
v_mul_f32_dpp v106, v106, v106 row_shr:4 row_mask:0xf bank_mask:0xf
v_mul_f32_dpp v107, v107, v107 row_shr:4 row_mask:0xf bank_mask:0xf
v_fmac_f32_dpp v42, v42, v108 row_shr:8 row_mask:0xf bank_mask:0xf
v_fmac_f32_dpp v43, v43, v109 row_shr:8 row_mask:0xf bank_mask:0xf
v_fmac_f32_dpp v40, v40, v106 row_shr:8 row_mask:0xf bank_mask:0xf
v_fmac_f32_dpp v41, v41, v107 row_shr:8 row_mask:0xf bank_mask:0xf
v_mul_f32_dpp v108, v108, v108 row_shr:8 row_mask:0xf bank_mask:0xf
v_mul_f32_dpp v109, v109, v109 row_shr:8 row_mask:0xf bank_mask:0xf
v_mul_f32_dpp v106, v106, v106 row_shr:8 row_mask:0xf bank_mask:0xf
v_mul_f32_dpp v107, v107, v107 row_shr:8 row_mask:0xf bank_mask:0xf

	s_nop 1
v_fmac_f32_dpp v46, v46, v32 row_shr:1 row_mask:0xf bank_mask:0xf
v_fmac_f32_dpp v47, v47, v37 row_shr:1 row_mask:0xf bank_mask:0xf
v_fmac_f32_dpp v44, v44, v36 row_shr:1 row_mask:0xf bank_mask:0xf
v_fmac_f32_dpp v45, v45, v39 row_shr:1 row_mask:0xf bank_mask:0xf
v_mul_f32_dpp v32, v32, v32 row_shr:1 row_mask:0xf bank_mask:0xf
v_mul_f32_dpp v37, v37, v37 row_shr:1 row_mask:0xf bank_mask:0xf
v_mul_f32_dpp v36, v36, v36 row_shr:1 row_mask:0xf bank_mask:0xf
v_mul_f32_dpp v39, v39, v39 row_shr:1 row_mask:0xf bank_mask:0xf
v_fmac_f32_dpp v46, v46, v32 row_shr:2 row_mask:0xf bank_mask:0xf
v_fmac_f32_dpp v47, v47, v37 row_shr:2 row_mask:0xf bank_mask:0xf
v_fmac_f32_dpp v44, v44, v36 row_shr:2 row_mask:0xf bank_mask:0xf
v_fmac_f32_dpp v45, v45, v39 row_shr:2 row_mask:0xf bank_mask:0xf
v_mul_f32_dpp v32, v32, v32 row_shr:2 row_mask:0xf bank_mask:0xf
v_mul_f32_dpp v37, v37, v37 row_shr:2 row_mask:0xf bank_mask:0xf
v_mul_f32_dpp v36, v36, v36 row_shr:2 row_mask:0xf bank_mask:0xf
v_mul_f32_dpp v39, v39, v39 row_shr:2 row_mask:0xf bank_mask:0xf
v_fmac_f32_dpp v46, v46, v32 row_shr:4 row_mask:0xf bank_mask:0xf
v_fmac_f32_dpp v47, v47, v37 row_shr:4 row_mask:0xf bank_mask:0xf
v_fmac_f32_dpp v44, v44, v36 row_shr:4 row_mask:0xf bank_mask:0xf
v_fmac_f32_dpp v45, v45, v39 row_shr:4 row_mask:0xf bank_mask:0xf
v_mul_f32_dpp v32, v32, v32 row_shr:4 row_mask:0xf bank_mask:0xf
v_mul_f32_dpp v37, v37, v37 row_shr:4 row_mask:0xf bank_mask:0xf
v_mul_f32_dpp v36, v36, v36 row_shr:4 row_mask:0xf bank_mask:0xf
v_mul_f32_dpp v39, v39, v39 row_shr:4 row_mask:0xf bank_mask:0xf
v_fmac_f32_dpp v46, v46, v32 row_shr:8 row_mask:0xf bank_mask:0xf
v_fmac_f32_dpp v47, v47, v37 row_shr:8 row_mask:0xf bank_mask:0xf
v_fmac_f32_dpp v44, v44, v36 row_shr:8 row_mask:0xf bank_mask:0xf
v_fmac_f32_dpp v45, v45, v39 row_shr:8 row_mask:0xf bank_mask:0xf
v_mul_f32_dpp v32, v32, v32 row_shr:8 row_mask:0xf bank_mask:0xf
v_mul_f32_dpp v37, v37, v37 row_shr:8 row_mask:0xf bank_mask:0xf
v_mul_f32_dpp v36, v36, v36 row_shr:8 row_mask:0xf bank_mask:0xf
v_mul_f32_dpp v39, v39, v39 row_shr:8 row_mask:0xf bank_mask:0xf

	s_add_i32 s49, s49, 6
	s_waitcnt lgkmcnt(0)
	v_fmac_f32_e32 v50, v104, v33
	v_mul_f32_e32 v92, v104, v34
	v_fmac_f32_e32 v51, v105, v35
	v_mul_f32_e32 v93, v105, v38
	v_fmac_f32_e32 v48, v102, v84
	v_mul_f32_e32 v94, v102, v85
	v_fmac_f32_e32 v49, v103, v86
	v_mul_f32_e32 v95, v103, v87
	ds_bpermute_b32 v33, v112, v50
	ds_bpermute_b32 v34, v112, v92
	ds_bpermute_b32 v35, v112, v51
	ds_bpermute_b32 v38, v112, v93
	ds_bpermute_b32 v84, v112, v48
	ds_bpermute_b32 v85, v112, v94
	ds_bpermute_b32 v87, v112, v49
	ds_bpermute_b32 v89, v112, v95
	s_waitcnt lgkmcnt(0)
	v_fmac_f32_e32 v42, v108, v33
	v_mul_f32_e32 v86, v108, v34
	v_fmac_f32_e32 v43, v109, v35
	v_mul_f32_e32 v88, v109, v38
	v_fmac_f32_e32 v40, v106, v84
	v_mul_f32_e32 v90, v106, v85
	v_fmac_f32_e32 v41, v107, v87
	v_mul_f32_e32 v91, v107, v89
	ds_bpermute_b32 v33, v112, v42
	ds_bpermute_b32 v34, v112, v86
	ds_bpermute_b32 v35, v112, v43
	ds_bpermute_b32 v38, v112, v88
	ds_bpermute_b32 v102, v112, v40
	ds_bpermute_b32 v103, v112, v90
	ds_bpermute_b32 v89, v112, v41
	ds_bpermute_b32 v104, v112, v91
	s_waitcnt lgkmcnt(0)
	v_fmac_f32_e32 v46, v32, v33
	v_mul_f32_e32 v84, v32, v34
	v_fmac_f32_e32 v47, v37, v35
	v_mul_f32_e32 v85, v37, v38
	v_fmac_f32_e32 v44, v36, v102
	v_mul_f32_e32 v87, v36, v103
	v_fmac_f32_e32 v45, v39, v89
	v_mul_f32_e32 v89, v39, v104
	ds_bpermute_b32 v33, v112, v46
	ds_bpermute_b32 v32, v112, v84
	ds_bpermute_b32 v35, v112, v47
	ds_bpermute_b32 v34, v112, v85
	ds_bpermute_b32 v37, v112, v44
	ds_bpermute_b32 v36, v112, v87
	ds_bpermute_b32 v39, v112, v45
	ds_bpermute_b32 v38, v112, v89
	s_and_b64 s[4:5], exec, s[54:55]
	s_cselect_b32 s49, 2, s49
	s_add_i32 s49, s49, s66
	s_and_saveexec_b64 s[54:55], s[10:11]
	s_cbranch_execz .LBB0_443
	s_add_u32 s4, s59, s49
	s_addc_u32 s5, s58, 0
	s_mulk_i32 s5, 0x2800
	s_mul_hi_u32 s10, s4, 0x2800
	s_add_i32 s10, s10, s5
	s_mulk_i32 s4, 0x2800
	s_add_u32 s4, s77, s4
	s_addc_u32 s5, s78, s10
	v_lshl_add_u64 v[102:103], v[176:177], 3, s[4:5]
	s_waitcnt lgkmcnt(0)
	flat_store_dwordx4 v[102:103], v[32:35] sc1
	flat_store_dwordx4 v[102:103], v[36:39] offset:16 sc1
.LBB0_443:
	s_or_b64 exec, exec, s[54:55]
	v_pk_fma_f32 v[30:31], v[30:31], s[36:37], v[74:75] op_sel_hi:[1,0,1] neg_lo:[1,0,0] neg_hi:[1,0,0]
	v_pk_fma_f32 v[26:27], v[26:27], s[36:37], v[70:71] op_sel_hi:[1,0,1] neg_lo:[1,0,0] neg_hi:[1,0,0]
	v_exp_f32_e32 v30, v30
	v_exp_f32_e32 v31, v31
	v_exp_f32_e32 v26, v26
	v_exp_f32_e32 v27, v27
	v_pk_fma_f32 v[28:29], v[28:29], s[36:37], v[72:73] op_sel_hi:[1,0,1] neg_lo:[1,0,0] neg_hi:[1,0,0]
	v_pk_add_f32 v[30:31], v[30:31], 1.0 op_sel_hi:[1,0]
	v_exp_f32_e32 v28, v28
	v_rcp_f32_e32 v30, v30
	v_rcp_f32_e32 v31, v31
	v_exp_f32_e32 v29, v29
	v_pk_add_f32 v[26:27], v[26:27], 1.0 op_sel_hi:[1,0]
	v_pk_fma_f32 v[20:21], v[20:21], s[36:37], v[72:73] op_sel_hi:[1,0,1] neg_lo:[1,0,0] neg_hi:[1,0,0]
	s_waitcnt lgkmcnt(0)
	v_rcp_f32_e32 v32, v26
	v_rcp_f32_e32 v33, v27
	v_pk_mul_f32 v[26:27], v[66:67], v[30:31]
	v_pk_add_f32 v[28:29], v[28:29], 1.0 op_sel_hi:[1,0]
	v_exp_f32_e32 v26, v26
	v_exp_f32_e32 v27, v27
	v_rcp_f32_e32 v28, v28
	v_rcp_f32_e32 v29, v29
	v_exp_f32_e32 v20, v20
	v_exp_f32_e32 v21, v21
	v_pk_fma_f32 v[24:25], v[24:25], s[36:37], v[68:69] op_sel_hi:[1,0,1] neg_lo:[1,0,0] neg_hi:[1,0,0]
	v_pk_fma_f32 v[30:31], v[26:27], v[26:27], 1.0 op_sel_hi:[1,1,0] neg_lo:[1,0,0] neg_hi:[1,0,0]
	v_exp_f32_e32 v24, v24
	v_exp_f32_e32 v25, v25
	v_pk_mul_f32 v[28:29], v[64:65], v[28:29]
	v_sqrt_f32_e32 v34, v30
	v_sqrt_f32_e32 v35, v31
	v_exp_f32_e32 v30, v28
	v_exp_f32_e32 v31, v29
	v_pk_add_f32 v[20:21], v[20:21], 1.0 op_sel_hi:[1,0]
	v_pk_add_f32 v[24:25], v[24:25], 1.0 op_sel_hi:[1,0]
	v_rcp_f32_e32 v20, v20
	v_rcp_f32_e32 v21, v21
	v_rcp_f32_e32 v28, v24
	v_rcp_f32_e32 v29, v25
	v_pk_fma_f32 v[24:25], v[30:31], v[30:31], 1.0 op_sel_hi:[1,1,0] neg_lo:[1,0,0] neg_hi:[1,0,0]
	v_pk_fma_f32 v[18:19], v[18:19], s[36:37], v[70:71] op_sel_hi:[1,0,1] neg_lo:[1,0,0] neg_hi:[1,0,0]
	v_pk_fma_f32 v[16:17], v[16:17], s[36:37], v[68:69] op_sel_hi:[1,0,1] neg_lo:[1,0,0] neg_hi:[1,0,0]
	v_pk_fma_f32 v[14:15], v[14:15], s[36:37], v[74:75] op_sel_hi:[1,0,1] neg_lo:[1,0,0] neg_hi:[1,0,0]
	v_sqrt_f32_e32 v36, v24
	v_sqrt_f32_e32 v37, v25
	v_pk_mul_f32 v[24:25], v[32:33], v[80:81]
	v_exp_f32_e32 v18, v18
	v_exp_f32_e32 v19, v19
	v_exp_f32_e32 v16, v16
	v_exp_f32_e32 v17, v17
	v_pk_mul_f32 v[20:21], v[64:65], v[20:21]
	v_exp_f32_e32 v14, v14
	v_exp_f32_e32 v15, v15
	v_pk_mul_f32 v[24:25], v[24:25], v[34:35]
	v_exp_f32_e32 v34, v20
	v_exp_f32_e32 v35, v21
	v_pk_fma_f32 v[12:13], v[12:13], s[36:37], v[72:73] op_sel_hi:[1,0,1] neg_lo:[1,0,0] neg_hi:[1,0,0]
	v_pk_add_f32 v[18:19], v[18:19], 1.0 op_sel_hi:[1,0]
	v_exp_f32_e32 v12, v12
	v_exp_f32_e32 v13, v13
	v_pk_add_f32 v[16:17], v[16:17], 1.0 op_sel_hi:[1,0]
	v_pk_add_f32 v[14:15], v[14:15], 1.0 op_sel_hi:[1,0]
	v_pk_mul_f32 v[28:29], v[28:29], v[78:79]
	v_rcp_f32_e32 v18, v18
	v_rcp_f32_e32 v19, v19
	v_rcp_f32_e32 v20, v16
	v_rcp_f32_e32 v21, v17
	v_pk_fma_f32 v[16:17], v[34:35], v[34:35], 1.0 op_sel_hi:[1,1,0] neg_lo:[1,0,0] neg_hi:[1,0,0]
	v_rcp_f32_e32 v14, v14
	v_rcp_f32_e32 v15, v15
	v_pk_mul_f32 v[28:29], v[28:29], v[36:37]
	v_sqrt_f32_e32 v36, v16
	v_sqrt_f32_e32 v37, v17
	v_pk_add_f32 v[12:13], v[12:13], 1.0 op_sel_hi:[1,0]
	v_pk_fma_f32 v[22:23], v[22:23], s[36:37], v[74:75] op_sel_hi:[1,0,1] neg_lo:[1,0,0] neg_hi:[1,0,0]
	v_pk_fma_f32 v[10:11], v[10:11], s[36:37], v[70:71] op_sel_hi:[1,0,1] neg_lo:[1,0,0] neg_hi:[1,0,0]
	v_rcp_f32_e32 v12, v12
	v_rcp_f32_e32 v13, v13
	v_pk_fma_f32 v[6:7], v[6:7], s[36:37], v[74:75] op_sel_hi:[1,0,1] neg_lo:[1,0,0] neg_hi:[1,0,0]
	v_pk_fma_f32 v[4:5], v[4:5], s[36:37], v[72:73] op_sel_hi:[1,0,1] neg_lo:[1,0,0] neg_hi:[1,0,0]
	v_exp_f32_e32 v22, v22
	v_exp_f32_e32 v23, v23
	v_pk_mul_f32 v[16:17], v[18:19], v[96:97]
	v_pk_mul_f32 v[18:19], v[20:21], v[82:83]
	v_exp_f32_e32 v10, v10
	v_exp_f32_e32 v11, v11
	v_pk_mul_f32 v[14:15], v[66:67], v[14:15]
	v_pk_fma_f32 v[8:9], v[8:9], s[36:37], v[68:69] op_sel_hi:[1,0,1] neg_lo:[1,0,0] neg_hi:[1,0,0]
	v_exp_f32_e32 v6, v6
	v_exp_f32_e32 v7, v7
	v_exp_f32_e32 v4, v4
	v_exp_f32_e32 v5, v5
	v_pk_mul_f32 v[18:19], v[18:19], v[36:37]
	v_exp_f32_e32 v36, v14
	v_exp_f32_e32 v37, v15
	v_exp_f32_e32 v8, v8
	v_exp_f32_e32 v9, v9
	v_pk_mul_f32 v[12:13], v[64:65], v[12:13]
	v_pk_add_f32 v[22:23], v[22:23], 1.0 op_sel_hi:[1,0]
	v_pk_add_f32 v[10:11], v[10:11], 1.0 op_sel_hi:[1,0]
	v_exp_f32_e32 v38, v12
	v_exp_f32_e32 v39, v13
	v_pk_add_f32 v[6:7], v[6:7], 1.0 op_sel_hi:[1,0]
	v_pk_add_f32 v[4:5], v[4:5], 1.0 op_sel_hi:[1,0]
	v_rcp_f32_e32 v22, v22
	v_rcp_f32_e32 v23, v23
	v_rcp_f32_e32 v10, v10
	v_rcp_f32_e32 v11, v11
	v_pk_fma_f32 v[14:15], v[36:37], v[36:37], 1.0 op_sel_hi:[1,1,0] neg_lo:[1,0,0] neg_hi:[1,0,0]
	v_pk_add_f32 v[8:9], v[8:9], 1.0 op_sel_hi:[1,0]
	v_rcp_f32_e32 v6, v6
	v_rcp_f32_e32 v7, v7
	v_rcp_f32_e32 v4, v4
	v_rcp_f32_e32 v5, v5
	v_sqrt_f32_e32 v14, v14
	v_sqrt_f32_e32 v15, v15
	v_rcp_f32_e32 v12, v8
	v_rcp_f32_e32 v13, v9
	v_pk_fma_f32 v[8:9], v[38:39], v[38:39], 1.0 op_sel_hi:[1,1,0] neg_lo:[1,0,0] neg_hi:[1,0,0]
	v_pk_fma_f32 v[2:3], v[2:3], s[36:37], v[70:71] op_sel_hi:[1,0,1] neg_lo:[1,0,0] neg_hi:[1,0,0]
	v_pk_fma_f32 v[0:1], v[0:1], s[36:37], v[68:69] op_sel_hi:[1,0,1] neg_lo:[1,0,0] neg_hi:[1,0,0]
	v_pk_mul_f32 v[22:23], v[66:67], v[22:23]
	v_sqrt_f32_e32 v20, v8
	v_sqrt_f32_e32 v21, v9
	v_pk_mul_f32 v[8:9], v[10:11], v[54:55]
	v_exp_f32_e32 v2, v2
	v_exp_f32_e32 v3, v3
	v_pk_mul_f32 v[6:7], v[66:67], v[6:7]
	v_exp_f32_e32 v0, v0
	v_exp_f32_e32 v1, v1
	v_pk_mul_f32 v[4:5], v[64:65], v[4:5]
	v_exp_f32_e32 v22, v22
	v_exp_f32_e32 v23, v23
	v_pk_mul_f32 v[8:9], v[8:9], v[14:15]
	v_pk_mul_f32 v[10:11], v[12:13], v[52:53]
	v_exp_f32_e32 v12, v6
	v_exp_f32_e32 v13, v7
	v_exp_f32_e32 v14, v4
	v_exp_f32_e32 v15, v5
	v_pk_add_f32 v[2:3], v[2:3], 1.0 op_sel_hi:[1,0]
	v_pk_add_f32 v[0:1], v[0:1], 1.0 op_sel_hi:[1,0]
	v_pk_fma_f32 v[32:33], v[22:23], v[22:23], 1.0 op_sel_hi:[1,1,0] neg_lo:[1,0,0] neg_hi:[1,0,0]
	v_rcp_f32_e32 v2, v2
	v_rcp_f32_e32 v3, v3
	v_pk_fma_f32 v[6:7], v[12:13], v[12:13], 1.0 op_sel_hi:[1,1,0] neg_lo:[1,0,0] neg_hi:[1,0,0]
	v_rcp_f32_e32 v0, v0
	v_rcp_f32_e32 v1, v1
	v_pk_fma_f32 v[4:5], v[14:15], v[14:15], 1.0 op_sel_hi:[1,1,0] neg_lo:[1,0,0] neg_hi:[1,0,0]
	v_sqrt_f32_e32 v32, v32
	v_sqrt_f32_e32 v33, v33
	v_sqrt_f32_e32 v6, v6
	v_sqrt_f32_e32 v7, v7
	v_sqrt_f32_e32 v4, v4
	v_sqrt_f32_e32 v5, v5
	v_pk_mul_f32 v[2:3], v[2:3], v[100:101]
	v_pk_mul_f32 v[0:1], v[0:1], v[98:99]
	v_mov_b32_e32 v78, v26
	v_mov_b32_e32 v79, v31
	v_pk_mul_f32 v[16:17], v[16:17], v[32:33]
	v_mov_b32_e32 v80, v34
	v_mov_b32_e32 v81, v22
	v_pk_mul_f32 v[10:11], v[10:11], v[20:21]
	v_mov_b32_e32 v34, v37
	v_mov_b32_e32 v22, v38
	v_pk_mul_f32 v[20:21], v[2:3], v[6:7]
	v_pk_mul_f32 v[32:33], v[0:1], v[4:5]
	s_nop 1
v_fmac_f32_dpp v28, v28, v30 row_shl:1 row_mask:0xf bank_mask:0xf
v_fmac_f32_dpp v29, v29, v79 row_shl:1 row_mask:0xf bank_mask:0xf
v_fmac_f32_dpp v24, v24, v78 row_shl:1 row_mask:0xf bank_mask:0xf
v_fmac_f32_dpp v25, v25, v27 row_shl:1 row_mask:0xf bank_mask:0xf
v_mul_f32_dpp v30, v30, v30 row_shl:1 row_mask:0xf bank_mask:0xf
v_mul_f32_dpp v79, v79, v79 row_shl:1 row_mask:0xf bank_mask:0xf
v_mul_f32_dpp v78, v78, v78 row_shl:1 row_mask:0xf bank_mask:0xf
v_mul_f32_dpp v27, v27, v27 row_shl:1 row_mask:0xf bank_mask:0xf
v_fmac_f32_dpp v28, v28, v30 row_shl:2 row_mask:0xf bank_mask:0xf
v_fmac_f32_dpp v29, v29, v79 row_shl:2 row_mask:0xf bank_mask:0xf
v_fmac_f32_dpp v24, v24, v78 row_shl:2 row_mask:0xf bank_mask:0xf
v_fmac_f32_dpp v25, v25, v27 row_shl:2 row_mask:0xf bank_mask:0xf
v_mul_f32_dpp v30, v30, v30 row_shl:2 row_mask:0xf bank_mask:0xf
v_mul_f32_dpp v79, v79, v79 row_shl:2 row_mask:0xf bank_mask:0xf
v_mul_f32_dpp v78, v78, v78 row_shl:2 row_mask:0xf bank_mask:0xf
v_mul_f32_dpp v27, v27, v27 row_shl:2 row_mask:0xf bank_mask:0xf
v_fmac_f32_dpp v28, v28, v30 row_shl:4 row_mask:0xf bank_mask:0xf
v_fmac_f32_dpp v29, v29, v79 row_shl:4 row_mask:0xf bank_mask:0xf
v_fmac_f32_dpp v24, v24, v78 row_shl:4 row_mask:0xf bank_mask:0xf
v_fmac_f32_dpp v25, v25, v27 row_shl:4 row_mask:0xf bank_mask:0xf
v_mul_f32_dpp v30, v30, v30 row_shl:4 row_mask:0xf bank_mask:0xf
v_mul_f32_dpp v79, v79, v79 row_shl:4 row_mask:0xf bank_mask:0xf
v_mul_f32_dpp v78, v78, v78 row_shl:4 row_mask:0xf bank_mask:0xf
v_mul_f32_dpp v27, v27, v27 row_shl:4 row_mask:0xf bank_mask:0xf
v_fmac_f32_dpp v28, v28, v30 row_shl:8 row_mask:0xf bank_mask:0xf
v_fmac_f32_dpp v29, v29, v79 row_shl:8 row_mask:0xf bank_mask:0xf
v_fmac_f32_dpp v24, v24, v78 row_shl:8 row_mask:0xf bank_mask:0xf
v_fmac_f32_dpp v25, v25, v27 row_shl:8 row_mask:0xf bank_mask:0xf
v_mul_f32_dpp v30, v30, v30 row_shl:8 row_mask:0xf bank_mask:0xf
v_mul_f32_dpp v79, v79, v79 row_shl:8 row_mask:0xf bank_mask:0xf
v_mul_f32_dpp v78, v78, v78 row_shl:8 row_mask:0xf bank_mask:0xf
v_mul_f32_dpp v27, v27, v27 row_shl:8 row_mask:0xf bank_mask:0xf

	s_nop 1
v_fmac_f32_dpp v18, v18, v80 row_shl:1 row_mask:0xf bank_mask:0xf
v_fmac_f32_dpp v19, v19, v35 row_shl:1 row_mask:0xf bank_mask:0xf
v_fmac_f32_dpp v16, v16, v81 row_shl:1 row_mask:0xf bank_mask:0xf
v_fmac_f32_dpp v17, v17, v23 row_shl:1 row_mask:0xf bank_mask:0xf
v_mul_f32_dpp v80, v80, v80 row_shl:1 row_mask:0xf bank_mask:0xf
v_mul_f32_dpp v35, v35, v35 row_shl:1 row_mask:0xf bank_mask:0xf
v_mul_f32_dpp v81, v81, v81 row_shl:1 row_mask:0xf bank_mask:0xf
v_mul_f32_dpp v23, v23, v23 row_shl:1 row_mask:0xf bank_mask:0xf
v_fmac_f32_dpp v18, v18, v80 row_shl:2 row_mask:0xf bank_mask:0xf
v_fmac_f32_dpp v19, v19, v35 row_shl:2 row_mask:0xf bank_mask:0xf
v_fmac_f32_dpp v16, v16, v81 row_shl:2 row_mask:0xf bank_mask:0xf
v_fmac_f32_dpp v17, v17, v23 row_shl:2 row_mask:0xf bank_mask:0xf
v_mul_f32_dpp v80, v80, v80 row_shl:2 row_mask:0xf bank_mask:0xf
v_mul_f32_dpp v35, v35, v35 row_shl:2 row_mask:0xf bank_mask:0xf
v_mul_f32_dpp v81, v81, v81 row_shl:2 row_mask:0xf bank_mask:0xf
v_mul_f32_dpp v23, v23, v23 row_shl:2 row_mask:0xf bank_mask:0xf
v_fmac_f32_dpp v18, v18, v80 row_shl:4 row_mask:0xf bank_mask:0xf
v_fmac_f32_dpp v19, v19, v35 row_shl:4 row_mask:0xf bank_mask:0xf
v_fmac_f32_dpp v16, v16, v81 row_shl:4 row_mask:0xf bank_mask:0xf
v_fmac_f32_dpp v17, v17, v23 row_shl:4 row_mask:0xf bank_mask:0xf
v_mul_f32_dpp v80, v80, v80 row_shl:4 row_mask:0xf bank_mask:0xf
v_mul_f32_dpp v35, v35, v35 row_shl:4 row_mask:0xf bank_mask:0xf
v_mul_f32_dpp v81, v81, v81 row_shl:4 row_mask:0xf bank_mask:0xf
v_mul_f32_dpp v23, v23, v23 row_shl:4 row_mask:0xf bank_mask:0xf
v_fmac_f32_dpp v18, v18, v80 row_shl:8 row_mask:0xf bank_mask:0xf
v_fmac_f32_dpp v19, v19, v35 row_shl:8 row_mask:0xf bank_mask:0xf
v_fmac_f32_dpp v16, v16, v81 row_shl:8 row_mask:0xf bank_mask:0xf
v_fmac_f32_dpp v17, v17, v23 row_shl:8 row_mask:0xf bank_mask:0xf
v_mul_f32_dpp v80, v80, v80 row_shl:8 row_mask:0xf bank_mask:0xf
v_mul_f32_dpp v35, v35, v35 row_shl:8 row_mask:0xf bank_mask:0xf
v_mul_f32_dpp v81, v81, v81 row_shl:8 row_mask:0xf bank_mask:0xf
v_mul_f32_dpp v23, v23, v23 row_shl:8 row_mask:0xf bank_mask:0xf

	s_nop 1
v_fmac_f32_dpp v10, v10, v22 row_shl:1 row_mask:0xf bank_mask:0xf
v_fmac_f32_dpp v11, v11, v39 row_shl:1 row_mask:0xf bank_mask:0xf
v_fmac_f32_dpp v8, v8, v36 row_shl:1 row_mask:0xf bank_mask:0xf
v_fmac_f32_dpp v9, v9, v34 row_shl:1 row_mask:0xf bank_mask:0xf
v_mul_f32_dpp v22, v22, v22 row_shl:1 row_mask:0xf bank_mask:0xf
v_mul_f32_dpp v39, v39, v39 row_shl:1 row_mask:0xf bank_mask:0xf
v_mul_f32_dpp v36, v36, v36 row_shl:1 row_mask:0xf bank_mask:0xf
v_mul_f32_dpp v34, v34, v34 row_shl:1 row_mask:0xf bank_mask:0xf
v_fmac_f32_dpp v10, v10, v22 row_shl:2 row_mask:0xf bank_mask:0xf
v_fmac_f32_dpp v11, v11, v39 row_shl:2 row_mask:0xf bank_mask:0xf
v_fmac_f32_dpp v8, v8, v36 row_shl:2 row_mask:0xf bank_mask:0xf
v_fmac_f32_dpp v9, v9, v34 row_shl:2 row_mask:0xf bank_mask:0xf
v_mul_f32_dpp v22, v22, v22 row_shl:2 row_mask:0xf bank_mask:0xf
v_mul_f32_dpp v39, v39, v39 row_shl:2 row_mask:0xf bank_mask:0xf
v_mul_f32_dpp v36, v36, v36 row_shl:2 row_mask:0xf bank_mask:0xf
v_mul_f32_dpp v34, v34, v34 row_shl:2 row_mask:0xf bank_mask:0xf
v_fmac_f32_dpp v10, v10, v22 row_shl:4 row_mask:0xf bank_mask:0xf
v_fmac_f32_dpp v11, v11, v39 row_shl:4 row_mask:0xf bank_mask:0xf
v_fmac_f32_dpp v8, v8, v36 row_shl:4 row_mask:0xf bank_mask:0xf
v_fmac_f32_dpp v9, v9, v34 row_shl:4 row_mask:0xf bank_mask:0xf
v_mul_f32_dpp v22, v22, v22 row_shl:4 row_mask:0xf bank_mask:0xf
v_mul_f32_dpp v39, v39, v39 row_shl:4 row_mask:0xf bank_mask:0xf
v_mul_f32_dpp v36, v36, v36 row_shl:4 row_mask:0xf bank_mask:0xf
v_mul_f32_dpp v34, v34, v34 row_shl:4 row_mask:0xf bank_mask:0xf
v_fmac_f32_dpp v10, v10, v22 row_shl:8 row_mask:0xf bank_mask:0xf
v_fmac_f32_dpp v11, v11, v39 row_shl:8 row_mask:0xf bank_mask:0xf
v_fmac_f32_dpp v8, v8, v36 row_shl:8 row_mask:0xf bank_mask:0xf
v_fmac_f32_dpp v9, v9, v34 row_shl:8 row_mask:0xf bank_mask:0xf
v_mul_f32_dpp v22, v22, v22 row_shl:8 row_mask:0xf bank_mask:0xf
v_mul_f32_dpp v39, v39, v39 row_shl:8 row_mask:0xf bank_mask:0xf
v_mul_f32_dpp v36, v36, v36 row_shl:8 row_mask:0xf bank_mask:0xf
v_mul_f32_dpp v34, v34, v34 row_shl:8 row_mask:0xf bank_mask:0xf

	s_nop 0
	s_nop 1
v_fmac_f32_dpp v32, v32, v14 row_shl:1 row_mask:0xf bank_mask:0xf
v_fmac_f32_dpp v33, v33, v15 row_shl:1 row_mask:0xf bank_mask:0xf
v_fmac_f32_dpp v20, v20, v12 row_shl:1 row_mask:0xf bank_mask:0xf
v_fmac_f32_dpp v21, v21, v13 row_shl:1 row_mask:0xf bank_mask:0xf
v_mul_f32_dpp v14, v14, v14 row_shl:1 row_mask:0xf bank_mask:0xf
v_mul_f32_dpp v15, v15, v15 row_shl:1 row_mask:0xf bank_mask:0xf
v_mul_f32_dpp v12, v12, v12 row_shl:1 row_mask:0xf bank_mask:0xf
v_mul_f32_dpp v13, v13, v13 row_shl:1 row_mask:0xf bank_mask:0xf
v_fmac_f32_dpp v32, v32, v14 row_shl:2 row_mask:0xf bank_mask:0xf
v_fmac_f32_dpp v33, v33, v15 row_shl:2 row_mask:0xf bank_mask:0xf
v_fmac_f32_dpp v20, v20, v12 row_shl:2 row_mask:0xf bank_mask:0xf
v_fmac_f32_dpp v21, v21, v13 row_shl:2 row_mask:0xf bank_mask:0xf
v_mul_f32_dpp v14, v14, v14 row_shl:2 row_mask:0xf bank_mask:0xf
v_mul_f32_dpp v15, v15, v15 row_shl:2 row_mask:0xf bank_mask:0xf
v_mul_f32_dpp v12, v12, v12 row_shl:2 row_mask:0xf bank_mask:0xf
v_mul_f32_dpp v13, v13, v13 row_shl:2 row_mask:0xf bank_mask:0xf
v_fmac_f32_dpp v32, v32, v14 row_shl:4 row_mask:0xf bank_mask:0xf
v_fmac_f32_dpp v33, v33, v15 row_shl:4 row_mask:0xf bank_mask:0xf
v_fmac_f32_dpp v20, v20, v12 row_shl:4 row_mask:0xf bank_mask:0xf
v_fmac_f32_dpp v21, v21, v13 row_shl:4 row_mask:0xf bank_mask:0xf
v_mul_f32_dpp v14, v14, v14 row_shl:4 row_mask:0xf bank_mask:0xf
v_mul_f32_dpp v15, v15, v15 row_shl:4 row_mask:0xf bank_mask:0xf
v_mul_f32_dpp v12, v12, v12 row_shl:4 row_mask:0xf bank_mask:0xf
v_mul_f32_dpp v13, v13, v13 row_shl:4 row_mask:0xf bank_mask:0xf
v_fmac_f32_dpp v32, v32, v14 row_shl:8 row_mask:0xf bank_mask:0xf
v_fmac_f32_dpp v33, v33, v15 row_shl:8 row_mask:0xf bank_mask:0xf
v_fmac_f32_dpp v20, v20, v12 row_shl:8 row_mask:0xf bank_mask:0xf
v_fmac_f32_dpp v21, v21, v13 row_shl:8 row_mask:0xf bank_mask:0xf
v_mul_f32_dpp v14, v14, v14 row_shl:8 row_mask:0xf bank_mask:0xf
v_mul_f32_dpp v15, v15, v15 row_shl:8 row_mask:0xf bank_mask:0xf
v_mul_f32_dpp v12, v12, v12 row_shl:8 row_mask:0xf bank_mask:0xf
v_mul_f32_dpp v13, v13, v13 row_shl:8 row_mask:0xf bank_mask:0xf

	ds_bpermute_b32 v1, v144, v14
	v_fmac_f32_e32 v32, 0, v14
	v_fmac_f32_e32 v33, 0, v15
	v_fmac_f32_e32 v20, 0, v12
	v_fmac_f32_e32 v21, 0, v13
	ds_bpermute_b32 v0, v144, v32
	ds_bpermute_b32 v2, v144, v33
	ds_bpermute_b32 v3, v144, v15
	ds_bpermute_b32 v4, v144, v20
	ds_bpermute_b32 v5, v144, v12
	ds_bpermute_b32 v6, v144, v21
	ds_bpermute_b32 v7, v144, v13
	s_waitcnt lgkmcnt(0)
	v_fmac_f32_e32 v10, v22, v0
	v_mul_f32_e32 v22, v22, v1
	v_fmac_f32_e32 v11, v39, v2
	v_mul_f32_e32 v26, v39, v3
	v_fmac_f32_e32 v8, v36, v4
	v_mul_f32_e32 v31, v36, v5
	v_fmac_f32_e32 v9, v34, v6
	v_mul_f32_e32 v34, v34, v7
	ds_bpermute_b32 v0, v144, v10
	ds_bpermute_b32 v1, v144, v22
	ds_bpermute_b32 v2, v144, v11
	ds_bpermute_b32 v3, v144, v26
	ds_bpermute_b32 v4, v144, v8
	ds_bpermute_b32 v5, v144, v31
	ds_bpermute_b32 v6, v144, v9
	ds_bpermute_b32 v7, v144, v34
	s_waitcnt lgkmcnt(0)
	v_fmac_f32_e32 v18, v80, v0
	v_mul_f32_e32 v36, v80, v1
	v_fmac_f32_e32 v19, v35, v2
	v_mul_f32_e32 v35, v35, v3
	v_fmac_f32_e32 v16, v81, v4
	v_mul_f32_e32 v37, v81, v5
	v_fmac_f32_e32 v17, v23, v6
	v_mul_f32_e32 v23, v23, v7
	ds_bpermute_b32 v0, v144, v18
	ds_bpermute_b32 v1, v144, v36
	ds_bpermute_b32 v2, v144, v19
	ds_bpermute_b32 v3, v144, v35
	ds_bpermute_b32 v4, v144, v16
	ds_bpermute_b32 v5, v144, v37
	ds_bpermute_b32 v6, v144, v17
	ds_bpermute_b32 v7, v144, v23
	s_waitcnt lgkmcnt(0)
	v_fmac_f32_e32 v28, v30, v0
	v_mul_f32_e32 v30, v30, v1
	v_fmac_f32_e32 v29, v79, v2
	v_mul_f32_e32 v38, v79, v3
	v_fmac_f32_e32 v24, v78, v4
	v_mul_f32_e32 v39, v78, v5
	v_fmac_f32_e32 v25, v27, v6
	v_mul_f32_e32 v27, v27, v7
	ds_bpermute_b32 v1, v144, v28
	ds_bpermute_b32 v0, v144, v30
	ds_bpermute_b32 v3, v144, v29
	ds_bpermute_b32 v2, v144, v38
	ds_bpermute_b32 v5, v144, v24
	ds_bpermute_b32 v4, v144, v39
	ds_bpermute_b32 v7, v144, v25
	ds_bpermute_b32 v6, v144, v27
	s_and_saveexec_b64 s[10:11], s[12:13]
	s_cbranch_execz .LBB0_445
	s_or_b32 s4, s47, 1
	s_mul_hi_i32 s5, s4, 0x84
	s_mulk_i32 s4, 0x84
	s_add_u32 s4, s4, s49
	s_addc_u32 s5, s5, 0
	s_mulk_i32 s5, 0x2800
	s_mul_hi_u32 s12, s4, 0x2800
	s_add_i32 s12, s12, s5
	s_mulk_i32 s4, 0x2800
	s_add_u32 s4, s77, s4
	s_addc_u32 s5, s78, s12
	v_lshl_add_u64 v[52:53], v[176:177], 3, s[4:5]
	s_waitcnt lgkmcnt(0)
	flat_store_dwordx4 v[52:53], v[0:3] sc1
	flat_store_dwordx4 v[52:53], v[4:7] offset:16 sc1
	s_or_b64 exec, exec, s[10:11]
	s_and_b64 vcc, exec, s[14:15]
	s_cbranch_vccnz .LBB0_447
	s_branch .LBB0_446

.LBB0_446:
	s_waitcnt lgkmcnt(0)
	v_lshlrev_b32_e32 v0, 16, v180
	v_and_b32_e32 v1, 0xffff0000, v180
	v_add_f32_e32 v4, v62, v28
	v_add_f32_e32 v5, v63, v29
	v_mul_f32_e32 v4, v4, v0
	v_mul_f32_e32 v5, v5, v1
	v_lshlrev_b32_e32 v2, 16, v181
	v_and_b32_e32 v3, 0xffff0000, v181
	v_cvt_pk_bf16_f32 v4, v4, v5
	v_add_f32_e32 v5, v60, v24
	v_add_f32_e32 v6, v61, v25
	v_mul_f32_e32 v5, v5, v2
	v_mul_f32_e32 v6, v6, v3
	v_cvt_pk_bf16_f32 v5, v5, v6
	v_mul_f32_e32 v6, v56, v0
	v_mul_f32_e32 v7, v57, v1
	v_mul_f32_e32 v0, v30, v0
	v_mul_f32_e32 v1, v38, v1
	v_cvt_pk_bf16_f32 v6, v6, v7
	v_mul_f32_e32 v7, v58, v2
	v_mul_f32_e32 v24, v59, v3
	v_cvt_pk_bf16_f32 v0, v0, v1
	v_mul_f32_e32 v1, v39, v2
	v_mul_f32_e32 v2, v27, v3
	v_cvt_pk_bf16_f32 v7, v7, v24
	v_cvt_pk_bf16_f32 v1, v1, v2
	v_lshlrev_b32_e32 v2, 16, v178
	v_and_b32_e32 v3, 0xffff0000, v178
	v_lshlrev_b32_e32 v24, 16, v179
	v_and_b32_e32 v25, 0xffff0000, v179
	v_add_f32_e32 v18, v50, v18
	v_add_f32_e32 v19, v51, v19
	v_add_f32_e32 v16, v48, v16
	v_add_f32_e32 v17, v49, v17
	v_mul_f32_e32 v18, v18, v2
	v_mul_f32_e32 v19, v19, v3
	v_mul_f32_e32 v16, v16, v24
	v_mul_f32_e32 v17, v17, v25
	v_cvt_pk_bf16_f32 v18, v18, v19
	v_cvt_pk_bf16_f32 v16, v16, v17
	v_mul_f32_e32 v17, v92, v2
	v_mul_f32_e32 v19, v93, v3
	v_mul_f32_e32 v2, v36, v2
	v_mul_f32_e32 v3, v35, v3
	v_cmp_lt_i32_e32 vcc, v111, v116
	v_cvt_pk_bf16_f32 v17, v17, v19
	v_mul_f32_e32 v19, v94, v24
	v_cvt_pk_bf16_f32 v2, v2, v3
	v_mul_f32_e32 v3, v37, v24
	v_mul_f32_e32 v23, v23, v25
	v_cndmask_b32_e64 v29, v0, v2, s[8:9]
	v_cndmask_b32_e64 v30, v2, v0, s[8:9]
	v_cndmask_b32_e32 v0, v214, v111, vcc
	v_mul_f32_e32 v27, v95, v25
	v_cvt_pk_bf16_f32 v19, v19, v27
	v_cvt_pk_bf16_f32 v3, v3, v23
	v_cndmask_b32_e64 v23, v5, v16, s[8:9]
	v_cndmask_b32_e64 v24, v4, v18, s[8:9]
	v_cndmask_b32_e64 v25, v7, v19, s[8:9]
	v_cndmask_b32_e64 v28, v1, v3, s[8:9]
	v_lshlrev_b32_e32 v36, 2, v0
	v_cndmask_b32_e64 v27, v6, v17, s[8:9]
	v_cndmask_b32_e64 v5, v16, v5, s[8:9]
	v_cndmask_b32_e64 v16, v17, v6, s[8:9]
	v_cndmask_b32_e64 v17, v19, v7, s[8:9]
	v_cndmask_b32_e64 v35, v3, v1, s[8:9]
	ds_bpermute_b32 v0, v36, v24
	ds_bpermute_b32 v1, v36, v23
	ds_bpermute_b32 v19, v36, v25
	ds_bpermute_b32 v24, v36, v28
	v_cndmask_b32_e64 v4, v18, v4, s[8:9]
	ds_bpermute_b32 v18, v36, v27
	ds_bpermute_b32 v23, v36, v29
	v_add_u32_e32 v52, 0x80, v110
	s_waitcnt lgkmcnt(0)
	v_cndmask_b32_e64 v3, v5, v1, s[8:9]
	v_cndmask_b32_e64 v1, v1, v5, s[8:9]
	v_cndmask_b32_e64 v7, v17, v19, s[8:9]
	v_cndmask_b32_e64 v5, v19, v17, s[8:9]
	v_cndmask_b32_e64 v19, v35, v24, s[8:9]
	v_cndmask_b32_e64 v17, v24, v35, s[8:9]
	v_mov_b64_e32 v[24:25], s[24:25]
	v_mad_i64_i32 v[28:29], s[4:5], v52, s88, v[24:25]
	v_cndmask_b32_e64 v2, v4, v0, s[8:9]
	v_cndmask_b32_e64 v0, v0, v4, s[8:9]
	v_cndmask_b32_e64 v6, v16, v18, s[8:9]
	v_cndmask_b32_e64 v4, v18, v16, s[8:9]
	v_cndmask_b32_e64 v18, v30, v23, s[8:9]
	v_cndmask_b32_e64 v16, v23, v30, s[8:9]
	v_ashrrev_i32_e32 v23, 31, v52
	v_lshl_add_u64 v[28:29], v[28:29], 0, v[76:77]
	v_cmp_gt_i32_e32 vcc, s85, v52
	flat_store_dwordx4 v[28:29], v[0:3] offset:2560 sc1
	flat_store_dwordx4 v[28:29], v[4:7] sc1
	v_mov_b32_e32 v27, s80
	v_add_u32_e32 v0, 0xffff8080, v110
	v_cndmask_b32_e32 v2, 0, v23, vcc
	v_mov_b32_e32 v23, s82
	v_mov_b32_e32 v28, s81
	v_mov_b32_e32 v29, s79
	v_cndmask_b32_e32 v3, v0, v52, vcc
	v_cndmask_b32_e32 v1, v23, v27, vcc
	v_cndmask_b32_e32 v0, v28, v29, vcc
	v_mad_u64_u32 v[0:1], s[4:5], v3, s3, v[0:1]
	v_mad_i32_i24 v1, v2, s3, v1
	v_lshl_add_u64 v[0:1], v[0:1], 0, v[76:77]
	flat_store_dwordx4 v[0:1], v[16:19] sc1
	v_lshlrev_b32_e32 v0, 16, v174
	v_and_b32_e32 v1, 0xffff0000, v174
	v_add_f32_e32 v4, v42, v10
	v_add_f32_e32 v5, v43, v11
	v_mul_f32_e32 v4, v4, v0
	v_mul_f32_e32 v5, v5, v1
	v_lshlrev_b32_e32 v2, 16, v175
	v_and_b32_e32 v3, 0xffff0000, v175
	v_cvt_pk_bf16_f32 v4, v4, v5
	v_add_f32_e32 v5, v40, v8
	v_add_f32_e32 v6, v41, v9
	v_mul_f32_e32 v5, v5, v2
	v_mul_f32_e32 v6, v6, v3
	v_cvt_pk_bf16_f32 v5, v5, v6
	v_mul_f32_e32 v6, v86, v0
	v_mul_f32_e32 v7, v88, v1
	v_mul_f32_e32 v0, v22, v0
	v_mul_f32_e32 v1, v26, v1
	v_cvt_pk_bf16_f32 v6, v6, v7
	v_mul_f32_e32 v7, v90, v2
	v_cvt_pk_bf16_f32 v0, v0, v1
	v_mul_f32_e32 v1, v31, v2
	v_mul_f32_e32 v2, v34, v3
	v_mul_f32_e32 v8, v91, v3
	v_cvt_pk_bf16_f32 v1, v1, v2
	v_lshlrev_b32_e32 v2, 16, v172
	v_and_b32_e32 v3, 0xffff0000, v172
	v_add_f32_e32 v10, v46, v32
	v_add_f32_e32 v11, v47, v33
	v_mul_f32_e32 v10, v10, v2
	v_mul_f32_e32 v11, v11, v3
	v_cvt_pk_bf16_f32 v7, v7, v8
	v_lshlrev_b32_e32 v8, 16, v173
	v_and_b32_e32 v9, 0xffff0000, v173
	v_cvt_pk_bf16_f32 v10, v10, v11
	v_add_f32_e32 v11, v44, v20
	v_add_f32_e32 v16, v45, v21
	v_mul_f32_e32 v11, v11, v8
	v_mul_f32_e32 v16, v16, v9
	v_cvt_pk_bf16_f32 v11, v11, v16
	v_mul_f32_e32 v16, v84, v2
	v_mul_f32_e32 v17, v85, v3
	v_mul_f32_e32 v2, v14, v2
	v_mul_f32_e32 v3, v15, v3
	v_cvt_pk_bf16_f32 v16, v16, v17
	v_mul_f32_e32 v17, v87, v8
	v_mul_f32_e32 v18, v89, v9
	v_cvt_pk_bf16_f32 v2, v2, v3
	v_mul_f32_e32 v3, v12, v8
	v_mul_f32_e32 v8, v13, v9
	v_cvt_pk_bf16_f32 v17, v17, v18
	v_cvt_pk_bf16_f32 v3, v3, v8
	v_cndmask_b32_e64 v8, v5, v11, s[8:9]
	v_cndmask_b32_e64 v9, v4, v10, s[8:9]
	v_cndmask_b32_e64 v12, v7, v17, s[8:9]
	v_cndmask_b32_e64 v13, v6, v16, s[8:9]
	v_cndmask_b32_e64 v15, v1, v3, s[8:9]
	v_cndmask_b32_e64 v18, v0, v2, s[8:9]
	v_cndmask_b32_e64 v4, v10, v4, s[8:9]
	v_cndmask_b32_e64 v5, v11, v5, s[8:9]
	v_cndmask_b32_e64 v10, v16, v6, s[8:9]
	v_cndmask_b32_e64 v11, v17, v7, s[8:9]
	v_cndmask_b32_e64 v16, v2, v0, s[8:9]
	v_cndmask_b32_e64 v17, v3, v1, s[8:9]
	ds_bpermute_b32 v0, v36, v9
	ds_bpermute_b32 v1, v36, v8
	ds_bpermute_b32 v8, v36, v13
	ds_bpermute_b32 v9, v36, v12
	ds_bpermute_b32 v12, v36, v18
	ds_bpermute_b32 v13, v36, v15
	v_add_u32_e32 v14, 0xa0, v110
	s_waitcnt lgkmcnt(0)
	v_cndmask_b32_e64 v3, v5, v1, s[8:9]
	v_cndmask_b32_e64 v2, v4, v0, s[8:9]
	v_cndmask_b32_e64 v1, v1, v5, s[8:9]
	v_cndmask_b32_e64 v0, v0, v4, s[8:9]
	v_cndmask_b32_e64 v7, v11, v9, s[8:9]
	v_cndmask_b32_e64 v6, v10, v8, s[8:9]
	v_cndmask_b32_e64 v5, v9, v11, s[8:9]
	v_cndmask_b32_e64 v4, v8, v10, s[8:9]
	v_cndmask_b32_e64 v11, v17, v13, s[8:9]
	v_cndmask_b32_e64 v10, v16, v12, s[8:9]
	v_cndmask_b32_e64 v9, v13, v17, s[8:9]
	v_cndmask_b32_e64 v8, v12, v16, s[8:9]
	v_mad_i64_i32 v[12:13], s[4:5], v14, s88, v[24:25]
	v_lshl_add_u64 v[12:13], v[12:13], 0, v[76:77]
	flat_store_dwordx4 v[12:13], v[0:3] offset:2560 sc1
	flat_store_dwordx4 v[12:13], v[4:7] sc1
	v_cmp_gt_i32_e32 vcc, s85, v14
	v_add_u32_e32 v0, 0xffff80a0, v110
	v_ashrrev_i32_e32 v15, 31, v14
	v_cndmask_b32_e32 v3, v0, v14, vcc
	v_cndmask_b32_e32 v1, v23, v27, vcc
	v_cndmask_b32_e32 v0, v28, v29, vcc
	v_cndmask_b32_e32 v2, 0, v15, vcc
	v_mad_u64_u32 v[0:1], s[4:5], v3, s3, v[0:1]
	v_mad_i32_i24 v1, v2, s3, v1
	v_lshl_add_u64 v[0:1], v[0:1], 0, v[76:77]
	flat_store_dwordx4 v[0:1], v[8:11] sc1

.LBB0_518:
	s_ashr_i32 s23, s22, 31
	s_lshl_b64 s[26:27], s[22:23], 8
	s_mov_b64 s[24:25], 0
	v_mov_b32_e32 v4, v196
	s_waitcnt lgkmcnt(0)
	s_barrier
	s_mul_i32 s72, s22, 0x340000
	s_mul_hi_u32 s73, s22, 0x340000
	s_add_u32 s98, s10, s72
	s_addc_u32 s99, s11, s73
	s_cmpk_lt_i32 s22, 0x80
	s_cselect_b32 s100, s39, s49
	s_cselect_b32 s101, s48, s50
	s_mul_i32 s72, s22, 0xa0000
	s_add_u32 s100, s100, s72
	s_addc_u32 s101, s101, 0
	v_mov_b32_e32 v60, v196
	v_mul_u32_u24_e32 v61, 0xcccd, v60
	v_lshrrev_b32_e32 v62, 23, v61
	v_mul_u32_u24_e32 v63, 0xa0, v62
	v_sub_u32_e32 v63, v60, v63
	v_mul_u32_u24_e32 v76, 0x3400, v62
	v_lshl_add_u32 v76, v63, 4, v76
	v_lshrrev_b32_e32 v77, 6, v62
	v_mul_u32_u24_e32 v77, 0x1400, v77
	v_lshl_add_u32 v77, v63, 5, v77
	v_lshlrev_b32_e32 v78, 4, v60
	global_load_dwordx4 v[68:71], v76, s[98:99]
	global_load_dwordx4 v[64:67], v76, s[98:99] offset:2560
	global_load_dwordx4 v[72:75], v78, s[100:101]
	v_add_u32_e32 v60, 0x200, v60
	v_mul_u32_u24_e32 v61, 0xcccd, v60
	v_lshrrev_b32_e32 v62, 23, v61
	v_mul_u32_u24_e32 v63, 0xa0, v62
	v_sub_u32_e32 v63, v60, v63
	v_mul_u32_u24_e32 v92, 0x3400, v62
	v_lshl_add_u32 v92, v63, 4, v92
	v_lshrrev_b32_e32 v93, 6, v62
	v_mul_u32_u24_e32 v93, 0x1400, v93
	v_lshl_add_u32 v93, v63, 5, v93
	v_lshlrev_b32_e32 v94, 4, v60
	global_load_dwordx4 v[84:87], v92, s[98:99]
	global_load_dwordx4 v[80:83], v92, s[98:99] offset:2560
	global_load_dwordx4 v[88:91], v94, s[100:101]
	v_add_u32_e32 v60, 0x200, v60
	v_mul_u32_u24_e32 v61, 0xcccd, v60
	v_lshrrev_b32_e32 v62, 23, v61
	v_mul_u32_u24_e32 v63, 0xa0, v62
	v_sub_u32_e32 v63, v60, v63
	v_mul_u32_u24_e32 v108, 0x3400, v62
	v_lshl_add_u32 v108, v63, 4, v108
	v_lshrrev_b32_e32 v109, 6, v62
	v_mul_u32_u24_e32 v109, 0x1400, v109
	v_lshl_add_u32 v109, v63, 5, v109
	v_lshlrev_b32_e32 v110, 4, v60
	global_load_dwordx4 v[100:103], v108, s[98:99]
	global_load_dwordx4 v[96:99], v108, s[98:99] offset:2560
	global_load_dwordx4 v[104:107], v110, s[100:101]
	v_add_u32_e32 v60, 0x200, v60
	v_mul_u32_u24_e32 v61, 0xcccd, v60
	v_lshrrev_b32_e32 v62, 23, v61
	v_mul_u32_u24_e32 v63, 0xa0, v62
	v_sub_u32_e32 v63, v60, v63
	v_mul_u32_u24_e32 v124, 0x3400, v62
	v_lshl_add_u32 v124, v63, 4, v124
	v_lshrrev_b32_e32 v125, 6, v62
	v_mul_u32_u24_e32 v125, 0x1400, v125
	v_lshl_add_u32 v125, v63, 5, v125
	v_lshlrev_b32_e32 v126, 4, v60
	global_load_dwordx4 v[116:119], v124, s[98:99]
	global_load_dwordx4 v[112:115], v124, s[98:99] offset:2560
	global_load_dwordx4 v[120:123], v126, s[100:101]
	v_add_u32_e32 v60, 0x200, v60
	ds_read_b128 v[128:131], v77
	ds_read_b128 v[132:135], v77 offset:16
	ds_read_b128 v[136:139], v77 offset:20480
	ds_read_b128 v[140:143], v77 offset:20496
	s_waitcnt vmcnt(9)
	s_waitcnt lgkmcnt(0)
	v_lshlrev_b32_e32 v144, 16, v64
	v_and_b32_e32 v145, 0xffff0000, v64
	v_lshlrev_b32_e32 v146, 16, v68
	v_and_b32_e32 v147, 0xffff0000, v68
	v_lshlrev_b32_e32 v148, 16, v72
	v_and_b32_e32 v149, 0xffff0000, v72
	v_pk_mul_f32 v[146:147], v[146:147], v[128:129]
	v_pk_mul_f32 v[148:149], v[148:149], v[136:137]
	v_pk_add_f32 v[146:147], v[146:147], v[144:145]
	v_pk_add_f32 v[146:147], v[146:147], v[148:149]
	v_cvt_pk_bf16_f32 v168, v146, v147
	v_lshlrev_b32_e32 v150, 16, v65
	v_and_b32_e32 v151, 0xffff0000, v65
	v_lshlrev_b32_e32 v152, 16, v69
	v_and_b32_e32 v153, 0xffff0000, v69
	v_lshlrev_b32_e32 v154, 16, v73
	v_and_b32_e32 v155, 0xffff0000, v73
	v_pk_mul_f32 v[152:153], v[152:153], v[130:131]
	v_pk_mul_f32 v[154:155], v[154:155], v[138:139]
	v_pk_add_f32 v[152:153], v[152:153], v[150:151]
	v_pk_add_f32 v[152:153], v[152:153], v[154:155]
	v_cvt_pk_bf16_f32 v169, v152, v153
	v_lshlrev_b32_e32 v156, 16, v66
	v_and_b32_e32 v157, 0xffff0000, v66
	v_lshlrev_b32_e32 v158, 16, v70
	v_and_b32_e32 v159, 0xffff0000, v70
	v_lshlrev_b32_e32 v160, 16, v74
	v_and_b32_e32 v161, 0xffff0000, v74
	v_pk_mul_f32 v[158:159], v[158:159], v[132:133]
	v_pk_mul_f32 v[160:161], v[160:161], v[140:141]
	v_pk_add_f32 v[158:159], v[158:159], v[156:157]
	v_pk_add_f32 v[158:159], v[158:159], v[160:161]
	v_cvt_pk_bf16_f32 v170, v158, v159
	v_lshlrev_b32_e32 v162, 16, v67
	v_and_b32_e32 v163, 0xffff0000, v67
	v_lshlrev_b32_e32 v164, 16, v71
	v_and_b32_e32 v165, 0xffff0000, v71
	v_lshlrev_b32_e32 v166, 16, v75
	v_and_b32_e32 v167, 0xffff0000, v75
	v_pk_mul_f32 v[164:165], v[164:165], v[134:135]
	v_pk_mul_f32 v[166:167], v[166:167], v[142:143]
	v_pk_add_f32 v[164:165], v[164:165], v[162:163]
	v_pk_add_f32 v[164:165], v[164:165], v[166:167]
	v_cvt_pk_bf16_f32 v171, v164, v165
	global_store_dwordx4 v76, v[168:171], s[98:99] offset:2560 sc1
	v_mul_u32_u24_e32 v61, 0xcccd, v60
	v_lshrrev_b32_e32 v62, 23, v61
	v_mul_u32_u24_e32 v63, 0xa0, v62
	v_sub_u32_e32 v63, v60, v63
	v_mul_u32_u24_e32 v76, 0x3400, v62
	v_lshl_add_u32 v76, v63, 4, v76
	v_lshrrev_b32_e32 v77, 6, v62
	v_mul_u32_u24_e32 v77, 0x1400, v77
	v_lshl_add_u32 v77, v63, 5, v77
	v_lshlrev_b32_e32 v78, 4, v60
	global_load_dwordx4 v[68:71], v76, s[98:99]
	global_load_dwordx4 v[64:67], v76, s[98:99] offset:2560
	global_load_dwordx4 v[72:75], v78, s[100:101]
	v_add_u32_e32 v60, 0x200, v60
	ds_read_b128 v[128:131], v93
	ds_read_b128 v[132:135], v93 offset:16
	ds_read_b128 v[136:139], v93 offset:20480
	ds_read_b128 v[140:143], v93 offset:20496
	s_waitcnt vmcnt(10)
	s_waitcnt lgkmcnt(0)
	v_lshlrev_b32_e32 v144, 16, v80
	v_and_b32_e32 v145, 0xffff0000, v80
	v_lshlrev_b32_e32 v146, 16, v84
	v_and_b32_e32 v147, 0xffff0000, v84
	v_lshlrev_b32_e32 v148, 16, v88
	v_and_b32_e32 v149, 0xffff0000, v88
	v_pk_mul_f32 v[146:147], v[146:147], v[128:129]
	v_pk_mul_f32 v[148:149], v[148:149], v[136:137]
	v_pk_add_f32 v[146:147], v[146:147], v[144:145]
	v_pk_add_f32 v[146:147], v[146:147], v[148:149]
	v_cvt_pk_bf16_f32 v172, v146, v147
	v_lshlrev_b32_e32 v150, 16, v81
	v_and_b32_e32 v151, 0xffff0000, v81
	v_lshlrev_b32_e32 v152, 16, v85
	v_and_b32_e32 v153, 0xffff0000, v85
	v_lshlrev_b32_e32 v154, 16, v89
	v_and_b32_e32 v155, 0xffff0000, v89
	v_pk_mul_f32 v[152:153], v[152:153], v[130:131]
	v_pk_mul_f32 v[154:155], v[154:155], v[138:139]
	v_pk_add_f32 v[152:153], v[152:153], v[150:151]
	v_pk_add_f32 v[152:153], v[152:153], v[154:155]
	v_cvt_pk_bf16_f32 v173, v152, v153
	v_lshlrev_b32_e32 v156, 16, v82
	v_and_b32_e32 v157, 0xffff0000, v82
	v_lshlrev_b32_e32 v158, 16, v86
	v_and_b32_e32 v159, 0xffff0000, v86
	v_lshlrev_b32_e32 v160, 16, v90
	v_and_b32_e32 v161, 0xffff0000, v90
	v_pk_mul_f32 v[158:159], v[158:159], v[132:133]
	v_pk_mul_f32 v[160:161], v[160:161], v[140:141]
	v_pk_add_f32 v[158:159], v[158:159], v[156:157]
	v_pk_add_f32 v[158:159], v[158:159], v[160:161]
	v_cvt_pk_bf16_f32 v174, v158, v159
	v_lshlrev_b32_e32 v162, 16, v83
	v_and_b32_e32 v163, 0xffff0000, v83
	v_lshlrev_b32_e32 v164, 16, v87
	v_and_b32_e32 v165, 0xffff0000, v87
	v_lshlrev_b32_e32 v166, 16, v91
	v_and_b32_e32 v167, 0xffff0000, v91
	v_pk_mul_f32 v[164:165], v[164:165], v[134:135]
	v_pk_mul_f32 v[166:167], v[166:167], v[142:143]
	v_pk_add_f32 v[164:165], v[164:165], v[162:163]
	v_pk_add_f32 v[164:165], v[164:165], v[166:167]
	v_cvt_pk_bf16_f32 v175, v164, v165
	global_store_dwordx4 v92, v[172:175], s[98:99] offset:2560 sc1
	v_mul_u32_u24_e32 v61, 0xcccd, v60
	v_lshrrev_b32_e32 v62, 23, v61
	v_mul_u32_u24_e32 v63, 0xa0, v62
	v_sub_u32_e32 v63, v60, v63
	v_mul_u32_u24_e32 v92, 0x3400, v62
	v_lshl_add_u32 v92, v63, 4, v92
	v_lshrrev_b32_e32 v93, 6, v62
	v_mul_u32_u24_e32 v93, 0x1400, v93
	v_lshl_add_u32 v93, v63, 5, v93
	v_lshlrev_b32_e32 v94, 4, v60
	global_load_dwordx4 v[84:87], v92, s[98:99]
	global_load_dwordx4 v[80:83], v92, s[98:99] offset:2560
	global_load_dwordx4 v[88:91], v94, s[100:101]
	v_add_u32_e32 v60, 0x200, v60
	ds_read_b128 v[128:131], v109
	ds_read_b128 v[132:135], v109 offset:16
	ds_read_b128 v[136:139], v109 offset:20480
	ds_read_b128 v[140:143], v109 offset:20496
	s_waitcnt vmcnt(11)
	s_waitcnt lgkmcnt(0)
	v_lshlrev_b32_e32 v144, 16, v96
	v_and_b32_e32 v145, 0xffff0000, v96
	v_lshlrev_b32_e32 v146, 16, v100
	v_and_b32_e32 v147, 0xffff0000, v100
	v_lshlrev_b32_e32 v148, 16, v104
	v_and_b32_e32 v149, 0xffff0000, v104
	v_pk_mul_f32 v[146:147], v[146:147], v[128:129]
	v_pk_mul_f32 v[148:149], v[148:149], v[136:137]
	v_pk_add_f32 v[146:147], v[146:147], v[144:145]
	v_pk_add_f32 v[146:147], v[146:147], v[148:149]
	v_cvt_pk_bf16_f32 v168, v146, v147
	v_lshlrev_b32_e32 v150, 16, v97
	v_and_b32_e32 v151, 0xffff0000, v97
	v_lshlrev_b32_e32 v152, 16, v101
	v_and_b32_e32 v153, 0xffff0000, v101
	v_lshlrev_b32_e32 v154, 16, v105
	v_and_b32_e32 v155, 0xffff0000, v105
	v_pk_mul_f32 v[152:153], v[152:153], v[130:131]
	v_pk_mul_f32 v[154:155], v[154:155], v[138:139]
	v_pk_add_f32 v[152:153], v[152:153], v[150:151]
	v_pk_add_f32 v[152:153], v[152:153], v[154:155]
	v_cvt_pk_bf16_f32 v169, v152, v153
	v_lshlrev_b32_e32 v156, 16, v98
	v_and_b32_e32 v157, 0xffff0000, v98
	v_lshlrev_b32_e32 v158, 16, v102
	v_and_b32_e32 v159, 0xffff0000, v102
	v_lshlrev_b32_e32 v160, 16, v106
	v_and_b32_e32 v161, 0xffff0000, v106
	v_pk_mul_f32 v[158:159], v[158:159], v[132:133]
	v_pk_mul_f32 v[160:161], v[160:161], v[140:141]
	v_pk_add_f32 v[158:159], v[158:159], v[156:157]
	v_pk_add_f32 v[158:159], v[158:159], v[160:161]
	v_cvt_pk_bf16_f32 v170, v158, v159
	v_lshlrev_b32_e32 v162, 16, v99
	v_and_b32_e32 v163, 0xffff0000, v99
	v_lshlrev_b32_e32 v164, 16, v103
	v_and_b32_e32 v165, 0xffff0000, v103
	v_lshlrev_b32_e32 v166, 16, v107
	v_and_b32_e32 v167, 0xffff0000, v107
	v_pk_mul_f32 v[164:165], v[164:165], v[134:135]
	v_pk_mul_f32 v[166:167], v[166:167], v[142:143]
	v_pk_add_f32 v[164:165], v[164:165], v[162:163]
	v_pk_add_f32 v[164:165], v[164:165], v[166:167]
	v_cvt_pk_bf16_f32 v171, v164, v165
	global_store_dwordx4 v108, v[168:171], s[98:99] offset:2560 sc1
	v_mul_u32_u24_e32 v61, 0xcccd, v60
	v_lshrrev_b32_e32 v62, 23, v61
	v_mul_u32_u24_e32 v63, 0xa0, v62
	v_sub_u32_e32 v63, v60, v63
	v_mul_u32_u24_e32 v108, 0x3400, v62
	v_lshl_add_u32 v108, v63, 4, v108
	v_lshrrev_b32_e32 v109, 6, v62
	v_mul_u32_u24_e32 v109, 0x1400, v109
	v_lshl_add_u32 v109, v63, 5, v109
	v_lshlrev_b32_e32 v110, 4, v60
	global_load_dwordx4 v[100:103], v108, s[98:99]
	global_load_dwordx4 v[96:99], v108, s[98:99] offset:2560
	global_load_dwordx4 v[104:107], v110, s[100:101]
	v_add_u32_e32 v60, 0x200, v60
	ds_read_b128 v[128:131], v125
	ds_read_b128 v[132:135], v125 offset:16
	ds_read_b128 v[136:139], v125 offset:20480
	ds_read_b128 v[140:143], v125 offset:20496
	s_waitcnt vmcnt(12)
	s_waitcnt lgkmcnt(0)
	v_lshlrev_b32_e32 v144, 16, v112
	v_and_b32_e32 v145, 0xffff0000, v112
	v_lshlrev_b32_e32 v146, 16, v116
	v_and_b32_e32 v147, 0xffff0000, v116
	v_lshlrev_b32_e32 v148, 16, v120
	v_and_b32_e32 v149, 0xffff0000, v120
	v_pk_mul_f32 v[146:147], v[146:147], v[128:129]
	v_pk_mul_f32 v[148:149], v[148:149], v[136:137]
	v_pk_add_f32 v[146:147], v[146:147], v[144:145]
	v_pk_add_f32 v[146:147], v[146:147], v[148:149]
	v_cvt_pk_bf16_f32 v172, v146, v147
	v_lshlrev_b32_e32 v150, 16, v113
	v_and_b32_e32 v151, 0xffff0000, v113
	v_lshlrev_b32_e32 v152, 16, v117
	v_and_b32_e32 v153, 0xffff0000, v117
	v_lshlrev_b32_e32 v154, 16, v121
	v_and_b32_e32 v155, 0xffff0000, v121
	v_pk_mul_f32 v[152:153], v[152:153], v[130:131]
	v_pk_mul_f32 v[154:155], v[154:155], v[138:139]
	v_pk_add_f32 v[152:153], v[152:153], v[150:151]
	v_pk_add_f32 v[152:153], v[152:153], v[154:155]
	v_cvt_pk_bf16_f32 v173, v152, v153
	v_lshlrev_b32_e32 v156, 16, v114
	v_and_b32_e32 v157, 0xffff0000, v114
	v_lshlrev_b32_e32 v158, 16, v118
	v_and_b32_e32 v159, 0xffff0000, v118
	v_lshlrev_b32_e32 v160, 16, v122
	v_and_b32_e32 v161, 0xffff0000, v122
	v_pk_mul_f32 v[158:159], v[158:159], v[132:133]
	v_pk_mul_f32 v[160:161], v[160:161], v[140:141]
	v_pk_add_f32 v[158:159], v[158:159], v[156:157]
	v_pk_add_f32 v[158:159], v[158:159], v[160:161]
	v_cvt_pk_bf16_f32 v174, v158, v159
	v_lshlrev_b32_e32 v162, 16, v115
	v_and_b32_e32 v163, 0xffff0000, v115
	v_lshlrev_b32_e32 v164, 16, v119
	v_and_b32_e32 v165, 0xffff0000, v119
	v_lshlrev_b32_e32 v166, 16, v123
	v_and_b32_e32 v167, 0xffff0000, v123
	v_pk_mul_f32 v[164:165], v[164:165], v[134:135]
	v_pk_mul_f32 v[166:167], v[166:167], v[142:143]
	v_pk_add_f32 v[164:165], v[164:165], v[162:163]
	v_pk_add_f32 v[164:165], v[164:165], v[166:167]
	v_cvt_pk_bf16_f32 v175, v164, v165
	global_store_dwordx4 v124, v[172:175], s[98:99] offset:2560 sc1
	v_mul_u32_u24_e32 v61, 0xcccd, v60
	v_lshrrev_b32_e32 v62, 23, v61
	v_mul_u32_u24_e32 v63, 0xa0, v62
	v_sub_u32_e32 v63, v60, v63
	v_mul_u32_u24_e32 v124, 0x3400, v62
	v_lshl_add_u32 v124, v63, 4, v124
	v_lshrrev_b32_e32 v125, 6, v62
	v_mul_u32_u24_e32 v125, 0x1400, v125
	v_lshl_add_u32 v125, v63, 5, v125
	v_lshlrev_b32_e32 v126, 4, v60
	global_load_dwordx4 v[116:119], v124, s[98:99]
	global_load_dwordx4 v[112:115], v124, s[98:99] offset:2560
	global_load_dwordx4 v[120:123], v126, s[100:101]
	v_add_u32_e32 v60, 0x200, v60
	s_mov_b32 s71, 18
.Lcf_loop:
	ds_read_b128 v[128:131], v77
	ds_read_b128 v[132:135], v77 offset:16
	ds_read_b128 v[136:139], v77 offset:20480
	ds_read_b128 v[140:143], v77 offset:20496
	s_waitcnt vmcnt(12)
	s_waitcnt lgkmcnt(0)
	v_lshlrev_b32_e32 v144, 16, v64
	v_and_b32_e32 v145, 0xffff0000, v64
	v_lshlrev_b32_e32 v146, 16, v68
	v_and_b32_e32 v147, 0xffff0000, v68
	v_lshlrev_b32_e32 v148, 16, v72
	v_and_b32_e32 v149, 0xffff0000, v72
	v_pk_mul_f32 v[146:147], v[146:147], v[128:129]
	v_pk_mul_f32 v[148:149], v[148:149], v[136:137]
	v_pk_add_f32 v[146:147], v[146:147], v[144:145]
	v_pk_add_f32 v[146:147], v[146:147], v[148:149]
	v_cvt_pk_bf16_f32 v168, v146, v147
	v_lshlrev_b32_e32 v150, 16, v65
	v_and_b32_e32 v151, 0xffff0000, v65
	v_lshlrev_b32_e32 v152, 16, v69
	v_and_b32_e32 v153, 0xffff0000, v69
	v_lshlrev_b32_e32 v154, 16, v73
	v_and_b32_e32 v155, 0xffff0000, v73
	v_pk_mul_f32 v[152:153], v[152:153], v[130:131]
	v_pk_mul_f32 v[154:155], v[154:155], v[138:139]
	v_pk_add_f32 v[152:153], v[152:153], v[150:151]
	v_pk_add_f32 v[152:153], v[152:153], v[154:155]
	v_cvt_pk_bf16_f32 v169, v152, v153
	v_lshlrev_b32_e32 v156, 16, v66
	v_and_b32_e32 v157, 0xffff0000, v66
	v_lshlrev_b32_e32 v158, 16, v70
	v_and_b32_e32 v159, 0xffff0000, v70
	v_lshlrev_b32_e32 v160, 16, v74
	v_and_b32_e32 v161, 0xffff0000, v74
	v_pk_mul_f32 v[158:159], v[158:159], v[132:133]
	v_pk_mul_f32 v[160:161], v[160:161], v[140:141]
	v_pk_add_f32 v[158:159], v[158:159], v[156:157]
	v_pk_add_f32 v[158:159], v[158:159], v[160:161]
	v_cvt_pk_bf16_f32 v170, v158, v159
	v_lshlrev_b32_e32 v162, 16, v67
	v_and_b32_e32 v163, 0xffff0000, v67
	v_lshlrev_b32_e32 v164, 16, v71
	v_and_b32_e32 v165, 0xffff0000, v71
	v_lshlrev_b32_e32 v166, 16, v75
	v_and_b32_e32 v167, 0xffff0000, v75
	v_pk_mul_f32 v[164:165], v[164:165], v[134:135]
	v_pk_mul_f32 v[166:167], v[166:167], v[142:143]
	v_pk_add_f32 v[164:165], v[164:165], v[162:163]
	v_pk_add_f32 v[164:165], v[164:165], v[166:167]
	v_cvt_pk_bf16_f32 v171, v164, v165
	global_store_dwordx4 v76, v[168:171], s[98:99] offset:2560 sc1
	v_mul_u32_u24_e32 v61, 0xcccd, v60
	v_lshrrev_b32_e32 v62, 23, v61
	v_mul_u32_u24_e32 v63, 0xa0, v62
	v_sub_u32_e32 v63, v60, v63
	v_mul_u32_u24_e32 v76, 0x3400, v62
	v_lshl_add_u32 v76, v63, 4, v76
	v_lshrrev_b32_e32 v77, 6, v62
	v_mul_u32_u24_e32 v77, 0x1400, v77
	v_lshl_add_u32 v77, v63, 5, v77
	v_lshlrev_b32_e32 v78, 4, v60
	global_load_dwordx4 v[68:71], v76, s[98:99]
	global_load_dwordx4 v[64:67], v76, s[98:99] offset:2560
	global_load_dwordx4 v[72:75], v78, s[100:101]
	v_add_u32_e32 v60, 0x200, v60
	ds_read_b128 v[128:131], v93
	ds_read_b128 v[132:135], v93 offset:16
	ds_read_b128 v[136:139], v93 offset:20480
	ds_read_b128 v[140:143], v93 offset:20496
	s_waitcnt vmcnt(12)
	s_waitcnt lgkmcnt(0)
	v_lshlrev_b32_e32 v144, 16, v80
	v_and_b32_e32 v145, 0xffff0000, v80
	v_lshlrev_b32_e32 v146, 16, v84
	v_and_b32_e32 v147, 0xffff0000, v84
	v_lshlrev_b32_e32 v148, 16, v88
	v_and_b32_e32 v149, 0xffff0000, v88
	v_pk_mul_f32 v[146:147], v[146:147], v[128:129]
	v_pk_mul_f32 v[148:149], v[148:149], v[136:137]
	v_pk_add_f32 v[146:147], v[146:147], v[144:145]
	v_pk_add_f32 v[146:147], v[146:147], v[148:149]
	v_cvt_pk_bf16_f32 v172, v146, v147
	v_lshlrev_b32_e32 v150, 16, v81
	v_and_b32_e32 v151, 0xffff0000, v81
	v_lshlrev_b32_e32 v152, 16, v85
	v_and_b32_e32 v153, 0xffff0000, v85
	v_lshlrev_b32_e32 v154, 16, v89
	v_and_b32_e32 v155, 0xffff0000, v89
	v_pk_mul_f32 v[152:153], v[152:153], v[130:131]
	v_pk_mul_f32 v[154:155], v[154:155], v[138:139]
	v_pk_add_f32 v[152:153], v[152:153], v[150:151]
	v_pk_add_f32 v[152:153], v[152:153], v[154:155]
	v_cvt_pk_bf16_f32 v173, v152, v153
	v_lshlrev_b32_e32 v156, 16, v82
	v_and_b32_e32 v157, 0xffff0000, v82
	v_lshlrev_b32_e32 v158, 16, v86
	v_and_b32_e32 v159, 0xffff0000, v86
	v_lshlrev_b32_e32 v160, 16, v90
	v_and_b32_e32 v161, 0xffff0000, v90
	v_pk_mul_f32 v[158:159], v[158:159], v[132:133]
	v_pk_mul_f32 v[160:161], v[160:161], v[140:141]
	v_pk_add_f32 v[158:159], v[158:159], v[156:157]
	v_pk_add_f32 v[158:159], v[158:159], v[160:161]
	v_cvt_pk_bf16_f32 v174, v158, v159
	v_lshlrev_b32_e32 v162, 16, v83
	v_and_b32_e32 v163, 0xffff0000, v83
	v_lshlrev_b32_e32 v164, 16, v87
	v_and_b32_e32 v165, 0xffff0000, v87
	v_lshlrev_b32_e32 v166, 16, v91
	v_and_b32_e32 v167, 0xffff0000, v91
	v_pk_mul_f32 v[164:165], v[164:165], v[134:135]
	v_pk_mul_f32 v[166:167], v[166:167], v[142:143]
	v_pk_add_f32 v[164:165], v[164:165], v[162:163]
	v_pk_add_f32 v[164:165], v[164:165], v[166:167]
	v_cvt_pk_bf16_f32 v175, v164, v165
	global_store_dwordx4 v92, v[172:175], s[98:99] offset:2560 sc1
	v_mul_u32_u24_e32 v61, 0xcccd, v60
	v_lshrrev_b32_e32 v62, 23, v61
	v_mul_u32_u24_e32 v63, 0xa0, v62
	v_sub_u32_e32 v63, v60, v63
	v_mul_u32_u24_e32 v92, 0x3400, v62
	v_lshl_add_u32 v92, v63, 4, v92
	v_lshrrev_b32_e32 v93, 6, v62
	v_mul_u32_u24_e32 v93, 0x1400, v93
	v_lshl_add_u32 v93, v63, 5, v93
	v_lshlrev_b32_e32 v94, 4, v60
	global_load_dwordx4 v[84:87], v92, s[98:99]
	global_load_dwordx4 v[80:83], v92, s[98:99] offset:2560
	global_load_dwordx4 v[88:91], v94, s[100:101]
	v_add_u32_e32 v60, 0x200, v60
	ds_read_b128 v[128:131], v109
	ds_read_b128 v[132:135], v109 offset:16
	ds_read_b128 v[136:139], v109 offset:20480
	ds_read_b128 v[140:143], v109 offset:20496
	s_waitcnt vmcnt(12)
	s_waitcnt lgkmcnt(0)
	v_lshlrev_b32_e32 v144, 16, v96
	v_and_b32_e32 v145, 0xffff0000, v96
	v_lshlrev_b32_e32 v146, 16, v100
	v_and_b32_e32 v147, 0xffff0000, v100
	v_lshlrev_b32_e32 v148, 16, v104
	v_and_b32_e32 v149, 0xffff0000, v104
	v_pk_mul_f32 v[146:147], v[146:147], v[128:129]
	v_pk_mul_f32 v[148:149], v[148:149], v[136:137]
	v_pk_add_f32 v[146:147], v[146:147], v[144:145]
	v_pk_add_f32 v[146:147], v[146:147], v[148:149]
	v_cvt_pk_bf16_f32 v168, v146, v147
	v_lshlrev_b32_e32 v150, 16, v97
	v_and_b32_e32 v151, 0xffff0000, v97
	v_lshlrev_b32_e32 v152, 16, v101
	v_and_b32_e32 v153, 0xffff0000, v101
	v_lshlrev_b32_e32 v154, 16, v105
	v_and_b32_e32 v155, 0xffff0000, v105
	v_pk_mul_f32 v[152:153], v[152:153], v[130:131]
	v_pk_mul_f32 v[154:155], v[154:155], v[138:139]
	v_pk_add_f32 v[152:153], v[152:153], v[150:151]
	v_pk_add_f32 v[152:153], v[152:153], v[154:155]
	v_cvt_pk_bf16_f32 v169, v152, v153
	v_lshlrev_b32_e32 v156, 16, v98
	v_and_b32_e32 v157, 0xffff0000, v98
	v_lshlrev_b32_e32 v158, 16, v102
	v_and_b32_e32 v159, 0xffff0000, v102
	v_lshlrev_b32_e32 v160, 16, v106
	v_and_b32_e32 v161, 0xffff0000, v106
	v_pk_mul_f32 v[158:159], v[158:159], v[132:133]
	v_pk_mul_f32 v[160:161], v[160:161], v[140:141]
	v_pk_add_f32 v[158:159], v[158:159], v[156:157]
	v_pk_add_f32 v[158:159], v[158:159], v[160:161]
	v_cvt_pk_bf16_f32 v170, v158, v159
	v_lshlrev_b32_e32 v162, 16, v99
	v_and_b32_e32 v163, 0xffff0000, v99
	v_lshlrev_b32_e32 v164, 16, v103
	v_and_b32_e32 v165, 0xffff0000, v103
	v_lshlrev_b32_e32 v166, 16, v107
	v_and_b32_e32 v167, 0xffff0000, v107
	v_pk_mul_f32 v[164:165], v[164:165], v[134:135]
	v_pk_mul_f32 v[166:167], v[166:167], v[142:143]
	v_pk_add_f32 v[164:165], v[164:165], v[162:163]
	v_pk_add_f32 v[164:165], v[164:165], v[166:167]
	v_cvt_pk_bf16_f32 v171, v164, v165
	global_store_dwordx4 v108, v[168:171], s[98:99] offset:2560 sc1
	v_mul_u32_u24_e32 v61, 0xcccd, v60
	v_lshrrev_b32_e32 v62, 23, v61
	v_mul_u32_u24_e32 v63, 0xa0, v62
	v_sub_u32_e32 v63, v60, v63
	v_mul_u32_u24_e32 v108, 0x3400, v62
	v_lshl_add_u32 v108, v63, 4, v108
	v_lshrrev_b32_e32 v109, 6, v62
	v_mul_u32_u24_e32 v109, 0x1400, v109
	v_lshl_add_u32 v109, v63, 5, v109
	v_lshlrev_b32_e32 v110, 4, v60
	global_load_dwordx4 v[100:103], v108, s[98:99]
	global_load_dwordx4 v[96:99], v108, s[98:99] offset:2560
	global_load_dwordx4 v[104:107], v110, s[100:101]
	v_add_u32_e32 v60, 0x200, v60
	ds_read_b128 v[128:131], v125
	ds_read_b128 v[132:135], v125 offset:16
	ds_read_b128 v[136:139], v125 offset:20480
	ds_read_b128 v[140:143], v125 offset:20496
	s_waitcnt vmcnt(12)
	s_waitcnt lgkmcnt(0)
	v_lshlrev_b32_e32 v144, 16, v112
	v_and_b32_e32 v145, 0xffff0000, v112
	v_lshlrev_b32_e32 v146, 16, v116
	v_and_b32_e32 v147, 0xffff0000, v116
	v_lshlrev_b32_e32 v148, 16, v120
	v_and_b32_e32 v149, 0xffff0000, v120
	v_pk_mul_f32 v[146:147], v[146:147], v[128:129]
	v_pk_mul_f32 v[148:149], v[148:149], v[136:137]
	v_pk_add_f32 v[146:147], v[146:147], v[144:145]
	v_pk_add_f32 v[146:147], v[146:147], v[148:149]
	v_cvt_pk_bf16_f32 v172, v146, v147
	v_lshlrev_b32_e32 v150, 16, v113
	v_and_b32_e32 v151, 0xffff0000, v113
	v_lshlrev_b32_e32 v152, 16, v117
	v_and_b32_e32 v153, 0xffff0000, v117
	v_lshlrev_b32_e32 v154, 16, v121
	v_and_b32_e32 v155, 0xffff0000, v121
	v_pk_mul_f32 v[152:153], v[152:153], v[130:131]
	v_pk_mul_f32 v[154:155], v[154:155], v[138:139]
	v_pk_add_f32 v[152:153], v[152:153], v[150:151]
	v_pk_add_f32 v[152:153], v[152:153], v[154:155]
	v_cvt_pk_bf16_f32 v173, v152, v153
	v_lshlrev_b32_e32 v156, 16, v114
	v_and_b32_e32 v157, 0xffff0000, v114
	v_lshlrev_b32_e32 v158, 16, v118
	v_and_b32_e32 v159, 0xffff0000, v118
	v_lshlrev_b32_e32 v160, 16, v122
	v_and_b32_e32 v161, 0xffff0000, v122
	v_pk_mul_f32 v[158:159], v[158:159], v[132:133]
	v_pk_mul_f32 v[160:161], v[160:161], v[140:141]
	v_pk_add_f32 v[158:159], v[158:159], v[156:157]
	v_pk_add_f32 v[158:159], v[158:159], v[160:161]
	v_cvt_pk_bf16_f32 v174, v158, v159
	v_lshlrev_b32_e32 v162, 16, v115
	v_and_b32_e32 v163, 0xffff0000, v115
	v_lshlrev_b32_e32 v164, 16, v119
	v_and_b32_e32 v165, 0xffff0000, v119
	v_lshlrev_b32_e32 v166, 16, v123
	v_and_b32_e32 v167, 0xffff0000, v123
	v_pk_mul_f32 v[164:165], v[164:165], v[134:135]
	v_pk_mul_f32 v[166:167], v[166:167], v[142:143]
	v_pk_add_f32 v[164:165], v[164:165], v[162:163]
	v_pk_add_f32 v[164:165], v[164:165], v[166:167]
	v_cvt_pk_bf16_f32 v175, v164, v165
	global_store_dwordx4 v124, v[172:175], s[98:99] offset:2560 sc1
	v_mul_u32_u24_e32 v61, 0xcccd, v60
	v_lshrrev_b32_e32 v62, 23, v61
	v_mul_u32_u24_e32 v63, 0xa0, v62
	v_sub_u32_e32 v63, v60, v63
	v_mul_u32_u24_e32 v124, 0x3400, v62
	v_lshl_add_u32 v124, v63, 4, v124
	v_lshrrev_b32_e32 v125, 6, v62
	v_mul_u32_u24_e32 v125, 0x1400, v125
	v_lshl_add_u32 v125, v63, 5, v125
	v_lshlrev_b32_e32 v126, 4, v60
	global_load_dwordx4 v[116:119], v124, s[98:99]
	global_load_dwordx4 v[112:115], v124, s[98:99] offset:2560
	global_load_dwordx4 v[120:123], v126, s[100:101]
	v_add_u32_e32 v60, 0x200, v60
	s_sub_u32 s71, s71, 1
	s_cmp_lg_u32 s71, 0
	s_cbranch_scc1 .Lcf_loop
	ds_read_b128 v[128:131], v77
	ds_read_b128 v[132:135], v77 offset:16
	ds_read_b128 v[136:139], v77 offset:20480
	ds_read_b128 v[140:143], v77 offset:20496
	s_waitcnt vmcnt(12)
	s_waitcnt lgkmcnt(0)
	v_lshlrev_b32_e32 v144, 16, v64
	v_and_b32_e32 v145, 0xffff0000, v64
	v_lshlrev_b32_e32 v146, 16, v68
	v_and_b32_e32 v147, 0xffff0000, v68
	v_lshlrev_b32_e32 v148, 16, v72
	v_and_b32_e32 v149, 0xffff0000, v72
	v_pk_mul_f32 v[146:147], v[146:147], v[128:129]
	v_pk_mul_f32 v[148:149], v[148:149], v[136:137]
	v_pk_add_f32 v[146:147], v[146:147], v[144:145]
	v_pk_add_f32 v[146:147], v[146:147], v[148:149]
	v_cvt_pk_bf16_f32 v168, v146, v147
	v_lshlrev_b32_e32 v150, 16, v65
	v_and_b32_e32 v151, 0xffff0000, v65
	v_lshlrev_b32_e32 v152, 16, v69
	v_and_b32_e32 v153, 0xffff0000, v69
	v_lshlrev_b32_e32 v154, 16, v73
	v_and_b32_e32 v155, 0xffff0000, v73
	v_pk_mul_f32 v[152:153], v[152:153], v[130:131]
	v_pk_mul_f32 v[154:155], v[154:155], v[138:139]
	v_pk_add_f32 v[152:153], v[152:153], v[150:151]
	v_pk_add_f32 v[152:153], v[152:153], v[154:155]
	v_cvt_pk_bf16_f32 v169, v152, v153
	v_lshlrev_b32_e32 v156, 16, v66
	v_and_b32_e32 v157, 0xffff0000, v66
	v_lshlrev_b32_e32 v158, 16, v70
	v_and_b32_e32 v159, 0xffff0000, v70
	v_lshlrev_b32_e32 v160, 16, v74
	v_and_b32_e32 v161, 0xffff0000, v74
	v_pk_mul_f32 v[158:159], v[158:159], v[132:133]
	v_pk_mul_f32 v[160:161], v[160:161], v[140:141]
	v_pk_add_f32 v[158:159], v[158:159], v[156:157]
	v_pk_add_f32 v[158:159], v[158:159], v[160:161]
	v_cvt_pk_bf16_f32 v170, v158, v159
	v_lshlrev_b32_e32 v162, 16, v67
	v_and_b32_e32 v163, 0xffff0000, v67
	v_lshlrev_b32_e32 v164, 16, v71
	v_and_b32_e32 v165, 0xffff0000, v71
	v_lshlrev_b32_e32 v166, 16, v75
	v_and_b32_e32 v167, 0xffff0000, v75
	v_pk_mul_f32 v[164:165], v[164:165], v[134:135]
	v_pk_mul_f32 v[166:167], v[166:167], v[142:143]
	v_pk_add_f32 v[164:165], v[164:165], v[162:163]
	v_pk_add_f32 v[164:165], v[164:165], v[166:167]
	v_cvt_pk_bf16_f32 v171, v164, v165
	global_store_dwordx4 v76, v[168:171], s[98:99] offset:2560 sc1
	ds_read_b128 v[128:131], v93
	ds_read_b128 v[132:135], v93 offset:16
	ds_read_b128 v[136:139], v93 offset:20480
	ds_read_b128 v[140:143], v93 offset:20496
	s_waitcnt vmcnt(9)
	s_waitcnt lgkmcnt(0)
	v_lshlrev_b32_e32 v144, 16, v80
	v_and_b32_e32 v145, 0xffff0000, v80
	v_lshlrev_b32_e32 v146, 16, v84
	v_and_b32_e32 v147, 0xffff0000, v84
	v_lshlrev_b32_e32 v148, 16, v88
	v_and_b32_e32 v149, 0xffff0000, v88
	v_pk_mul_f32 v[146:147], v[146:147], v[128:129]
	v_pk_mul_f32 v[148:149], v[148:149], v[136:137]
	v_pk_add_f32 v[146:147], v[146:147], v[144:145]
	v_pk_add_f32 v[146:147], v[146:147], v[148:149]
	v_cvt_pk_bf16_f32 v172, v146, v147
	v_lshlrev_b32_e32 v150, 16, v81
	v_and_b32_e32 v151, 0xffff0000, v81
	v_lshlrev_b32_e32 v152, 16, v85
	v_and_b32_e32 v153, 0xffff0000, v85
	v_lshlrev_b32_e32 v154, 16, v89
	v_and_b32_e32 v155, 0xffff0000, v89
	v_pk_mul_f32 v[152:153], v[152:153], v[130:131]
	v_pk_mul_f32 v[154:155], v[154:155], v[138:139]
	v_pk_add_f32 v[152:153], v[152:153], v[150:151]
	v_pk_add_f32 v[152:153], v[152:153], v[154:155]
	v_cvt_pk_bf16_f32 v173, v152, v153
	v_lshlrev_b32_e32 v156, 16, v82
	v_and_b32_e32 v157, 0xffff0000, v82
	v_lshlrev_b32_e32 v158, 16, v86
	v_and_b32_e32 v159, 0xffff0000, v86
	v_lshlrev_b32_e32 v160, 16, v90
	v_and_b32_e32 v161, 0xffff0000, v90
	v_pk_mul_f32 v[158:159], v[158:159], v[132:133]
	v_pk_mul_f32 v[160:161], v[160:161], v[140:141]
	v_pk_add_f32 v[158:159], v[158:159], v[156:157]
	v_pk_add_f32 v[158:159], v[158:159], v[160:161]
	v_cvt_pk_bf16_f32 v174, v158, v159
	v_lshlrev_b32_e32 v162, 16, v83
	v_and_b32_e32 v163, 0xffff0000, v83
	v_lshlrev_b32_e32 v164, 16, v87
	v_and_b32_e32 v165, 0xffff0000, v87
	v_lshlrev_b32_e32 v166, 16, v91
	v_and_b32_e32 v167, 0xffff0000, v91
	v_pk_mul_f32 v[164:165], v[164:165], v[134:135]
	v_pk_mul_f32 v[166:167], v[166:167], v[142:143]
	v_pk_add_f32 v[164:165], v[164:165], v[162:163]
	v_pk_add_f32 v[164:165], v[164:165], v[166:167]
	v_cvt_pk_bf16_f32 v175, v164, v165
	global_store_dwordx4 v92, v[172:175], s[98:99] offset:2560 sc1
	ds_read_b128 v[128:131], v109
	ds_read_b128 v[132:135], v109 offset:16
	ds_read_b128 v[136:139], v109 offset:20480
	ds_read_b128 v[140:143], v109 offset:20496
	s_waitcnt vmcnt(6)
	s_waitcnt lgkmcnt(0)
	v_lshlrev_b32_e32 v144, 16, v96
	v_and_b32_e32 v145, 0xffff0000, v96
	v_lshlrev_b32_e32 v146, 16, v100
	v_and_b32_e32 v147, 0xffff0000, v100
	v_lshlrev_b32_e32 v148, 16, v104
	v_and_b32_e32 v149, 0xffff0000, v104
	v_pk_mul_f32 v[146:147], v[146:147], v[128:129]
	v_pk_mul_f32 v[148:149], v[148:149], v[136:137]
	v_pk_add_f32 v[146:147], v[146:147], v[144:145]
	v_pk_add_f32 v[146:147], v[146:147], v[148:149]
	v_cvt_pk_bf16_f32 v168, v146, v147
	v_lshlrev_b32_e32 v150, 16, v97
	v_and_b32_e32 v151, 0xffff0000, v97
	v_lshlrev_b32_e32 v152, 16, v101
	v_and_b32_e32 v153, 0xffff0000, v101
	v_lshlrev_b32_e32 v154, 16, v105
	v_and_b32_e32 v155, 0xffff0000, v105
	v_pk_mul_f32 v[152:153], v[152:153], v[130:131]
	v_pk_mul_f32 v[154:155], v[154:155], v[138:139]
	v_pk_add_f32 v[152:153], v[152:153], v[150:151]
	v_pk_add_f32 v[152:153], v[152:153], v[154:155]
	v_cvt_pk_bf16_f32 v169, v152, v153
	v_lshlrev_b32_e32 v156, 16, v98
	v_and_b32_e32 v157, 0xffff0000, v98
	v_lshlrev_b32_e32 v158, 16, v102
	v_and_b32_e32 v159, 0xffff0000, v102
	v_lshlrev_b32_e32 v160, 16, v106
	v_and_b32_e32 v161, 0xffff0000, v106
	v_pk_mul_f32 v[158:159], v[158:159], v[132:133]
	v_pk_mul_f32 v[160:161], v[160:161], v[140:141]
	v_pk_add_f32 v[158:159], v[158:159], v[156:157]
	v_pk_add_f32 v[158:159], v[158:159], v[160:161]
	v_cvt_pk_bf16_f32 v170, v158, v159
	v_lshlrev_b32_e32 v162, 16, v99
	v_and_b32_e32 v163, 0xffff0000, v99
	v_lshlrev_b32_e32 v164, 16, v103
	v_and_b32_e32 v165, 0xffff0000, v103
	v_lshlrev_b32_e32 v166, 16, v107
	v_and_b32_e32 v167, 0xffff0000, v107
	v_pk_mul_f32 v[164:165], v[164:165], v[134:135]
	v_pk_mul_f32 v[166:167], v[166:167], v[142:143]
	v_pk_add_f32 v[164:165], v[164:165], v[162:163]
	v_pk_add_f32 v[164:165], v[164:165], v[166:167]
	v_cvt_pk_bf16_f32 v171, v164, v165
	global_store_dwordx4 v108, v[168:171], s[98:99] offset:2560 sc1
	ds_read_b128 v[128:131], v125
	ds_read_b128 v[132:135], v125 offset:16
	ds_read_b128 v[136:139], v125 offset:20480
	ds_read_b128 v[140:143], v125 offset:20496
	s_waitcnt vmcnt(3)
	s_waitcnt lgkmcnt(0)
	v_lshlrev_b32_e32 v144, 16, v112
	v_and_b32_e32 v145, 0xffff0000, v112
	v_lshlrev_b32_e32 v146, 16, v116
	v_and_b32_e32 v147, 0xffff0000, v116
	v_lshlrev_b32_e32 v148, 16, v120
	v_and_b32_e32 v149, 0xffff0000, v120
	v_pk_mul_f32 v[146:147], v[146:147], v[128:129]
	v_pk_mul_f32 v[148:149], v[148:149], v[136:137]
	v_pk_add_f32 v[146:147], v[146:147], v[144:145]
	v_pk_add_f32 v[146:147], v[146:147], v[148:149]
	v_cvt_pk_bf16_f32 v172, v146, v147
	v_lshlrev_b32_e32 v150, 16, v113
	v_and_b32_e32 v151, 0xffff0000, v113
	v_lshlrev_b32_e32 v152, 16, v117
	v_and_b32_e32 v153, 0xffff0000, v117
	v_lshlrev_b32_e32 v154, 16, v121
	v_and_b32_e32 v155, 0xffff0000, v121
	v_pk_mul_f32 v[152:153], v[152:153], v[130:131]
	v_pk_mul_f32 v[154:155], v[154:155], v[138:139]
	v_pk_add_f32 v[152:153], v[152:153], v[150:151]
	v_pk_add_f32 v[152:153], v[152:153], v[154:155]
	v_cvt_pk_bf16_f32 v173, v152, v153
	v_lshlrev_b32_e32 v156, 16, v114
	v_and_b32_e32 v157, 0xffff0000, v114
	v_lshlrev_b32_e32 v158, 16, v118
	v_and_b32_e32 v159, 0xffff0000, v118
	v_lshlrev_b32_e32 v160, 16, v122
	v_and_b32_e32 v161, 0xffff0000, v122
	v_pk_mul_f32 v[158:159], v[158:159], v[132:133]
	v_pk_mul_f32 v[160:161], v[160:161], v[140:141]
	v_pk_add_f32 v[158:159], v[158:159], v[156:157]
	v_pk_add_f32 v[158:159], v[158:159], v[160:161]
	v_cvt_pk_bf16_f32 v174, v158, v159
	v_lshlrev_b32_e32 v162, 16, v115
	v_and_b32_e32 v163, 0xffff0000, v115
	v_lshlrev_b32_e32 v164, 16, v119
	v_and_b32_e32 v165, 0xffff0000, v119
	v_lshlrev_b32_e32 v166, 16, v123
	v_and_b32_e32 v167, 0xffff0000, v123
	v_pk_mul_f32 v[164:165], v[164:165], v[134:135]
	v_pk_mul_f32 v[166:167], v[166:167], v[142:143]
	v_pk_add_f32 v[164:165], v[164:165], v[162:163]
	v_pk_add_f32 v[164:165], v[164:165], v[166:167]
	v_cvt_pk_bf16_f32 v175, v164, v165
	global_store_dwordx4 v124, v[172:175], s[98:99] offset:2560 sc1
	s_add_i32 s22, s22, s38
	s_add_i32 s62, s62, 1
	s_add_i32 s61, s61, s52
	s_cmpk_gt_i32 s22, 0xff
	s_cbranch_scc0 .LBB0_500

.LBB0_600:
	s_waitcnt vmcnt(0) lgkmcnt(0)
	v_lshlrev_b32_e32 v214, 16, v192
	v_lshlrev_b32_e32 v230, 16, v194
	v_and_b32_e32 v215, 0xffff0000, v192
	v_max_f32_e32 v192, v214, v214
	v_max_f32_e32 v214, v230, v230
	v_max_f32_e32 v214, 0xc2700000, v214
	v_and_b32_e32 v231, 0xffff0000, v194
	v_mul_f32_e32 v214, 0xbfb8aa3b, v214
	v_exp_f32_e32 v230, v214
	v_max_f32_e32 v214, v231, v231
	v_max_f32_e32 v214, 0xc2700000, v214
	v_lshlrev_b32_e32 v232, 16, v195
	v_mul_f32_e32 v214, 0xbfb8aa3b, v214
	v_exp_f32_e32 v231, v214
	v_max_f32_e32 v214, v232, v232
	v_max_f32_e32 v214, 0xc2700000, v214
	v_lshlrev_b32_e32 v220, 16, v193
	v_and_b32_e32 v221, 0xffff0000, v193
	v_and_b32_e32 v233, 0xffff0000, v195
	v_max_f32_e32 v193, v215, v215
	v_mul_f32_e32 v214, 0xbfb8aa3b, v214
	v_max_f32_e32 v192, 0xc2700000, v192
	v_max_f32_e32 v193, 0xc2700000, v193
	v_max_f32_e32 v194, v220, v220
	v_max_f32_e32 v195, v221, v221
	v_exp_f32_e32 v232, v214
	v_max_f32_e32 v214, v233, v233
	v_mul_f32_e32 v192, 0xbfb8aa3b, v192
	v_mul_f32_e32 v193, 0xbfb8aa3b, v193
	v_max_f32_e32 v194, 0xc2700000, v194
	v_max_f32_e32 v195, 0xc2700000, v195
	v_max_f32_e32 v214, 0xc2700000, v214
	v_exp_f32_e32 v192, v192
	v_exp_f32_e32 v193, v193
	v_mul_f32_e32 v194, 0xbfb8aa3b, v194
	v_mul_f32_e32 v195, 0xbfb8aa3b, v195
	v_mul_f32_e32 v214, 0xbfb8aa3b, v214
	v_exp_f32_e32 v194, v194
	v_exp_f32_e32 v195, v195
	v_exp_f32_e32 v233, v214
	v_pk_add_f32 v[220:221], v[192:193], 1.0 op_sel_hi:[1,0]
	v_pk_add_f32 v[192:193], v[230:231], 1.0 op_sel_hi:[1,0]
	v_cndmask_b32_e64 v230, 0, 1, s[34:35]
	v_pk_add_f32 v[214:215], v[194:195], 1.0 op_sel_hi:[1,0]
	v_pk_add_f32 v[194:195], v[232:233], 1.0 op_sel_hi:[1,0]
	v_cmp_ne_u32_e64 s[8:9], 1, v230
	s_andn2_b64 vcc, exec, s[34:35]
	s_mov_b64 s[34:35], -1
	s_cbranch_vccnz .LBB0_602
	v_rcp_f32_e32 v230, v220
	v_rcp_f32_e32 v231, v221
	v_rcp_f32_e32 v232, v214
	v_rcp_f32_e32 v234, v192
	v_rcp_f32_e32 v235, v193
	v_rcp_f32_e32 v233, v215
	v_rcp_f32_e32 v236, v194
	v_rcp_f32_e32 v237, v195
	v_mul_f32_e32 v230, v128, v230
	v_mul_f32_e32 v231, v129, v231
	v_mul_f32_e32 v232, v130, v232
	v_mul_f32_e32 v234, v124, v234
	v_mul_f32_e32 v235, v125, v235
	v_mul_f32_e32 v233, v131, v233
	v_cvt_pk_bf16_f32 v230, v230, v231
	v_cvt_pk_bf16_f32 v231, v232, v233
	v_cvt_pk_bf16_f32 v232, v234, v235
	v_lshl_add_u64 v[234:235], v[2:3], 1, v[218:219]
	s_mov_b64 s[34:35], 0
	v_mul_f32_e32 v236, v126, v236
	v_mul_f32_e32 v237, v127, v237
	v_cvt_pk_bf16_f32 v233, v236, v237
	flat_store_dwordx4 v[234:235], v[230:233] sc1

.LBB0_604:
	v_lshlrev_b32_e32 v192, 16, v188
	v_lshlrev_b32_e32 v214, 16, v190
	v_and_b32_e32 v193, 0xffff0000, v188
	v_max_f32_e32 v188, v192, v192
	v_max_f32_e32 v192, v214, v214
	v_max_f32_e32 v192, 0xc2700000, v192
	v_and_b32_e32 v215, 0xffff0000, v190
	v_mul_f32_e32 v192, 0xbfb8aa3b, v192
	v_exp_f32_e32 v214, v192
	v_max_f32_e32 v192, v215, v215
	v_max_f32_e32 v192, 0xc2700000, v192
	v_lshlrev_b32_e32 v220, 16, v191
	v_mul_f32_e32 v192, 0xbfb8aa3b, v192
	v_exp_f32_e32 v215, v192
	v_max_f32_e32 v192, v220, v220
	v_max_f32_e32 v192, 0xc2700000, v192
	v_lshlrev_b32_e32 v194, 16, v189
	v_and_b32_e32 v195, 0xffff0000, v189
	v_and_b32_e32 v221, 0xffff0000, v191
	v_max_f32_e32 v189, v193, v193
	v_mul_f32_e32 v192, 0xbfb8aa3b, v192
	v_max_f32_e32 v188, 0xc2700000, v188
	v_max_f32_e32 v189, 0xc2700000, v189
	v_max_f32_e32 v190, v194, v194
	v_max_f32_e32 v191, v195, v195
	v_exp_f32_e32 v220, v192
	v_max_f32_e32 v192, v221, v221
	v_mul_f32_e32 v188, 0xbfb8aa3b, v188
	v_mul_f32_e32 v189, 0xbfb8aa3b, v189
	v_max_f32_e32 v190, 0xc2700000, v190
	v_max_f32_e32 v191, 0xc2700000, v191
	v_max_f32_e32 v192, 0xc2700000, v192
	v_exp_f32_e32 v188, v188
	v_exp_f32_e32 v189, v189
	v_mul_f32_e32 v190, 0xbfb8aa3b, v190
	v_mul_f32_e32 v191, 0xbfb8aa3b, v191
	v_mul_f32_e32 v192, 0xbfb8aa3b, v192
	v_exp_f32_e32 v190, v190
	v_exp_f32_e32 v191, v191
	v_exp_f32_e32 v221, v192
	v_add_u32_e32 v229, 0x80, v229
	v_pk_add_f32 v[194:195], v[188:189], 1.0 op_sel_hi:[1,0]
	v_pk_add_f32 v[188:189], v[214:215], 1.0 op_sel_hi:[1,0]
	v_add_u32_e32 v214, s64, v229
	v_pk_add_f32 v[192:193], v[190:191], 1.0 op_sel_hi:[1,0]
	v_pk_add_f32 v[190:191], v[220:221], 1.0 op_sel_hi:[1,0]
	s_mov_b64 s[34:35], -1
	s_and_b64 vcc, exec, s[8:9]
	v_ashrrev_i32_e32 v215, 31, v214
	s_cbranch_vccnz .LBB0_606
	v_rcp_f32_e32 v230, v193
	v_rcp_f32_e32 v232, v189
	v_rcp_f32_e32 v233, v190
	v_rcp_f32_e32 v220, v194
	v_rcp_f32_e32 v221, v195
	v_rcp_f32_e32 v229, v192
	v_mul_f32_e32 v231, v99, v230
	v_rcp_f32_e32 v230, v188
	v_rcp_f32_e32 v234, v191
	v_mul_f32_e32 v232, v93, v232
	v_mul_f32_e32 v233, v94, v233
	v_lshl_add_u64 v[218:219], v[214:215], 1, v[218:219]
	s_mov_b64 s[34:35], 0
	v_mul_f32_e32 v220, v96, v220
	v_mul_f32_e32 v221, v97, v221
	v_mul_f32_e32 v229, v98, v229
	v_mul_f32_e32 v235, v92, v230
	v_mul_f32_e32 v234, v95, v234
	v_cvt_pk_bf16_f32 v230, v220, v221
	v_cvt_pk_bf16_f32 v231, v229, v231
	v_cvt_pk_bf16_f32 v232, v235, v232
	v_cvt_pk_bf16_f32 v233, v233, v234
	flat_store_dwordx4 v[218:219], v[230:233] sc1

.LBB0_608:
	v_lshlrev_b32_e32 v188, 16, v184
	v_lshlrev_b32_e32 v192, 16, v186
	v_and_b32_e32 v189, 0xffff0000, v184
	v_max_f32_e32 v184, v188, v188
	v_max_f32_e32 v188, v192, v192
	v_max_f32_e32 v188, 0xc2700000, v188
	v_and_b32_e32 v193, 0xffff0000, v186
	v_mul_f32_e32 v188, 0xbfb8aa3b, v188
	v_exp_f32_e32 v192, v188
	v_max_f32_e32 v188, v193, v193
	v_max_f32_e32 v188, 0xc2700000, v188
	v_lshlrev_b32_e32 v194, 16, v187
	v_mul_f32_e32 v188, 0xbfb8aa3b, v188
	v_exp_f32_e32 v193, v188
	v_max_f32_e32 v188, v194, v194
	v_max_f32_e32 v188, 0xc2700000, v188
	v_lshlrev_b32_e32 v190, 16, v185
	v_and_b32_e32 v191, 0xffff0000, v185
	v_and_b32_e32 v195, 0xffff0000, v187
	v_mul_f32_e32 v188, 0xbfb8aa3b, v188
	v_max_f32_e32 v185, v189, v189
	v_max_f32_e32 v186, v190, v190
	v_max_f32_e32 v187, v191, v191
	v_exp_f32_e32 v194, v188
	v_max_f32_e32 v188, v195, v195
	v_max_f32_e32 v184, 0xc2700000, v184
	v_max_f32_e32 v185, 0xc2700000, v185
	v_max_f32_e32 v186, 0xc2700000, v186
	v_max_f32_e32 v187, 0xc2700000, v187
	v_max_f32_e32 v188, 0xc2700000, v188
	v_mul_f32_e32 v184, 0xbfb8aa3b, v184
	v_mul_f32_e32 v185, 0xbfb8aa3b, v185
	v_mul_f32_e32 v186, 0xbfb8aa3b, v186
	v_mul_f32_e32 v187, 0xbfb8aa3b, v187
	v_mul_f32_e32 v188, 0xbfb8aa3b, v188
	v_exp_f32_e32 v184, v184
	v_exp_f32_e32 v185, v185
	v_exp_f32_e32 v186, v186
	v_exp_f32_e32 v187, v187
	v_exp_f32_e32 v195, v188
	v_add_u32_e32 v218, 16, v1
	v_pk_add_f32 v[190:191], v[184:185], 1.0 op_sel_hi:[1,0]
	v_pk_add_f32 v[188:189], v[186:187], 1.0 op_sel_hi:[1,0]
	v_pk_add_f32 v[184:185], v[192:193], 1.0 op_sel_hi:[1,0]
	v_pk_add_f32 v[186:187], v[194:195], 1.0 op_sel_hi:[1,0]
	s_mov_b64 s[34:35], -1
	s_and_b64 vcc, exec, s[8:9]
	v_add_u32_e32 v192, s27, v218
	s_cbranch_vccnz .LBB0_610
	v_rcp_f32_e32 v218, v189
	v_rcp_f32_e32 v194, v191
	v_rcp_f32_e32 v195, v188
	v_rcp_f32_e32 v193, v190
	v_mul_f32_e32 v219, v123, v218
	v_rcp_f32_e32 v218, v184
	v_rcp_f32_e32 v220, v185
	v_rcp_f32_e32 v221, v186
	v_mul_f32_e32 v194, v121, v194
	v_mul_f32_e32 v195, v122, v195
	v_rcp_f32_e32 v229, v187
	v_mul_f32_e32 v193, v120, v193
	v_mul_f32_e32 v230, v116, v218
	v_cvt_pk_bf16_f32 v218, v193, v194
	v_cvt_pk_bf16_f32 v219, v195, v219
	v_mov_b64_e32 v[194:195], s[16:17]
	v_mad_i64_i32 v[194:195], s[4:5], v192, s58, v[194:195]
	v_mul_f32_e32 v220, v117, v220
	v_mul_f32_e32 v221, v118, v221
	v_lshl_add_u64 v[194:195], v[2:3], 1, v[194:195]
	s_mov_b64 s[34:35], 0
	v_mul_f32_e32 v229, v119, v229
	v_cvt_pk_bf16_f32 v220, v230, v220
	v_cvt_pk_bf16_f32 v221, v221, v229
	flat_store_dwordx4 v[194:195], v[218:221] sc1

.LBB0_612:
	v_lshlrev_b32_e32 v184, 16, v180
	v_lshlrev_b32_e32 v188, 16, v182
	v_and_b32_e32 v185, 0xffff0000, v180
	v_max_f32_e32 v180, v184, v184
	v_max_f32_e32 v184, v188, v188
	v_max_f32_e32 v184, 0xc2700000, v184
	v_and_b32_e32 v189, 0xffff0000, v182
	v_mul_f32_e32 v184, 0xbfb8aa3b, v184
	v_exp_f32_e32 v188, v184
	v_max_f32_e32 v184, v189, v189
	v_max_f32_e32 v184, 0xc2700000, v184
	v_lshlrev_b32_e32 v190, 16, v183
	v_mul_f32_e32 v184, 0xbfb8aa3b, v184
	v_exp_f32_e32 v189, v184
	v_max_f32_e32 v184, v190, v190
	v_max_f32_e32 v184, 0xc2700000, v184
	v_lshlrev_b32_e32 v186, 16, v181
	v_and_b32_e32 v187, 0xffff0000, v181
	v_and_b32_e32 v191, 0xffff0000, v183
	v_mul_f32_e32 v184, 0xbfb8aa3b, v184
	v_max_f32_e32 v181, v185, v185
	v_max_f32_e32 v182, v186, v186
	v_max_f32_e32 v183, v187, v187
	v_exp_f32_e32 v190, v184
	v_max_f32_e32 v184, v191, v191
	v_max_f32_e32 v180, 0xc2700000, v180
	v_max_f32_e32 v181, 0xc2700000, v181
	v_max_f32_e32 v182, 0xc2700000, v182
	v_max_f32_e32 v183, 0xc2700000, v183
	v_max_f32_e32 v184, 0xc2700000, v184
	v_mul_f32_e32 v180, 0xbfb8aa3b, v180
	v_mul_f32_e32 v181, 0xbfb8aa3b, v181
	v_mul_f32_e32 v182, 0xbfb8aa3b, v182
	v_mul_f32_e32 v183, 0xbfb8aa3b, v183
	v_mul_f32_e32 v184, 0xbfb8aa3b, v184
	v_exp_f32_e32 v180, v180
	v_exp_f32_e32 v181, v181
	v_exp_f32_e32 v182, v182
	v_exp_f32_e32 v183, v183
	v_exp_f32_e32 v191, v184
	v_pk_add_f32 v[186:187], v[180:181], 1.0 op_sel_hi:[1,0]
	v_pk_add_f32 v[180:181], v[188:189], 1.0 op_sel_hi:[1,0]
	v_pk_add_f32 v[184:185], v[182:183], 1.0 op_sel_hi:[1,0]
	v_pk_add_f32 v[182:183], v[190:191], 1.0 op_sel_hi:[1,0]
	s_and_b64 vcc, exec, s[8:9]
	s_mov_b64 s[34:35], -1
	s_cbranch_vccnz .LBB0_614
	v_rcp_f32_e32 v188, v186
	v_rcp_f32_e32 v189, v187
	v_rcp_f32_e32 v190, v184
	v_rcp_f32_e32 v191, v185
	v_rcp_f32_e32 v194, v181
	v_rcp_f32_e32 v195, v182
	v_rcp_f32_e32 v193, v180
	v_rcp_f32_e32 v218, v183
	v_mul_f32_e32 v188, v88, v188
	v_mul_f32_e32 v189, v89, v189
	v_mul_f32_e32 v190, v90, v190
	v_mul_f32_e32 v191, v91, v191
	v_mul_f32_e32 v194, v85, v194
	v_mul_f32_e32 v195, v86, v195
	v_mul_f32_e32 v193, v84, v193
	v_mul_f32_e32 v218, v87, v218
	v_cvt_pk_bf16_f32 v188, v188, v189
	v_cvt_pk_bf16_f32 v189, v190, v191
	v_cvt_pk_bf16_f32 v190, v193, v194
	v_cvt_pk_bf16_f32 v191, v195, v218
	v_mov_b64_e32 v[194:195], s[16:17]
	v_mad_i64_i32 v[192:193], s[4:5], v192, s58, v[194:195]
	v_lshl_add_u64 v[192:193], v[214:215], 1, v[192:193]
	s_mov_b64 s[34:35], 0
	flat_store_dwordx4 v[192:193], v[188:191] sc1

.LBB0_616:
	v_lshlrev_b32_e32 v180, 16, v176
	v_lshlrev_b32_e32 v184, 16, v178
	v_and_b32_e32 v181, 0xffff0000, v176
	v_max_f32_e32 v176, v180, v180
	v_max_f32_e32 v180, v184, v184
	v_max_f32_e32 v180, 0xc2700000, v180
	v_and_b32_e32 v185, 0xffff0000, v178
	v_mul_f32_e32 v180, 0xbfb8aa3b, v180
	v_exp_f32_e32 v184, v180
	v_max_f32_e32 v180, v185, v185
	v_max_f32_e32 v180, 0xc2700000, v180
	v_lshlrev_b32_e32 v186, 16, v179
	v_mul_f32_e32 v180, 0xbfb8aa3b, v180
	v_exp_f32_e32 v185, v180
	v_max_f32_e32 v180, v186, v186
	v_max_f32_e32 v180, 0xc2700000, v180
	v_lshlrev_b32_e32 v182, 16, v177
	v_and_b32_e32 v183, 0xffff0000, v177
	v_and_b32_e32 v187, 0xffff0000, v179
	v_mul_f32_e32 v180, 0xbfb8aa3b, v180
	v_max_f32_e32 v177, v181, v181
	v_max_f32_e32 v178, v182, v182
	v_max_f32_e32 v179, v183, v183
	v_exp_f32_e32 v186, v180
	v_max_f32_e32 v180, v187, v187
	v_max_f32_e32 v176, 0xc2700000, v176
	v_max_f32_e32 v177, 0xc2700000, v177
	v_max_f32_e32 v178, 0xc2700000, v178
	v_max_f32_e32 v179, 0xc2700000, v179
	v_max_f32_e32 v180, 0xc2700000, v180
	v_mul_f32_e32 v176, 0xbfb8aa3b, v176
	v_mul_f32_e32 v177, 0xbfb8aa3b, v177
	v_mul_f32_e32 v178, 0xbfb8aa3b, v178
	v_mul_f32_e32 v179, 0xbfb8aa3b, v179
	v_mul_f32_e32 v180, 0xbfb8aa3b, v180
	v_exp_f32_e32 v176, v176
	v_exp_f32_e32 v177, v177
	v_exp_f32_e32 v178, v178
	v_exp_f32_e32 v179, v179
	v_exp_f32_e32 v187, v180
	v_add_u32_e32 v188, 32, v1
	v_pk_add_f32 v[182:183], v[176:177], 1.0 op_sel_hi:[1,0]
	v_pk_add_f32 v[180:181], v[178:179], 1.0 op_sel_hi:[1,0]
	v_pk_add_f32 v[176:177], v[184:185], 1.0 op_sel_hi:[1,0]
	v_pk_add_f32 v[178:179], v[186:187], 1.0 op_sel_hi:[1,0]
	s_mov_b64 s[34:35], -1
	s_and_b64 vcc, exec, s[8:9]
	v_add_u32_e32 v184, s27, v188
	s_cbranch_vccnz .LBB0_618
	v_rcp_f32_e32 v187, v180
	v_rcp_f32_e32 v188, v181
	v_rcp_f32_e32 v189, v176
	v_rcp_f32_e32 v190, v177
	v_rcp_f32_e32 v191, v178
	v_rcp_f32_e32 v192, v179
	v_rcp_f32_e32 v186, v183
	v_rcp_f32_e32 v185, v182
	v_mul_f32_e32 v187, v114, v187
	v_mul_f32_e32 v188, v115, v188
	v_mul_f32_e32 v189, v108, v189
	v_mul_f32_e32 v190, v109, v190
	v_mul_f32_e32 v191, v110, v191
	v_mul_f32_e32 v192, v111, v192
	v_cvt_pk_bf16_f32 v187, v187, v188
	v_cvt_pk_bf16_f32 v188, v189, v190
	v_cvt_pk_bf16_f32 v189, v191, v192
	v_mov_b64_e32 v[190:191], s[16:17]
	v_mad_i64_i32 v[190:191], s[4:5], v184, s58, v[190:191]
	v_mul_f32_e32 v186, v113, v186
	v_lshl_add_u64 v[190:191], v[2:3], 1, v[190:191]
	s_mov_b64 s[34:35], 0
	v_mul_f32_e32 v185, v112, v185
	v_cvt_pk_bf16_f32 v186, v185, v186
	flat_store_dwordx4 v[190:191], v[186:189] sc1

.LBB0_620:
	v_lshlrev_b32_e32 v176, 16, v172
	v_lshlrev_b32_e32 v180, 16, v174
	v_and_b32_e32 v177, 0xffff0000, v172
	v_max_f32_e32 v172, v176, v176
	v_max_f32_e32 v176, v180, v180
	v_max_f32_e32 v176, 0xc2700000, v176
	v_and_b32_e32 v181, 0xffff0000, v174
	v_mul_f32_e32 v176, 0xbfb8aa3b, v176
	v_exp_f32_e32 v180, v176
	v_max_f32_e32 v176, v181, v181
	v_max_f32_e32 v176, 0xc2700000, v176
	v_lshlrev_b32_e32 v182, 16, v175
	v_mul_f32_e32 v176, 0xbfb8aa3b, v176
	v_exp_f32_e32 v181, v176
	v_max_f32_e32 v176, v182, v182
	v_max_f32_e32 v176, 0xc2700000, v176
	v_lshlrev_b32_e32 v178, 16, v173
	v_and_b32_e32 v179, 0xffff0000, v173
	v_and_b32_e32 v183, 0xffff0000, v175
	v_mul_f32_e32 v176, 0xbfb8aa3b, v176
	v_max_f32_e32 v173, v177, v177
	v_max_f32_e32 v174, v178, v178
	v_max_f32_e32 v175, v179, v179
	v_exp_f32_e32 v182, v176
	v_max_f32_e32 v176, v183, v183
	v_max_f32_e32 v172, 0xc2700000, v172
	v_max_f32_e32 v173, 0xc2700000, v173
	v_max_f32_e32 v174, 0xc2700000, v174
	v_max_f32_e32 v175, 0xc2700000, v175
	v_max_f32_e32 v176, 0xc2700000, v176
	v_mul_f32_e32 v172, 0xbfb8aa3b, v172
	v_mul_f32_e32 v173, 0xbfb8aa3b, v173
	v_mul_f32_e32 v174, 0xbfb8aa3b, v174
	v_mul_f32_e32 v175, 0xbfb8aa3b, v175
	v_mul_f32_e32 v176, 0xbfb8aa3b, v176
	v_exp_f32_e32 v172, v172
	v_exp_f32_e32 v173, v173
	v_exp_f32_e32 v174, v174
	v_exp_f32_e32 v175, v175
	v_exp_f32_e32 v183, v176
	v_pk_add_f32 v[178:179], v[172:173], 1.0 op_sel_hi:[1,0]
	v_pk_add_f32 v[172:173], v[180:181], 1.0 op_sel_hi:[1,0]
	v_pk_add_f32 v[176:177], v[174:175], 1.0 op_sel_hi:[1,0]
	v_pk_add_f32 v[174:175], v[182:183], 1.0 op_sel_hi:[1,0]
	s_and_b64 vcc, exec, s[8:9]
	s_mov_b64 s[34:35], -1
	s_cbranch_vccnz .LBB0_622
	v_rcp_f32_e32 v180, v178
	v_rcp_f32_e32 v181, v179
	v_rcp_f32_e32 v182, v176
	v_rcp_f32_e32 v183, v177
	v_rcp_f32_e32 v186, v173
	v_rcp_f32_e32 v187, v174
	v_rcp_f32_e32 v185, v172
	v_rcp_f32_e32 v188, v175
	v_mul_f32_e32 v180, v80, v180
	v_mul_f32_e32 v181, v81, v181
	v_mul_f32_e32 v182, v82, v182
	v_mul_f32_e32 v183, v83, v183
	v_mul_f32_e32 v186, v77, v186
	v_mul_f32_e32 v187, v78, v187
	v_mul_f32_e32 v185, v76, v185
	v_mul_f32_e32 v188, v79, v188
	v_cvt_pk_bf16_f32 v180, v180, v181
	v_cvt_pk_bf16_f32 v181, v182, v183
	v_cvt_pk_bf16_f32 v182, v185, v186
	v_cvt_pk_bf16_f32 v183, v187, v188
	v_mov_b64_e32 v[186:187], s[16:17]
	v_mad_i64_i32 v[184:185], s[4:5], v184, s58, v[186:187]
	v_lshl_add_u64 v[184:185], v[214:215], 1, v[184:185]
	s_mov_b64 s[34:35], 0
	flat_store_dwordx4 v[184:185], v[180:183] sc1

.LBB0_624:
	v_lshlrev_b32_e32 v172, 16, v168
	v_lshlrev_b32_e32 v176, 16, v170
	v_and_b32_e32 v173, 0xffff0000, v168
	v_max_f32_e32 v168, v172, v172
	v_max_f32_e32 v172, v176, v176
	v_max_f32_e32 v172, 0xc2700000, v172
	v_and_b32_e32 v177, 0xffff0000, v170
	v_mul_f32_e32 v172, 0xbfb8aa3b, v172
	v_exp_f32_e32 v176, v172
	v_max_f32_e32 v172, v177, v177
	v_max_f32_e32 v172, 0xc2700000, v172
	v_lshlrev_b32_e32 v178, 16, v171
	v_mul_f32_e32 v172, 0xbfb8aa3b, v172
	v_exp_f32_e32 v177, v172
	v_max_f32_e32 v172, v178, v178
	v_max_f32_e32 v172, 0xc2700000, v172
	v_lshlrev_b32_e32 v174, 16, v169
	v_and_b32_e32 v175, 0xffff0000, v169
	v_and_b32_e32 v179, 0xffff0000, v171
	v_mul_f32_e32 v172, 0xbfb8aa3b, v172
	v_max_f32_e32 v169, v173, v173
	v_max_f32_e32 v170, v174, v174
	v_max_f32_e32 v171, v175, v175
	v_exp_f32_e32 v178, v172
	v_max_f32_e32 v172, v179, v179
	v_max_f32_e32 v168, 0xc2700000, v168
	v_max_f32_e32 v169, 0xc2700000, v169
	v_max_f32_e32 v170, 0xc2700000, v170
	v_max_f32_e32 v171, 0xc2700000, v171
	v_max_f32_e32 v172, 0xc2700000, v172
	v_mul_f32_e32 v168, 0xbfb8aa3b, v168
	v_mul_f32_e32 v169, 0xbfb8aa3b, v169
	v_mul_f32_e32 v170, 0xbfb8aa3b, v170
	v_mul_f32_e32 v171, 0xbfb8aa3b, v171
	v_mul_f32_e32 v172, 0xbfb8aa3b, v172
	v_exp_f32_e32 v168, v168
	v_exp_f32_e32 v169, v169
	v_exp_f32_e32 v170, v170
	v_exp_f32_e32 v171, v171
	v_exp_f32_e32 v179, v172
	v_add_u32_e32 v180, 48, v1
	v_pk_add_f32 v[174:175], v[168:169], 1.0 op_sel_hi:[1,0]
	v_pk_add_f32 v[172:173], v[170:171], 1.0 op_sel_hi:[1,0]
	v_pk_add_f32 v[168:169], v[176:177], 1.0 op_sel_hi:[1,0]
	v_pk_add_f32 v[170:171], v[178:179], 1.0 op_sel_hi:[1,0]
	s_mov_b64 s[34:35], -1
	s_and_b64 vcc, exec, s[8:9]
	v_add_u32_e32 v176, s27, v180
	s_cbranch_vccnz .LBB0_626
	v_rcp_f32_e32 v179, v172
	v_rcp_f32_e32 v180, v173
	v_rcp_f32_e32 v181, v168
	v_rcp_f32_e32 v182, v169
	v_rcp_f32_e32 v183, v170
	v_rcp_f32_e32 v184, v171
	v_rcp_f32_e32 v178, v175
	v_rcp_f32_e32 v177, v174
	v_mul_f32_e32 v179, v106, v179
	v_mul_f32_e32 v180, v107, v180
	v_mul_f32_e32 v181, v100, v181
	v_mul_f32_e32 v182, v101, v182
	v_mul_f32_e32 v183, v102, v183
	v_mul_f32_e32 v184, v103, v184
	v_cvt_pk_bf16_f32 v179, v179, v180
	v_cvt_pk_bf16_f32 v180, v181, v182
	v_cvt_pk_bf16_f32 v181, v183, v184
	v_mov_b64_e32 v[182:183], s[16:17]
	v_mad_i64_i32 v[182:183], s[4:5], v176, s58, v[182:183]
	v_mul_f32_e32 v178, v105, v178
	v_lshl_add_u64 v[182:183], v[2:3], 1, v[182:183]
	s_mov_b64 s[34:35], 0
	v_mul_f32_e32 v177, v104, v177
	v_cvt_pk_bf16_f32 v178, v177, v178
	flat_store_dwordx4 v[182:183], v[178:181] sc1

.LBB0_628:
	v_lshlrev_b32_e32 v168, 16, v164
	v_lshlrev_b32_e32 v172, 16, v166
	v_and_b32_e32 v169, 0xffff0000, v164
	v_max_f32_e32 v164, v168, v168
	v_max_f32_e32 v168, v172, v172
	v_max_f32_e32 v168, 0xc2700000, v168
	v_and_b32_e32 v173, 0xffff0000, v166
	v_mul_f32_e32 v168, 0xbfb8aa3b, v168
	v_exp_f32_e32 v172, v168
	v_max_f32_e32 v168, v173, v173
	v_max_f32_e32 v168, 0xc2700000, v168
	v_lshlrev_b32_e32 v174, 16, v167
	v_mul_f32_e32 v168, 0xbfb8aa3b, v168
	v_exp_f32_e32 v173, v168
	v_max_f32_e32 v168, v174, v174
	v_max_f32_e32 v168, 0xc2700000, v168
	v_lshlrev_b32_e32 v170, 16, v165
	v_and_b32_e32 v171, 0xffff0000, v165
	v_and_b32_e32 v175, 0xffff0000, v167
	v_mul_f32_e32 v168, 0xbfb8aa3b, v168
	v_max_f32_e32 v165, v169, v169
	v_max_f32_e32 v166, v170, v170
	v_max_f32_e32 v167, v171, v171
	v_exp_f32_e32 v174, v168
	v_max_f32_e32 v168, v175, v175
	v_max_f32_e32 v164, 0xc2700000, v164
	v_max_f32_e32 v165, 0xc2700000, v165
	v_max_f32_e32 v166, 0xc2700000, v166
	v_max_f32_e32 v167, 0xc2700000, v167
	v_max_f32_e32 v168, 0xc2700000, v168
	v_mul_f32_e32 v164, 0xbfb8aa3b, v164
	v_mul_f32_e32 v165, 0xbfb8aa3b, v165
	v_mul_f32_e32 v166, 0xbfb8aa3b, v166
	v_mul_f32_e32 v167, 0xbfb8aa3b, v167
	v_mul_f32_e32 v168, 0xbfb8aa3b, v168
	v_exp_f32_e32 v164, v164
	v_exp_f32_e32 v165, v165
	v_exp_f32_e32 v166, v166
	v_exp_f32_e32 v167, v167
	v_exp_f32_e32 v175, v168
	v_pk_add_f32 v[170:171], v[164:165], 1.0 op_sel_hi:[1,0]
	v_pk_add_f32 v[164:165], v[172:173], 1.0 op_sel_hi:[1,0]
	v_pk_add_f32 v[168:169], v[166:167], 1.0 op_sel_hi:[1,0]
	v_pk_add_f32 v[166:167], v[174:175], 1.0 op_sel_hi:[1,0]
	s_and_b64 vcc, exec, s[8:9]
	s_mov_b64 s[34:35], -1
	s_cbranch_vccnz .LBB0_630
	v_rcp_f32_e32 v172, v170
	v_rcp_f32_e32 v173, v171
	v_rcp_f32_e32 v174, v168
	v_rcp_f32_e32 v175, v169
	v_rcp_f32_e32 v178, v165
	v_rcp_f32_e32 v179, v166
	v_rcp_f32_e32 v177, v164
	v_rcp_f32_e32 v180, v167
	v_mul_f32_e32 v172, v72, v172
	v_mul_f32_e32 v173, v73, v173
	v_mul_f32_e32 v174, v74, v174
	v_mul_f32_e32 v175, v75, v175
	v_mul_f32_e32 v178, v69, v178
	v_mul_f32_e32 v179, v70, v179
	v_mul_f32_e32 v177, v68, v177
	v_mul_f32_e32 v180, v71, v180
	v_cvt_pk_bf16_f32 v172, v172, v173
	v_cvt_pk_bf16_f32 v173, v174, v175
	v_cvt_pk_bf16_f32 v174, v177, v178
	v_cvt_pk_bf16_f32 v175, v179, v180
	v_mov_b64_e32 v[178:179], s[16:17]
	v_mad_i64_i32 v[176:177], s[4:5], v176, s58, v[178:179]
	v_lshl_add_u64 v[176:177], v[214:215], 1, v[176:177]
	s_mov_b64 s[34:35], 0
	flat_store_dwordx4 v[176:177], v[172:175] sc1

.LBB0_640:
	s_waitcnt vmcnt(0) lgkmcnt(0)
	v_lshlrev_b32_e32 v216, 16, v192
	v_lshlrev_b32_e32 v228, 16, v194
	v_and_b32_e32 v217, 0xffff0000, v192
	v_max_f32_e32 v192, v216, v216
	v_max_f32_e32 v216, v228, v228
	v_max_f32_e32 v216, 0xc2700000, v216
	v_and_b32_e32 v229, 0xffff0000, v194
	v_mul_f32_e32 v216, 0xbfb8aa3b, v216
	v_exp_f32_e32 v228, v216
	v_max_f32_e32 v216, v229, v229
	v_max_f32_e32 v216, 0xc2700000, v216
	v_lshlrev_b32_e32 v230, 16, v195
	v_mul_f32_e32 v216, 0xbfb8aa3b, v216
	v_exp_f32_e32 v229, v216
	v_max_f32_e32 v216, v230, v230
	v_max_f32_e32 v216, 0xc2700000, v216
	v_lshlrev_b32_e32 v220, 16, v193
	v_and_b32_e32 v221, 0xffff0000, v193
	v_and_b32_e32 v231, 0xffff0000, v195
	v_mul_f32_e32 v216, 0xbfb8aa3b, v216
	v_max_f32_e32 v193, v217, v217
	v_max_f32_e32 v194, v220, v220
	v_max_f32_e32 v195, v221, v221
	v_exp_f32_e32 v230, v216
	v_max_f32_e32 v216, v231, v231
	v_max_f32_e32 v192, 0xc2700000, v192
	v_max_f32_e32 v193, 0xc2700000, v193
	v_max_f32_e32 v194, 0xc2700000, v194
	v_max_f32_e32 v195, 0xc2700000, v195
	v_max_f32_e32 v216, 0xc2700000, v216
	v_mul_f32_e32 v192, 0xbfb8aa3b, v192
	v_mul_f32_e32 v193, 0xbfb8aa3b, v193
	v_mul_f32_e32 v194, 0xbfb8aa3b, v194
	v_mul_f32_e32 v195, 0xbfb8aa3b, v195
	v_mul_f32_e32 v216, 0xbfb8aa3b, v216
	v_exp_f32_e32 v192, v192
	v_exp_f32_e32 v193, v193
	v_exp_f32_e32 v194, v194
	v_exp_f32_e32 v195, v195
	v_exp_f32_e32 v231, v216
	v_pk_add_f32 v[220:221], v[192:193], 1.0 op_sel_hi:[1,0]
	v_pk_add_f32 v[192:193], v[228:229], 1.0 op_sel_hi:[1,0]
	v_pk_add_f32 v[216:217], v[194:195], 1.0 op_sel_hi:[1,0]
	v_pk_add_f32 v[194:195], v[230:231], 1.0 op_sel_hi:[1,0]
	s_and_b64 vcc, exec, s[8:9]
	s_mov_b64 s[10:11], -1
	s_cbranch_vccnz .LBB0_642
	v_rcp_f32_e32 v228, v220
	v_rcp_f32_e32 v229, v221
	v_rcp_f32_e32 v230, v216
	v_rcp_f32_e32 v232, v192
	v_rcp_f32_e32 v233, v193
	v_rcp_f32_e32 v231, v217
	v_rcp_f32_e32 v234, v194
	v_rcp_f32_e32 v235, v195
	v_mul_f32_e32 v228, v64, v228
	v_mul_f32_e32 v229, v65, v229
	v_mul_f32_e32 v230, v66, v230
	v_mul_f32_e32 v232, v60, v232
	v_mul_f32_e32 v233, v61, v233
	v_mul_f32_e32 v231, v67, v231
	v_cvt_pk_bf16_f32 v228, v228, v229
	v_cvt_pk_bf16_f32 v229, v230, v231
	v_cvt_pk_bf16_f32 v230, v232, v233
	v_lshl_add_u64 v[232:233], v[2:3], 1, v[218:219]
	s_mov_b64 s[10:11], 0
	v_mul_f32_e32 v234, v62, v234
	v_mul_f32_e32 v235, v63, v235
	v_cvt_pk_bf16_f32 v231, v234, v235
	flat_store_dwordx4 v[232:233], v[228:231] sc1

.LBB0_644:
	v_lshlrev_b32_e32 v160, 16, v188
	v_and_b32_e32 v161, 0xffff0000, v188
	v_lshlrev_b32_e32 v188, 16, v190
	v_max_f32_e32 v188, v188, v188
	v_max_f32_e32 v188, 0xc2700000, v188
	v_lshlrev_b32_e32 v162, 16, v189
	v_and_b32_e32 v163, 0xffff0000, v189
	v_and_b32_e32 v189, 0xffff0000, v190
	v_mul_f32_e32 v188, 0xbfb8aa3b, v188
	v_exp_f32_e32 v192, v188
	v_max_f32_e32 v188, v189, v189
	v_max_f32_e32 v188, 0xc2700000, v188
	v_lshlrev_b32_e32 v190, 16, v191
	v_mul_f32_e32 v188, 0xbfb8aa3b, v188
	v_exp_f32_e32 v193, v188
	v_max_f32_e32 v188, v190, v190
	v_max_f32_e32 v188, 0xc2700000, v188
	v_and_b32_e32 v191, 0xffff0000, v191
	v_mul_f32_e32 v188, 0xbfb8aa3b, v188
	v_max_f32_e32 v160, v160, v160
	v_max_f32_e32 v161, v161, v161
	v_max_f32_e32 v162, v162, v162
	v_max_f32_e32 v163, v163, v163
	v_exp_f32_e32 v194, v188
	v_max_f32_e32 v188, v191, v191
	v_max_f32_e32 v160, 0xc2700000, v160
	v_max_f32_e32 v161, 0xc2700000, v161
	v_max_f32_e32 v162, 0xc2700000, v162
	v_max_f32_e32 v163, 0xc2700000, v163
	v_max_f32_e32 v188, 0xc2700000, v188
	v_mul_f32_e32 v160, 0xbfb8aa3b, v160
	v_mul_f32_e32 v161, 0xbfb8aa3b, v161
	v_mul_f32_e32 v162, 0xbfb8aa3b, v162
	v_mul_f32_e32 v163, 0xbfb8aa3b, v163
	v_mul_f32_e32 v188, 0xbfb8aa3b, v188
	v_exp_f32_e32 v160, v160
	v_exp_f32_e32 v161, v161
	v_exp_f32_e32 v162, v162
	v_exp_f32_e32 v163, v163
	v_exp_f32_e32 v195, v188
	v_pk_add_f32 v[190:191], v[160:161], 1.0 op_sel_hi:[1,0]
	v_pk_add_f32 v[160:161], v[192:193], 1.0 op_sel_hi:[1,0]
	v_pk_add_f32 v[188:189], v[162:163], 1.0 op_sel_hi:[1,0]
	v_pk_add_f32 v[162:163], v[194:195], 1.0 op_sel_hi:[1,0]
	s_and_b64 vcc, exec, s[8:9]
	s_mov_b64 s[10:11], -1
	s_cbranch_vccnz .LBB0_646
	v_rcp_f32_e32 v192, v190
	v_rcp_f32_e32 v193, v191
	v_rcp_f32_e32 v194, v188
	v_rcp_f32_e32 v216, v160
	v_rcp_f32_e32 v217, v161
	v_rcp_f32_e32 v195, v189
	v_rcp_f32_e32 v220, v162
	v_rcp_f32_e32 v221, v163
	v_mul_f32_e32 v192, v32, v192
	v_mul_f32_e32 v193, v33, v193
	v_mul_f32_e32 v194, v34, v194
	v_mul_f32_e32 v216, v28, v216
	v_mul_f32_e32 v217, v29, v217
	v_mul_f32_e32 v195, v35, v195
	v_cvt_pk_bf16_f32 v192, v192, v193
	v_cvt_pk_bf16_f32 v193, v194, v195
	v_cvt_pk_bf16_f32 v194, v216, v217
	v_lshl_add_u64 v[216:217], v[214:215], 1, v[218:219]
	s_mov_b64 s[10:11], 0
	v_mul_f32_e32 v220, v30, v220
	v_mul_f32_e32 v221, v31, v221
	v_cvt_pk_bf16_f32 v195, v220, v221
	flat_store_dwordx4 v[216:217], v[192:195] sc1

.LBB0_648:
	v_lshlrev_b32_e32 v160, 16, v186
	v_max_f32_e32 v160, v160, v160
	v_max_f32_e32 v160, 0xc2700000, v160
	v_and_b32_e32 v161, 0xffff0000, v186
	v_mul_f32_e32 v160, 0xbfb8aa3b, v160
	v_lshlrev_b32_e32 v156, 16, v184
	v_and_b32_e32 v157, 0xffff0000, v184
	v_exp_f32_e32 v184, v160
	v_max_f32_e32 v160, v161, v161
	v_max_f32_e32 v160, 0xc2700000, v160
	v_lshlrev_b32_e32 v162, 16, v187
	v_mul_f32_e32 v160, 0xbfb8aa3b, v160
	v_lshlrev_b32_e32 v158, 16, v185
	v_and_b32_e32 v159, 0xffff0000, v185
	v_exp_f32_e32 v185, v160
	v_max_f32_e32 v160, v162, v162
	v_max_f32_e32 v160, 0xc2700000, v160
	v_and_b32_e32 v163, 0xffff0000, v187
	v_mul_f32_e32 v160, 0xbfb8aa3b, v160
	v_max_f32_e32 v156, v156, v156
	v_max_f32_e32 v157, v157, v157
	v_max_f32_e32 v158, v158, v158
	v_max_f32_e32 v159, v159, v159
	v_exp_f32_e32 v186, v160
	v_max_f32_e32 v160, v163, v163
	v_max_f32_e32 v156, 0xc2700000, v156
	v_max_f32_e32 v157, 0xc2700000, v157
	v_max_f32_e32 v158, 0xc2700000, v158
	v_max_f32_e32 v159, 0xc2700000, v159
	v_max_f32_e32 v160, 0xc2700000, v160
	v_mul_f32_e32 v156, 0xbfb8aa3b, v156
	v_mul_f32_e32 v157, 0xbfb8aa3b, v157
	v_mul_f32_e32 v158, 0xbfb8aa3b, v158
	v_mul_f32_e32 v159, 0xbfb8aa3b, v159
	v_mul_f32_e32 v160, 0xbfb8aa3b, v160
	v_exp_f32_e32 v156, v156
	v_exp_f32_e32 v157, v157
	v_exp_f32_e32 v158, v158
	v_exp_f32_e32 v159, v159
	v_exp_f32_e32 v187, v160
	v_add_u32_e32 v188, 0x90, v1
	v_pk_add_f32 v[162:163], v[156:157], 1.0 op_sel_hi:[1,0]
	v_pk_add_f32 v[160:161], v[158:159], 1.0 op_sel_hi:[1,0]
	v_pk_add_f32 v[156:157], v[184:185], 1.0 op_sel_hi:[1,0]
	v_pk_add_f32 v[158:159], v[186:187], 1.0 op_sel_hi:[1,0]
	s_mov_b64 s[10:11], -1
	s_and_b64 vcc, exec, s[8:9]
	v_add_u32_e32 v184, s27, v188
	s_cbranch_vccnz .LBB0_650
	v_rcp_f32_e32 v187, v160
	v_rcp_f32_e32 v188, v161
	v_rcp_f32_e32 v189, v156
	v_rcp_f32_e32 v190, v157
	v_rcp_f32_e32 v191, v158
	v_rcp_f32_e32 v192, v159
	v_rcp_f32_e32 v186, v163
	v_rcp_f32_e32 v185, v162
	v_mul_f32_e32 v187, v58, v187
	v_mul_f32_e32 v188, v59, v188
	v_mul_f32_e32 v189, v52, v189
	v_mul_f32_e32 v190, v53, v190
	v_mul_f32_e32 v191, v54, v191
	v_mul_f32_e32 v192, v55, v192
	v_cvt_pk_bf16_f32 v187, v187, v188
	v_cvt_pk_bf16_f32 v188, v189, v190
	v_cvt_pk_bf16_f32 v189, v191, v192
	v_mov_b64_e32 v[190:191], s[16:17]
	v_mad_i64_i32 v[190:191], s[4:5], v184, s58, v[190:191]
	v_mul_f32_e32 v186, v57, v186
	v_lshl_add_u64 v[190:191], v[2:3], 1, v[190:191]
	s_mov_b64 s[10:11], 0
	v_mul_f32_e32 v185, v56, v185
	v_cvt_pk_bf16_f32 v186, v185, v186
	flat_store_dwordx4 v[190:191], v[186:189] sc1

.LBB0_652:
	v_lshlrev_b32_e32 v156, 16, v182
	v_max_f32_e32 v156, v156, v156
	v_max_f32_e32 v156, 0xc2700000, v156
	v_and_b32_e32 v157, 0xffff0000, v182
	v_mul_f32_e32 v156, 0xbfb8aa3b, v156
	v_exp_f32_e32 v160, v156
	v_max_f32_e32 v156, v157, v157
	v_max_f32_e32 v156, 0xc2700000, v156
	v_lshlrev_b32_e32 v158, 16, v183
	v_mul_f32_e32 v156, 0xbfb8aa3b, v156
	v_exp_f32_e32 v161, v156
	v_max_f32_e32 v156, v158, v158
	v_max_f32_e32 v156, 0xc2700000, v156
	v_lshlrev_b32_e32 v152, 16, v180
	v_and_b32_e32 v153, 0xffff0000, v180
	v_lshlrev_b32_e32 v154, 16, v181
	v_and_b32_e32 v155, 0xffff0000, v181
	v_and_b32_e32 v159, 0xffff0000, v183
	v_mul_f32_e32 v156, 0xbfb8aa3b, v156
	v_max_f32_e32 v152, v152, v152
	v_max_f32_e32 v153, v153, v153
	v_max_f32_e32 v154, v154, v154
	v_max_f32_e32 v155, v155, v155
	v_exp_f32_e32 v162, v156
	v_max_f32_e32 v156, v159, v159
	v_max_f32_e32 v152, 0xc2700000, v152
	v_max_f32_e32 v153, 0xc2700000, v153
	v_max_f32_e32 v154, 0xc2700000, v154
	v_max_f32_e32 v155, 0xc2700000, v155
	v_max_f32_e32 v156, 0xc2700000, v156
	v_mul_f32_e32 v152, 0xbfb8aa3b, v152
	v_mul_f32_e32 v153, 0xbfb8aa3b, v153
	v_mul_f32_e32 v154, 0xbfb8aa3b, v154
	v_mul_f32_e32 v155, 0xbfb8aa3b, v155
	v_mul_f32_e32 v156, 0xbfb8aa3b, v156
	v_exp_f32_e32 v152, v152
	v_exp_f32_e32 v153, v153
	v_exp_f32_e32 v154, v154
	v_exp_f32_e32 v155, v155
	v_exp_f32_e32 v163, v156
	v_pk_add_f32 v[158:159], v[152:153], 1.0 op_sel_hi:[1,0]
	v_pk_add_f32 v[152:153], v[160:161], 1.0 op_sel_hi:[1,0]
	v_pk_add_f32 v[156:157], v[154:155], 1.0 op_sel_hi:[1,0]
	v_pk_add_f32 v[154:155], v[162:163], 1.0 op_sel_hi:[1,0]
	s_and_b64 vcc, exec, s[8:9]
	s_mov_b64 s[10:11], -1
	s_cbranch_vccnz .LBB0_654
	v_rcp_f32_e32 v160, v158
	v_rcp_f32_e32 v161, v159
	v_rcp_f32_e32 v162, v156
	v_rcp_f32_e32 v180, v152
	v_rcp_f32_e32 v181, v153
	v_rcp_f32_e32 v163, v157
	v_mul_f32_e32 v160, v24, v160
	v_mul_f32_e32 v161, v25, v161
	v_mul_f32_e32 v162, v26, v162
	v_rcp_f32_e32 v182, v154
	v_rcp_f32_e32 v183, v155
	v_mul_f32_e32 v180, v20, v180
	v_mul_f32_e32 v181, v21, v181
	v_mul_f32_e32 v163, v27, v163
	v_cvt_pk_bf16_f32 v160, v160, v161
	v_cvt_pk_bf16_f32 v161, v162, v163
	v_cvt_pk_bf16_f32 v162, v180, v181
	v_mov_b64_e32 v[180:181], s[16:17]
	v_mad_i64_i32 v[180:181], s[4:5], v184, s58, v[180:181]
	v_lshl_add_u64 v[180:181], v[214:215], 1, v[180:181]
	s_mov_b64 s[10:11], 0
	v_mul_f32_e32 v182, v22, v182
	v_mul_f32_e32 v183, v23, v183
	v_cvt_pk_bf16_f32 v163, v182, v183
	flat_store_dwordx4 v[180:181], v[160:163] sc1

.LBB0_656:
	v_lshlrev_b32_e32 v152, 16, v178
	v_max_f32_e32 v152, v152, v152
	v_max_f32_e32 v152, 0xc2700000, v152
	v_and_b32_e32 v153, 0xffff0000, v178
	v_mul_f32_e32 v152, 0xbfb8aa3b, v152
	v_exp_f32_e32 v156, v152
	v_max_f32_e32 v152, v153, v153
	v_max_f32_e32 v152, 0xc2700000, v152
	v_lshlrev_b32_e32 v154, 16, v179
	v_mul_f32_e32 v152, 0xbfb8aa3b, v152
	v_exp_f32_e32 v157, v152
	v_max_f32_e32 v152, v154, v154
	v_max_f32_e32 v152, 0xc2700000, v152
	v_lshlrev_b32_e32 v148, 16, v176
	v_and_b32_e32 v149, 0xffff0000, v176
	v_lshlrev_b32_e32 v150, 16, v177
	v_and_b32_e32 v151, 0xffff0000, v177
	v_and_b32_e32 v155, 0xffff0000, v179
	v_mul_f32_e32 v152, 0xbfb8aa3b, v152
	v_max_f32_e32 v148, v148, v148
	v_max_f32_e32 v149, v149, v149
	v_max_f32_e32 v150, v150, v150
	v_max_f32_e32 v151, v151, v151
	v_exp_f32_e32 v158, v152
	v_max_f32_e32 v152, v155, v155
	v_max_f32_e32 v148, 0xc2700000, v148
	v_max_f32_e32 v149, 0xc2700000, v149
	v_max_f32_e32 v150, 0xc2700000, v150
	v_max_f32_e32 v151, 0xc2700000, v151
	v_max_f32_e32 v152, 0xc2700000, v152
	v_mul_f32_e32 v148, 0xbfb8aa3b, v148
	v_mul_f32_e32 v149, 0xbfb8aa3b, v149
	v_mul_f32_e32 v150, 0xbfb8aa3b, v150
	v_mul_f32_e32 v151, 0xbfb8aa3b, v151
	v_mul_f32_e32 v152, 0xbfb8aa3b, v152
	v_exp_f32_e32 v148, v148
	v_exp_f32_e32 v149, v149
	v_exp_f32_e32 v150, v150
	v_exp_f32_e32 v151, v151
	v_exp_f32_e32 v159, v152
	v_add_u32_e32 v160, 0xa0, v1
	v_pk_add_f32 v[154:155], v[148:149], 1.0 op_sel_hi:[1,0]
	v_pk_add_f32 v[152:153], v[150:151], 1.0 op_sel_hi:[1,0]
	v_pk_add_f32 v[148:149], v[156:157], 1.0 op_sel_hi:[1,0]
	v_pk_add_f32 v[150:151], v[158:159], 1.0 op_sel_hi:[1,0]
	s_mov_b64 s[10:11], -1
	s_and_b64 vcc, exec, s[8:9]
	v_add_u32_e32 v156, s27, v160
	s_cbranch_vccnz .LBB0_658
	v_rcp_f32_e32 v159, v152
	v_rcp_f32_e32 v160, v153
	v_rcp_f32_e32 v161, v148
	v_rcp_f32_e32 v162, v149
	v_rcp_f32_e32 v163, v150
	v_rcp_f32_e32 v176, v151
	v_rcp_f32_e32 v158, v155
	v_rcp_f32_e32 v157, v154
	v_mul_f32_e32 v159, v50, v159
	v_mul_f32_e32 v160, v51, v160
	v_mul_f32_e32 v161, v44, v161
	v_mul_f32_e32 v162, v45, v162
	v_mul_f32_e32 v163, v46, v163
	v_mul_f32_e32 v176, v47, v176
	v_cvt_pk_bf16_f32 v159, v159, v160
	v_cvt_pk_bf16_f32 v160, v161, v162
	v_cvt_pk_bf16_f32 v161, v163, v176
	v_mov_b64_e32 v[162:163], s[16:17]
	v_mad_i64_i32 v[162:163], s[4:5], v156, s58, v[162:163]
	v_mul_f32_e32 v158, v49, v158
	v_lshl_add_u64 v[162:163], v[2:3], 1, v[162:163]
	s_mov_b64 s[10:11], 0
	v_mul_f32_e32 v157, v48, v157
	v_cvt_pk_bf16_f32 v158, v157, v158
	flat_store_dwordx4 v[162:163], v[158:161] sc1

.LBB0_660:
	v_lshlrev_b32_e32 v148, 16, v174
	v_max_f32_e32 v148, v148, v148
	v_max_f32_e32 v148, 0xc2700000, v148
	v_and_b32_e32 v149, 0xffff0000, v174
	v_mul_f32_e32 v148, 0xbfb8aa3b, v148
	v_exp_f32_e32 v152, v148
	v_max_f32_e32 v148, v149, v149
	v_max_f32_e32 v148, 0xc2700000, v148
	v_lshlrev_b32_e32 v150, 16, v175
	v_mul_f32_e32 v148, 0xbfb8aa3b, v148
	v_exp_f32_e32 v153, v148
	v_max_f32_e32 v148, v150, v150
	v_max_f32_e32 v148, 0xc2700000, v148
	v_lshlrev_b32_e32 v144, 16, v172
	v_and_b32_e32 v145, 0xffff0000, v172
	v_lshlrev_b32_e32 v146, 16, v173
	v_and_b32_e32 v147, 0xffff0000, v173
	v_and_b32_e32 v151, 0xffff0000, v175
	v_mul_f32_e32 v148, 0xbfb8aa3b, v148
	v_max_f32_e32 v144, v144, v144
	v_max_f32_e32 v145, v145, v145
	v_max_f32_e32 v146, v146, v146
	v_max_f32_e32 v147, v147, v147
	v_exp_f32_e32 v154, v148
	v_max_f32_e32 v148, v151, v151
	v_max_f32_e32 v144, 0xc2700000, v144
	v_max_f32_e32 v145, 0xc2700000, v145
	v_max_f32_e32 v146, 0xc2700000, v146
	v_max_f32_e32 v147, 0xc2700000, v147
	v_max_f32_e32 v148, 0xc2700000, v148
	v_mul_f32_e32 v144, 0xbfb8aa3b, v144
	v_mul_f32_e32 v145, 0xbfb8aa3b, v145
	v_mul_f32_e32 v146, 0xbfb8aa3b, v146
	v_mul_f32_e32 v147, 0xbfb8aa3b, v147
	v_mul_f32_e32 v148, 0xbfb8aa3b, v148
	v_exp_f32_e32 v144, v144
	v_exp_f32_e32 v145, v145
	v_exp_f32_e32 v146, v146
	v_exp_f32_e32 v147, v147
	v_exp_f32_e32 v155, v148
	v_pk_add_f32 v[150:151], v[144:145], 1.0 op_sel_hi:[1,0]
	v_pk_add_f32 v[144:145], v[152:153], 1.0 op_sel_hi:[1,0]
	v_pk_add_f32 v[148:149], v[146:147], 1.0 op_sel_hi:[1,0]
	v_pk_add_f32 v[146:147], v[154:155], 1.0 op_sel_hi:[1,0]
	s_and_b64 vcc, exec, s[8:9]
	s_mov_b64 s[10:11], -1
	s_cbranch_vccnz .LBB0_662
	v_rcp_f32_e32 v152, v150
	v_rcp_f32_e32 v153, v151
	v_rcp_f32_e32 v154, v148
	v_rcp_f32_e32 v155, v149
	v_rcp_f32_e32 v158, v145
	v_rcp_f32_e32 v159, v146
	v_rcp_f32_e32 v157, v144
	v_rcp_f32_e32 v160, v147
	v_mul_f32_e32 v152, v16, v152
	v_mul_f32_e32 v153, v17, v153
	v_mul_f32_e32 v154, v18, v154
	v_mul_f32_e32 v155, v19, v155
	v_mul_f32_e32 v158, v13, v158
	v_mul_f32_e32 v159, v14, v159
	v_mul_f32_e32 v157, v12, v157
	v_mul_f32_e32 v160, v15, v160
	v_cvt_pk_bf16_f32 v152, v152, v153
	v_cvt_pk_bf16_f32 v153, v154, v155
	v_cvt_pk_bf16_f32 v154, v157, v158
	v_cvt_pk_bf16_f32 v155, v159, v160
	v_mov_b64_e32 v[158:159], s[16:17]
	v_mad_i64_i32 v[156:157], s[4:5], v156, s58, v[158:159]
	v_lshl_add_u64 v[156:157], v[214:215], 1, v[156:157]
	s_mov_b64 s[10:11], 0
	flat_store_dwordx4 v[156:157], v[152:155] sc1

.LBB0_664:
	v_lshlrev_b32_e32 v144, 16, v170
	v_max_f32_e32 v144, v144, v144
	v_max_f32_e32 v144, 0xc2700000, v144
	v_and_b32_e32 v145, 0xffff0000, v170
	v_mul_f32_e32 v144, 0xbfb8aa3b, v144
	v_exp_f32_e32 v148, v144
	v_max_f32_e32 v144, v145, v145
	v_max_f32_e32 v144, 0xc2700000, v144
	v_lshlrev_b32_e32 v146, 16, v171
	v_mul_f32_e32 v144, 0xbfb8aa3b, v144
	v_exp_f32_e32 v149, v144
	v_max_f32_e32 v144, v146, v146
	v_max_f32_e32 v144, 0xc2700000, v144
	v_lshlrev_b32_e32 v140, 16, v168
	v_and_b32_e32 v141, 0xffff0000, v168
	v_lshlrev_b32_e32 v142, 16, v169
	v_and_b32_e32 v143, 0xffff0000, v169
	v_and_b32_e32 v147, 0xffff0000, v171
	v_mul_f32_e32 v144, 0xbfb8aa3b, v144
	v_max_f32_e32 v140, v140, v140
	v_max_f32_e32 v141, v141, v141
	v_max_f32_e32 v142, v142, v142
	v_max_f32_e32 v143, v143, v143
	v_exp_f32_e32 v150, v144
	v_max_f32_e32 v144, v147, v147
	v_max_f32_e32 v140, 0xc2700000, v140
	v_max_f32_e32 v141, 0xc2700000, v141
	v_max_f32_e32 v142, 0xc2700000, v142
	v_max_f32_e32 v143, 0xc2700000, v143
	v_max_f32_e32 v144, 0xc2700000, v144
	v_mul_f32_e32 v140, 0xbfb8aa3b, v140
	v_mul_f32_e32 v141, 0xbfb8aa3b, v141
	v_mul_f32_e32 v142, 0xbfb8aa3b, v142
	v_mul_f32_e32 v143, 0xbfb8aa3b, v143
	v_mul_f32_e32 v144, 0xbfb8aa3b, v144
	v_exp_f32_e32 v140, v140
	v_exp_f32_e32 v141, v141
	v_exp_f32_e32 v142, v142
	v_exp_f32_e32 v143, v143
	v_exp_f32_e32 v151, v144
	v_add_u32_e32 v1, 0xb0, v1
	v_pk_add_f32 v[146:147], v[140:141], 1.0 op_sel_hi:[1,0]
	v_pk_add_f32 v[144:145], v[142:143], 1.0 op_sel_hi:[1,0]
	v_pk_add_f32 v[140:141], v[148:149], 1.0 op_sel_hi:[1,0]
	v_pk_add_f32 v[142:143], v[150:151], 1.0 op_sel_hi:[1,0]
	s_mov_b64 s[10:11], -1
	s_and_b64 vcc, exec, s[8:9]
	v_add_u32_e32 v1, s27, v1
	s_cbranch_vccnz .LBB0_666
	v_rcp_f32_e32 v148, v146
	v_rcp_f32_e32 v149, v147
	v_rcp_f32_e32 v150, v144
	v_rcp_f32_e32 v152, v140
	v_rcp_f32_e32 v153, v141
	v_rcp_f32_e32 v151, v145
	v_mul_f32_e32 v148, v40, v148
	v_mul_f32_e32 v149, v41, v149
	v_mul_f32_e32 v150, v42, v150
	v_rcp_f32_e32 v154, v142
	v_rcp_f32_e32 v155, v143
	v_mul_f32_e32 v152, v36, v152
	v_mul_f32_e32 v153, v37, v153
	v_mul_f32_e32 v151, v43, v151
	v_cvt_pk_bf16_f32 v148, v148, v149
	v_cvt_pk_bf16_f32 v149, v150, v151
	v_cvt_pk_bf16_f32 v150, v152, v153
	v_mov_b64_e32 v[152:153], s[16:17]
	v_mad_i64_i32 v[152:153], s[4:5], v1, s58, v[152:153]
	v_lshl_add_u64 v[2:3], v[2:3], 1, v[152:153]
	s_mov_b64 s[10:11], 0
	v_mul_f32_e32 v154, v38, v154
	v_mul_f32_e32 v155, v39, v155
	v_cvt_pk_bf16_f32 v151, v154, v155
	flat_store_dwordx4 v[2:3], v[148:151] sc1

.LBB0_668:
	v_lshlrev_b32_e32 v138, 16, v166
	v_max_f32_e32 v138, v138, v138
	v_max_f32_e32 v138, 0xc2700000, v138
	v_and_b32_e32 v139, 0xffff0000, v166
	v_mul_f32_e32 v138, 0xbfb8aa3b, v138
	v_exp_f32_e32 v142, v138
	v_max_f32_e32 v138, v139, v139
	v_max_f32_e32 v138, 0xc2700000, v138
	v_lshlrev_b32_e32 v140, 16, v167
	v_mul_f32_e32 v138, 0xbfb8aa3b, v138
	v_exp_f32_e32 v143, v138
	v_max_f32_e32 v138, v140, v140
	v_max_f32_e32 v138, 0xc2700000, v138
	v_lshlrev_b32_e32 v2, 16, v164
	v_and_b32_e32 v3, 0xffff0000, v164
	v_lshlrev_b32_e32 v136, 16, v165
	v_and_b32_e32 v137, 0xffff0000, v165
	v_and_b32_e32 v141, 0xffff0000, v167
	v_mul_f32_e32 v138, 0xbfb8aa3b, v138
	v_max_f32_e32 v2, v2, v2
	v_max_f32_e32 v3, v3, v3
	v_max_f32_e32 v136, v136, v136
	v_max_f32_e32 v137, v137, v137
	v_exp_f32_e32 v144, v138
	v_max_f32_e32 v138, v141, v141
	v_max_f32_e32 v2, 0xc2700000, v2
	v_max_f32_e32 v3, 0xc2700000, v3
	v_max_f32_e32 v136, 0xc2700000, v136
	v_max_f32_e32 v137, 0xc2700000, v137
	v_max_f32_e32 v138, 0xc2700000, v138
	v_mul_f32_e32 v2, 0xbfb8aa3b, v2
	v_mul_f32_e32 v3, 0xbfb8aa3b, v3
	v_mul_f32_e32 v136, 0xbfb8aa3b, v136
	v_mul_f32_e32 v137, 0xbfb8aa3b, v137
	v_mul_f32_e32 v138, 0xbfb8aa3b, v138
	v_exp_f32_e32 v2, v2
	v_exp_f32_e32 v3, v3
	v_exp_f32_e32 v136, v136
	v_exp_f32_e32 v137, v137
	v_exp_f32_e32 v145, v138
	v_pk_add_f32 v[140:141], v[2:3], 1.0 op_sel_hi:[1,0]
	v_pk_add_f32 v[2:3], v[142:143], 1.0 op_sel_hi:[1,0]
	v_pk_add_f32 v[138:139], v[136:137], 1.0 op_sel_hi:[1,0]
	v_pk_add_f32 v[136:137], v[144:145], 1.0 op_sel_hi:[1,0]
	s_and_b64 vcc, exec, s[8:9]
	s_mov_b64 s[10:11], -1
	s_cbranch_vccnz .LBB0_671
	v_rcp_f32_e32 v142, v140
	v_rcp_f32_e32 v143, v141
	v_rcp_f32_e32 v144, v138
	v_rcp_f32_e32 v146, v2
	v_rcp_f32_e32 v147, v3
	v_rcp_f32_e32 v145, v139
	v_mul_f32_e32 v142, v8, v142
	v_mul_f32_e32 v143, v9, v143
	v_mul_f32_e32 v144, v10, v144
	v_rcp_f32_e32 v148, v136
	v_rcp_f32_e32 v149, v137
	v_mul_f32_e32 v146, v4, v146
	v_mul_f32_e32 v147, v5, v147
	v_mul_f32_e32 v145, v11, v145
	v_cvt_pk_bf16_f32 v142, v142, v143
	v_cvt_pk_bf16_f32 v143, v144, v145
	v_cvt_pk_bf16_f32 v144, v146, v147
	v_mov_b64_e32 v[146:147], s[16:17]
	v_mad_i64_i32 v[146:147], s[4:5], v1, s58, v[146:147]
	v_lshl_add_u64 v[146:147], v[214:215], 1, v[146:147]
	v_mul_f32_e32 v148, v6, v148
	v_mul_f32_e32 v149, v7, v149
	v_cvt_pk_bf16_f32 v145, v148, v149
	flat_store_dwordx4 v[146:147], v[142:145] sc1
	s_cbranch_execz .LBB0_672

.LBB0_757:
	s_ashr_i32 s4, s16, 5
	s_mul_hi_i32 s5, s4, 0x6000
	s_mulk_i32 s4, 0x6000
	s_add_u32 s23, s51, s4
	s_addc_u32 s28, s52, s5
	s_lshl_b32 s8, s63, 8
	s_ashr_i32 s9, s8, 31
	s_lshl_b64 s[4:5], s[8:9], 2
	s_add_u32 s23, s23, s4
	s_addc_u32 s29, s28, s5
	s_lshl_b32 s28, s54, 2
	s_add_u32 s28, s23, s28
	v_mov_b32_e32 v132, v166
	v_mov_b32_e32 v128, v167
	s_addc_u32 s29, s29, 0
	s_lshl_b32 s16, s16, 8
	s_add_i32 s16, s16, s53
	v_lshlrev_b32_e32 v160, 3, v128
	v_ashrrev_i32_e32 v161, 31, v160
	v_add_u32_e32 v164, s16, v132
	s_add_u32 s4, s57, s4
	v_lshlrev_b64 v[128:129], 2, v[160:161]
	s_addc_u32 s5, s58, s5
	v_ashrrev_i32_e32 v165, 31, v164
	v_lshl_add_u64 v[130:131], s[28:29], 0, v[128:129]
	v_lshl_add_u64 v[162:163], s[4:5], 0, v[128:129]
	v_lshlrev_b64 v[128:129], 12, v[164:165]
	v_lshl_add_u64 v[184:185], v[162:163], 0, v[128:129]
	v_add_u32_e32 v232, 16, v164
	flat_load_dwordx4 v[172:175], v[184:185]
	flat_load_dwordx4 v[140:143], v[130:131]
	flat_load_dwordx4 v[136:139], v[130:131] offset:16
	flat_load_dwordx4 v[176:179], v[184:185] offset:16
	flat_load_dwordx4 v[180:183], v[184:185] offset:512
	flat_load_dwordx4 v[132:135], v[130:131] offset:512
	s_nop 0
	flat_load_dwordx4 v[128:131], v[130:131] offset:528
	s_nop 0
	flat_load_dwordx4 v[184:187], v[184:185] offset:528
	v_ashrrev_i32_e32 v233, 31, v232
	v_lshlrev_b64 v[188:189], 12, v[232:233]
	v_lshl_add_u64 v[202:203], v[162:163], 0, v[188:189]
	flat_load_dwordx4 v[188:191], v[202:203]
	flat_load_dwordx4 v[192:195], v[202:203] offset:16
	flat_load_dwordx4 v[198:201], v[202:203] offset:512
	s_nop 0
	flat_load_dwordx4 v[202:205], v[202:203] offset:528
	v_add_u32_e32 v240, 32, v164
	v_ashrrev_i32_e32 v241, 31, v240
	v_lshlrev_b64 v[206:207], 12, v[240:241]
	v_lshl_add_u64 v[218:219], v[162:163], 0, v[206:207]
	flat_load_dwordx4 v[206:209], v[218:219]
	flat_load_dwordx4 v[210:213], v[218:219] offset:16
	flat_load_dwordx4 v[214:217], v[218:219] offset:512
	s_nop 0
	flat_load_dwordx4 v[218:221], v[218:219] offset:528
	v_add_u32_e32 v242, 48, v164
	v_ashrrev_i32_e32 v243, 31, v242
	v_lshlrev_b64 v[224:225], 12, v[242:243]
	v_lshl_add_u64 v[236:237], v[162:163], 0, v[224:225]
	v_lshlrev_b64 v[234:235], 11, v[164:165]
	flat_load_dwordx4 v[224:227], v[236:237]
	flat_load_dwordx4 v[228:231], v[236:237] offset:16
	s_lshl_b64 s[8:9], s[8:9], 1
	v_lshl_add_u64 v[234:235], s[12:13], 0, v[234:235]
	v_lshlrev_b64 v[232:233], 11, v[232:233]
	v_lshl_add_u64 v[244:245], v[234:235], 0, s[8:9]
	v_lshl_add_u64 v[246:247], s[12:13], 0, v[232:233]
	flat_load_dwordx4 v[232:235], v[236:237] offset:512
	s_nop 0
	flat_load_dwordx4 v[236:239], v[236:237] offset:528
	s_lshl_b32 s16, s54, 1
	v_lshlrev_b64 v[160:161], 1, v[160:161]
	v_lshl_add_u64 v[244:245], v[244:245], 0, s[16:17]
	v_lshl_add_u64 v[246:247], v[246:247], 0, s[8:9]
	v_lshl_add_u64 v[244:245], v[244:245], 0, v[160:161]
	s_and_b64 vcc, exec, s[6:7]
	s_mov_b64 s[6:7], -1
	s_waitcnt vmcnt(0) lgkmcnt(0)
	v_pk_fma_f32 v[126:127], v[126:127], v[142:143], v[174:175]
	v_pk_fma_f32 v[124:125], v[124:125], v[140:141], v[172:173]
	v_pk_fma_f32 v[122:123], v[122:123], v[138:139], v[178:179]
	v_pk_fma_f32 v[120:121], v[120:121], v[136:137], v[176:177]
	v_pk_fma_f32 v[108:109], v[108:109], v[132:133], v[180:181]
	v_pk_fma_f32 v[110:111], v[110:111], v[134:135], v[182:183]
	v_pk_fma_f32 v[172:173], v[106:107], v[130:131], v[186:187]
	v_pk_fma_f32 v[174:175], v[104:105], v[128:129], v[184:185]
	v_cvt_pk_bf16_f32 v104, v124, v125
	v_cvt_pk_bf16_f32 v105, v126, v127
	v_cvt_pk_bf16_f32 v106, v120, v121
	v_cvt_pk_bf16_f32 v107, v122, v123
	v_cvt_pk_bf16_f32 v108, v108, v109
	v_cvt_pk_bf16_f32 v109, v110, v111
	s_nop 0
	v_cvt_pk_bf16_f32 v110, v174, v175
	v_cvt_pk_bf16_f32 v111, v172, v173
	flat_store_dwordx4 v[244:245], v[104:107] sc1
	flat_store_dwordx4 v[244:245], v[108:111] offset:256 sc1
	v_pk_fma_f32 v[118:119], v[118:119], v[142:143], v[190:191]
	v_pk_fma_f32 v[116:117], v[116:117], v[140:141], v[188:189]
	v_lshl_add_u64 v[108:109], v[246:247], 0, s[16:17]
	v_cvt_pk_bf16_f32 v104, v116, v117
	v_cvt_pk_bf16_f32 v105, v118, v119
	v_lshl_add_u64 v[108:109], v[108:109], 0, v[160:161]
	v_pk_fma_f32 v[114:115], v[114:115], v[138:139], v[194:195]
	v_pk_fma_f32 v[112:113], v[112:113], v[136:137], v[192:193]
	v_cvt_pk_bf16_f32 v107, v114, v115
	v_pk_fma_f32 v[102:103], v[102:103], v[134:135], v[200:201]
	v_cvt_pk_bf16_f32 v106, v112, v113
	flat_store_dwordx4 v[108:109], v[104:107] sc1
	v_pk_fma_f32 v[100:101], v[100:101], v[132:133], v[198:199]
	v_pk_fma_f32 v[96:97], v[96:97], v[140:141], v[206:207]
	v_pk_fma_f32 v[104:105], v[94:95], v[130:131], v[204:205]
	v_pk_fma_f32 v[94:95], v[92:93], v[128:129], v[202:203]
	v_cvt_pk_bf16_f32 v92, v100, v101
	v_cvt_pk_bf16_f32 v93, v102, v103
	v_pk_fma_f32 v[86:87], v[86:87], v[134:135], v[216:217]
	v_cvt_pk_bf16_f32 v94, v94, v95
	v_cvt_pk_bf16_f32 v95, v104, v105
	flat_store_dwordx4 v[108:109], v[92:95] offset:256 sc1
	v_pk_fma_f32 v[84:85], v[84:85], v[132:133], v[214:215]
	v_pk_fma_f32 v[80:81], v[80:81], v[140:141], v[224:225]
	v_lshlrev_b64 v[92:93], 11, v[240:241]
	v_lshl_add_u64 v[92:93], s[12:13], 0, v[92:93]
	v_lshl_add_u64 v[92:93], v[92:93], 0, s[8:9]
	v_lshl_add_u64 v[92:93], v[92:93], 0, s[16:17]
	v_pk_fma_f32 v[94:95], v[98:99], v[142:143], v[208:209]
	v_pk_fma_f32 v[98:99], v[90:91], v[138:139], v[212:213]
	v_pk_fma_f32 v[90:91], v[88:89], v[136:137], v[210:211]
	v_cvt_pk_bf16_f32 v88, v96, v97
	v_cvt_pk_bf16_f32 v89, v94, v95
	v_lshl_add_u64 v[92:93], v[92:93], 0, v[160:161]
	v_cvt_pk_bf16_f32 v90, v90, v91
	v_cvt_pk_bf16_f32 v91, v98, v99
	flat_store_dwordx4 v[92:93], v[88:91] sc1
	v_add_u32_e32 v172, 0x80, v164
	v_pk_fma_f32 v[70:71], v[70:71], v[134:135], v[234:235]
	v_pk_fma_f32 v[88:89], v[78:79], v[130:131], v[220:221]
	v_pk_fma_f32 v[78:79], v[76:77], v[128:129], v[218:219]
	v_cvt_pk_bf16_f32 v76, v84, v85
	v_cvt_pk_bf16_f32 v77, v86, v87
	v_pk_fma_f32 v[68:69], v[68:69], v[132:133], v[232:233]
	v_cvt_pk_bf16_f32 v78, v78, v79
	v_cvt_pk_bf16_f32 v79, v88, v89
	flat_store_dwordx4 v[92:93], v[76:79] offset:256 sc1
	v_ashrrev_i32_e32 v173, 31, v172
	v_add_u32_e32 v174, 0x90, v164
	v_lshlrev_b64 v[76:77], 11, v[242:243]
	v_lshl_add_u64 v[76:77], s[12:13], 0, v[76:77]
	v_lshl_add_u64 v[76:77], v[76:77], 0, s[8:9]
	v_lshl_add_u64 v[76:77], v[76:77], 0, s[16:17]
	v_pk_fma_f32 v[78:79], v[82:83], v[142:143], v[226:227]
	v_pk_fma_f32 v[82:83], v[74:75], v[138:139], v[230:231]
	v_pk_fma_f32 v[74:75], v[72:73], v[136:137], v[228:229]
	v_cvt_pk_bf16_f32 v72, v80, v81
	v_cvt_pk_bf16_f32 v73, v78, v79
	v_lshl_add_u64 v[76:77], v[76:77], 0, v[160:161]
	v_cvt_pk_bf16_f32 v74, v74, v75
	v_cvt_pk_bf16_f32 v75, v82, v83
	flat_store_dwordx4 v[76:77], v[72:75] sc1
	v_ashrrev_i32_e32 v175, 31, v174
	v_lshlrev_b64 v[80:81], 12, v[174:175]
	v_pk_fma_f32 v[72:73], v[66:67], v[130:131], v[238:239]
	v_pk_fma_f32 v[66:67], v[64:65], v[128:129], v[236:237]
	v_cvt_pk_bf16_f32 v64, v68, v69
	v_cvt_pk_bf16_f32 v65, v70, v71
	v_lshl_add_u64 v[92:93], v[162:163], 0, v[80:81]
	v_cvt_pk_bf16_f32 v66, v66, v67
	v_cvt_pk_bf16_f32 v67, v72, v73
	flat_store_dwordx4 v[76:77], v[64:67] offset:256 sc1
	v_add_u32_e32 v176, 0xa0, v164
	v_ashrrev_i32_e32 v177, 31, v176
	v_lshlrev_b64 v[64:65], 12, v[172:173]
	v_lshl_add_u64 v[76:77], v[162:163], 0, v[64:65]
	flat_load_dwordx4 v[64:67], v[76:77]
	flat_load_dwordx4 v[68:71], v[76:77] offset:16
	flat_load_dwordx4 v[72:75], v[76:77] offset:512
	s_nop 0
	flat_load_dwordx4 v[76:79], v[76:77] offset:528
	s_nop 0
	flat_load_dwordx4 v[80:83], v[92:93]
	flat_load_dwordx4 v[84:87], v[92:93] offset:16
	flat_load_dwordx4 v[88:91], v[92:93] offset:512
	s_nop 0
	flat_load_dwordx4 v[92:95], v[92:93] offset:528
	v_lshlrev_b64 v[96:97], 12, v[176:177]
	v_lshl_add_u64 v[108:109], v[162:163], 0, v[96:97]
	flat_load_dwordx4 v[96:99], v[108:109]
	flat_load_dwordx4 v[100:103], v[108:109] offset:16
	flat_load_dwordx4 v[104:107], v[108:109] offset:512
	s_nop 0
	flat_load_dwordx4 v[108:111], v[108:109] offset:528
	v_add_u32_e32 v164, 0xb0, v164
	v_ashrrev_i32_e32 v165, 31, v164
	v_lshlrev_b64 v[112:113], 12, v[164:165]
	v_lshl_add_u64 v[124:125], v[162:163], 0, v[112:113]
	flat_load_dwordx4 v[112:115], v[124:125]
	flat_load_dwordx4 v[116:119], v[124:125] offset:16
	flat_load_dwordx4 v[120:123], v[124:125] offset:512
	s_nop 0
	flat_load_dwordx4 v[124:127], v[124:125] offset:528
	v_lshlrev_b64 v[162:163], 11, v[172:173]
	s_waitcnt vmcnt(0) lgkmcnt(0)
	v_pk_fma_f32 v[60:61], v[60:61], v[140:141], v[64:65]
	v_pk_fma_f32 v[64:65], v[58:59], v[138:139], v[70:71]
	v_pk_fma_f32 v[58:59], v[56:57], v[136:137], v[68:69]
	v_cvt_pk_bf16_f32 v56, v60, v61
	v_lshl_add_u64 v[60:61], s[12:13], 0, v[162:163]
	v_lshl_add_u64 v[60:61], v[60:61], 0, s[8:9]
	v_lshl_add_u64 v[60:61], v[60:61], 0, s[16:17]
	v_pk_fma_f32 v[62:63], v[62:63], v[142:143], v[66:67]
	v_lshl_add_u64 v[60:61], v[60:61], 0, v[160:161]
	v_cvt_pk_bf16_f32 v57, v62, v63
	v_cvt_pk_bf16_f32 v58, v58, v59
	v_cvt_pk_bf16_f32 v59, v64, v65
	flat_store_dwordx4 v[60:61], v[56:59] sc1
	v_pk_fma_f32 v[54:55], v[54:55], v[134:135], v[74:75]
	v_pk_fma_f32 v[52:53], v[52:53], v[132:133], v[72:73]
	v_pk_fma_f32 v[56:57], v[46:47], v[130:131], v[78:79]
	v_pk_fma_f32 v[46:47], v[44:45], v[128:129], v[76:77]
	v_cvt_pk_bf16_f32 v44, v52, v53
	v_cvt_pk_bf16_f32 v45, v54, v55
	v_pk_fma_f32 v[48:49], v[48:49], v[140:141], v[80:81]
	v_cvt_pk_bf16_f32 v46, v46, v47
	v_cvt_pk_bf16_f32 v47, v56, v57
	flat_store_dwordx4 v[60:61], v[44:47] offset:256 sc1
	v_pk_fma_f32 v[38:39], v[38:39], v[134:135], v[90:91]
	v_pk_fma_f32 v[36:37], v[36:37], v[132:133], v[88:89]
	v_lshlrev_b64 v[44:45], 11, v[174:175]
	v_lshl_add_u64 v[44:45], s[12:13], 0, v[44:45]
	v_lshl_add_u64 v[44:45], v[44:45], 0, s[8:9]
	v_lshl_add_u64 v[44:45], v[44:45], 0, s[16:17]
	v_pk_fma_f32 v[46:47], v[50:51], v[142:143], v[82:83]
	v_pk_fma_f32 v[50:51], v[42:43], v[138:139], v[86:87]
	v_pk_fma_f32 v[42:43], v[40:41], v[136:137], v[84:85]
	v_cvt_pk_bf16_f32 v40, v48, v49
	v_cvt_pk_bf16_f32 v41, v46, v47
	v_lshl_add_u64 v[44:45], v[44:45], 0, v[160:161]
	v_cvt_pk_bf16_f32 v42, v42, v43
	v_cvt_pk_bf16_f32 v43, v50, v51
	flat_store_dwordx4 v[44:45], v[40:43] sc1
	v_pk_fma_f32 v[32:33], v[32:33], v[140:141], v[96:97]
	v_pk_fma_f32 v[22:23], v[22:23], v[134:135], v[106:107]
	v_pk_fma_f32 v[40:41], v[30:31], v[130:131], v[94:95]
	v_pk_fma_f32 v[30:31], v[28:29], v[128:129], v[92:93]
	v_cvt_pk_bf16_f32 v28, v36, v37
	v_cvt_pk_bf16_f32 v29, v38, v39
	v_pk_fma_f32 v[20:21], v[20:21], v[132:133], v[104:105]
	v_cvt_pk_bf16_f32 v30, v30, v31
	v_cvt_pk_bf16_f32 v31, v40, v41
	flat_store_dwordx4 v[44:45], v[28:31] offset:256 sc1
	v_pk_fma_f32 v[16:17], v[16:17], v[140:141], v[112:113]
	v_pk_fma_f32 v[6:7], v[6:7], v[134:135], v[122:123]
	v_lshlrev_b64 v[28:29], 11, v[176:177]
	v_lshl_add_u64 v[28:29], s[12:13], 0, v[28:29]
	v_lshl_add_u64 v[28:29], v[28:29], 0, s[8:9]
	v_lshl_add_u64 v[28:29], v[28:29], 0, s[16:17]
	v_pk_fma_f32 v[30:31], v[34:35], v[142:143], v[98:99]
	v_pk_fma_f32 v[34:35], v[26:27], v[138:139], v[102:103]
	v_pk_fma_f32 v[26:27], v[24:25], v[136:137], v[100:101]
	v_cvt_pk_bf16_f32 v24, v32, v33
	v_cvt_pk_bf16_f32 v25, v30, v31
	v_lshl_add_u64 v[28:29], v[28:29], 0, v[160:161]
	v_cvt_pk_bf16_f32 v26, v26, v27
	v_cvt_pk_bf16_f32 v27, v34, v35
	flat_store_dwordx4 v[28:29], v[24:27] sc1
	v_pk_fma_f32 v[4:5], v[4:5], v[132:133], v[120:121]
	s_nop 0
	v_pk_fma_f32 v[24:25], v[14:15], v[130:131], v[110:111]
	v_pk_fma_f32 v[14:15], v[12:13], v[128:129], v[108:109]
	v_cvt_pk_bf16_f32 v12, v20, v21
	v_cvt_pk_bf16_f32 v13, v22, v23
	s_nop 0
	v_cvt_pk_bf16_f32 v14, v14, v15
	v_cvt_pk_bf16_f32 v15, v24, v25
	flat_store_dwordx4 v[28:29], v[12:15] offset:256 sc1
	s_nop 1
	v_lshlrev_b64 v[12:13], 11, v[164:165]
	v_lshl_add_u64 v[12:13], s[12:13], 0, v[12:13]
	v_lshl_add_u64 v[12:13], v[12:13], 0, s[8:9]
	v_lshl_add_u64 v[12:13], v[12:13], 0, s[16:17]
	v_pk_fma_f32 v[14:15], v[18:19], v[142:143], v[114:115]
	v_pk_fma_f32 v[18:19], v[10:11], v[138:139], v[118:119]
	v_pk_fma_f32 v[10:11], v[8:9], v[136:137], v[116:117]
	v_cvt_pk_bf16_f32 v8, v16, v17
	v_cvt_pk_bf16_f32 v9, v14, v15
	v_lshl_add_u64 v[12:13], v[12:13], 0, v[160:161]
	v_cvt_pk_bf16_f32 v10, v10, v11
	v_cvt_pk_bf16_f32 v11, v18, v19
	flat_store_dwordx4 v[12:13], v[8:11] sc1
	s_nop 1
	v_pk_fma_f32 v[8:9], v[2:3], v[130:131], v[126:127]
	v_pk_fma_f32 v[2:3], v[0:1], v[128:129], v[124:125]
	v_cvt_pk_bf16_f32 v0, v4, v5
	v_cvt_pk_bf16_f32 v1, v6, v7
	s_nop 0
	v_cvt_pk_bf16_f32 v2, v2, v3
	v_cvt_pk_bf16_f32 v3, v8, v9
	flat_store_dwordx4 v[12:13], v[0:3] offset:256 sc1
	s_cbranch_vccnz .LBB0_744
	s_andn2_b64 vcc, exec, s[18:19]
	s_cbranch_vccnz .LBB0_743
	s_barrier
	s_branch .LBB0_743

.LBB0_817:
	v_lshl_add_u64 v[42:43], v[22:23], 0, s[14:15]
	flat_load_dwordx4 v[34:37], v[42:43]
	flat_load_dwordx4 v[38:41], v[42:43] offset:1024
	v_lshl_add_u64 v[58:59], v[20:21], 0, s[14:15]
	v_add_co_u32_e32 v60, vcc, s20, v58
	ds_read_b128 v[42:45], v24 offset:2048
	ds_read_b128 v[46:49], v24 offset:2064
	ds_read_b128 v[50:53], v24 offset:6144
	ds_read_b128 v[54:57], v24 offset:6160
	v_addc_co_u32_e32 v61, vcc, 0, v59, vcc
	v_add_co_u32_e32 v58, vcc, 0x5201000, v58
	s_add_u32 s14, s14, 0x800
	s_nop 0
	v_addc_co_u32_e32 v59, vcc, 0, v59, vcc
	s_addc_u32 s15, s15, 0
	s_cmp_eq_u32 s14, 0x10000
	s_waitcnt vmcnt(0) lgkmcnt(0)
	v_and_b32_e32 v65, 0xffff0000, v36
	v_and_b32_e32 v64, 0xffff0000, v34
	v_lshlrev_b32_e32 v63, 16, v36
	v_lshlrev_b32_e32 v62, 16, v34
	v_lshlrev_b32_e32 v66, 16, v35
	v_and_b32_e32 v36, 0xffff0000, v35
	v_lshlrev_b32_e32 v35, 16, v38
	v_lshlrev_b32_e32 v34, 16, v40
	v_and_b32_e32 v69, 0xffff0000, v38
	v_and_b32_e32 v68, 0xffff0000, v40
	v_lshlrev_b32_e32 v70, 16, v41
	v_and_b32_e32 v38, 0xffff0000, v41
	v_pk_mul_f32 v[40:41], v[64:65], v[64:65]
	v_lshlrev_b32_e32 v67, 16, v37
	v_pk_mul_f32 v[72:73], v[68:69], v[68:69]
	v_pk_fma_f32 v[40:41], v[62:63], v[62:63], v[40:41]
	v_and_b32_e32 v37, 0xffff0000, v37
	v_lshlrev_b32_e32 v71, 16, v39
	v_mov_b32_e32 v74, v62
	v_mov_b32_e32 v75, v64
	v_mov_b32_e32 v64, v63
	v_pk_fma_f32 v[62:63], v[34:35], v[34:35], v[72:73]
	v_pk_fma_f32 v[40:41], v[66:67], v[66:67], v[40:41]
	v_and_b32_e32 v39, 0xffff0000, v39
	v_pk_fma_f32 v[62:63], v[70:71], v[70:71], v[62:63]
	v_pk_fma_f32 v[40:41], v[36:37], v[36:37], v[40:41]
	v_mov_b32_e32 v80, v71
	v_mov_b32_e32 v81, v39
	v_mov_b32_e32 v71, v38
	v_pk_fma_f32 v[38:39], v[38:39], v[38:39], v[62:63]
	v_add_f32_e32 v16, v40, v41
	v_add_f32_e32 v16, v16, v39
	v_add_f32_e32 v16, v38, v16
	ds_bpermute_b32 v38, v25, v16
	v_mov_b32_e32 v77, v36
	v_mov_b32_e32 v36, v67
	v_mov_b32_e32 v76, v66
	v_mov_b32_e32 v78, v35
	s_waitcnt lgkmcnt(0)
	v_add_f32_e32 v16, v16, v38
	ds_bpermute_b32 v38, v26, v16
	v_mov_b32_e32 v35, v68
	v_mov_b32_e32 v79, v69
	s_waitcnt lgkmcnt(0)
	v_add_f32_e32 v16, v16, v38
	ds_bpermute_b32 v38, v27, v16
	s_waitcnt lgkmcnt(0)
	v_add_f32_e32 v16, v16, v38
	ds_bpermute_b32 v38, v28, v16
	s_waitcnt lgkmcnt(0)
	v_add_f32_e32 v16, v16, v38
	ds_bpermute_b32 v38, v29, v16
	s_waitcnt lgkmcnt(0)
	v_add_f32_e32 v16, v16, v38
	ds_bpermute_b32 v38, v30, v16
	s_waitcnt lgkmcnt(0)
	v_add_f32_e32 v16, v16, v38
	v_fmamk_f32 v16, v16, 0x3a800000, v33
	v_mul_f32_e32 v38, 0x4b800000, v16
	v_cmp_gt_f32_e32 vcc, s19, v16
	s_nop 1
	v_cndmask_b32_e32 v16, v16, v38, vcc
	v_rsq_f32_e32 v16, v16
	s_nop 0
	v_mul_f32_e32 v38, 0x45800000, v16
	v_cndmask_b32_e32 v16, v16, v38, vcc
	v_pk_mul_f32 v[62:63], v[64:65], v[16:17] op_sel_hi:[1,0]
	v_pk_mul_f32 v[36:37], v[36:37], v[16:17] op_sel_hi:[1,0]
	v_pk_mul_f32 v[38:39], v[74:75], v[16:17] op_sel_hi:[1,0]
	v_pk_mul_f32 v[40:41], v[76:77], v[16:17] op_sel_hi:[1,0]
	v_pk_mul_f32 v[34:35], v[34:35], v[16:17] op_sel_hi:[1,0]
	v_pk_mul_f32 v[68:69], v[70:71], v[16:17] op_sel_hi:[1,0]
	v_pk_fma_f32 v[70:71], v[6:7], v[36:37], v[14:15]
	v_pk_fma_f32 v[36:37], v[4:5], v[62:63], v[12:13]
	v_pk_mul_f32 v[64:65], v[78:79], v[16:17] op_sel_hi:[1,0]
	v_pk_mul_f32 v[66:67], v[80:81], v[16:17] op_sel_hi:[1,0]
	v_pk_fma_f32 v[40:41], v[2:3], v[40:41], v[10:11]
	v_pk_fma_f32 v[38:39], v[0:1], v[38:39], v[8:9]
	v_pk_fma_f32 v[46:47], v[46:47], v[34:35], v[54:55]
	v_cvt_pk_bf16_f32 v34, v38, v39
	v_cvt_pk_bf16_f32 v35, v40, v41
	v_cvt_pk_bf16_f32 v36, v36, v37
	v_cvt_pk_bf16_f32 v37, v70, v71
	v_pk_fma_f32 v[44:45], v[44:45], v[66:67], v[52:53]
	v_pk_fma_f32 v[42:43], v[42:43], v[64:65], v[50:51]
	v_pk_fma_f32 v[48:49], v[48:49], v[68:69], v[56:57]
	v_cvt_pk_bf16_f32 v38, v42, v43
	v_cvt_pk_bf16_f32 v39, v44, v45
	v_cvt_pk_bf16_f32 v40, v46, v47
	s_nop 0
	v_cvt_pk_bf16_f32 v41, v48, v49
	flat_store_dwordx4 v[60:61], v[34:37] offset:3584 sc1
	flat_store_dwordx4 v[58:59], v[38:41] offset:512 sc1
	s_cbranch_scc0 .LBB0_817
	s_add_i32 s21, s21, s38
	v_lshl_add_u64 v[20:21], v[20:21], 0, s[10:11]
	s_cmpk_gt_i32 s21, 0xff
	v_lshl_add_u64 v[22:23], v[22:23], 0, s[10:11]
	s_cbranch_scc0 .LBB0_810

.LBB0_878:
	s_lshl_b32 s4, s62, 8
	s_add_i32 s5, s4, 0xfffff500
	s_cmp_lt_i32 s62, 11
	s_cselect_b32 s19, s60, 0x23200e00
	s_cselect_b32 s21, s4, s5
	s_add_u32 s4, s10, s19
	s_addc_u32 s5, s11, 0
	s_lshl_b32 s19, s26, 8
	v_mov_b32_e32 v144, v146
	v_mov_b32_e32 v145, v147
	s_add_i32 s19, s19, s54
	v_cvt_pk_bf16_f32 v68, v68, v69
	v_cvt_pk_bf16_f32 v69, v70, v71
	v_cvt_pk_bf16_f32 v70, v64, v65
	v_cvt_pk_bf16_f32 v124, v124, v125
	v_cvt_pk_bf16_f32 v125, v126, v127
	s_nop 0
	v_add_u32_e32 v156, s19, v144
	s_or_b32 s19, s21, s55
	v_lshl_add_u32 v152, v145, 3, s19
	v_mov_b64_e32 v[144:145], s[4:5]
	v_ashrrev_i32_e32 v153, 31, v152
	v_add_u32_e32 v64, 0x80, v156
	v_mad_i64_i32 v[154:155], s[4:5], v156, s61, v[144:145]
	v_cvt_pk_bf16_f32 v126, v120, v121
	v_lshlrev_b64 v[120:121], 1, v[152:153]
	v_mad_i64_i32 v[64:65], s[4:5], v64, s61, v[144:145]
	v_cvt_pk_bf16_f32 v127, v122, v123
	v_lshl_add_u64 v[122:123], v[154:155], 0, v[120:121]
	v_cvt_pk_bf16_f32 v112, v112, v113
	v_cvt_pk_bf16_f32 v113, v114, v115
	v_cvt_pk_bf16_f32 v114, v104, v105
	v_add_u32_e32 v104, 16, v156
	v_cvt_pk_bf16_f32 v60, v60, v61
	v_cvt_pk_bf16_f32 v61, v62, v63
	v_cvt_pk_bf16_f32 v62, v56, v57
	v_lshl_add_u64 v[56:57], v[64:65], 0, v[120:121]
	v_cvt_pk_bf16_f32 v48, v48, v49
	v_cvt_pk_bf16_f32 v49, v50, v51
	v_cvt_pk_bf16_f32 v50, v40, v41
	v_add_u32_e32 v40, 0x90, v156
	v_cvt_pk_bf16_f32 v115, v106, v107
	flat_store_dwordx4 v[122:123], v[112:115] offset:256 sc1
	v_cvt_pk_bf16_f32 v51, v42, v43
	flat_store_dwordx4 v[56:57], v[48:51] offset:256 sc1
	v_cvt_pk_bf16_f32 v106, v108, v109
	v_cvt_pk_bf16_f32 v96, v96, v97
	v_cvt_pk_bf16_f32 v97, v98, v99
	s_nop 0
	v_mad_i64_i32 v[112:113], s[4:5], v104, s61, v[144:145]
	v_mad_i64_i32 v[48:49], s[4:5], v40, s61, v[144:145]
	v_lshl_add_u64 v[108:109], v[112:113], 0, v[120:121]
	v_cvt_pk_bf16_f32 v98, v88, v89
	v_add_u32_e32 v88, 32, v156
	v_cvt_pk_bf16_f32 v42, v44, v45
	v_lshl_add_u64 v[44:45], v[48:49], 0, v[120:121]
	v_cvt_pk_bf16_f32 v32, v32, v33
	v_cvt_pk_bf16_f32 v33, v34, v35
	v_cvt_pk_bf16_f32 v34, v24, v25
	v_add_u32_e32 v24, 0xa0, v156
	v_cvt_pk_bf16_f32 v99, v90, v91
	flat_store_dwordx4 v[108:109], v[96:99] offset:256 sc1
	v_cvt_pk_bf16_f32 v35, v26, v27
	flat_store_dwordx4 v[44:45], v[32:35] offset:256 sc1
	v_cvt_pk_bf16_f32 v90, v92, v93
	v_cvt_pk_bf16_f32 v80, v80, v81
	v_cvt_pk_bf16_f32 v81, v82, v83
	s_nop 0
	v_mad_i64_i32 v[96:97], s[4:5], v88, s61, v[144:145]
	v_mad_i64_i32 v[32:33], s[4:5], v24, s61, v[144:145]
	v_lshl_add_u64 v[92:93], v[96:97], 0, v[120:121]
	v_cvt_pk_bf16_f32 v82, v72, v73
	v_add_u32_e32 v72, 48, v156
	v_cvt_pk_bf16_f32 v26, v28, v29
	v_lshl_add_u64 v[28:29], v[32:33], 0, v[120:121]
	v_cvt_pk_bf16_f32 v16, v16, v17
	v_cvt_pk_bf16_f32 v17, v18, v19
	v_cvt_pk_bf16_f32 v18, v8, v9
	v_add_u32_e32 v8, 0xb0, v156
	v_cvt_pk_bf16_f32 v83, v74, v75
	flat_store_dwordx4 v[92:93], v[80:83] offset:256 sc1
	v_cvt_pk_bf16_f32 v19, v10, v11
	flat_store_dwordx4 v[28:29], v[16:19] offset:256 sc1
	v_cvt_pk_bf16_f32 v74, v76, v77
	v_cvt_pk_bf16_f32 v10, v12, v13
	s_andn2_b64 vcc, exec, s[6:7]
	v_mad_i64_i32 v[80:81], s[4:5], v72, s61, v[144:145]
	v_mad_i64_i32 v[16:17], s[4:5], v8, s61, v[144:145]
	v_lshl_add_u64 v[76:77], v[80:81], 0, v[120:121]
	v_lshl_add_u64 v[12:13], v[16:17], 0, v[120:121]
	s_mov_b64 s[6:7], -1
	flat_store_dwordx4 v[122:123], v[124:127] sc1
	v_cvt_pk_bf16_f32 v104, v116, v117
	v_cvt_pk_bf16_f32 v105, v118, v119
	v_cvt_pk_bf16_f32 v107, v110, v111
	flat_store_dwordx4 v[108:109], v[104:107] sc1
	v_cvt_pk_bf16_f32 v88, v100, v101
	v_cvt_pk_bf16_f32 v89, v102, v103
	v_cvt_pk_bf16_f32 v91, v94, v95
	flat_store_dwordx4 v[92:93], v[88:91] sc1
	v_cvt_pk_bf16_f32 v72, v84, v85
	v_cvt_pk_bf16_f32 v73, v86, v87
	v_cvt_pk_bf16_f32 v75, v78, v79
	flat_store_dwordx4 v[76:77], v[72:75] sc1
	v_cvt_pk_bf16_f32 v71, v66, v67
	flat_store_dwordx4 v[76:77], v[68:71] offset:256 sc1
	v_cvt_pk_bf16_f32 v63, v58, v59
	flat_store_dwordx4 v[56:57], v[60:63] sc1
	v_cvt_pk_bf16_f32 v40, v52, v53
	v_cvt_pk_bf16_f32 v41, v54, v55
	v_cvt_pk_bf16_f32 v43, v46, v47
	flat_store_dwordx4 v[44:45], v[40:43] sc1
	v_cvt_pk_bf16_f32 v24, v36, v37
	v_cvt_pk_bf16_f32 v25, v38, v39
	v_cvt_pk_bf16_f32 v27, v30, v31
	flat_store_dwordx4 v[28:29], v[24:27] sc1
	v_cvt_pk_bf16_f32 v8, v20, v21
	v_cvt_pk_bf16_f32 v9, v22, v23
	v_cvt_pk_bf16_f32 v11, v14, v15
	flat_store_dwordx4 v[12:13], v[8:11] sc1
	v_cvt_pk_bf16_f32 v4, v4, v5
	v_cvt_pk_bf16_f32 v5, v6, v7
	v_cvt_pk_bf16_f32 v6, v0, v1
	v_cvt_pk_bf16_f32 v7, v2, v3
	flat_store_dwordx4 v[12:13], v[4:7] offset:256 sc1
	s_cbranch_vccnz .LBB0_871
	s_andn2_b64 vcc, exec, s[12:13]
	s_cbranch_vccnz .LBB0_870
	s_barrier
	s_branch .LBB0_870

.LBB0_949:
	s_or_b64 exec, exec, s[10:11]
	v_add_co_u32_e32 v86, vcc, s63, v128
	v_pk_mul_f32 v[94:95], v[6:7], v[76:77]
	s_nop 0
	v_addc_co_u32_e32 v87, vcc, 0, v129, vcc
	flat_load_dwordx2 v[88:89], v[86:87] offset:2560
	v_lshl_add_u64 v[178:179], v[116:117], 0, s[100:101]
	v_lshl_add_u64 v[180:181], v[110:111], 0, s[100:101]
	v_lshl_add_u64 v[182:183], v[100:101], 0, s[100:101]
	global_load_dwordx2 v[184:185], v[178:179], off offset:2560
	global_load_dwordx2 v[186:187], v[180:181], off offset:2560
	global_load_dwordx2 v[188:189], v[182:183], off offset:2560
	v_pk_mul_f32 v[96:97], v[4:5], v[72:73]
	v_lshlrev_b32_e32 v62, 16, v148
	v_and_b32_e32 v63, 0xffff0000, v148
	v_lshlrev_b32_e32 v64, 16, v149
	v_and_b32_e32 v65, 0xffff0000, v149
	v_pk_mul_f32 v[106:107], v[18:19], v[80:81]
	v_pk_mul_f32 v[108:109], v[16:17], v[78:79]
	v_pk_fma_f32 v[94:95], v[2:3], v[144:145], v[94:95]
	v_pk_fma_f32 v[96:97], v[0:1], v[142:143], v[96:97]
	v_lshlrev_b32_e32 v66, 16, v152
	v_and_b32_e32 v67, 0xffff0000, v152
	v_lshlrev_b32_e32 v68, 16, v153
	v_and_b32_e32 v69, 0xffff0000, v153
	v_lshlrev_b32_e32 v70, 16, v150
	v_and_b32_e32 v71, 0xffff0000, v150
	v_lshlrev_b32_e32 v74, 16, v151
	v_and_b32_e32 v75, 0xffff0000, v151
	v_pk_mul_f32 v[148:149], v[30:31], v[84:85]
	v_pk_mul_f32 v[150:151], v[28:29], v[82:83]
	v_pk_fma_f32 v[106:107], v[14:15], v[136:137], v[106:107]
	v_pk_fma_f32 v[108:109], v[12:13], v[134:135], v[108:109]
	v_pk_fma_f32 v[94:95], v[10:11], v[64:65], v[94:95]
	v_pk_fma_f32 v[96:97], v[8:9], v[62:63], v[96:97]
	v_pk_fma_f32 v[142:143], v[26:27], v[126:127], v[148:149]
	v_pk_fma_f32 v[144:145], v[24:25], v[122:123], v[150:151]
	v_pk_fma_f32 v[106:107], v[22:23], v[68:69], v[106:107]
	v_pk_fma_f32 v[108:109], v[20:21], v[66:67], v[108:109]
	v_pk_add_f32 v[94:95], v[38:39], v[94:95]
	v_pk_add_f32 v[96:97], v[36:37], v[96:97]
	v_pk_fma_f32 v[142:143], v[34:35], v[74:75], v[142:143]
	v_pk_fma_f32 v[144:145], v[32:33], v[70:71], v[144:145]
	v_pk_add_f32 v[94:95], v[106:107], v[94:95]
	v_pk_add_f32 v[96:97], v[108:109], v[96:97]
	v_pk_add_f32 v[94:95], v[142:143], v[94:95]
	v_pk_add_f32 v[96:97], v[144:145], v[96:97]
	v_mov_b64_e32 v[128:129], s[28:29]
	v_pk_mul_f32 v[106:107], v[94:95], v[94:95]
	v_pk_mul_f32 v[108:109], v[96:97], v[96:97]
	v_pk_fma_f32 v[106:107], v[106:107], s[26:27], v[128:129] op_sel_hi:[1,0,0] neg_lo:[1,0,0] neg_hi:[1,0,0]
	v_pk_fma_f32 v[108:109], v[108:109], s[26:27], v[128:129] op_sel_hi:[1,0,0] neg_lo:[1,0,0] neg_hi:[1,0,0]
	v_pk_mul_f32 v[106:107], v[94:95], v[106:107]
	v_pk_mul_f32 v[108:109], v[96:97], v[108:109]
	v_exp_f32_e32 v106, v106
	v_exp_f32_e32 v108, v108
	v_exp_f32_e32 v109, v109
	v_exp_f32_e32 v107, v107
	v_add_co_u32_e32 v116, vcc, s63, v116
	v_pk_add_f32 v[108:109], v[108:109], 1.0 op_sel_hi:[1,0]
	v_pk_add_f32 v[106:107], v[106:107], 1.0 op_sel_hi:[1,0]
	v_rcp_f32_e32 v108, v108
	v_rcp_f32_e32 v109, v109
	v_rcp_f32_e32 v106, v106
	v_rcp_f32_e32 v107, v107
	v_addc_co_u32_e32 v117, vcc, 0, v117, vcc
	v_pk_mul_f32 v[96:97], v[96:97], v[108:109]
	v_pk_mul_f32 v[94:95], v[94:95], v[106:107]
	v_pk_mul_f32 v[108:109], v[18:19], v[84:85]
	v_pk_mul_f32 v[142:143], v[16:17], v[82:83]
	v_pk_mul_f32 v[144:145], v[30:31], v[92:93]
	v_pk_fma_f32 v[108:109], v[14:15], v[126:127], v[108:109]
	v_add_co_u32_e32 v110, vcc, s63, v110
	v_pk_fma_f32 v[108:109], v[22:23], v[74:75], v[108:109]
	s_nop 0
	v_addc_co_u32_e32 v111, vcc, 0, v111, vcc
	v_add_co_u32_e32 v100, vcc, s63, v100
	s_waitcnt vmcnt(0) lgkmcnt(0)
	v_mov_b64_e32 v[148:149], v[158:159]
	v_addc_co_u32_e32 v101, vcc, 0, v101, vcc
	v_mov_b64_e32 v[152:153], v[154:155]
	v_mov_b64_e32 v[150:151], v[156:157]
	v_lshlrev_b32_e32 v43, 16, v88
	v_and_b32_e32 v88, 0xffff0000, v88
	v_lshlrev_b32_e32 v106, 16, v89
	v_and_b32_e32 v89, 0xffff0000, v89
	v_mul_f32_e32 v88, v97, v88
	v_mul_f32_e32 v89, v95, v89
	v_mul_f32_e32 v43, v96, v43
	v_mul_f32_e32 v94, v94, v106
	v_cvt_pk_bf16_f32 v88, v43, v88
	v_cvt_pk_bf16_f32 v89, v94, v89
	flat_store_dwordx2 v[86:87], v[88:89] offset:2560 sc1
	s_nop 1
	v_mov_b64_e32 v[94:95], v[184:185]
	v_pk_mul_f32 v[96:97], v[6:7], v[80:81]
	v_pk_mul_f32 v[106:107], v[4:5], v[78:79]
	v_pk_fma_f32 v[96:97], v[2:3], v[136:137], v[96:97]
	v_pk_fma_f32 v[106:107], v[0:1], v[134:135], v[106:107]
	v_lshlrev_b32_e32 v86, 16, v146
	v_and_b32_e32 v87, 0xffff0000, v146
	v_lshlrev_b32_e32 v88, 16, v147
	v_and_b32_e32 v89, 0xffff0000, v147
	v_pk_mul_f32 v[146:147], v[28:29], v[90:91]
	v_pk_fma_f32 v[134:135], v[12:13], v[122:123], v[142:143]
	v_pk_fma_f32 v[96:97], v[10:11], v[68:69], v[96:97]
	v_pk_fma_f32 v[106:107], v[8:9], v[66:67], v[106:107]
	v_pk_fma_f32 v[136:137], v[26:27], v[120:121], v[144:145]
	v_pk_fma_f32 v[142:143], v[24:25], v[118:119], v[146:147]
	v_pk_fma_f32 v[134:135], v[20:21], v[70:71], v[134:135]
	v_pk_add_f32 v[96:97], v[38:39], v[96:97]
	v_pk_add_f32 v[106:107], v[36:37], v[106:107]
	v_pk_fma_f32 v[136:137], v[34:35], v[88:89], v[136:137]
	v_pk_fma_f32 v[142:143], v[32:33], v[86:87], v[142:143]
	v_pk_add_f32 v[96:97], v[108:109], v[96:97]
	v_pk_add_f32 v[106:107], v[134:135], v[106:107]
	v_pk_add_f32 v[96:97], v[136:137], v[96:97]
	v_pk_add_f32 v[106:107], v[142:143], v[106:107]
	v_pk_mul_f32 v[108:109], v[96:97], v[96:97]
	v_pk_mul_f32 v[134:135], v[106:107], v[106:107]
	v_pk_fma_f32 v[108:109], v[108:109], s[26:27], v[128:129] op_sel_hi:[1,0,0] neg_lo:[1,0,0] neg_hi:[1,0,0]
	v_pk_fma_f32 v[134:135], v[134:135], s[26:27], v[128:129] op_sel_hi:[1,0,0] neg_lo:[1,0,0] neg_hi:[1,0,0]
	v_pk_mul_f32 v[108:109], v[96:97], v[108:109]
	v_pk_mul_f32 v[134:135], v[106:107], v[134:135]
	v_exp_f32_e32 v108, v108
	v_exp_f32_e32 v134, v134
	v_exp_f32_e32 v135, v135
	v_exp_f32_e32 v109, v109
	v_pk_mul_f32 v[136:137], v[30:31], v[102:103]
	v_pk_mul_f32 v[142:143], v[28:29], v[98:99]
	v_pk_add_f32 v[134:135], v[134:135], 1.0 op_sel_hi:[1,0]
	v_pk_add_f32 v[108:109], v[108:109], 1.0 op_sel_hi:[1,0]
	v_rcp_f32_e32 v134, v134
	v_rcp_f32_e32 v135, v135
	v_rcp_f32_e32 v108, v108
	v_rcp_f32_e32 v109, v109
	v_mov_b64_e32 v[146:147], v[160:161]
	v_pk_mul_f32 v[106:107], v[106:107], v[134:135]
	v_pk_mul_f32 v[134:135], v[16:17], v[90:91]
	v_pk_mul_f32 v[96:97], v[96:97], v[108:109]
	s_nop 0
	v_lshlrev_b32_e32 v43, 16, v94
	v_and_b32_e32 v94, 0xffff0000, v94
	v_lshlrev_b32_e32 v108, 16, v95
	v_and_b32_e32 v95, 0xffff0000, v95
	v_mul_f32_e32 v94, v107, v94
	v_mul_f32_e32 v95, v97, v95
	v_mul_f32_e32 v43, v106, v43
	v_mul_f32_e32 v96, v96, v108
	v_cvt_pk_bf16_f32 v94, v43, v94
	v_cvt_pk_bf16_f32 v95, v96, v95
	flat_store_dwordx2 v[116:117], v[94:95] offset:2560 sc1
	s_nop 1
	v_mov_b64_e32 v[106:107], v[186:187]
	v_pk_mul_f32 v[108:109], v[6:7], v[84:85]
	v_pk_mul_f32 v[116:117], v[4:5], v[82:83]
	v_lshlrev_b32_e32 v94, 16, v124
	v_and_b32_e32 v95, 0xffff0000, v124
	v_lshlrev_b32_e32 v96, 16, v125
	v_and_b32_e32 v97, 0xffff0000, v125
	v_pk_mul_f32 v[124:125], v[18:19], v[92:93]
	v_pk_fma_f32 v[108:109], v[2:3], v[126:127], v[108:109]
	v_pk_fma_f32 v[116:117], v[0:1], v[122:123], v[116:117]
	v_pk_fma_f32 v[122:123], v[14:15], v[120:121], v[124:125]
	v_pk_fma_f32 v[124:125], v[12:13], v[118:119], v[134:135]
	v_pk_fma_f32 v[108:109], v[10:11], v[74:75], v[108:109]
	v_pk_fma_f32 v[116:117], v[8:9], v[70:71], v[116:117]
	v_pk_fma_f32 v[126:127], v[26:27], v[132:133], v[136:137]
	v_pk_fma_f32 v[134:135], v[24:25], v[130:131], v[142:143]
	v_pk_fma_f32 v[122:123], v[22:23], v[88:89], v[122:123]
	v_pk_fma_f32 v[124:125], v[20:21], v[86:87], v[124:125]
	v_pk_add_f32 v[108:109], v[38:39], v[108:109]
	v_pk_add_f32 v[116:117], v[36:37], v[116:117]
	v_pk_fma_f32 v[126:127], v[34:35], v[96:97], v[126:127]
	v_pk_fma_f32 v[134:135], v[32:33], v[94:95], v[134:135]
	v_pk_add_f32 v[108:109], v[122:123], v[108:109]
	v_pk_add_f32 v[116:117], v[124:125], v[116:117]
	v_pk_add_f32 v[108:109], v[126:127], v[108:109]
	v_pk_add_f32 v[116:117], v[134:135], v[116:117]
	v_pk_mul_f32 v[122:123], v[108:109], v[108:109]
	v_pk_mul_f32 v[124:125], v[116:117], v[116:117]
	v_pk_fma_f32 v[122:123], v[122:123], s[26:27], v[128:129] op_sel_hi:[1,0,0] neg_lo:[1,0,0] neg_hi:[1,0,0]
	v_pk_fma_f32 v[124:125], v[124:125], s[26:27], v[128:129] op_sel_hi:[1,0,0] neg_lo:[1,0,0] neg_hi:[1,0,0]
	v_pk_mul_f32 v[122:123], v[108:109], v[122:123]
	v_pk_mul_f32 v[124:125], v[116:117], v[124:125]
	v_exp_f32_e32 v122, v122
	v_exp_f32_e32 v124, v124
	v_exp_f32_e32 v125, v125
	v_exp_f32_e32 v123, v123
	v_pk_mul_f32 v[126:127], v[30:31], v[114:115]
	v_pk_mul_f32 v[134:135], v[28:29], v[112:113]
	v_pk_add_f32 v[124:125], v[124:125], 1.0 op_sel_hi:[1,0]
	v_pk_add_f32 v[122:123], v[122:123], 1.0 op_sel_hi:[1,0]
	v_rcp_f32_e32 v124, v124
	v_rcp_f32_e32 v125, v125
	v_rcp_f32_e32 v122, v122
	v_rcp_f32_e32 v123, v123
	v_pk_mul_f32 v[116:117], v[116:117], v[124:125]
	v_pk_mul_f32 v[124:125], v[16:17], v[98:99]
	v_pk_mul_f32 v[108:109], v[108:109], v[122:123]
	s_nop 0
	v_lshlrev_b32_e32 v43, 16, v106
	v_and_b32_e32 v106, 0xffff0000, v106
	v_lshlrev_b32_e32 v122, 16, v107
	v_and_b32_e32 v107, 0xffff0000, v107
	v_mul_f32_e32 v106, v117, v106
	v_mul_f32_e32 v107, v109, v107
	v_mul_f32_e32 v43, v116, v43
	v_mul_f32_e32 v108, v108, v122
	v_cvt_pk_bf16_f32 v106, v43, v106
	v_cvt_pk_bf16_f32 v107, v108, v107
	flat_store_dwordx2 v[110:111], v[106:107] offset:2560 sc1
	s_nop 1
	v_mov_b64_e32 v[110:111], v[188:189]
	v_lshlrev_b32_e32 v106, 16, v104
	v_and_b32_e32 v107, 0xffff0000, v104
	v_lshlrev_b32_e32 v108, 16, v105
	v_and_b32_e32 v109, 0xffff0000, v105
	v_pk_mul_f32 v[104:105], v[6:7], v[92:93]
	v_pk_mul_f32 v[116:117], v[4:5], v[90:91]
	v_pk_mul_f32 v[122:123], v[18:19], v[102:103]
	v_pk_fma_f32 v[104:105], v[2:3], v[120:121], v[104:105]
	v_pk_fma_f32 v[116:117], v[0:1], v[118:119], v[116:117]
	v_pk_fma_f32 v[118:119], v[14:15], v[132:133], v[122:123]
	v_pk_fma_f32 v[104:105], v[10:11], v[88:89], v[104:105]
	v_pk_fma_f32 v[120:121], v[12:13], v[130:131], v[124:125]
	v_pk_fma_f32 v[122:123], v[26:27], v[140:141], v[126:127]
	v_pk_fma_f32 v[116:117], v[8:9], v[86:87], v[116:117]
	v_pk_fma_f32 v[118:119], v[22:23], v[96:97], v[118:119]
	v_pk_add_f32 v[104:105], v[38:39], v[104:105]
	v_pk_fma_f32 v[124:125], v[24:25], v[138:139], v[134:135]
	v_pk_fma_f32 v[120:121], v[20:21], v[94:95], v[120:121]
	v_pk_fma_f32 v[122:123], v[34:35], v[108:109], v[122:123]
	v_pk_add_f32 v[116:117], v[36:37], v[116:117]
	v_pk_add_f32 v[104:105], v[118:119], v[104:105]
	v_pk_fma_f32 v[124:125], v[32:33], v[106:107], v[124:125]
	v_pk_add_f32 v[116:117], v[120:121], v[116:117]
	v_pk_add_f32 v[104:105], v[122:123], v[104:105]
	v_pk_add_f32 v[116:117], v[124:125], v[116:117]
	v_pk_mul_f32 v[118:119], v[104:105], v[104:105]
	v_pk_mul_f32 v[120:121], v[116:117], v[116:117]
	v_pk_fma_f32 v[118:119], v[118:119], s[26:27], v[128:129] op_sel_hi:[1,0,0] neg_lo:[1,0,0] neg_hi:[1,0,0]
	v_pk_fma_f32 v[120:121], v[120:121], s[26:27], v[128:129] op_sel_hi:[1,0,0] neg_lo:[1,0,0] neg_hi:[1,0,0]
	v_pk_mul_f32 v[118:119], v[104:105], v[118:119]
	v_pk_mul_f32 v[120:121], v[116:117], v[120:121]
	v_exp_f32_e32 v118, v118
	v_exp_f32_e32 v119, v119
	v_exp_f32_e32 v120, v120
	v_exp_f32_e32 v121, v121
	v_mov_b64_e32 v[124:125], v[162:163]
	v_pk_add_f32 v[118:119], v[118:119], 1.0 op_sel_hi:[1,0]
	v_pk_add_f32 v[120:121], v[120:121], 1.0 op_sel_hi:[1,0]
	v_rcp_f32_e32 v118, v118
	v_rcp_f32_e32 v119, v119
	v_rcp_f32_e32 v120, v120
	v_rcp_f32_e32 v121, v121
	v_pk_mul_f32 v[104:105], v[104:105], v[118:119]
	v_pk_mul_f32 v[116:117], v[116:117], v[120:121]
	s_nop 0
	v_lshlrev_b32_e32 v118, 16, v111
	v_and_b32_e32 v111, 0xffff0000, v111
	v_lshlrev_b32_e32 v43, 16, v110
	v_and_b32_e32 v110, 0xffff0000, v110
	v_mul_f32_e32 v105, v105, v111
	v_mul_f32_e32 v43, v116, v43
	v_mul_f32_e32 v110, v117, v110
	v_mul_f32_e32 v116, v104, v118
	v_cvt_pk_bf16_f32 v104, v43, v110
	v_cvt_pk_bf16_f32 v105, v116, v105
	flat_store_dwordx2 v[100:101], v[104:105] offset:2560 sc1
	v_mov_b64_e32 v[104:105], v[164:165]

.LBB0_959:
	s_or_b64 exec, exec, s[10:11]
	v_add_co_u32_e32 v130, vcc, s61, v128
	v_lshlrev_b32_e32 v142, 16, v118
	s_nop 0
	v_addc_co_u32_e32 v131, vcc, 0, v129, vcc
	flat_load_dwordx2 v[138:139], v[130:131] offset:3584
	v_lshl_add_u64 v[178:179], v[116:117], 0, s[98:99]
	v_lshl_add_u64 v[180:181], v[110:111], 0, s[98:99]
	v_lshl_add_u64 v[182:183], v[100:101], 0, s[98:99]
	global_load_dwordx2 v[184:185], v[178:179], off offset:3584
	global_load_dwordx2 v[186:187], v[180:181], off offset:3584
	global_load_dwordx2 v[188:189], v[182:183], off offset:3584
	v_and_b32_e32 v143, 0xffff0000, v118
	v_lshlrev_b32_e32 v144, 16, v119
	v_and_b32_e32 v145, 0xffff0000, v119
	v_pk_mul_f32 v[118:119], v[6:7], v[64:65]
	v_pk_mul_f32 v[156:157], v[4:5], v[62:63]
	v_pk_mul_f32 v[158:159], v[18:19], v[68:69]
	v_pk_fma_f32 v[118:119], v[2:3], v[76:77], v[118:119]
	v_lshlrev_b32_e32 v136, 16, v123
	v_and_b32_e32 v137, 0xffff0000, v123
	v_pk_mul_f32 v[160:161], v[16:17], v[66:67]
	v_pk_mul_f32 v[162:163], v[30:31], v[74:75]
	v_pk_fma_f32 v[156:157], v[0:1], v[72:73], v[156:157]
	v_pk_fma_f32 v[158:159], v[14:15], v[80:81], v[158:159]
	v_pk_fma_f32 v[118:119], v[10:11], v[144:145], v[118:119]
	v_lshlrev_b32_e32 v134, 16, v122
	v_and_b32_e32 v135, 0xffff0000, v122
	v_lshlrev_b32_e32 v122, 16, v126
	v_and_b32_e32 v123, 0xffff0000, v126
	v_lshlrev_b32_e32 v126, 16, v127
	v_and_b32_e32 v127, 0xffff0000, v127
	v_pk_mul_f32 v[164:165], v[28:29], v[70:71]
	v_pk_fma_f32 v[160:161], v[12:13], v[78:79], v[160:161]
	v_pk_fma_f32 v[162:163], v[26:27], v[84:85], v[162:163]
	v_pk_fma_f32 v[156:157], v[8:9], v[142:143], v[156:157]
	v_pk_fma_f32 v[158:159], v[22:23], v[136:137], v[158:159]
	v_pk_add_f32 v[118:119], v[38:39], v[118:119]
	v_pk_fma_f32 v[164:165], v[24:25], v[82:83], v[164:165]
	v_pk_fma_f32 v[160:161], v[20:21], v[134:135], v[160:161]
	v_pk_fma_f32 v[162:163], v[34:35], v[126:127], v[162:163]
	v_pk_add_f32 v[156:157], v[36:37], v[156:157]
	v_pk_add_f32 v[118:119], v[118:119], v[158:159]
	v_pk_fma_f32 v[164:165], v[32:33], v[122:123], v[164:165]
	v_pk_add_f32 v[156:157], v[156:157], v[160:161]
	v_pk_add_f32 v[118:119], v[118:119], v[162:163]
	v_mov_b64_e32 v[154:155], s[28:29]
	v_pk_add_f32 v[156:157], v[156:157], v[164:165]
	v_pk_mul_f32 v[158:159], v[118:119], v[118:119]
	v_pk_mul_f32 v[160:161], v[156:157], v[156:157]
	v_pk_fma_f32 v[158:159], v[158:159], s[26:27], v[154:155] op_sel_hi:[1,0,0] neg_lo:[1,0,0] neg_hi:[1,0,0]
	v_pk_fma_f32 v[160:161], v[160:161], s[26:27], v[154:155] op_sel_hi:[1,0,0] neg_lo:[1,0,0] neg_hi:[1,0,0]
	v_pk_mul_f32 v[158:159], v[118:119], v[158:159]
	v_pk_mul_f32 v[160:161], v[156:157], v[160:161]
	v_exp_f32_e32 v158, v158
	v_exp_f32_e32 v159, v159
	v_exp_f32_e32 v160, v160
	v_exp_f32_e32 v161, v161
	v_add_co_u32_e32 v162, vcc, s61, v116
	v_pk_add_f32 v[158:159], v[158:159], 1.0 op_sel_hi:[1,0]
	v_pk_add_f32 v[160:161], v[160:161], 1.0 op_sel_hi:[1,0]
	v_rcp_f32_e32 v158, v158
	v_rcp_f32_e32 v159, v159
	v_rcp_f32_e32 v160, v160
	v_rcp_f32_e32 v161, v161
	v_addc_co_u32_e32 v163, vcc, 0, v117, vcc
	v_pk_mul_f32 v[118:119], v[118:119], v[158:159]
	v_pk_mul_f32 v[156:157], v[156:157], v[160:161]
	v_pk_mul_f32 v[160:161], v[16:17], v[70:71]
	v_pk_mul_f32 v[164:165], v[30:31], v[88:89]
	v_pk_mul_f32 v[170:171], v[28:29], v[86:87]
	v_pk_fma_f32 v[160:161], v[12:13], v[82:83], v[160:161]
	v_pk_fma_f32 v[170:171], v[24:25], v[90:91], v[170:171]
	v_pk_fma_f32 v[164:165], v[26:27], v[92:93], v[164:165]
	v_pk_fma_f32 v[160:161], v[20:21], v[122:123], v[160:161]
	v_pk_mul_f32 v[172:173], v[28:29], v[94:95]
	v_pk_mul_f32 v[174:175], v[28:29], v[106:107]
	v_pk_fma_f32 v[172:173], v[24:25], v[98:99], v[172:173]
	v_pk_fma_f32 v[174:175], v[24:25], v[112:113], v[174:175]
	s_waitcnt vmcnt(0) lgkmcnt(0)
	v_lshlrev_b32_e32 v158, 16, v139
	v_and_b32_e32 v139, 0xffff0000, v139
	v_lshlrev_b32_e32 v43, 16, v138
	v_and_b32_e32 v138, 0xffff0000, v138
	v_mul_f32_e32 v119, v119, v139
	v_mul_f32_e32 v43, v156, v43
	v_mul_f32_e32 v138, v157, v138
	v_mul_f32_e32 v156, v118, v158
	v_cvt_pk_bf16_f32 v118, v43, v138
	v_cvt_pk_bf16_f32 v119, v156, v119
	flat_store_dwordx2 v[130:131], v[118:119] offset:3584 sc1
	s_nop 1
	v_mov_b64_e32 v[130:131], v[184:185]
	v_pk_mul_f32 v[138:139], v[6:7], v[68:69]
	v_pk_mul_f32 v[156:157], v[4:5], v[66:67]
	v_pk_mul_f32 v[158:159], v[18:19], v[74:75]
	v_pk_fma_f32 v[156:157], v[0:1], v[78:79], v[156:157]
	v_pk_fma_f32 v[138:139], v[2:3], v[80:81], v[138:139]
	v_pk_fma_f32 v[158:159], v[14:15], v[84:85], v[158:159]
	v_pk_fma_f32 v[138:139], v[10:11], v[136:137], v[138:139]
	v_pk_fma_f32 v[156:157], v[8:9], v[134:135], v[156:157]
	v_lshlrev_b32_e32 v118, 16, v120
	v_and_b32_e32 v119, 0xffff0000, v120
	v_lshlrev_b32_e32 v120, 16, v121
	v_and_b32_e32 v121, 0xffff0000, v121
	v_pk_fma_f32 v[158:159], v[22:23], v[126:127], v[158:159]
	v_pk_add_f32 v[156:157], v[36:37], v[156:157]
	v_pk_add_f32 v[138:139], v[38:39], v[138:139]
	v_pk_fma_f32 v[164:165], v[34:35], v[120:121], v[164:165]
	v_pk_fma_f32 v[170:171], v[32:33], v[118:119], v[170:171]
	v_pk_add_f32 v[138:139], v[138:139], v[158:159]
	v_pk_add_f32 v[156:157], v[156:157], v[160:161]
	v_pk_add_f32 v[138:139], v[138:139], v[164:165]
	v_pk_add_f32 v[156:157], v[156:157], v[170:171]
	v_pk_mul_f32 v[158:159], v[138:139], v[138:139]
	v_pk_mul_f32 v[160:161], v[156:157], v[156:157]
	v_pk_fma_f32 v[158:159], v[158:159], s[26:27], v[154:155] op_sel_hi:[1,0,0] neg_lo:[1,0,0] neg_hi:[1,0,0]
	v_pk_fma_f32 v[160:161], v[160:161], s[26:27], v[154:155] op_sel_hi:[1,0,0] neg_lo:[1,0,0] neg_hi:[1,0,0]
	v_pk_mul_f32 v[158:159], v[138:139], v[158:159]
	v_pk_mul_f32 v[160:161], v[156:157], v[160:161]
	v_exp_f32_e32 v158, v158
	v_exp_f32_e32 v160, v160
	v_exp_f32_e32 v161, v161
	v_exp_f32_e32 v159, v159
	v_add_co_u32_e32 v164, vcc, s61, v110
	v_pk_add_f32 v[160:161], v[160:161], 1.0 op_sel_hi:[1,0]
	v_pk_add_f32 v[158:159], v[158:159], 1.0 op_sel_hi:[1,0]
	v_rcp_f32_e32 v160, v160
	v_rcp_f32_e32 v161, v161
	v_rcp_f32_e32 v158, v158
	v_rcp_f32_e32 v159, v159
	v_addc_co_u32_e32 v165, vcc, 0, v111, vcc
	v_pk_mul_f32 v[156:157], v[156:157], v[160:161]
	v_pk_mul_f32 v[138:139], v[138:139], v[158:159]
	v_pk_mul_f32 v[160:161], v[18:19], v[88:89]
	v_pk_mul_f32 v[170:171], v[30:31], v[96:97]
	v_pk_fma_f32 v[160:161], v[14:15], v[92:93], v[160:161]
	v_pk_fma_f32 v[170:171], v[26:27], v[102:103], v[170:171]
	v_pk_fma_f32 v[160:161], v[22:23], v[120:121], v[160:161]
	s_nop 0
	v_lshlrev_b32_e32 v43, 16, v130
	v_and_b32_e32 v130, 0xffff0000, v130
	v_lshlrev_b32_e32 v158, 16, v131
	v_and_b32_e32 v131, 0xffff0000, v131
	v_mul_f32_e32 v130, v157, v130
	v_mul_f32_e32 v131, v139, v131
	v_mul_f32_e32 v43, v156, v43
	v_mul_f32_e32 v138, v138, v158
	v_cvt_pk_bf16_f32 v130, v43, v130
	v_cvt_pk_bf16_f32 v131, v138, v131
	flat_store_dwordx2 v[162:163], v[130:131] offset:3584 sc1
	s_nop 1
	v_mov_b64_e32 v[138:139], v[186:187]
	v_pk_mul_f32 v[156:157], v[6:7], v[74:75]
	v_pk_mul_f32 v[158:159], v[4:5], v[70:71]
	v_pk_mul_f32 v[162:163], v[16:17], v[86:87]
	v_pk_fma_f32 v[158:159], v[0:1], v[82:83], v[158:159]
	v_pk_fma_f32 v[156:157], v[2:3], v[84:85], v[156:157]
	v_pk_fma_f32 v[162:163], v[12:13], v[90:91], v[162:163]
	v_pk_fma_f32 v[156:157], v[10:11], v[126:127], v[156:157]
	v_pk_fma_f32 v[158:159], v[8:9], v[122:123], v[158:159]
	v_lshlrev_b32_e32 v130, 16, v132
	v_and_b32_e32 v131, 0xffff0000, v132
	v_lshlrev_b32_e32 v132, 16, v133
	v_and_b32_e32 v133, 0xffff0000, v133
	v_pk_fma_f32 v[162:163], v[20:21], v[118:119], v[162:163]
	v_pk_add_f32 v[158:159], v[36:37], v[158:159]
	v_pk_add_f32 v[156:157], v[38:39], v[156:157]
	v_pk_fma_f32 v[170:171], v[34:35], v[132:133], v[170:171]
	v_pk_fma_f32 v[172:173], v[32:33], v[130:131], v[172:173]
	v_pk_add_f32 v[156:157], v[156:157], v[160:161]
	v_pk_add_f32 v[158:159], v[158:159], v[162:163]
	v_pk_add_f32 v[156:157], v[156:157], v[170:171]
	v_pk_add_f32 v[158:159], v[158:159], v[172:173]
	v_pk_mul_f32 v[160:161], v[156:157], v[156:157]
	v_pk_mul_f32 v[162:163], v[158:159], v[158:159]
	v_pk_fma_f32 v[160:161], v[160:161], s[26:27], v[154:155] op_sel_hi:[1,0,0] neg_lo:[1,0,0] neg_hi:[1,0,0]
	v_pk_fma_f32 v[162:163], v[162:163], s[26:27], v[154:155] op_sel_hi:[1,0,0] neg_lo:[1,0,0] neg_hi:[1,0,0]
	v_pk_mul_f32 v[160:161], v[156:157], v[160:161]
	v_pk_mul_f32 v[162:163], v[158:159], v[162:163]
	v_exp_f32_e32 v160, v160
	v_exp_f32_e32 v162, v162
	v_exp_f32_e32 v163, v163
	v_exp_f32_e32 v161, v161
	v_add_co_u32_e32 v170, vcc, s61, v100
	v_pk_add_f32 v[162:163], v[162:163], 1.0 op_sel_hi:[1,0]
	v_pk_add_f32 v[160:161], v[160:161], 1.0 op_sel_hi:[1,0]
	v_rcp_f32_e32 v162, v162
	v_rcp_f32_e32 v163, v163
	v_rcp_f32_e32 v160, v160
	v_rcp_f32_e32 v161, v161
	v_addc_co_u32_e32 v171, vcc, 0, v101, vcc
	v_pk_mul_f32 v[158:159], v[158:159], v[162:163]
	v_pk_mul_f32 v[156:157], v[156:157], v[160:161]
	v_pk_mul_f32 v[162:163], v[18:19], v[96:97]
	v_pk_mul_f32 v[172:173], v[30:31], v[108:109]
	v_pk_fma_f32 v[162:163], v[14:15], v[102:103], v[162:163]
	v_pk_fma_f32 v[172:173], v[26:27], v[114:115], v[172:173]
	v_pk_fma_f32 v[162:163], v[22:23], v[132:133], v[162:163]
	s_nop 0
	v_lshlrev_b32_e32 v43, 16, v138
	v_and_b32_e32 v138, 0xffff0000, v138
	v_lshlrev_b32_e32 v160, 16, v139
	v_and_b32_e32 v139, 0xffff0000, v139
	v_mul_f32_e32 v138, v159, v138
	v_mul_f32_e32 v139, v157, v139
	v_mul_f32_e32 v43, v158, v43
	v_mul_f32_e32 v156, v156, v160
	v_cvt_pk_bf16_f32 v138, v43, v138
	v_cvt_pk_bf16_f32 v139, v156, v139
	flat_store_dwordx2 v[164:165], v[138:139] offset:3584 sc1
	s_nop 1
	v_mov_b64_e32 v[156:157], v[188:189]
	v_pk_mul_f32 v[158:159], v[6:7], v[88:89]
	v_pk_mul_f32 v[160:161], v[4:5], v[86:87]
	v_pk_mul_f32 v[164:165], v[16:17], v[94:95]
	v_pk_fma_f32 v[160:161], v[0:1], v[90:91], v[160:161]
	v_pk_fma_f32 v[158:159], v[2:3], v[92:93], v[158:159]
	v_pk_fma_f32 v[164:165], v[12:13], v[98:99], v[164:165]
	v_pk_fma_f32 v[158:159], v[10:11], v[120:121], v[158:159]
	v_pk_fma_f32 v[160:161], v[8:9], v[118:119], v[160:161]
	v_lshlrev_b32_e32 v138, 16, v140
	v_and_b32_e32 v139, 0xffff0000, v140
	v_lshlrev_b32_e32 v140, 16, v141
	v_and_b32_e32 v141, 0xffff0000, v141
	v_pk_fma_f32 v[164:165], v[20:21], v[130:131], v[164:165]
	v_pk_add_f32 v[160:161], v[36:37], v[160:161]
	v_pk_add_f32 v[158:159], v[38:39], v[158:159]
	v_pk_fma_f32 v[172:173], v[34:35], v[140:141], v[172:173]
	v_pk_fma_f32 v[174:175], v[32:33], v[138:139], v[174:175]
	v_pk_add_f32 v[158:159], v[158:159], v[162:163]
	v_pk_add_f32 v[160:161], v[160:161], v[164:165]
	v_pk_add_f32 v[158:159], v[158:159], v[172:173]
	v_pk_add_f32 v[160:161], v[160:161], v[174:175]
	v_pk_mul_f32 v[162:163], v[158:159], v[158:159]
	v_pk_mul_f32 v[164:165], v[160:161], v[160:161]
	v_add_u32_e32 v43, 1, v168
	v_pk_fma_f32 v[164:165], v[164:165], s[26:27], v[154:155] op_sel_hi:[1,0,0] neg_lo:[1,0,0] neg_hi:[1,0,0]
	v_pk_fma_f32 v[154:155], v[162:163], s[26:27], v[154:155] op_sel_hi:[1,0,0] neg_lo:[1,0,0] neg_hi:[1,0,0]
	v_pk_mul_f32 v[162:163], v[160:161], v[164:165]
	v_pk_mul_f32 v[154:155], v[158:159], v[154:155]
	v_exp_f32_e32 v162, v162
	v_exp_f32_e32 v154, v154
	v_exp_f32_e32 v155, v155
	v_exp_f32_e32 v163, v163
	v_cmp_lt_u32_e32 vcc, v43, v53
	v_pk_add_f32 v[154:155], v[154:155], 1.0 op_sel_hi:[1,0]
	v_pk_add_f32 v[162:163], v[162:163], 1.0 op_sel_hi:[1,0]
	v_rcp_f32_e32 v154, v154
	v_rcp_f32_e32 v155, v155
	v_rcp_f32_e32 v162, v162
	v_rcp_f32_e32 v163, v163
	v_pk_mul_f32 v[154:155], v[158:159], v[154:155]
	v_pk_mul_f32 v[160:161], v[160:161], v[162:163]
	s_nop 0
	v_lshlrev_b32_e32 v159, 16, v157
	v_and_b32_e32 v157, 0xffff0000, v157
	v_lshlrev_b32_e32 v158, 16, v156
	v_and_b32_e32 v156, 0xffff0000, v156
	v_mul_f32_e32 v155, v155, v157
	v_mul_f32_e32 v158, v160, v158
	v_mul_f32_e32 v156, v161, v156
	v_mul_f32_e32 v159, v154, v159
	v_cvt_pk_bf16_f32 v154, v158, v156
	v_cvt_pk_bf16_f32 v155, v159, v155
	flat_store_dwordx2 v[170:171], v[154:155] offset:3584 sc1
	s_and_saveexec_b64 s[36:37], vcc
	s_cbranch_execz .LBB0_969
	v_cmp_gt_u32_e64 s[10:11], 61, v168
	v_mov_b32_e32 v154, v42
	v_mov_b32_e32 v155, v42
	s_and_b64 s[4:5], s[6:7], s[10:11]
	v_mov_b64_e32 v[158:159], v[154:155]
	s_and_saveexec_b64 s[46:47], s[4:5]
	s_cbranch_execz .LBB0_962
	v_add_u32_e32 v43, s34, v52
	v_add_u32_e32 v72, 0xfffac200, v43
	v_mov_b32_e32 v73, v42
	v_lshl_add_u64 v[72:73], v[44:45], 0, v[72:73]
	flat_load_dwordx2 v[158:159], v[72:73]

.LBB0_968:
	s_or_b64 exec, exec, s[10:11]
	v_add_co_u32_e32 v90, vcc, s62, v128
	v_pk_mul_f32 v[98:99], v[2:3], v[64:65]
	s_nop 0
	v_addc_co_u32_e32 v91, vcc, 0, v129, vcc
	flat_load_dwordx2 v[92:93], v[90:91] offset:1024
	v_lshl_add_u64 v[178:179], v[116:117], 0, s[100:101]
	v_lshl_add_u64 v[180:181], v[110:111], 0, s[100:101]
	v_lshl_add_u64 v[182:183], v[100:101], 0, s[100:101]
	global_load_dwordx2 v[184:185], v[178:179], off offset:-3072
	global_load_dwordx2 v[186:187], v[180:181], off offset:-3072
	global_load_dwordx2 v[188:189], v[182:183], off offset:-3072
	v_pk_mul_f32 v[102:103], v[0:1], v[62:63]
	v_lshlrev_b32_e32 v72, 16, v148
	v_and_b32_e32 v73, 0xffff0000, v148
	v_lshlrev_b32_e32 v76, 16, v149
	v_and_b32_e32 v77, 0xffff0000, v149
	v_pk_mul_f32 v[112:113], v[14:15], v[68:69]
	v_pk_mul_f32 v[114:115], v[12:13], v[66:67]
	v_pk_fma_f32 v[98:99], v[6:7], v[144:145], v[98:99]
	v_pk_fma_f32 v[102:103], v[4:5], v[142:143], v[102:103]
	v_lshlrev_b32_e32 v78, 16, v152
	v_and_b32_e32 v79, 0xffff0000, v152
	v_lshlrev_b32_e32 v80, 16, v153
	v_and_b32_e32 v81, 0xffff0000, v153
	v_pk_mul_f32 v[148:149], v[26:27], v[74:75]
	v_pk_mul_f32 v[152:153], v[24:25], v[70:71]
	v_pk_fma_f32 v[112:113], v[18:19], v[136:137], v[112:113]
	v_pk_fma_f32 v[114:115], v[16:17], v[134:135], v[114:115]
	v_pk_fma_f32 v[98:99], v[10:11], v[76:77], v[98:99]
	v_pk_fma_f32 v[102:103], v[8:9], v[72:73], v[102:103]
	v_lshlrev_b32_e32 v82, 16, v150
	v_and_b32_e32 v83, 0xffff0000, v150
	v_lshlrev_b32_e32 v84, 16, v151
	v_and_b32_e32 v85, 0xffff0000, v151
	v_pk_fma_f32 v[148:149], v[30:31], v[126:127], v[148:149]
	v_pk_fma_f32 v[152:153], v[28:29], v[122:123], v[152:153]
	v_pk_fma_f32 v[112:113], v[22:23], v[80:81], v[112:113]
	v_pk_fma_f32 v[114:115], v[20:21], v[78:79], v[114:115]
	v_pk_add_f32 v[98:99], v[38:39], v[98:99]
	v_pk_add_f32 v[102:103], v[36:37], v[102:103]
	v_pk_fma_f32 v[148:149], v[34:35], v[84:85], v[148:149]
	v_pk_fma_f32 v[152:153], v[32:33], v[82:83], v[152:153]
	v_pk_add_f32 v[98:99], v[98:99], v[112:113]
	v_pk_add_f32 v[102:103], v[102:103], v[114:115]
	v_pk_add_f32 v[98:99], v[98:99], v[148:149]
	v_pk_add_f32 v[102:103], v[102:103], v[152:153]
	v_mov_b64_e32 v[150:151], s[28:29]
	v_pk_mul_f32 v[112:113], v[98:99], v[98:99]
	v_pk_mul_f32 v[114:115], v[102:103], v[102:103]
	v_pk_fma_f32 v[112:113], v[112:113], s[26:27], v[150:151] op_sel_hi:[1,0,0] neg_lo:[1,0,0] neg_hi:[1,0,0]
	v_pk_fma_f32 v[114:115], v[114:115], s[26:27], v[150:151] op_sel_hi:[1,0,0] neg_lo:[1,0,0] neg_hi:[1,0,0]
	v_pk_mul_f32 v[112:113], v[98:99], v[112:113]
	v_pk_mul_f32 v[114:115], v[102:103], v[114:115]
	v_exp_f32_e32 v112, v112
	v_exp_f32_e32 v114, v114
	v_exp_f32_e32 v115, v115
	v_exp_f32_e32 v113, v113
	v_add_co_u32_e32 v148, vcc, s62, v116
	v_pk_add_f32 v[114:115], v[114:115], 1.0 op_sel_hi:[1,0]
	v_pk_add_f32 v[112:113], v[112:113], 1.0 op_sel_hi:[1,0]
	v_rcp_f32_e32 v114, v114
	v_rcp_f32_e32 v115, v115
	v_rcp_f32_e32 v112, v112
	v_rcp_f32_e32 v113, v113
	v_addc_co_u32_e32 v149, vcc, 0, v117, vcc
	v_pk_mul_f32 v[102:103], v[102:103], v[114:115]
	v_pk_mul_f32 v[98:99], v[98:99], v[112:113]
	v_pk_mul_f32 v[114:115], v[14:15], v[74:75]
	v_pk_mul_f32 v[152:153], v[26:27], v[88:89]
	v_pk_mul_f32 v[170:171], v[24:25], v[86:87]
	v_pk_fma_f32 v[114:115], v[18:19], v[126:127], v[114:115]
	v_pk_fma_f32 v[152:153], v[30:31], v[120:121], v[152:153]
	v_pk_fma_f32 v[170:171], v[28:29], v[118:119], v[170:171]
	v_pk_fma_f32 v[114:115], v[22:23], v[84:85], v[114:115]
	v_pk_mul_f32 v[172:173], v[24:25], v[94:95]
	v_pk_mul_f32 v[174:175], v[26:27], v[108:109]
	v_pk_fma_f32 v[172:173], v[28:29], v[130:131], v[172:173]
	v_pk_mul_f32 v[176:177], v[24:25], v[106:107]
	s_waitcnt vmcnt(0) lgkmcnt(0)
	v_lshlrev_b32_e32 v43, 16, v92
	v_and_b32_e32 v92, 0xffff0000, v92
	v_lshlrev_b32_e32 v112, 16, v93
	v_and_b32_e32 v93, 0xffff0000, v93
	v_mul_f32_e32 v92, v103, v92
	v_mul_f32_e32 v93, v99, v93
	v_mul_f32_e32 v43, v102, v43
	v_mul_f32_e32 v98, v98, v112
	v_cvt_pk_bf16_f32 v92, v43, v92
	v_cvt_pk_bf16_f32 v93, v98, v93
	flat_store_dwordx2 v[90:91], v[92:93] offset:1024 sc1
	s_nop 1
	v_mov_b64_e32 v[98:99], v[184:185]
	v_pk_mul_f32 v[102:103], v[2:3], v[68:69]
	v_pk_mul_f32 v[112:113], v[0:1], v[66:67]
	v_lshlrev_b32_e32 v90, 16, v146
	v_and_b32_e32 v91, 0xffff0000, v146
	v_lshlrev_b32_e32 v92, 16, v147
	v_and_b32_e32 v93, 0xffff0000, v147
	v_pk_mul_f32 v[146:147], v[12:13], v[70:71]
	v_pk_fma_f32 v[102:103], v[6:7], v[136:137], v[102:103]
	v_pk_fma_f32 v[112:113], v[4:5], v[134:135], v[112:113]
	v_pk_fma_f32 v[146:147], v[16:17], v[122:123], v[146:147]
	v_pk_fma_f32 v[102:103], v[10:11], v[80:81], v[102:103]
	v_pk_fma_f32 v[112:113], v[8:9], v[78:79], v[112:113]
	v_pk_fma_f32 v[146:147], v[20:21], v[82:83], v[146:147]
	v_pk_add_f32 v[102:103], v[38:39], v[102:103]
	v_pk_add_f32 v[112:113], v[36:37], v[112:113]
	v_pk_fma_f32 v[152:153], v[34:35], v[92:93], v[152:153]
	v_pk_fma_f32 v[170:171], v[32:33], v[90:91], v[170:171]
	v_pk_add_f32 v[102:103], v[102:103], v[114:115]
	v_pk_add_f32 v[112:113], v[112:113], v[146:147]
	v_pk_add_f32 v[102:103], v[102:103], v[152:153]
	v_pk_add_f32 v[112:113], v[112:113], v[170:171]
	v_pk_mul_f32 v[114:115], v[102:103], v[102:103]
	v_pk_mul_f32 v[146:147], v[112:113], v[112:113]
	v_pk_fma_f32 v[114:115], v[114:115], s[26:27], v[150:151] op_sel_hi:[1,0,0] neg_lo:[1,0,0] neg_hi:[1,0,0]
	v_pk_fma_f32 v[146:147], v[146:147], s[26:27], v[150:151] op_sel_hi:[1,0,0] neg_lo:[1,0,0] neg_hi:[1,0,0]
	v_pk_mul_f32 v[114:115], v[102:103], v[114:115]
	v_pk_mul_f32 v[146:147], v[112:113], v[146:147]
	v_exp_f32_e32 v114, v114
	v_exp_f32_e32 v146, v146
	v_exp_f32_e32 v147, v147
	v_exp_f32_e32 v115, v115
	v_add_co_u32_e32 v152, vcc, s62, v110
	v_pk_add_f32 v[146:147], v[146:147], 1.0 op_sel_hi:[1,0]
	v_pk_add_f32 v[114:115], v[114:115], 1.0 op_sel_hi:[1,0]
	v_rcp_f32_e32 v146, v146
	v_rcp_f32_e32 v147, v147
	v_rcp_f32_e32 v114, v114
	v_rcp_f32_e32 v115, v115
	v_addc_co_u32_e32 v153, vcc, 0, v111, vcc
	v_pk_mul_f32 v[112:113], v[112:113], v[146:147]
	v_pk_mul_f32 v[102:103], v[102:103], v[114:115]
	v_pk_mul_f32 v[146:147], v[14:15], v[88:89]
	v_pk_mul_f32 v[170:171], v[26:27], v[96:97]
	v_pk_fma_f32 v[146:147], v[18:19], v[120:121], v[146:147]
	v_pk_fma_f32 v[170:171], v[30:31], v[132:133], v[170:171]
	v_pk_fma_f32 v[146:147], v[22:23], v[92:93], v[146:147]
	s_nop 0
	v_lshlrev_b32_e32 v43, 16, v98
	v_and_b32_e32 v98, 0xffff0000, v98
	v_lshlrev_b32_e32 v114, 16, v99
	v_and_b32_e32 v99, 0xffff0000, v99
	v_mul_f32_e32 v98, v113, v98
	v_mul_f32_e32 v99, v103, v99
	v_mul_f32_e32 v43, v112, v43
	v_mul_f32_e32 v102, v102, v114
	v_cvt_pk_bf16_f32 v98, v43, v98
	v_cvt_pk_bf16_f32 v99, v102, v99
	flat_store_dwordx2 v[148:149], v[98:99] offset:1024 sc1
	s_nop 1
	v_mov_b64_e32 v[112:113], v[186:187]
	v_lshlrev_b32_e32 v98, 16, v124
	v_and_b32_e32 v99, 0xffff0000, v124
	v_lshlrev_b32_e32 v102, 16, v125
	v_and_b32_e32 v103, 0xffff0000, v125
	v_pk_mul_f32 v[114:115], v[2:3], v[74:75]
	v_pk_mul_f32 v[124:125], v[0:1], v[70:71]
	v_pk_mul_f32 v[148:149], v[12:13], v[86:87]
	v_pk_fma_f32 v[114:115], v[6:7], v[126:127], v[114:115]
	v_pk_fma_f32 v[124:125], v[4:5], v[122:123], v[124:125]
	v_pk_fma_f32 v[148:149], v[16:17], v[118:119], v[148:149]
	v_pk_fma_f32 v[114:115], v[10:11], v[84:85], v[114:115]
	v_pk_fma_f32 v[124:125], v[8:9], v[82:83], v[124:125]
	v_pk_fma_f32 v[148:149], v[20:21], v[90:91], v[148:149]
	v_pk_add_f32 v[114:115], v[38:39], v[114:115]
	v_pk_add_f32 v[124:125], v[36:37], v[124:125]
	v_pk_fma_f32 v[170:171], v[34:35], v[102:103], v[170:171]
	v_pk_fma_f32 v[172:173], v[32:33], v[98:99], v[172:173]
	v_pk_add_f32 v[114:115], v[114:115], v[146:147]
	v_pk_add_f32 v[124:125], v[124:125], v[148:149]
	v_pk_add_f32 v[114:115], v[114:115], v[170:171]
	v_pk_add_f32 v[124:125], v[124:125], v[172:173]
	v_pk_mul_f32 v[146:147], v[114:115], v[114:115]
	v_pk_mul_f32 v[148:149], v[124:125], v[124:125]
	v_pk_fma_f32 v[146:147], v[146:147], s[26:27], v[150:151] op_sel_hi:[1,0,0] neg_lo:[1,0,0] neg_hi:[1,0,0]
	v_pk_fma_f32 v[148:149], v[148:149], s[26:27], v[150:151] op_sel_hi:[1,0,0] neg_lo:[1,0,0] neg_hi:[1,0,0]
	v_pk_mul_f32 v[146:147], v[114:115], v[146:147]
	v_pk_mul_f32 v[148:149], v[124:125], v[148:149]
	v_exp_f32_e32 v146, v146
	v_exp_f32_e32 v148, v148
	v_exp_f32_e32 v149, v149
	v_exp_f32_e32 v147, v147
	v_add_co_u32_e32 v170, vcc, s62, v100
	v_pk_add_f32 v[148:149], v[148:149], 1.0 op_sel_hi:[1,0]
	v_pk_add_f32 v[146:147], v[146:147], 1.0 op_sel_hi:[1,0]
	v_rcp_f32_e32 v148, v148
	v_rcp_f32_e32 v149, v149
	v_rcp_f32_e32 v146, v146
	v_rcp_f32_e32 v147, v147
	v_addc_co_u32_e32 v171, vcc, 0, v101, vcc
	v_pk_mul_f32 v[124:125], v[124:125], v[148:149]
	v_pk_mul_f32 v[114:115], v[114:115], v[146:147]
	v_mov_b64_e32 v[148:149], v[158:159]
	v_pk_fma_f32 v[158:159], v[30:31], v[140:141], v[174:175]
	v_pk_fma_f32 v[174:175], v[28:29], v[138:139], v[176:177]
	s_nop 0
	v_lshlrev_b32_e32 v43, 16, v112
	v_and_b32_e32 v112, 0xffff0000, v112
	v_lshlrev_b32_e32 v146, 16, v113
	v_and_b32_e32 v113, 0xffff0000, v113
	v_mul_f32_e32 v112, v125, v112
	v_mul_f32_e32 v113, v115, v113
	v_mul_f32_e32 v43, v124, v43
	v_mul_f32_e32 v114, v114, v146
	v_cvt_pk_bf16_f32 v112, v43, v112
	v_cvt_pk_bf16_f32 v113, v114, v113
	flat_store_dwordx2 v[152:153], v[112:113] offset:1024 sc1
	s_nop 1
	v_mov_b64_e32 v[172:173], v[188:189]
	v_lshlrev_b32_e32 v112, 16, v104
	v_and_b32_e32 v113, 0xffff0000, v104
	v_lshlrev_b32_e32 v114, 16, v105
	v_and_b32_e32 v115, 0xffff0000, v105
	v_pk_mul_f32 v[104:105], v[2:3], v[88:89]
	v_pk_mul_f32 v[124:125], v[0:1], v[86:87]
	v_pk_mul_f32 v[146:147], v[14:15], v[96:97]
	v_pk_mul_f32 v[152:153], v[12:13], v[94:95]
	v_pk_fma_f32 v[104:105], v[6:7], v[120:121], v[104:105]
	v_pk_fma_f32 v[124:125], v[4:5], v[118:119], v[124:125]
	v_pk_fma_f32 v[146:147], v[18:19], v[132:133], v[146:147]
	v_pk_fma_f32 v[152:153], v[16:17], v[130:131], v[152:153]
	v_pk_fma_f32 v[104:105], v[10:11], v[92:93], v[104:105]
	v_pk_fma_f32 v[124:125], v[8:9], v[90:91], v[124:125]
	v_pk_fma_f32 v[146:147], v[22:23], v[102:103], v[146:147]
	v_pk_fma_f32 v[152:153], v[20:21], v[98:99], v[152:153]
	v_pk_add_f32 v[104:105], v[38:39], v[104:105]
	v_pk_add_f32 v[124:125], v[36:37], v[124:125]
	v_pk_fma_f32 v[158:159], v[34:35], v[114:115], v[158:159]
	v_pk_fma_f32 v[174:175], v[32:33], v[112:113], v[174:175]
	v_pk_add_f32 v[104:105], v[104:105], v[146:147]
	v_pk_add_f32 v[124:125], v[124:125], v[152:153]
	v_pk_add_f32 v[104:105], v[104:105], v[158:159]
	v_pk_add_f32 v[158:159], v[124:125], v[174:175]
	v_pk_mul_f32 v[124:125], v[104:105], v[104:105]
	v_pk_mul_f32 v[146:147], v[158:159], v[158:159]
	v_pk_fma_f32 v[124:125], v[124:125], s[26:27], v[150:151] op_sel_hi:[1,0,0] neg_lo:[1,0,0] neg_hi:[1,0,0]
	v_pk_fma_f32 v[146:147], v[146:147], s[26:27], v[150:151] op_sel_hi:[1,0,0] neg_lo:[1,0,0] neg_hi:[1,0,0]
	v_pk_mul_f32 v[124:125], v[104:105], v[124:125]
	v_pk_mul_f32 v[146:147], v[158:159], v[146:147]
	v_exp_f32_e32 v124, v124
	v_exp_f32_e32 v146, v146
	v_exp_f32_e32 v147, v147
	v_exp_f32_e32 v125, v125
	v_mov_b64_e32 v[152:153], v[154:155]
	v_mov_b64_e32 v[150:151], v[156:157]
	v_pk_add_f32 v[146:147], v[146:147], 1.0 op_sel_hi:[1,0]
	v_pk_add_f32 v[124:125], v[124:125], 1.0 op_sel_hi:[1,0]
	v_rcp_f32_e32 v154, v146
	v_rcp_f32_e32 v155, v147
	v_rcp_f32_e32 v156, v124
	v_rcp_f32_e32 v157, v125
	v_mov_b64_e32 v[146:147], v[160:161]
	v_pk_mul_f32 v[154:155], v[158:159], v[154:155]
	v_mov_b64_e32 v[124:125], v[162:163]
	v_pk_mul_f32 v[104:105], v[104:105], v[156:157]
	s_nop 0
	v_and_b32_e32 v158, 0xffff0000, v173
	v_lshlrev_b32_e32 v43, 16, v172
	v_and_b32_e32 v156, 0xffff0000, v172
	v_lshlrev_b32_e32 v157, 16, v173
	v_mul_f32_e32 v105, v105, v158
	v_mul_f32_e32 v43, v154, v43
	v_mul_f32_e32 v154, v155, v156
	v_mul_f32_e32 v155, v104, v157
	v_cvt_pk_bf16_f32 v104, v43, v154
	v_cvt_pk_bf16_f32 v105, v155, v105
	flat_store_dwordx2 v[170:171], v[104:105] offset:1024 sc1
	v_mov_b64_e32 v[104:105], v[164:165]

.LBB0_1046:
	s_ashr_i32 s4, s14, 5
	s_mul_hi_i32 s5, s4, 0x6000
	s_mulk_i32 s4, 0x6000
	s_add_u32 s26, s49, s4
	s_addc_u32 s27, s50, s5
	s_lshl_b32 s4, s62, 8
	s_ashr_i32 s5, s4, 31
	s_lshl_b64 s[24:25], s[4:5], 2
	s_add_u32 s24, s26, s24
	s_addc_u32 s25, s27, s25
	s_lshl_b32 s26, s52, 2
	v_mov_b32_e32 v130, v214
	v_mov_b32_e32 v128, v215
	s_add_u32 s26, s24, s26
	s_addc_u32 s27, s25, 0
	s_lshl_b32 s14, s14, 8
	v_lshlrev_b32_e32 v128, 3, v128
	s_add_i32 s14, s14, s51
	s_lshl_b64 s[24:25], s[4:5], 1
	v_ashrrev_i32_e32 v129, 31, v128
	v_add_u32_e32 v144, s14, v130
	s_add_u32 s4, s55, s24
	s_addc_u32 s5, s56, s25
	v_lshlrev_b64 v[202:203], 1, v[128:129]
	v_ashrrev_i32_e32 v145, 31, v144
	v_lshl_add_u64 v[146:147], s[4:5], 0, v[202:203]
	v_lshlrev_b64 v[148:149], 11, v[144:145]
	v_lshl_add_u64 v[130:131], v[146:147], 0, v[148:149]
	flat_load_dwordx4 v[220:223], v[130:131]
	v_add_u32_e32 v150, 16, v144
	v_ashrrev_i32_e32 v151, 31, v150
	v_lshl_add_u64 v[128:129], v[128:129], 2, s[26:27]
	v_lshlrev_b64 v[244:245], 11, v[150:151]
	flat_load_dwordx4 v[140:143], v[128:129]
	flat_load_dwordx4 v[136:139], v[128:129] offset:16
	flat_load_dwordx4 v[224:227], v[130:131] offset:256
	flat_load_dwordx4 v[132:135], v[128:129] offset:512
	s_nop 0
	flat_load_dwordx4 v[128:131], v[128:129] offset:528
	v_lshl_add_u64 v[150:151], v[146:147], 0, v[244:245]
	flat_load_dwordx4 v[228:231], v[150:151]
	flat_load_dwordx4 v[232:235], v[150:151] offset:256
	v_add_u32_e32 v152, 32, v144
	v_add_u32_e32 v154, 48, v144
	v_add_u32_e32 v156, 0x80, v144
	v_add_u32_e32 v158, 0x90, v144
	v_add_u32_e32 v160, 0xa0, v144
	v_add_u32_e32 v144, 0xb0, v144
	v_ashrrev_i32_e32 v153, 31, v152
	v_ashrrev_i32_e32 v155, 31, v154
	v_ashrrev_i32_e32 v157, 31, v156
	v_ashrrev_i32_e32 v159, 31, v158
	v_ashrrev_i32_e32 v161, 31, v160
	v_ashrrev_i32_e32 v145, 31, v144
	v_lshlrev_b64 v[246:247], 11, v[152:153]
	v_lshlrev_b64 v[212:213], 11, v[154:155]
	v_lshlrev_b64 v[210:211], 11, v[156:157]
	v_lshlrev_b64 v[208:209], 11, v[158:159]
	v_lshlrev_b64 v[206:207], 11, v[160:161]
	v_lshlrev_b64 v[204:205], 11, v[144:145]
	v_lshl_add_u64 v[144:145], s[18:19], 0, v[148:149]
	v_lshl_add_u64 v[148:149], v[146:147], 0, v[246:247]
	v_lshl_add_u64 v[150:151], v[146:147], 0, v[212:213]
	v_lshl_add_u64 v[152:153], v[146:147], 0, v[210:211]
	v_lshl_add_u64 v[154:155], v[146:147], 0, v[208:209]
	v_lshl_add_u64 v[248:249], v[146:147], 0, v[206:207]
	v_lshl_add_u64 v[146:147], v[146:147], 0, v[204:205]
	v_lshl_add_u64 v[250:251], v[144:145], 0, s[24:25]
	flat_load_dwordx4 v[236:239], v[148:149]
	flat_load_dwordx4 v[240:243], v[148:149] offset:256
	flat_load_dwordx4 v[180:183], v[150:151]
	flat_load_dwordx4 v[176:179], v[150:151] offset:256
	flat_load_dwordx4 v[172:175], v[152:153]
	flat_load_dwordx4 v[168:171], v[152:153] offset:256
	flat_load_dwordx4 v[164:167], v[154:155]
	flat_load_dwordx4 v[160:163], v[154:155] offset:256
	flat_load_dwordx4 v[156:159], v[248:249]
	s_nop 0
	flat_load_dwordx4 v[152:155], v[248:249] offset:256
	flat_load_dwordx4 v[148:151], v[146:147]
	s_nop 0
	flat_load_dwordx4 v[144:147], v[146:147] offset:256
	s_lshl_b32 s14, s52, 1
	v_lshl_add_u64 v[248:249], v[250:251], 0, s[14:15]
	s_and_b64 vcc, exec, s[6:7]
	s_mov_b64 s[6:7], -1
	s_waitcnt vmcnt(0) lgkmcnt(0)
	v_lshlrev_b32_e32 v250, 16, v220
	v_and_b32_e32 v251, 0xffff0000, v220
	v_lshlrev_b32_e32 v220, 16, v221
	v_and_b32_e32 v221, 0xffff0000, v221
	v_lshlrev_b32_e32 v252, 16, v222
	v_and_b32_e32 v253, 0xffff0000, v222
	v_lshlrev_b32_e32 v222, 16, v223
	v_and_b32_e32 v223, 0xffff0000, v223
	v_pk_fma_f32 v[126:127], v[126:127], v[142:143], v[220:221]
	v_pk_fma_f32 v[124:125], v[124:125], v[140:141], v[250:251]
	v_pk_fma_f32 v[220:221], v[122:123], v[138:139], v[222:223]
	v_pk_fma_f32 v[122:123], v[120:121], v[136:137], v[252:253]
	v_cvt_pk_bf16_f32 v120, v124, v125
	v_cvt_pk_bf16_f32 v121, v126, v127
	v_lshl_add_u64 v[124:125], v[248:249], 0, v[202:203]
	v_cvt_pk_bf16_f32 v122, v122, v123
	v_cvt_pk_bf16_f32 v123, v220, v221
	flat_store_dwordx4 v[124:125], v[120:123] sc1
	v_lshlrev_b32_e32 v126, 16, v226
	v_and_b32_e32 v127, 0xffff0000, v226
	v_lshlrev_b32_e32 v120, 16, v224
	v_and_b32_e32 v121, 0xffff0000, v224
	v_lshlrev_b32_e32 v122, 16, v225
	v_and_b32_e32 v123, 0xffff0000, v225
	v_lshlrev_b32_e32 v220, 16, v227
	v_and_b32_e32 v221, 0xffff0000, v227
	v_pk_fma_f32 v[118:119], v[118:119], v[134:135], v[122:123]
	v_pk_fma_f32 v[116:117], v[116:117], v[132:133], v[120:121]
	v_pk_fma_f32 v[120:121], v[114:115], v[130:131], v[220:221]
	v_pk_fma_f32 v[114:115], v[112:113], v[128:129], v[126:127]
	v_cvt_pk_bf16_f32 v112, v116, v117
	v_cvt_pk_bf16_f32 v113, v118, v119
	v_lshlrev_b32_e32 v116, 16, v230
	v_cvt_pk_bf16_f32 v114, v114, v115
	v_cvt_pk_bf16_f32 v115, v120, v121
	flat_store_dwordx4 v[124:125], v[112:115] offset:256 sc1
	v_and_b32_e32 v117, 0xffff0000, v230
	v_lshlrev_b32_e32 v118, 16, v231
	v_lshlrev_b32_e32 v112, 16, v228
	v_and_b32_e32 v113, 0xffff0000, v228
	v_and_b32_e32 v119, 0xffff0000, v231
	v_pk_fma_f32 v[108:109], v[108:109], v[140:141], v[112:113]
	v_pk_fma_f32 v[112:113], v[106:107], v[138:139], v[118:119]
	v_pk_fma_f32 v[106:107], v[104:105], v[136:137], v[116:117]
	v_cvt_pk_bf16_f32 v104, v108, v109
	v_lshl_add_u64 v[108:109], s[18:19], 0, v[244:245]
	v_lshl_add_u64 v[108:109], v[108:109], 0, s[24:25]
	v_lshlrev_b32_e32 v114, 16, v229
	v_and_b32_e32 v115, 0xffff0000, v229
	v_lshl_add_u64 v[108:109], v[108:109], 0, s[14:15]
	v_pk_fma_f32 v[110:111], v[110:111], v[142:143], v[114:115]
	v_cvt_pk_bf16_f32 v106, v106, v107
	v_cvt_pk_bf16_f32 v107, v112, v113
	v_lshl_add_u64 v[108:109], v[108:109], 0, v[202:203]
	v_cvt_pk_bf16_f32 v105, v110, v111
	flat_store_dwordx4 v[108:109], v[104:107] sc1
	v_lshlrev_b32_e32 v110, 16, v234
	v_and_b32_e32 v111, 0xffff0000, v234
	v_lshlrev_b32_e32 v104, 16, v232
	v_and_b32_e32 v105, 0xffff0000, v232
	v_lshlrev_b32_e32 v106, 16, v233
	v_and_b32_e32 v107, 0xffff0000, v233
	v_lshlrev_b32_e32 v112, 16, v235
	v_and_b32_e32 v113, 0xffff0000, v235
	v_pk_fma_f32 v[102:103], v[102:103], v[134:135], v[106:107]
	v_pk_fma_f32 v[100:101], v[100:101], v[132:133], v[104:105]
	v_pk_fma_f32 v[104:105], v[98:99], v[130:131], v[112:113]
	v_pk_fma_f32 v[98:99], v[96:97], v[128:129], v[110:111]
	v_cvt_pk_bf16_f32 v96, v100, v101
	v_cvt_pk_bf16_f32 v97, v102, v103
	v_lshlrev_b32_e32 v100, 16, v238
	v_cvt_pk_bf16_f32 v98, v98, v99
	v_cvt_pk_bf16_f32 v99, v104, v105
	flat_store_dwordx4 v[108:109], v[96:99] offset:256 sc1
	v_and_b32_e32 v101, 0xffff0000, v238
	v_lshlrev_b32_e32 v102, 16, v239
	v_lshlrev_b32_e32 v96, 16, v236
	v_and_b32_e32 v97, 0xffff0000, v236
	v_and_b32_e32 v103, 0xffff0000, v239
	v_pk_fma_f32 v[92:93], v[92:93], v[140:141], v[96:97]
	v_pk_fma_f32 v[96:97], v[90:91], v[138:139], v[102:103]
	v_pk_fma_f32 v[90:91], v[88:89], v[136:137], v[100:101]
	v_cvt_pk_bf16_f32 v88, v92, v93
	v_lshl_add_u64 v[92:93], s[18:19], 0, v[246:247]
	v_lshl_add_u64 v[92:93], v[92:93], 0, s[24:25]
	v_lshlrev_b32_e32 v98, 16, v237
	v_and_b32_e32 v99, 0xffff0000, v237
	v_lshl_add_u64 v[92:93], v[92:93], 0, s[14:15]
	v_pk_fma_f32 v[94:95], v[94:95], v[142:143], v[98:99]
	v_cvt_pk_bf16_f32 v90, v90, v91
	v_cvt_pk_bf16_f32 v91, v96, v97
	v_lshl_add_u64 v[92:93], v[92:93], 0, v[202:203]
	v_cvt_pk_bf16_f32 v89, v94, v95
	flat_store_dwordx4 v[92:93], v[88:91] sc1
	v_lshlrev_b32_e32 v94, 16, v242
	v_and_b32_e32 v95, 0xffff0000, v242
	v_lshlrev_b32_e32 v88, 16, v240
	v_and_b32_e32 v89, 0xffff0000, v240
	v_lshlrev_b32_e32 v90, 16, v241
	v_and_b32_e32 v91, 0xffff0000, v241
	v_lshlrev_b32_e32 v96, 16, v243
	v_and_b32_e32 v97, 0xffff0000, v243
	v_pk_fma_f32 v[86:87], v[86:87], v[134:135], v[90:91]
	v_pk_fma_f32 v[84:85], v[84:85], v[132:133], v[88:89]
	v_pk_fma_f32 v[88:89], v[82:83], v[130:131], v[96:97]
	v_pk_fma_f32 v[82:83], v[80:81], v[128:129], v[94:95]
	v_cvt_pk_bf16_f32 v80, v84, v85
	v_cvt_pk_bf16_f32 v81, v86, v87
	v_lshlrev_b32_e32 v84, 16, v182
	v_cvt_pk_bf16_f32 v82, v82, v83
	v_cvt_pk_bf16_f32 v83, v88, v89
	flat_store_dwordx4 v[92:93], v[80:83] offset:256 sc1
	v_and_b32_e32 v85, 0xffff0000, v182
	v_lshlrev_b32_e32 v86, 16, v183
	v_lshlrev_b32_e32 v80, 16, v180
	v_and_b32_e32 v81, 0xffff0000, v180
	v_and_b32_e32 v87, 0xffff0000, v183
	v_pk_fma_f32 v[76:77], v[76:77], v[140:141], v[80:81]
	v_pk_fma_f32 v[80:81], v[74:75], v[138:139], v[86:87]
	v_pk_fma_f32 v[74:75], v[72:73], v[136:137], v[84:85]
	v_cvt_pk_bf16_f32 v72, v76, v77
	v_lshl_add_u64 v[76:77], s[18:19], 0, v[212:213]
	v_lshl_add_u64 v[76:77], v[76:77], 0, s[24:25]
	v_lshlrev_b32_e32 v82, 16, v181
	v_and_b32_e32 v83, 0xffff0000, v181
	v_lshl_add_u64 v[76:77], v[76:77], 0, s[14:15]
	v_pk_fma_f32 v[78:79], v[78:79], v[142:143], v[82:83]
	v_cvt_pk_bf16_f32 v74, v74, v75
	v_cvt_pk_bf16_f32 v75, v80, v81
	v_lshl_add_u64 v[76:77], v[76:77], 0, v[202:203]
	v_cvt_pk_bf16_f32 v73, v78, v79
	flat_store_dwordx4 v[76:77], v[72:75] sc1
	v_lshlrev_b32_e32 v78, 16, v178
	v_and_b32_e32 v79, 0xffff0000, v178
	v_lshlrev_b32_e32 v72, 16, v176
	v_and_b32_e32 v73, 0xffff0000, v176
	v_lshlrev_b32_e32 v74, 16, v177
	v_and_b32_e32 v75, 0xffff0000, v177
	v_lshlrev_b32_e32 v80, 16, v179
	v_and_b32_e32 v81, 0xffff0000, v179
	v_pk_fma_f32 v[70:71], v[70:71], v[134:135], v[74:75]
	v_pk_fma_f32 v[68:69], v[68:69], v[132:133], v[72:73]
	v_pk_fma_f32 v[72:73], v[66:67], v[130:131], v[80:81]
	v_pk_fma_f32 v[66:67], v[64:65], v[128:129], v[78:79]
	v_cvt_pk_bf16_f32 v64, v68, v69
	v_cvt_pk_bf16_f32 v65, v70, v71
	v_lshlrev_b32_e32 v68, 16, v174
	v_cvt_pk_bf16_f32 v66, v66, v67
	v_cvt_pk_bf16_f32 v67, v72, v73
	flat_store_dwordx4 v[76:77], v[64:67] offset:256 sc1
	v_and_b32_e32 v69, 0xffff0000, v174
	v_lshlrev_b32_e32 v70, 16, v175
	v_lshlrev_b32_e32 v64, 16, v172
	v_and_b32_e32 v65, 0xffff0000, v172
	v_and_b32_e32 v71, 0xffff0000, v175
	v_pk_fma_f32 v[60:61], v[60:61], v[140:141], v[64:65]
	v_pk_fma_f32 v[64:65], v[58:59], v[138:139], v[70:71]
	v_pk_fma_f32 v[58:59], v[56:57], v[136:137], v[68:69]
	v_cvt_pk_bf16_f32 v56, v60, v61
	v_lshl_add_u64 v[60:61], s[18:19], 0, v[210:211]
	v_lshl_add_u64 v[60:61], v[60:61], 0, s[24:25]
	v_lshlrev_b32_e32 v66, 16, v173
	v_and_b32_e32 v67, 0xffff0000, v173
	v_lshl_add_u64 v[60:61], v[60:61], 0, s[14:15]
	v_pk_fma_f32 v[62:63], v[62:63], v[142:143], v[66:67]
	v_cvt_pk_bf16_f32 v58, v58, v59
	v_cvt_pk_bf16_f32 v59, v64, v65
	v_lshl_add_u64 v[60:61], v[60:61], 0, v[202:203]
	v_cvt_pk_bf16_f32 v57, v62, v63
	flat_store_dwordx4 v[60:61], v[56:59] sc1
	v_lshlrev_b32_e32 v62, 16, v170
	v_and_b32_e32 v63, 0xffff0000, v170
	v_lshlrev_b32_e32 v56, 16, v168
	v_and_b32_e32 v57, 0xffff0000, v168
	v_lshlrev_b32_e32 v58, 16, v169
	v_and_b32_e32 v59, 0xffff0000, v169
	v_lshlrev_b32_e32 v64, 16, v171
	v_and_b32_e32 v65, 0xffff0000, v171
	v_pk_fma_f32 v[54:55], v[54:55], v[134:135], v[58:59]
	v_pk_fma_f32 v[52:53], v[52:53], v[132:133], v[56:57]
	v_pk_fma_f32 v[56:57], v[50:51], v[130:131], v[64:65]
	v_pk_fma_f32 v[50:51], v[48:49], v[128:129], v[62:63]
	v_cvt_pk_bf16_f32 v48, v52, v53
	v_cvt_pk_bf16_f32 v49, v54, v55
	v_lshlrev_b32_e32 v52, 16, v166
	v_cvt_pk_bf16_f32 v50, v50, v51
	v_cvt_pk_bf16_f32 v51, v56, v57
	flat_store_dwordx4 v[60:61], v[48:51] offset:256 sc1
	v_and_b32_e32 v53, 0xffff0000, v166
	v_lshlrev_b32_e32 v54, 16, v167
	v_lshlrev_b32_e32 v48, 16, v164
	v_and_b32_e32 v49, 0xffff0000, v164
	v_and_b32_e32 v55, 0xffff0000, v167
	v_pk_fma_f32 v[44:45], v[44:45], v[140:141], v[48:49]
	v_pk_fma_f32 v[48:49], v[42:43], v[138:139], v[54:55]
	v_pk_fma_f32 v[42:43], v[40:41], v[136:137], v[52:53]
	v_cvt_pk_bf16_f32 v40, v44, v45
	v_lshl_add_u64 v[44:45], s[18:19], 0, v[208:209]
	v_lshl_add_u64 v[44:45], v[44:45], 0, s[24:25]
	v_lshlrev_b32_e32 v50, 16, v165
	v_and_b32_e32 v51, 0xffff0000, v165
	v_lshl_add_u64 v[44:45], v[44:45], 0, s[14:15]
	v_pk_fma_f32 v[46:47], v[46:47], v[142:143], v[50:51]
	v_cvt_pk_bf16_f32 v42, v42, v43
	v_cvt_pk_bf16_f32 v43, v48, v49
	v_lshl_add_u64 v[44:45], v[44:45], 0, v[202:203]
	v_cvt_pk_bf16_f32 v41, v46, v47
	flat_store_dwordx4 v[44:45], v[40:43] sc1
	v_lshlrev_b32_e32 v46, 16, v162
	v_and_b32_e32 v47, 0xffff0000, v162
	v_lshlrev_b32_e32 v40, 16, v160
	v_and_b32_e32 v41, 0xffff0000, v160
	v_lshlrev_b32_e32 v42, 16, v161
	v_and_b32_e32 v43, 0xffff0000, v161
	v_lshlrev_b32_e32 v48, 16, v163
	v_and_b32_e32 v49, 0xffff0000, v163
	v_pk_fma_f32 v[38:39], v[38:39], v[134:135], v[42:43]
	v_pk_fma_f32 v[36:37], v[36:37], v[132:133], v[40:41]
	v_pk_fma_f32 v[40:41], v[34:35], v[130:131], v[48:49]
	v_pk_fma_f32 v[34:35], v[32:33], v[128:129], v[46:47]
	v_cvt_pk_bf16_f32 v32, v36, v37
	v_cvt_pk_bf16_f32 v33, v38, v39
	v_lshlrev_b32_e32 v36, 16, v158
	v_cvt_pk_bf16_f32 v34, v34, v35
	v_cvt_pk_bf16_f32 v35, v40, v41
	flat_store_dwordx4 v[44:45], v[32:35] offset:256 sc1
	v_and_b32_e32 v37, 0xffff0000, v158
	v_lshlrev_b32_e32 v38, 16, v159
	v_lshlrev_b32_e32 v32, 16, v156
	v_and_b32_e32 v33, 0xffff0000, v156
	v_and_b32_e32 v39, 0xffff0000, v159
	v_pk_fma_f32 v[28:29], v[28:29], v[140:141], v[32:33]
	v_pk_fma_f32 v[32:33], v[26:27], v[138:139], v[38:39]
	v_pk_fma_f32 v[26:27], v[24:25], v[136:137], v[36:37]
	v_cvt_pk_bf16_f32 v24, v28, v29
	v_lshl_add_u64 v[28:29], s[18:19], 0, v[206:207]
	v_lshl_add_u64 v[28:29], v[28:29], 0, s[24:25]
	v_lshlrev_b32_e32 v34, 16, v157
	v_and_b32_e32 v35, 0xffff0000, v157
	v_lshl_add_u64 v[28:29], v[28:29], 0, s[14:15]
	v_pk_fma_f32 v[30:31], v[30:31], v[142:143], v[34:35]
	v_cvt_pk_bf16_f32 v26, v26, v27
	v_cvt_pk_bf16_f32 v27, v32, v33
	v_lshl_add_u64 v[28:29], v[28:29], 0, v[202:203]
	v_cvt_pk_bf16_f32 v25, v30, v31
	flat_store_dwordx4 v[28:29], v[24:27] sc1
	v_lshlrev_b32_e32 v30, 16, v154
	v_and_b32_e32 v31, 0xffff0000, v154
	v_lshlrev_b32_e32 v24, 16, v152
	v_and_b32_e32 v25, 0xffff0000, v152
	v_lshlrev_b32_e32 v26, 16, v153
	v_and_b32_e32 v27, 0xffff0000, v153
	v_lshlrev_b32_e32 v32, 16, v155
	v_and_b32_e32 v33, 0xffff0000, v155
	v_pk_fma_f32 v[22:23], v[22:23], v[134:135], v[26:27]
	v_pk_fma_f32 v[20:21], v[20:21], v[132:133], v[24:25]
	v_pk_fma_f32 v[24:25], v[18:19], v[130:131], v[32:33]
	v_pk_fma_f32 v[18:19], v[16:17], v[128:129], v[30:31]
	v_cvt_pk_bf16_f32 v16, v20, v21
	v_cvt_pk_bf16_f32 v17, v22, v23
	v_lshlrev_b32_e32 v20, 16, v150
	v_cvt_pk_bf16_f32 v18, v18, v19
	v_cvt_pk_bf16_f32 v19, v24, v25
	flat_store_dwordx4 v[28:29], v[16:19] offset:256 sc1
	v_and_b32_e32 v21, 0xffff0000, v150
	v_lshlrev_b32_e32 v22, 16, v151
	v_lshlrev_b32_e32 v16, 16, v148
	v_and_b32_e32 v17, 0xffff0000, v148
	v_and_b32_e32 v23, 0xffff0000, v151
	v_pk_fma_f32 v[12:13], v[12:13], v[140:141], v[16:17]
	v_pk_fma_f32 v[16:17], v[10:11], v[138:139], v[22:23]
	v_pk_fma_f32 v[10:11], v[8:9], v[136:137], v[20:21]
	v_cvt_pk_bf16_f32 v8, v12, v13
	v_lshl_add_u64 v[12:13], s[18:19], 0, v[204:205]
	v_lshl_add_u64 v[12:13], v[12:13], 0, s[24:25]
	v_lshlrev_b32_e32 v18, 16, v149
	v_and_b32_e32 v19, 0xffff0000, v149
	v_lshl_add_u64 v[12:13], v[12:13], 0, s[14:15]
	v_pk_fma_f32 v[14:15], v[14:15], v[142:143], v[18:19]
	v_lshl_add_u64 v[12:13], v[12:13], 0, v[202:203]
	v_cvt_pk_bf16_f32 v9, v14, v15
	v_cvt_pk_bf16_f32 v10, v10, v11
	v_cvt_pk_bf16_f32 v11, v16, v17
	flat_store_dwordx4 v[12:13], v[8:11] sc1
	v_lshlrev_b32_e32 v14, 16, v146
	v_and_b32_e32 v15, 0xffff0000, v146
	v_lshlrev_b32_e32 v8, 16, v144
	v_and_b32_e32 v9, 0xffff0000, v144
	v_lshlrev_b32_e32 v16, 16, v147
	v_and_b32_e32 v17, 0xffff0000, v147
	v_lshlrev_b32_e32 v10, 16, v145
	v_and_b32_e32 v11, 0xffff0000, v145
	v_pk_fma_f32 v[4:5], v[4:5], v[132:133], v[8:9]
	v_pk_fma_f32 v[8:9], v[2:3], v[130:131], v[16:17]
	v_pk_fma_f32 v[2:3], v[0:1], v[128:129], v[14:15]
	v_pk_fma_f32 v[6:7], v[6:7], v[134:135], v[10:11]
	v_cvt_pk_bf16_f32 v0, v4, v5
	v_cvt_pk_bf16_f32 v2, v2, v3
	v_cvt_pk_bf16_f32 v3, v8, v9
	s_nop 0
	v_cvt_pk_bf16_f32 v1, v6, v7
	flat_store_dwordx4 v[12:13], v[0:3] offset:256 sc1
	s_cbranch_vccnz .LBB0_1031
	s_andn2_b64 vcc, exec, s[16:17]
	s_cbranch_vccnz .LBB0_1030
	s_barrier
	s_branch .LBB0_1030

.LBB0_1099:
	v_ashrrev_i32_e32 v17, 31, v16
	v_lshlrev_b64 v[30:31], 11, v[16:17]
	v_lshl_add_u64 v[38:39], v[18:19], 0, v[30:31]
	flat_load_dwordx4 v[30:33], v[38:39]
	flat_load_dwordx4 v[34:37], v[38:39] offset:1024
	s_waitcnt vmcnt(0) lgkmcnt(0)
	v_and_b32_e32 v41, 0xffff0000, v32
	v_and_b32_e32 v40, 0xffff0000, v30
	v_lshlrev_b32_e32 v39, 16, v32
	v_lshlrev_b32_e32 v38, 16, v30
	v_lshlrev_b32_e32 v42, 16, v31
	v_and_b32_e32 v32, 0xffff0000, v31
	v_lshlrev_b32_e32 v31, 16, v34
	v_lshlrev_b32_e32 v30, 16, v36
	v_and_b32_e32 v45, 0xffff0000, v34
	v_and_b32_e32 v44, 0xffff0000, v36
	v_lshlrev_b32_e32 v46, 16, v37
	v_and_b32_e32 v34, 0xffff0000, v37
	v_pk_mul_f32 v[36:37], v[40:41], v[40:41]
	v_lshlrev_b32_e32 v43, 16, v33
	v_pk_mul_f32 v[48:49], v[44:45], v[44:45]
	v_pk_fma_f32 v[36:37], v[38:39], v[38:39], v[36:37]
	v_and_b32_e32 v33, 0xffff0000, v33
	v_lshlrev_b32_e32 v47, 16, v35
	v_pk_fma_f32 v[48:49], v[30:31], v[30:31], v[48:49]
	v_pk_fma_f32 v[36:37], v[42:43], v[42:43], v[36:37]
	v_and_b32_e32 v35, 0xffff0000, v35
	v_pk_fma_f32 v[48:49], v[46:47], v[46:47], v[48:49]
	v_pk_fma_f32 v[36:37], v[32:33], v[32:33], v[36:37]
	v_pk_fma_f32 v[48:49], v[34:35], v[34:35], v[48:49]
	v_add_f32_e32 v29, v36, v37
	v_add_f32_e32 v29, v29, v49
	v_add_f32_e32 v29, v48, v29
	ds_bpermute_b32 v36, v22, v29
	v_mov_b32_e32 v50, v42
	v_mov_b32_e32 v51, v32
	v_mov_b32_e32 v52, v47
	v_mov_b32_e32 v47, v34
	s_waitcnt lgkmcnt(0)
	v_add_f32_e32 v29, v29, v36
	ds_bpermute_b32 v36, v23, v29
	v_mov_b32_e32 v53, v35
	v_mov_b32_e32 v32, v43
	s_waitcnt lgkmcnt(0)
	v_add_f32_e32 v29, v29, v36
	ds_bpermute_b32 v48, v24, v29
	v_lshlrev_b64 v[36:37], 12, v[16:17]
	v_add_u32_e32 v16, s2, v16
	v_cmp_lt_i32_e32 vcc, s4, v16
	s_or_b64 s[0:1], vcc, s[0:1]
	s_waitcnt lgkmcnt(0)
	v_add_f32_e32 v17, v29, v48
	ds_bpermute_b32 v29, v25, v17
	v_lshl_add_u64 v[48:49], v[20:21], 0, v[36:37]
	v_mov_b32_e32 v36, v38
	v_mov_b32_e32 v37, v40
	v_mov_b32_e32 v40, v39
	s_waitcnt lgkmcnt(0)
	v_add_f32_e32 v17, v17, v29
	ds_bpermute_b32 v29, v26, v17
	v_mov_b32_e32 v38, v31
	v_mov_b32_e32 v39, v45
	v_mov_b32_e32 v31, v44
	s_waitcnt lgkmcnt(0)
	v_add_f32_e32 v17, v17, v29
	ds_bpermute_b32 v29, v27, v17
	s_waitcnt lgkmcnt(0)
	v_add_f32_e32 v17, v17, v29
	v_fmamk_f32 v17, v17, 0x3a800000, v28
	v_mul_f32_e32 v29, 0x4b800000, v17
	v_cmp_gt_f32_e32 vcc, s3, v17
	s_nop 1
	v_cndmask_b32_e32 v17, v17, v29, vcc
	v_rsq_f32_e32 v17, v17
	s_nop 0
	v_mul_f32_e32 v29, 0x45800000, v17
	v_cndmask_b32_e32 v34, v17, v29, vcc
	v_pk_mul_f32 v[36:37], v[36:37], v[34:35] op_sel_hi:[1,0]
	v_pk_mul_f32 v[42:43], v[50:51], v[34:35] op_sel_hi:[1,0]
	v_pk_mul_f32 v[40:41], v[40:41], v[34:35] op_sel_hi:[1,0]
	v_pk_mul_f32 v[44:45], v[32:33], v[34:35] op_sel_hi:[1,0]
	v_pk_mul_f32 v[38:39], v[38:39], v[34:35] op_sel_hi:[1,0]
	v_pk_mul_f32 v[50:51], v[52:53], v[34:35] op_sel_hi:[1,0]
	v_pk_mul_f32 v[52:53], v[30:31], v[34:35] op_sel_hi:[1,0]
	v_pk_mul_f32 v[46:47], v[46:47], v[34:35] op_sel_hi:[1,0]
	v_pk_mul_f32 v[32:33], v[2:3], v[42:43]
	v_pk_mul_f32 v[30:31], v[0:1], v[36:37]
	v_pk_mul_f32 v[36:37], v[6:7], v[44:45]
	v_pk_mul_f32 v[34:35], v[4:5], v[40:41]
	v_pk_mul_f32 v[40:41], v[10:11], v[50:51]
	v_pk_mul_f32 v[38:39], v[8:9], v[38:39]
	v_pk_mul_f32 v[44:45], v[14:15], v[46:47]
	v_pk_mul_f32 v[42:43], v[12:13], v[52:53]
	flat_store_dwordx4 v[48:49], v[30:33] nt sc1
	flat_store_dwordx4 v[48:49], v[34:37] offset:16 nt sc1
	flat_store_dwordx4 v[48:49], v[38:41] offset:2048 nt sc1
	flat_store_dwordx4 v[48:49], v[42:45] offset:2064 nt sc1
	s_andn2_b64 exec, exec, s[0:1]
	s_cbranch_execnz .LBB0_1099
